# adds counted vmcnt waits at first consumers in EpiRes epilogues (no full drains), PG coalescing, barrier after initial loads
# speedup vs baseline: 1.0299x; 1.0086x over previous
.LBB0_250:
	ds_read_b128 v[128:131], v173
	ds_read_b128 v[132:135], v173 offset:1024
	ds_read_b128 v[136:139], v173 offset:2048
	ds_read_b128 v[140:143], v173 offset:3072
	ds_read_b128 v[156:159], v174
	ds_read_b128 v[160:163], v174 offset:1024
	ds_read_b128 v[164:167], v174 offset:2048
	ds_read_b128 v[178:181], v174 offset:3072
	s_add_u32 s56, s54, 0x100
	s_addc_u32 s57, s55, 0
	s_cmp_eq_u32 s86, 40
	s_cselect_b32 s61, s5, s57
	s_cselect_b32 s60, s4, s56
	s_cselect_b32 s59, s53, s85
	s_cselect_b32 s58, s52, s84
	v_lshl_add_u64 v[168:169], s[54:55], 0, v[150:151]
	s_add_i32 m0, s67, 0xc000
	ds_read_b128 v[182:185], v175
	ds_read_b128 v[186:189], v175 offset:1024
	ds_read_b128 v[192:195], v175 offset:2048
	ds_read_b128 v[196:199], v175 offset:3072
	ds_read_b128 v[200:203], v175 offset:4096
	ds_read_b128 v[204:207], v175 offset:5120
	ds_read_b128 v[208:211], v175 offset:6144
	ds_read_b128 v[212:215], v175 offset:7168
	global_load_lds_dwordx4 v[168:169], off
	v_lshl_add_u64 v[168:169], s[54:55], 0, v[148:149]
	s_add_i32 m0, s67, 0xe000
	s_nop 0
	global_load_lds_dwordx4 v[168:169], off
	s_waitcnt vmcnt(8)
	s_waitcnt lgkmcnt(0)
	s_barrier
	s_setprio 1
	s_waitcnt lgkmcnt(0)
	v_mfma_f32_16x16x32_bf16 v[124:127], v[128:131], v[182:185], v[124:127]
	v_mfma_f32_16x16x32_bf16 v[120:123], v[136:139], v[182:185], v[120:123]
	v_mfma_f32_16x16x32_bf16 v[108:111], v[128:131], v[192:195], v[108:111]
	v_mfma_f32_16x16x32_bf16 v[104:107], v[136:139], v[192:195], v[104:107]
	v_mfma_f32_16x16x32_bf16 v[92:95], v[128:131], v[200:203], v[92:95]
	v_mfma_f32_16x16x32_bf16 v[88:91], v[136:139], v[200:203], v[88:91]
	v_mfma_f32_16x16x32_bf16 v[76:79], v[128:131], v[208:211], v[76:79]
	v_mfma_f32_16x16x32_bf16 v[72:75], v[136:139], v[208:211], v[72:75]
	v_mfma_f32_16x16x32_bf16 v[124:127], v[132:135], v[186:189], v[124:127]
	v_mfma_f32_16x16x32_bf16 v[120:123], v[140:143], v[186:189], v[120:123]
	v_mfma_f32_16x16x32_bf16 v[108:111], v[132:135], v[196:199], v[108:111]
	v_mfma_f32_16x16x32_bf16 v[104:107], v[140:143], v[196:199], v[104:107]
	v_mfma_f32_16x16x32_bf16 v[92:95], v[132:135], v[204:207], v[92:95]
	v_mfma_f32_16x16x32_bf16 v[88:91], v[140:143], v[204:207], v[88:91]
	v_mfma_f32_16x16x32_bf16 v[76:79], v[132:135], v[212:215], v[76:79]
	v_mfma_f32_16x16x32_bf16 v[72:75], v[140:143], v[212:215], v[72:75]
	s_setprio 0
	s_setprio 1
	v_mfma_f32_16x16x32_bf16 v[116:119], v[156:159], v[182:185], v[116:119]
	v_mfma_f32_16x16x32_bf16 v[112:115], v[164:167], v[182:185], v[112:115]
	v_mfma_f32_16x16x32_bf16 v[100:103], v[156:159], v[192:195], v[100:103]
	v_mfma_f32_16x16x32_bf16 v[96:99], v[164:167], v[192:195], v[96:99]
	v_mfma_f32_16x16x32_bf16 v[84:87], v[156:159], v[200:203], v[84:87]
	v_mfma_f32_16x16x32_bf16 v[80:83], v[164:167], v[200:203], v[80:83]
	v_mfma_f32_16x16x32_bf16 v[68:71], v[156:159], v[208:211], v[68:71]
	v_mfma_f32_16x16x32_bf16 v[64:67], v[164:167], v[208:211], v[64:67]
	v_mfma_f32_16x16x32_bf16 v[116:119], v[160:163], v[186:189], v[116:119]
	v_mfma_f32_16x16x32_bf16 v[112:115], v[178:181], v[186:189], v[112:115]
	v_mfma_f32_16x16x32_bf16 v[100:103], v[160:163], v[196:199], v[100:103]
	v_mfma_f32_16x16x32_bf16 v[96:99], v[178:181], v[196:199], v[96:99]
	v_mfma_f32_16x16x32_bf16 v[84:87], v[160:163], v[204:207], v[84:87]
	v_mfma_f32_16x16x32_bf16 v[80:83], v[178:181], v[204:207], v[80:83]
	v_mfma_f32_16x16x32_bf16 v[68:71], v[160:163], v[212:215], v[68:71]
	v_mfma_f32_16x16x32_bf16 v[64:67], v[178:181], v[212:215], v[64:67]
	s_setprio 0
	s_barrier
	s_add_i32 s54, s79, s66
	v_lshl_add_u64 v[168:169], s[58:59], 0, v[144:145]
	s_mov_b32 m0, s54
	ds_read_b128 v[182:185], v175 offset:16384
	ds_read_b128 v[186:189], v175 offset:17408
	ds_read_b128 v[192:195], v175 offset:18432
	ds_read_b128 v[196:199], v175 offset:19456
	ds_read_b128 v[200:203], v175 offset:20480
	ds_read_b128 v[204:207], v175 offset:21504
	ds_read_b128 v[208:211], v175 offset:22528
	ds_read_b128 v[212:215], v175 offset:23552
	global_load_lds_dwordx4 v[168:169], off
	s_add_i32 m0, s54, 0x2000
	s_add_u32 s54, s58, 0xb0000
	v_lshl_add_u64 v[216:217], s[58:59], 0, v[146:147]
	s_addc_u32 s55, s59, 0
	s_add_i32 s87, s80, s66
	global_load_lds_dwordx4 v[216:217], off
	v_lshl_add_u64 v[218:219], s[54:55], 0, v[144:145]
	s_mov_b32 m0, s87
	v_lshl_add_u64 v[220:221], s[60:61], 0, v[146:147]
	global_load_lds_dwordx4 v[218:219], off
	v_lshl_add_u64 v[218:219], s[54:55], 0, v[146:147]
	s_add_i32 m0, s87, 0x2000
	s_nop 0
	global_load_lds_dwordx4 v[218:219], off
	v_lshl_add_u64 v[218:219], s[60:61], 0, v[144:145]
	s_mov_b32 m0, s67
	s_nop 0
	global_load_lds_dwordx4 v[218:219], off
	s_mov_b32 m0, s68
	s_nop 0
	global_load_lds_dwordx4 v[220:221], off
	s_waitcnt vmcnt(8)
	s_waitcnt lgkmcnt(0)
	s_barrier
	s_setprio 1
	s_waitcnt lgkmcnt(0)
	v_mfma_f32_16x16x32_bf16 v[60:63], v[128:131], v[182:185], v[60:63]
	v_mfma_f32_16x16x32_bf16 v[56:59], v[136:139], v[182:185], v[56:59]
	v_mfma_f32_16x16x32_bf16 v[44:47], v[128:131], v[192:195], v[44:47]
	v_mfma_f32_16x16x32_bf16 v[40:43], v[136:139], v[192:195], v[40:43]
	v_mfma_f32_16x16x32_bf16 v[28:31], v[128:131], v[200:203], v[28:31]
	v_mfma_f32_16x16x32_bf16 v[24:27], v[136:139], v[200:203], v[24:27]
	v_mfma_f32_16x16x32_bf16 v[12:15], v[128:131], v[208:211], v[12:15]
	v_mfma_f32_16x16x32_bf16 v[8:11], v[136:139], v[208:211], v[8:11]
	v_mfma_f32_16x16x32_bf16 v[60:63], v[132:135], v[186:189], v[60:63]
	v_mfma_f32_16x16x32_bf16 v[56:59], v[140:143], v[186:189], v[56:59]
	v_mfma_f32_16x16x32_bf16 v[44:47], v[132:135], v[196:199], v[44:47]
	v_mfma_f32_16x16x32_bf16 v[40:43], v[140:143], v[196:199], v[40:43]
	v_mfma_f32_16x16x32_bf16 v[28:31], v[132:135], v[204:207], v[28:31]
	v_mfma_f32_16x16x32_bf16 v[24:27], v[140:143], v[204:207], v[24:27]
	v_mfma_f32_16x16x32_bf16 v[12:15], v[132:135], v[212:215], v[12:15]
	v_mfma_f32_16x16x32_bf16 v[8:11], v[140:143], v[212:215], v[8:11]
	s_setprio 0
	s_setprio 1
	v_mfma_f32_16x16x32_bf16 v[52:55], v[156:159], v[182:185], v[52:55]
	v_mfma_f32_16x16x32_bf16 v[48:51], v[164:167], v[182:185], v[48:51]
	v_mfma_f32_16x16x32_bf16 v[36:39], v[156:159], v[192:195], v[36:39]
	v_mfma_f32_16x16x32_bf16 v[32:35], v[164:167], v[192:195], v[32:35]
	v_mfma_f32_16x16x32_bf16 v[20:23], v[156:159], v[200:203], v[20:23]
	v_mfma_f32_16x16x32_bf16 v[16:19], v[164:167], v[200:203], v[16:19]
	v_mfma_f32_16x16x32_bf16 v[4:7], v[156:159], v[208:211], v[4:7]
	v_mfma_f32_16x16x32_bf16 v[0:3], v[164:167], v[208:211], v[0:3]
	v_mfma_f32_16x16x32_bf16 v[52:55], v[160:163], v[186:189], v[52:55]
	v_mfma_f32_16x16x32_bf16 v[48:51], v[178:181], v[186:189], v[48:51]
	v_mfma_f32_16x16x32_bf16 v[36:39], v[160:163], v[196:199], v[36:39]
	v_mfma_f32_16x16x32_bf16 v[32:35], v[178:181], v[196:199], v[32:35]
	v_mfma_f32_16x16x32_bf16 v[20:23], v[160:163], v[204:207], v[20:23]
	v_mfma_f32_16x16x32_bf16 v[16:19], v[178:181], v[204:207], v[16:19]
	v_mfma_f32_16x16x32_bf16 v[4:7], v[160:163], v[212:215], v[4:7]
	v_mfma_f32_16x16x32_bf16 v[0:3], v[178:181], v[212:215], v[0:3]
	s_setprio 0
	s_barrier
	s_add_i32 s87, 0, 0x18000
	s_add_i32 s88, 0, 0x1c000
	v_add_u32_e32 v140, s87, v171
	v_add_u32_e32 v177, s88, v171
	ds_read_b128 v[128:131], v140
	ds_read_b128 v[132:135], v140 offset:1024
	ds_read_b128 v[136:139], v140 offset:2048
	ds_read_b128 v[140:143], v140 offset:3072
	ds_read_b128 v[156:159], v177
	ds_read_b128 v[160:163], v177 offset:1024
	ds_read_b128 v[164:167], v177 offset:2048
	ds_read_b128 v[178:181], v177 offset:3072
	s_add_u32 s54, s60, 0xb0000
	s_addc_u32 s55, s61, 0
	s_mov_b32 m0, s69
	v_lshl_add_u64 v[222:223], s[54:55], 0, v[144:145]
	ds_read_b128 v[182:185], v175 offset:32768
	ds_read_b128 v[186:189], v175 offset:33792
	ds_read_b128 v[192:195], v175 offset:34816
	ds_read_b128 v[196:199], v175 offset:35840
	ds_read_b128 v[200:203], v175 offset:36864
	ds_read_b128 v[204:207], v175 offset:37888
	ds_read_b128 v[208:211], v175 offset:38912
	ds_read_b128 v[212:215], v175 offset:39936
	global_load_lds_dwordx4 v[222:223], off
	v_lshl_add_u64 v[222:223], s[54:55], 0, v[146:147]
	s_mov_b32 m0, s70
	s_nop 0
	global_load_lds_dwordx4 v[222:223], off
	s_waitcnt vmcnt(8)
	s_waitcnt lgkmcnt(0)
	s_barrier
	s_setprio 1
	s_waitcnt lgkmcnt(0)
	v_mfma_f32_16x16x32_bf16 v[124:127], v[128:131], v[182:185], v[124:127]
	v_mfma_f32_16x16x32_bf16 v[120:123], v[136:139], v[182:185], v[120:123]
	v_mfma_f32_16x16x32_bf16 v[108:111], v[128:131], v[192:195], v[108:111]
	v_mfma_f32_16x16x32_bf16 v[104:107], v[136:139], v[192:195], v[104:107]
	v_mfma_f32_16x16x32_bf16 v[92:95], v[128:131], v[200:203], v[92:95]
	v_mfma_f32_16x16x32_bf16 v[88:91], v[136:139], v[200:203], v[88:91]
	v_mfma_f32_16x16x32_bf16 v[76:79], v[128:131], v[208:211], v[76:79]
	v_mfma_f32_16x16x32_bf16 v[72:75], v[136:139], v[208:211], v[72:75]
	v_mfma_f32_16x16x32_bf16 v[124:127], v[132:135], v[186:189], v[124:127]
	v_mfma_f32_16x16x32_bf16 v[120:123], v[140:143], v[186:189], v[120:123]
	v_mfma_f32_16x16x32_bf16 v[108:111], v[132:135], v[196:199], v[108:111]
	v_mfma_f32_16x16x32_bf16 v[104:107], v[140:143], v[196:199], v[104:107]
	v_mfma_f32_16x16x32_bf16 v[92:95], v[132:135], v[204:207], v[92:95]
	v_mfma_f32_16x16x32_bf16 v[88:91], v[140:143], v[204:207], v[88:91]
	v_mfma_f32_16x16x32_bf16 v[76:79], v[132:135], v[212:215], v[76:79]
	v_mfma_f32_16x16x32_bf16 v[72:75], v[140:143], v[212:215], v[72:75]
	s_setprio 0
	s_setprio 1
	v_mfma_f32_16x16x32_bf16 v[116:119], v[156:159], v[182:185], v[116:119]
	v_mfma_f32_16x16x32_bf16 v[112:115], v[164:167], v[182:185], v[112:115]
	v_mfma_f32_16x16x32_bf16 v[100:103], v[156:159], v[192:195], v[100:103]
	v_mfma_f32_16x16x32_bf16 v[96:99], v[164:167], v[192:195], v[96:99]
	v_mfma_f32_16x16x32_bf16 v[84:87], v[156:159], v[200:203], v[84:87]
	v_mfma_f32_16x16x32_bf16 v[80:83], v[164:167], v[200:203], v[80:83]
	v_mfma_f32_16x16x32_bf16 v[68:71], v[156:159], v[208:211], v[68:71]
	v_mfma_f32_16x16x32_bf16 v[64:67], v[164:167], v[208:211], v[64:67]
	v_mfma_f32_16x16x32_bf16 v[116:119], v[160:163], v[186:189], v[116:119]
	v_mfma_f32_16x16x32_bf16 v[112:115], v[178:181], v[186:189], v[112:115]
	v_mfma_f32_16x16x32_bf16 v[100:103], v[160:163], v[196:199], v[100:103]
	v_mfma_f32_16x16x32_bf16 v[96:99], v[178:181], v[196:199], v[96:99]
	v_mfma_f32_16x16x32_bf16 v[84:87], v[160:163], v[204:207], v[84:87]
	v_mfma_f32_16x16x32_bf16 v[80:83], v[178:181], v[204:207], v[80:83]
	v_mfma_f32_16x16x32_bf16 v[68:71], v[160:163], v[212:215], v[68:71]
	v_mfma_f32_16x16x32_bf16 v[64:67], v[178:181], v[212:215], v[64:67]
	s_setprio 0
	s_barrier
	s_add_i32 s54, s87, s66
	v_lshl_add_u64 v[168:169], v[168:169], 0, s[30:31]
	s_mov_b32 m0, s54
	ds_read_b128 v[182:185], v175 offset:49152
	ds_read_b128 v[186:189], v175 offset:50176
	ds_read_b128 v[192:195], v175 offset:51200
	ds_read_b128 v[196:199], v175 offset:52224
	ds_read_b128 v[200:203], v175 offset:53248
	ds_read_b128 v[204:207], v175 offset:54272
	ds_read_b128 v[208:211], v175 offset:55296
	ds_read_b128 v[212:215], v175 offset:56320
	global_load_lds_dwordx4 v[168:169], off
	s_add_i32 m0, s54, 0x2000
	s_add_u32 s54, s58, 0xb0080
	v_lshl_add_u64 v[168:169], v[216:217], 0, s[30:31]
	s_addc_u32 s55, s59, 0
	s_add_i32 s58, s88, s66
	global_load_lds_dwordx4 v[168:169], off
	v_lshl_add_u64 v[168:169], s[54:55], 0, v[144:145]
	s_mov_b32 m0, s58
	s_nop 0
	global_load_lds_dwordx4 v[168:169], off
	v_lshl_add_u64 v[168:169], s[54:55], 0, v[146:147]
	s_add_i32 m0, s58, 0x2000
	s_nop 0
	global_load_lds_dwordx4 v[168:169], off
	v_lshl_add_u64 v[168:169], v[218:219], 0, s[30:31]
	s_mov_b32 m0, s72
	s_nop 0
	global_load_lds_dwordx4 v[168:169], off
	v_lshl_add_u64 v[168:169], v[220:221], 0, s[30:31]
	s_mov_b32 m0, s73
	s_nop 0
	global_load_lds_dwordx4 v[168:169], off
	s_waitcnt vmcnt(8)
	s_waitcnt lgkmcnt(0)
	s_barrier
	s_setprio 1
	s_waitcnt lgkmcnt(0)
	v_mfma_f32_16x16x32_bf16 v[60:63], v[128:131], v[182:185], v[60:63]
	v_mfma_f32_16x16x32_bf16 v[56:59], v[136:139], v[182:185], v[56:59]
	v_mfma_f32_16x16x32_bf16 v[44:47], v[128:131], v[192:195], v[44:47]
	v_mfma_f32_16x16x32_bf16 v[40:43], v[136:139], v[192:195], v[40:43]
	v_mfma_f32_16x16x32_bf16 v[28:31], v[128:131], v[200:203], v[28:31]
	v_mfma_f32_16x16x32_bf16 v[24:27], v[136:139], v[200:203], v[24:27]
	v_mfma_f32_16x16x32_bf16 v[12:15], v[128:131], v[208:211], v[12:15]
	v_mfma_f32_16x16x32_bf16 v[8:11], v[136:139], v[208:211], v[8:11]
	v_mfma_f32_16x16x32_bf16 v[60:63], v[132:135], v[186:189], v[60:63]
	v_mfma_f32_16x16x32_bf16 v[56:59], v[140:143], v[186:189], v[56:59]
	v_mfma_f32_16x16x32_bf16 v[44:47], v[132:135], v[196:199], v[44:47]
	v_mfma_f32_16x16x32_bf16 v[40:43], v[140:143], v[196:199], v[40:43]
	v_mfma_f32_16x16x32_bf16 v[28:31], v[132:135], v[204:207], v[28:31]
	v_mfma_f32_16x16x32_bf16 v[24:27], v[140:143], v[204:207], v[24:27]
	v_mfma_f32_16x16x32_bf16 v[12:15], v[132:135], v[212:215], v[12:15]
	v_mfma_f32_16x16x32_bf16 v[8:11], v[140:143], v[212:215], v[8:11]
	s_setprio 0
	s_setprio 1
	v_mfma_f32_16x16x32_bf16 v[52:55], v[156:159], v[182:185], v[52:55]
	v_mfma_f32_16x16x32_bf16 v[48:51], v[164:167], v[182:185], v[48:51]
	v_mfma_f32_16x16x32_bf16 v[36:39], v[156:159], v[192:195], v[36:39]
	v_mfma_f32_16x16x32_bf16 v[32:35], v[164:167], v[192:195], v[32:35]
	v_mfma_f32_16x16x32_bf16 v[20:23], v[156:159], v[200:203], v[20:23]
	v_mfma_f32_16x16x32_bf16 v[16:19], v[164:167], v[200:203], v[16:19]
	v_mfma_f32_16x16x32_bf16 v[4:7], v[156:159], v[208:211], v[4:7]
	v_mfma_f32_16x16x32_bf16 v[0:3], v[164:167], v[208:211], v[0:3]
	v_mfma_f32_16x16x32_bf16 v[52:55], v[160:163], v[186:189], v[52:55]
	v_mfma_f32_16x16x32_bf16 v[48:51], v[178:181], v[186:189], v[48:51]
	v_mfma_f32_16x16x32_bf16 v[36:39], v[160:163], v[196:199], v[36:39]
	v_mfma_f32_16x16x32_bf16 v[32:35], v[178:181], v[196:199], v[32:35]
	v_mfma_f32_16x16x32_bf16 v[20:23], v[160:163], v[204:207], v[20:23]
	v_mfma_f32_16x16x32_bf16 v[16:19], v[178:181], v[204:207], v[16:19]
	v_mfma_f32_16x16x32_bf16 v[4:7], v[160:163], v[212:215], v[4:7]
	v_mfma_f32_16x16x32_bf16 v[0:3], v[178:181], v[212:215], v[0:3]
	s_setprio 0
	s_barrier
	s_add_i32 s86, s86, 2
	s_add_u32 s84, s84, 0x100
	s_addc_u32 s85, s85, 0
	s_cmp_gt_u32 s86, 41
	s_mov_b64 s[54:55], s[56:57]
	s_cbranch_scc0 .LBB0_250
	v_mbcnt_lo_u32_b32 v235, -1, 0
	v_mbcnt_hi_u32_b32 v235, -1, v235
	v_lshrrev_b32_e32 v236, 2, v235
	v_and_b32_e32 v237, 3, v235
	v_lshl_add_u32 v232, v237, 4, v236
	v_lshlrev_b32_e32 v232, 2, v232
	v_and_b32_e32 v233, -16, v170
	v_or_b32_e32 v233, v233, v236
	v_lshlrev_b32_e32 v237, 2, v237
	v_and_b32_e32 v234, -13, v172
	v_or_b32_e32 v234, v234, v237
	ds_bpermute_b32 v127, v232, v127
	ds_bpermute_b32 v126, v232, v126
	ds_bpermute_b32 v125, v232, v125
	ds_bpermute_b32 v124, v232, v124
	ds_bpermute_b32 v123, v232, v123
	ds_bpermute_b32 v122, v232, v122
	ds_bpermute_b32 v121, v232, v121
	ds_bpermute_b32 v120, v232, v120
	ds_bpermute_b32 v119, v232, v119
	ds_bpermute_b32 v118, v232, v118
	ds_bpermute_b32 v117, v232, v117
	ds_bpermute_b32 v116, v232, v116
	ds_bpermute_b32 v115, v232, v115
	ds_bpermute_b32 v114, v232, v114
	ds_bpermute_b32 v113, v232, v113
	ds_bpermute_b32 v112, v232, v112
	ds_bpermute_b32 v111, v232, v111
	ds_bpermute_b32 v110, v232, v110
	ds_bpermute_b32 v109, v232, v109
	ds_bpermute_b32 v108, v232, v108
	ds_bpermute_b32 v107, v232, v107
	ds_bpermute_b32 v106, v232, v106
	ds_bpermute_b32 v105, v232, v105
	ds_bpermute_b32 v104, v232, v104
	ds_bpermute_b32 v103, v232, v103
	ds_bpermute_b32 v102, v232, v102
	ds_bpermute_b32 v101, v232, v101
	ds_bpermute_b32 v100, v232, v100
	ds_bpermute_b32 v99, v232, v99
	ds_bpermute_b32 v98, v232, v98
	ds_bpermute_b32 v97, v232, v97
	ds_bpermute_b32 v96, v232, v96
	ds_bpermute_b32 v95, v232, v95
	ds_bpermute_b32 v94, v232, v94
	ds_bpermute_b32 v93, v232, v93
	ds_bpermute_b32 v92, v232, v92
	ds_bpermute_b32 v91, v232, v91
	ds_bpermute_b32 v90, v232, v90
	ds_bpermute_b32 v89, v232, v89
	ds_bpermute_b32 v88, v232, v88
	ds_bpermute_b32 v87, v232, v87
	ds_bpermute_b32 v86, v232, v86
	ds_bpermute_b32 v85, v232, v85
	ds_bpermute_b32 v84, v232, v84
	ds_bpermute_b32 v83, v232, v83
	ds_bpermute_b32 v82, v232, v82
	ds_bpermute_b32 v81, v232, v81
	ds_bpermute_b32 v80, v232, v80
	ds_bpermute_b32 v79, v232, v79
	ds_bpermute_b32 v78, v232, v78
	ds_bpermute_b32 v77, v232, v77
	ds_bpermute_b32 v76, v232, v76
	ds_bpermute_b32 v75, v232, v75
	ds_bpermute_b32 v74, v232, v74
	ds_bpermute_b32 v73, v232, v73
	ds_bpermute_b32 v72, v232, v72
	ds_bpermute_b32 v71, v232, v71
	ds_bpermute_b32 v70, v232, v70
	ds_bpermute_b32 v69, v232, v69
	ds_bpermute_b32 v68, v232, v68
	ds_bpermute_b32 v67, v232, v67
	ds_bpermute_b32 v66, v232, v66
	ds_bpermute_b32 v65, v232, v65
	ds_bpermute_b32 v64, v232, v64
	ds_bpermute_b32 v63, v232, v63
	ds_bpermute_b32 v62, v232, v62
	ds_bpermute_b32 v61, v232, v61
	ds_bpermute_b32 v60, v232, v60
	ds_bpermute_b32 v59, v232, v59
	ds_bpermute_b32 v58, v232, v58
	ds_bpermute_b32 v57, v232, v57
	ds_bpermute_b32 v56, v232, v56
	ds_bpermute_b32 v55, v232, v55
	ds_bpermute_b32 v54, v232, v54
	ds_bpermute_b32 v53, v232, v53
	ds_bpermute_b32 v52, v232, v52
	ds_bpermute_b32 v51, v232, v51
	ds_bpermute_b32 v50, v232, v50
	ds_bpermute_b32 v49, v232, v49
	ds_bpermute_b32 v48, v232, v48
	ds_bpermute_b32 v47, v232, v47
	ds_bpermute_b32 v46, v232, v46
	ds_bpermute_b32 v45, v232, v45
	ds_bpermute_b32 v44, v232, v44
	ds_bpermute_b32 v43, v232, v43
	ds_bpermute_b32 v42, v232, v42
	ds_bpermute_b32 v41, v232, v41
	ds_bpermute_b32 v40, v232, v40
	ds_bpermute_b32 v39, v232, v39
	ds_bpermute_b32 v38, v232, v38
	ds_bpermute_b32 v37, v232, v37
	ds_bpermute_b32 v36, v232, v36
	ds_bpermute_b32 v35, v232, v35
	ds_bpermute_b32 v34, v232, v34
	ds_bpermute_b32 v33, v232, v33
	ds_bpermute_b32 v32, v232, v32
	ds_bpermute_b32 v31, v232, v31
	ds_bpermute_b32 v30, v232, v30
	ds_bpermute_b32 v29, v232, v29
	ds_bpermute_b32 v28, v232, v28
	ds_bpermute_b32 v27, v232, v27
	ds_bpermute_b32 v26, v232, v26
	ds_bpermute_b32 v25, v232, v25
	ds_bpermute_b32 v24, v232, v24
	ds_bpermute_b32 v23, v232, v23
	ds_bpermute_b32 v22, v232, v22
	ds_bpermute_b32 v21, v232, v21
	ds_bpermute_b32 v20, v232, v20
	ds_bpermute_b32 v19, v232, v19
	ds_bpermute_b32 v18, v232, v18
	ds_bpermute_b32 v17, v232, v17
	ds_bpermute_b32 v16, v232, v16
	ds_bpermute_b32 v15, v232, v15
	ds_bpermute_b32 v14, v232, v14
	ds_bpermute_b32 v13, v232, v13
	ds_bpermute_b32 v12, v232, v12
	ds_bpermute_b32 v11, v232, v11
	ds_bpermute_b32 v10, v232, v10
	ds_bpermute_b32 v9, v232, v9
	ds_bpermute_b32 v8, v232, v8
	ds_bpermute_b32 v7, v232, v7
	ds_bpermute_b32 v6, v232, v6
	ds_bpermute_b32 v5, v232, v5
	ds_bpermute_b32 v4, v232, v4
	ds_bpermute_b32 v3, v232, v3
	ds_bpermute_b32 v2, v232, v2
	ds_bpermute_b32 v1, v232, v1
	ds_bpermute_b32 v0, v232, v0
	s_waitcnt lgkmcnt(0)
	v_readlane_b32 s12, v254, 0
	v_lshl_add_u32 v160, s82, 8, v233
	v_lshl_or_b32 v156, s83, 8, v234
	s_cmpk_lt_i32 s82, 0x100
	v_readlane_b32 s13, v254, 1
	v_ashrrev_i32_e32 v161, 31, v160
	s_cselect_b32 s55, s13, s78
	s_cselect_b32 s54, s12, s77
	v_lshlrev_b64 v[192:193], 12, v[160:161]
	v_ashrrev_i32_e32 v157, 31, v156
	v_lshl_add_u64 v[128:129], s[54:55], 0, v[192:193]
	v_lshlrev_b64 v[158:159], 2, v[156:157]
	v_lshl_add_u64 v[128:129], v[128:129], 0, v[158:159]
	global_load_dwordx4 v[166:169], v[128:129], off
	global_load_dwordx4 v[178:181], v[128:129], off offset:64
	global_load_dwordx4 v[182:185], v[128:129], off offset:512
	global_load_dwordx4 v[186:189], v[128:129], off offset:576
	v_or_b32_e32 v162, 16, v160
	v_ashrrev_i32_e32 v163, 31, v162
	v_lshlrev_b64 v[164:165], 12, v[162:163]
	v_lshl_add_u64 v[128:129], s[54:55], 0, v[164:165]
	v_lshl_add_u64 v[128:129], v[128:129], 0, v[158:159]
	global_load_dwordx4 v[140:143], v[128:129], off
	global_load_dwordx4 v[136:139], v[128:129], off offset:64
	global_load_dwordx4 v[132:135], v[128:129], off offset:512
	s_nop 0
	global_load_dwordx4 v[128:131], v[128:129], off offset:576
	v_readlane_b32 s14, v254, 2
	v_readlane_b32 s15, v254, 3
	v_readlane_b32 s16, v254, 4
	v_readlane_b32 s17, v254, 5
	v_readlane_b32 s18, v254, 6
	v_readlane_b32 s19, v254, 7
	v_readlane_b32 s20, v254, 8
	v_readlane_b32 s21, v254, 9
	v_readlane_b32 s22, v254, 10
	v_readlane_b32 s23, v254, 11
	v_readlane_b32 s24, v254, 12
	v_readlane_b32 s25, v254, 13
	v_readlane_b32 s26, v254, 14
	v_readlane_b32 s27, v254, 15
	s_and_b64 vcc, exec, s[34:35]
	s_cbranch_vccz .LBB0_253
	s_barrier
.LBB0_253:
	s_waitcnt vmcnt(7)
	v_pk_fma_f32 v[126:127], v[126:127], 0.5, v[168:169] op_sel_hi:[1,0,1]
	v_pk_fma_f32 v[124:125], v[124:125], 0.5, v[166:167] op_sel_hi:[1,0,1]
	v_mul_f32_e32 v167, v127, v127
	v_mul_f32_e32 v166, v125, v125
	v_fmac_f32_e32 v166, v124, v124
	v_fmac_f32_e32 v167, v126, v126
	v_add_f32_e32 v177, v166, v167
	v_lshl_add_u64 v[166:167], s[6:7], 0, v[192:193]
	v_lshlrev_b64 v[168:169], 11, v[160:161]
	v_lshl_add_u64 v[166:167], v[166:167], 0, v[158:159]
	v_lshl_add_u64 v[168:169], s[10:11], 0, v[168:169]
	global_store_dwordx4 v[166:167], v[124:127], off
	v_lshl_add_u64 v[168:169], v[156:157], 1, v[168:169]
	s_waitcnt vmcnt(7)
	v_pk_fma_f32 v[120:121], v[120:121], 0.5, v[178:179] op_sel_hi:[1,0,1]
	v_cvt_pk_bf16_f32 v124, v124, v125
	v_cvt_pk_bf16_f32 v125, v126, v127
	global_store_dwordx2 v[168:169], v[124:125], off
	v_pk_fma_f32 v[122:123], v[122:123], 0.5, v[180:181] op_sel_hi:[1,0,1]
	v_mul_f32_e32 v124, v121, v121
	v_fmac_f32_e32 v124, v120, v120
	global_store_dwordx4 v[166:167], v[120:123], off offset:64
	s_waitcnt vmcnt(8)
	v_pk_fma_f32 v[116:117], v[116:117], 0.5, v[182:183] op_sel_hi:[1,0,1]
	v_pk_fma_f32 v[118:119], v[118:119], 0.5, v[184:185] op_sel_hi:[1,0,1]
	v_cvt_pk_bf16_f32 v120, v120, v121
	v_cvt_pk_bf16_f32 v121, v122, v123
	global_store_dwordx2 v[168:169], v[120:121], off offset:32
	v_mul_f32_e32 v120, v117, v117
	v_fmac_f32_e32 v120, v116, v116
	global_store_dwordx4 v[166:167], v[116:119], off offset:512
	s_waitcnt vmcnt(9)
	v_pk_fma_f32 v[112:113], v[112:113], 0.5, v[186:187] op_sel_hi:[1,0,1]
	v_pk_fma_f32 v[114:115], v[114:115], 0.5, v[188:189] op_sel_hi:[1,0,1]
	v_cvt_pk_bf16_f32 v116, v116, v117
	v_cvt_pk_bf16_f32 v117, v118, v119
	global_store_dwordx2 v[168:169], v[116:117], off offset:256
	v_mul_f32_e32 v116, v113, v113
	v_mul_f32_e32 v125, v123, v123
	v_fmac_f32_e32 v116, v112, v112
	global_store_dwordx4 v[166:167], v[112:115], off offset:576
	v_fmac_f32_e32 v125, v122, v122
	v_mul_f32_e32 v121, v119, v119
	v_cvt_pk_bf16_f32 v112, v112, v113
	v_cvt_pk_bf16_f32 v113, v114, v115
	global_store_dwordx2 v[168:169], v[112:113], off offset:288
	v_and_b32_e32 v113, 64, v176
	v_add_f32_e32 v124, v124, v125
	v_fmac_f32_e32 v121, v118, v118
	v_mul_f32_e32 v117, v115, v115
	v_xor_b32_e32 v112, 1, v176
	v_add_u32_e32 v113, 64, v113
	v_add_f32_e32 v124, v177, v124
	v_add_f32_e32 v120, v120, v121
	v_fmac_f32_e32 v117, v114, v114
	v_cmp_lt_i32_e32 vcc, v112, v113
	v_add_f32_e32 v120, v124, v120
	v_add_f32_e32 v116, v116, v117
	v_cndmask_b32_e32 v112, v176, v112, vcc
	v_add_f32_e32 v116, v120, v116
	v_lshlrev_b32_e32 v177, 2, v112
	ds_bpermute_b32 v112, v177, v116
	v_xor_b32_e32 v114, 2, v176
	v_cmp_lt_i32_e32 vcc, v114, v113
	s_waitcnt lgkmcnt(0)
	v_add_f32_e32 v112, v116, v112
	v_cndmask_b32_e32 v113, v176, v114, vcc
	v_lshlrev_b32_e32 v178, 2, v113
	ds_bpermute_b32 v113, v178, v112
	s_mov_b32 vcc_lo, 0x11111111
	s_mov_b32 vcc_hi, 0x11111111
	s_and_saveexec_b64 s[56:57], vcc
	s_cbranch_execz .LBB0_255
	v_lshl_add_u64 v[114:115], v[160:161], 2, s[90:91]
	s_waitcnt lgkmcnt(0)
	v_add_f32_e32 v112, v112, v113
	global_atomic_add_f32 v[114:115], v112, off
.LBB0_255:
	s_or_b64 exec, exec, s[56:57]
	v_or_b32_e32 v166, 32, v160
	v_ashrrev_i32_e32 v167, 31, v166
	v_lshlrev_b64 v[168:169], 12, v[166:167]
	s_waitcnt lgkmcnt(0)
	v_lshl_add_u64 v[112:113], s[54:55], 0, v[168:169]
	v_lshl_add_u64 v[112:113], v[112:113], 0, v[158:159]
	global_load_dwordx4 v[124:127], v[112:113], off
	global_load_dwordx4 v[120:123], v[112:113], off offset:64
	global_load_dwordx4 v[116:119], v[112:113], off offset:512
	s_nop 0
	global_load_dwordx4 v[112:115], v[112:113], off offset:576
	s_waitcnt vmcnt(15)
	v_pk_fma_f32 v[110:111], v[110:111], 0.5, v[142:143] op_sel_hi:[1,0,1]
	v_pk_fma_f32 v[108:109], v[108:109], 0.5, v[140:141] op_sel_hi:[1,0,1]
	v_mul_f32_e32 v141, v111, v111
	v_mul_f32_e32 v140, v109, v109
	v_fmac_f32_e32 v140, v108, v108
	v_fmac_f32_e32 v141, v110, v110
	v_add_f32_e32 v161, v140, v141
	v_lshl_add_u64 v[140:141], s[6:7], 0, v[164:165]
	v_lshlrev_b64 v[142:143], 11, v[162:163]
	v_lshl_add_u64 v[140:141], v[140:141], 0, v[158:159]
	v_lshl_add_u64 v[142:143], s[10:11], 0, v[142:143]
	global_store_dwordx4 v[140:141], v[108:111], off
	v_lshl_add_u64 v[142:143], v[156:157], 1, v[142:143]
	s_waitcnt vmcnt(15)
	v_pk_fma_f32 v[104:105], v[104:105], 0.5, v[136:137] op_sel_hi:[1,0,1]
	v_cvt_pk_bf16_f32 v108, v108, v109
	v_cvt_pk_bf16_f32 v109, v110, v111
	global_store_dwordx2 v[142:143], v[108:109], off
	v_pk_fma_f32 v[106:107], v[106:107], 0.5, v[138:139] op_sel_hi:[1,0,1]
	v_mul_f32_e32 v108, v105, v105
	v_fmac_f32_e32 v108, v104, v104
	v_mul_f32_e32 v109, v107, v107
	global_store_dwordx4 v[140:141], v[104:107], off offset:64
	s_waitcnt vmcnt(16)
	v_pk_fma_f32 v[102:103], v[102:103], 0.5, v[134:135] op_sel_hi:[1,0,1]
	v_pk_fma_f32 v[100:101], v[100:101], 0.5, v[132:133] op_sel_hi:[1,0,1]
	v_cvt_pk_bf16_f32 v104, v104, v105
	v_cvt_pk_bf16_f32 v105, v106, v107
	v_fmac_f32_e32 v109, v106, v106
	global_store_dwordx2 v[142:143], v[104:105], off offset:32
	v_mul_f32_e32 v104, v101, v101
	v_mul_f32_e32 v105, v103, v103
	v_add_f32_e32 v108, v108, v109
	v_fmac_f32_e32 v104, v100, v100
	v_fmac_f32_e32 v105, v102, v102
	v_add_f32_e32 v108, v161, v108
	v_add_f32_e32 v104, v104, v105
	v_add_f32_e32 v108, v108, v104
	s_waitcnt vmcnt(16)
	v_pk_fma_f32 v[106:107], v[98:99], 0.5, v[130:131] op_sel_hi:[1,0,1]
	v_pk_fma_f32 v[104:105], v[96:97], 0.5, v[128:129] op_sel_hi:[1,0,1]
	v_mul_f32_e32 v97, v107, v107
	v_mul_f32_e32 v96, v105, v105
	v_fmac_f32_e32 v96, v104, v104
	v_fmac_f32_e32 v97, v106, v106
	v_add_f32_e32 v96, v96, v97
	v_add_f32_e32 v98, v108, v96
	ds_bpermute_b32 v99, v177, v98
	v_cvt_pk_bf16_f32 v96, v100, v101
	v_cvt_pk_bf16_f32 v97, v102, v103
	global_store_dwordx4 v[140:141], v[100:103], off offset:512
	global_store_dwordx2 v[142:143], v[96:97], off offset:256
	s_waitcnt lgkmcnt(0)
	v_add_f32_e32 v96, v98, v99
	ds_bpermute_b32 v97, v178, v96
	v_cvt_pk_bf16_f32 v98, v104, v105
	v_cvt_pk_bf16_f32 v99, v106, v107
	global_store_dwordx4 v[140:141], v[104:107], off offset:576
	global_store_dwordx2 v[142:143], v[98:99], off offset:288
	s_mov_b32 vcc_lo, 0x11111111
	s_mov_b32 vcc_hi, 0x11111111
	s_and_saveexec_b64 s[56:57], vcc
	s_cbranch_execz .LBB0_257
	v_lshl_add_u64 v[98:99], v[162:163], 2, s[90:91]
	s_waitcnt lgkmcnt(0)
	v_add_f32_e32 v96, v96, v97
	global_atomic_add_f32 v[98:99], v96, off
.LBB0_257:
	s_or_b64 exec, exec, s[56:57]
	v_or_b32_e32 v128, 48, v160
	v_ashrrev_i32_e32 v129, 31, v128
	v_lshlrev_b64 v[130:131], 12, v[128:129]
	s_waitcnt lgkmcnt(0)
	v_lshl_add_u64 v[96:97], s[54:55], 0, v[130:131]
	v_lshl_add_u64 v[96:97], v[96:97], 0, v[158:159]
	global_load_dwordx4 v[108:111], v[96:97], off
	global_load_dwordx4 v[104:107], v[96:97], off offset:64
	global_load_dwordx4 v[100:103], v[96:97], off offset:512
	s_nop 0
	global_load_dwordx4 v[96:99], v[96:97], off offset:576
	s_waitcnt vmcnt(15)
	v_pk_fma_f32 v[94:95], v[94:95], 0.5, v[126:127] op_sel_hi:[1,0,1]
	v_pk_fma_f32 v[92:93], v[92:93], 0.5, v[124:125] op_sel_hi:[1,0,1]
	v_mul_f32_e32 v125, v95, v95
	v_mul_f32_e32 v124, v93, v93
	v_fmac_f32_e32 v124, v92, v92
	v_fmac_f32_e32 v125, v94, v94
	v_add_f32_e32 v132, v124, v125
	v_lshl_add_u64 v[124:125], s[6:7], 0, v[168:169]
	v_lshlrev_b64 v[126:127], 11, v[166:167]
	v_lshl_add_u64 v[124:125], v[124:125], 0, v[158:159]
	v_lshl_add_u64 v[126:127], s[10:11], 0, v[126:127]
	global_store_dwordx4 v[124:125], v[92:95], off
	v_lshl_add_u64 v[126:127], v[156:157], 1, v[126:127]
	s_waitcnt vmcnt(15)
	v_pk_fma_f32 v[88:89], v[88:89], 0.5, v[120:121] op_sel_hi:[1,0,1]
	v_cvt_pk_bf16_f32 v92, v92, v93
	v_cvt_pk_bf16_f32 v93, v94, v95
	global_store_dwordx2 v[126:127], v[92:93], off
	v_pk_fma_f32 v[90:91], v[90:91], 0.5, v[122:123] op_sel_hi:[1,0,1]
	v_mul_f32_e32 v92, v89, v89
	v_fmac_f32_e32 v92, v88, v88
	v_mul_f32_e32 v93, v91, v91
	global_store_dwordx4 v[124:125], v[88:91], off offset:64
	s_waitcnt vmcnt(16)
	v_pk_fma_f32 v[86:87], v[86:87], 0.5, v[118:119] op_sel_hi:[1,0,1]
	v_pk_fma_f32 v[84:85], v[84:85], 0.5, v[116:117] op_sel_hi:[1,0,1]
	v_cvt_pk_bf16_f32 v88, v88, v89
	v_cvt_pk_bf16_f32 v89, v90, v91
	v_fmac_f32_e32 v93, v90, v90
	global_store_dwordx2 v[126:127], v[88:89], off offset:32
	v_mul_f32_e32 v88, v85, v85
	v_mul_f32_e32 v89, v87, v87
	v_add_f32_e32 v92, v92, v93
	v_fmac_f32_e32 v88, v84, v84
	v_fmac_f32_e32 v89, v86, v86
	v_add_f32_e32 v92, v132, v92
	v_add_f32_e32 v88, v88, v89
	v_add_f32_e32 v92, v92, v88
	s_waitcnt vmcnt(16)
	v_pk_fma_f32 v[90:91], v[82:83], 0.5, v[114:115] op_sel_hi:[1,0,1]
	v_pk_fma_f32 v[88:89], v[80:81], 0.5, v[112:113] op_sel_hi:[1,0,1]
	v_mul_f32_e32 v81, v91, v91
	v_mul_f32_e32 v80, v89, v89
	v_fmac_f32_e32 v80, v88, v88
	v_fmac_f32_e32 v81, v90, v90
	v_add_f32_e32 v80, v80, v81
	v_add_f32_e32 v82, v92, v80
	ds_bpermute_b32 v83, v177, v82
	v_cvt_pk_bf16_f32 v80, v84, v85
	v_cvt_pk_bf16_f32 v81, v86, v87
	global_store_dwordx4 v[124:125], v[84:87], off offset:512
	global_store_dwordx2 v[126:127], v[80:81], off offset:256
	s_waitcnt lgkmcnt(0)
	v_add_f32_e32 v80, v82, v83
	ds_bpermute_b32 v81, v178, v80
	v_cvt_pk_bf16_f32 v82, v88, v89
	v_cvt_pk_bf16_f32 v83, v90, v91
	global_store_dwordx4 v[124:125], v[88:91], off offset:576
	global_store_dwordx2 v[126:127], v[82:83], off offset:288
	s_mov_b32 vcc_lo, 0x11111111
	s_mov_b32 vcc_hi, 0x11111111
	s_and_saveexec_b64 s[56:57], vcc
	s_cbranch_execz .LBB0_259
	v_lshl_add_u64 v[82:83], v[166:167], 2, s[90:91]
	s_waitcnt lgkmcnt(0)
	v_add_f32_e32 v80, v80, v81
	global_atomic_add_f32 v[82:83], v80, off
.LBB0_259:
	s_or_b64 exec, exec, s[56:57]
	v_add_u32_e32 v112, 0x80, v160
	v_ashrrev_i32_e32 v113, 31, v112
	v_lshlrev_b64 v[114:115], 12, v[112:113]
	s_waitcnt lgkmcnt(0)
	v_lshl_add_u64 v[80:81], s[54:55], 0, v[114:115]
	v_lshl_add_u64 v[80:81], v[80:81], 0, v[158:159]
	global_load_dwordx4 v[92:95], v[80:81], off
	global_load_dwordx4 v[88:91], v[80:81], off offset:64
	global_load_dwordx4 v[84:87], v[80:81], off offset:512
	s_nop 0
	global_load_dwordx4 v[80:83], v[80:81], off offset:576
	s_waitcnt vmcnt(15)
	v_pk_fma_f32 v[78:79], v[78:79], 0.5, v[110:111] op_sel_hi:[1,0,1]
	v_pk_fma_f32 v[76:77], v[76:77], 0.5, v[108:109] op_sel_hi:[1,0,1]
	v_mul_f32_e32 v109, v79, v79
	v_mul_f32_e32 v108, v77, v77
	v_fmac_f32_e32 v108, v76, v76
	v_fmac_f32_e32 v109, v78, v78
	v_add_f32_e32 v116, v108, v109
	v_lshl_add_u64 v[108:109], s[6:7], 0, v[130:131]
	v_lshlrev_b64 v[110:111], 11, v[128:129]
	v_lshl_add_u64 v[108:109], v[108:109], 0, v[158:159]
	v_lshl_add_u64 v[110:111], s[10:11], 0, v[110:111]
	global_store_dwordx4 v[108:109], v[76:79], off
	v_lshl_add_u64 v[110:111], v[156:157], 1, v[110:111]
	s_waitcnt vmcnt(15)
	v_pk_fma_f32 v[72:73], v[72:73], 0.5, v[104:105] op_sel_hi:[1,0,1]
	v_cvt_pk_bf16_f32 v76, v76, v77
	v_cvt_pk_bf16_f32 v77, v78, v79
	global_store_dwordx2 v[110:111], v[76:77], off
	v_pk_fma_f32 v[74:75], v[74:75], 0.5, v[106:107] op_sel_hi:[1,0,1]
	v_mul_f32_e32 v76, v73, v73
	v_fmac_f32_e32 v76, v72, v72
	v_mul_f32_e32 v77, v75, v75
	global_store_dwordx4 v[108:109], v[72:75], off offset:64
	s_waitcnt vmcnt(16)
	v_pk_fma_f32 v[70:71], v[70:71], 0.5, v[102:103] op_sel_hi:[1,0,1]
	v_pk_fma_f32 v[68:69], v[68:69], 0.5, v[100:101] op_sel_hi:[1,0,1]
	v_cvt_pk_bf16_f32 v72, v72, v73
	v_cvt_pk_bf16_f32 v73, v74, v75
	v_fmac_f32_e32 v77, v74, v74
	global_store_dwordx2 v[110:111], v[72:73], off offset:32
	v_mul_f32_e32 v72, v69, v69
	v_mul_f32_e32 v73, v71, v71
	v_add_f32_e32 v76, v76, v77
	v_fmac_f32_e32 v72, v68, v68
	v_fmac_f32_e32 v73, v70, v70
	v_add_f32_e32 v76, v116, v76
	v_add_f32_e32 v72, v72, v73
	v_add_f32_e32 v76, v76, v72
	s_waitcnt vmcnt(16)
	v_pk_fma_f32 v[74:75], v[66:67], 0.5, v[98:99] op_sel_hi:[1,0,1]
	v_pk_fma_f32 v[72:73], v[64:65], 0.5, v[96:97] op_sel_hi:[1,0,1]
	v_mul_f32_e32 v65, v75, v75
	v_mul_f32_e32 v64, v73, v73
	v_fmac_f32_e32 v64, v72, v72
	v_fmac_f32_e32 v65, v74, v74
	v_add_f32_e32 v64, v64, v65
	v_add_f32_e32 v66, v76, v64
	ds_bpermute_b32 v67, v177, v66
	v_cvt_pk_bf16_f32 v64, v68, v69
	v_cvt_pk_bf16_f32 v65, v70, v71
	global_store_dwordx4 v[108:109], v[68:71], off offset:512
	global_store_dwordx2 v[110:111], v[64:65], off offset:256
	s_waitcnt lgkmcnt(0)
	v_add_f32_e32 v64, v66, v67
	ds_bpermute_b32 v65, v178, v64
	v_cvt_pk_bf16_f32 v66, v72, v73
	v_cvt_pk_bf16_f32 v67, v74, v75
	global_store_dwordx4 v[108:109], v[72:75], off offset:576
	global_store_dwordx2 v[110:111], v[66:67], off offset:288
	s_mov_b32 vcc_lo, 0x11111111
	s_mov_b32 vcc_hi, 0x11111111
	s_and_saveexec_b64 s[56:57], vcc
	s_cbranch_execz .LBB0_261
	v_lshl_add_u64 v[66:67], v[128:129], 2, s[90:91]
	s_waitcnt lgkmcnt(0)
	v_add_f32_e32 v64, v64, v65
	global_atomic_add_f32 v[66:67], v64, off
.LBB0_261:
	s_or_b64 exec, exec, s[56:57]
	v_or_b32_e32 v96, 16, v112
	v_ashrrev_i32_e32 v97, 31, v96
	v_lshlrev_b64 v[98:99], 12, v[96:97]
	s_waitcnt lgkmcnt(0)
	v_lshl_add_u64 v[64:65], s[54:55], 0, v[98:99]
	v_lshl_add_u64 v[64:65], v[64:65], 0, v[158:159]
	global_load_dwordx4 v[76:79], v[64:65], off
	global_load_dwordx4 v[72:75], v[64:65], off offset:64
	global_load_dwordx4 v[68:71], v[64:65], off offset:512
	s_nop 0
	global_load_dwordx4 v[64:67], v[64:65], off offset:576
	s_waitcnt vmcnt(15)
	v_pk_fma_f32 v[62:63], v[62:63], 0.5, v[94:95] op_sel_hi:[1,0,1]
	v_pk_fma_f32 v[60:61], v[60:61], 0.5, v[92:93] op_sel_hi:[1,0,1]
	v_mul_f32_e32 v93, v63, v63
	v_mul_f32_e32 v92, v61, v61
	v_fmac_f32_e32 v92, v60, v60
	v_fmac_f32_e32 v93, v62, v62
	v_add_f32_e32 v100, v92, v93
	v_lshl_add_u64 v[92:93], s[6:7], 0, v[114:115]
	v_lshlrev_b64 v[94:95], 11, v[112:113]
	v_lshl_add_u64 v[92:93], v[92:93], 0, v[158:159]
	v_lshl_add_u64 v[94:95], s[10:11], 0, v[94:95]
	global_store_dwordx4 v[92:93], v[60:63], off
	v_lshl_add_u64 v[94:95], v[156:157], 1, v[94:95]
	s_waitcnt vmcnt(15)
	v_pk_fma_f32 v[56:57], v[56:57], 0.5, v[88:89] op_sel_hi:[1,0,1]
	v_cvt_pk_bf16_f32 v60, v60, v61
	v_cvt_pk_bf16_f32 v61, v62, v63
	global_store_dwordx2 v[94:95], v[60:61], off
	v_pk_fma_f32 v[58:59], v[58:59], 0.5, v[90:91] op_sel_hi:[1,0,1]
	v_mul_f32_e32 v60, v57, v57
	v_fmac_f32_e32 v60, v56, v56
	v_mul_f32_e32 v61, v59, v59
	global_store_dwordx4 v[92:93], v[56:59], off offset:64
	s_waitcnt vmcnt(16)
	v_pk_fma_f32 v[54:55], v[54:55], 0.5, v[86:87] op_sel_hi:[1,0,1]
	v_pk_fma_f32 v[52:53], v[52:53], 0.5, v[84:85] op_sel_hi:[1,0,1]
	v_cvt_pk_bf16_f32 v56, v56, v57
	v_cvt_pk_bf16_f32 v57, v58, v59
	v_fmac_f32_e32 v61, v58, v58
	global_store_dwordx2 v[94:95], v[56:57], off offset:32
	v_mul_f32_e32 v56, v53, v53
	v_mul_f32_e32 v57, v55, v55
	v_add_f32_e32 v60, v60, v61
	v_fmac_f32_e32 v56, v52, v52
	v_fmac_f32_e32 v57, v54, v54
	v_add_f32_e32 v60, v100, v60
	v_add_f32_e32 v56, v56, v57
	v_add_f32_e32 v60, v60, v56
	s_waitcnt vmcnt(16)
	v_pk_fma_f32 v[58:59], v[50:51], 0.5, v[82:83] op_sel_hi:[1,0,1]
	v_pk_fma_f32 v[56:57], v[48:49], 0.5, v[80:81] op_sel_hi:[1,0,1]
	v_mul_f32_e32 v49, v59, v59
	v_mul_f32_e32 v48, v57, v57
	v_fmac_f32_e32 v48, v56, v56
	v_fmac_f32_e32 v49, v58, v58
	v_add_f32_e32 v48, v48, v49
	v_add_f32_e32 v50, v60, v48
	ds_bpermute_b32 v51, v177, v50
	v_cvt_pk_bf16_f32 v48, v52, v53
	v_cvt_pk_bf16_f32 v49, v54, v55
	global_store_dwordx4 v[92:93], v[52:55], off offset:512
	global_store_dwordx2 v[94:95], v[48:49], off offset:256
	s_waitcnt lgkmcnt(0)
	v_add_f32_e32 v48, v50, v51
	ds_bpermute_b32 v49, v178, v48
	v_cvt_pk_bf16_f32 v50, v56, v57
	v_cvt_pk_bf16_f32 v51, v58, v59
	global_store_dwordx4 v[92:93], v[56:59], off offset:576
	global_store_dwordx2 v[94:95], v[50:51], off offset:288
	s_mov_b32 vcc_lo, 0x11111111
	s_mov_b32 vcc_hi, 0x11111111
	s_and_saveexec_b64 s[56:57], vcc
	s_cbranch_execz .LBB0_263
	v_lshl_add_u64 v[50:51], v[112:113], 2, s[90:91]
	s_waitcnt lgkmcnt(0)
	v_add_f32_e32 v48, v48, v49
	global_atomic_add_f32 v[50:51], v48, off
.LBB0_263:
	s_or_b64 exec, exec, s[56:57]
	v_or_b32_e32 v80, 32, v112
	v_ashrrev_i32_e32 v81, 31, v80
	v_lshlrev_b64 v[82:83], 12, v[80:81]
	s_waitcnt lgkmcnt(0)
	v_lshl_add_u64 v[48:49], s[54:55], 0, v[82:83]
	v_lshl_add_u64 v[48:49], v[48:49], 0, v[158:159]
	global_load_dwordx4 v[60:63], v[48:49], off
	global_load_dwordx4 v[56:59], v[48:49], off offset:64
	global_load_dwordx4 v[52:55], v[48:49], off offset:512
	s_nop 0
	global_load_dwordx4 v[48:51], v[48:49], off offset:576
	s_waitcnt vmcnt(15)
	v_pk_fma_f32 v[46:47], v[46:47], 0.5, v[78:79] op_sel_hi:[1,0,1]
	v_pk_fma_f32 v[44:45], v[44:45], 0.5, v[76:77] op_sel_hi:[1,0,1]
	v_mul_f32_e32 v77, v47, v47
	v_mul_f32_e32 v76, v45, v45
	v_fmac_f32_e32 v76, v44, v44
	v_fmac_f32_e32 v77, v46, v46
	v_add_f32_e32 v84, v76, v77
	v_lshl_add_u64 v[76:77], s[6:7], 0, v[98:99]
	v_lshlrev_b64 v[78:79], 11, v[96:97]
	v_lshl_add_u64 v[76:77], v[76:77], 0, v[158:159]
	v_lshl_add_u64 v[78:79], s[10:11], 0, v[78:79]
	global_store_dwordx4 v[76:77], v[44:47], off
	v_lshl_add_u64 v[78:79], v[156:157], 1, v[78:79]
	s_waitcnt vmcnt(15)
	v_pk_fma_f32 v[40:41], v[40:41], 0.5, v[72:73] op_sel_hi:[1,0,1]
	v_cvt_pk_bf16_f32 v44, v44, v45
	v_cvt_pk_bf16_f32 v45, v46, v47
	global_store_dwordx2 v[78:79], v[44:45], off
	v_pk_fma_f32 v[42:43], v[42:43], 0.5, v[74:75] op_sel_hi:[1,0,1]
	v_mul_f32_e32 v44, v41, v41
	v_fmac_f32_e32 v44, v40, v40
	v_mul_f32_e32 v45, v43, v43
	global_store_dwordx4 v[76:77], v[40:43], off offset:64
	s_waitcnt vmcnt(16)
	v_pk_fma_f32 v[38:39], v[38:39], 0.5, v[70:71] op_sel_hi:[1,0,1]
	v_pk_fma_f32 v[36:37], v[36:37], 0.5, v[68:69] op_sel_hi:[1,0,1]
	v_cvt_pk_bf16_f32 v40, v40, v41
	v_cvt_pk_bf16_f32 v41, v42, v43
	v_fmac_f32_e32 v45, v42, v42
	global_store_dwordx2 v[78:79], v[40:41], off offset:32
	v_mul_f32_e32 v40, v37, v37
	v_mul_f32_e32 v41, v39, v39
	v_add_f32_e32 v44, v44, v45
	v_fmac_f32_e32 v40, v36, v36
	v_fmac_f32_e32 v41, v38, v38
	v_add_f32_e32 v44, v84, v44
	v_add_f32_e32 v40, v40, v41
	v_add_f32_e32 v44, v44, v40
	s_waitcnt vmcnt(16)
	v_pk_fma_f32 v[42:43], v[34:35], 0.5, v[66:67] op_sel_hi:[1,0,1]
	v_pk_fma_f32 v[40:41], v[32:33], 0.5, v[64:65] op_sel_hi:[1,0,1]
	v_mul_f32_e32 v33, v43, v43
	v_mul_f32_e32 v32, v41, v41
	v_fmac_f32_e32 v32, v40, v40
	v_fmac_f32_e32 v33, v42, v42
	v_add_f32_e32 v32, v32, v33
	v_add_f32_e32 v34, v44, v32
	ds_bpermute_b32 v35, v177, v34
	v_cvt_pk_bf16_f32 v32, v36, v37
	v_cvt_pk_bf16_f32 v33, v38, v39
	global_store_dwordx4 v[76:77], v[36:39], off offset:512
	global_store_dwordx2 v[78:79], v[32:33], off offset:256
	s_waitcnt lgkmcnt(0)
	v_add_f32_e32 v32, v34, v35
	ds_bpermute_b32 v33, v178, v32
	v_cvt_pk_bf16_f32 v34, v40, v41
	v_cvt_pk_bf16_f32 v35, v42, v43
	global_store_dwordx4 v[76:77], v[40:43], off offset:576
	global_store_dwordx2 v[78:79], v[34:35], off offset:288
	s_mov_b32 vcc_lo, 0x11111111
	s_mov_b32 vcc_hi, 0x11111111
	s_and_saveexec_b64 s[56:57], vcc
	s_cbranch_execz .LBB0_265
	v_lshl_add_u64 v[34:35], v[96:97], 2, s[90:91]
	s_waitcnt lgkmcnt(0)
	v_add_f32_e32 v32, v32, v33
	global_atomic_add_f32 v[34:35], v32, off
.LBB0_265:
	s_or_b64 exec, exec, s[56:57]
	v_or_b32_e32 v64, 48, v112
	v_ashrrev_i32_e32 v65, 31, v64
	v_lshlrev_b64 v[66:67], 12, v[64:65]
	s_waitcnt lgkmcnt(0)
	v_lshl_add_u64 v[32:33], s[54:55], 0, v[66:67]
	v_lshl_add_u64 v[32:33], v[32:33], 0, v[158:159]
	global_load_dwordx4 v[44:47], v[32:33], off
	global_load_dwordx4 v[40:43], v[32:33], off offset:64
	global_load_dwordx4 v[36:39], v[32:33], off offset:512
	s_nop 0
	global_load_dwordx4 v[32:35], v[32:33], off offset:576
	s_waitcnt vmcnt(15)
	v_pk_fma_f32 v[30:31], v[30:31], 0.5, v[62:63] op_sel_hi:[1,0,1]
	v_pk_fma_f32 v[28:29], v[28:29], 0.5, v[60:61] op_sel_hi:[1,0,1]
	v_mul_f32_e32 v61, v31, v31
	v_mul_f32_e32 v60, v29, v29
	v_fmac_f32_e32 v60, v28, v28
	v_fmac_f32_e32 v61, v30, v30
	v_add_f32_e32 v68, v60, v61
	v_lshl_add_u64 v[60:61], s[6:7], 0, v[82:83]
	v_lshlrev_b64 v[62:63], 11, v[80:81]
	v_lshl_add_u64 v[60:61], v[60:61], 0, v[158:159]
	v_lshl_add_u64 v[62:63], s[10:11], 0, v[62:63]
	global_store_dwordx4 v[60:61], v[28:31], off
	v_lshl_add_u64 v[62:63], v[156:157], 1, v[62:63]
	s_waitcnt vmcnt(15)
	v_pk_fma_f32 v[24:25], v[24:25], 0.5, v[56:57] op_sel_hi:[1,0,1]
	v_cvt_pk_bf16_f32 v28, v28, v29
	v_cvt_pk_bf16_f32 v29, v30, v31
	global_store_dwordx2 v[62:63], v[28:29], off
	v_pk_fma_f32 v[26:27], v[26:27], 0.5, v[58:59] op_sel_hi:[1,0,1]
	v_mul_f32_e32 v28, v25, v25
	v_fmac_f32_e32 v28, v24, v24
	v_mul_f32_e32 v29, v27, v27
	global_store_dwordx4 v[60:61], v[24:27], off offset:64
	s_waitcnt vmcnt(16)
	v_pk_fma_f32 v[22:23], v[22:23], 0.5, v[54:55] op_sel_hi:[1,0,1]
	v_pk_fma_f32 v[20:21], v[20:21], 0.5, v[52:53] op_sel_hi:[1,0,1]
	v_cvt_pk_bf16_f32 v24, v24, v25
	v_cvt_pk_bf16_f32 v25, v26, v27
	v_fmac_f32_e32 v29, v26, v26
	global_store_dwordx2 v[62:63], v[24:25], off offset:32
	v_mul_f32_e32 v24, v21, v21
	v_mul_f32_e32 v25, v23, v23
	v_add_f32_e32 v28, v28, v29
	v_fmac_f32_e32 v24, v20, v20
	v_fmac_f32_e32 v25, v22, v22
	v_add_f32_e32 v28, v68, v28
	v_add_f32_e32 v24, v24, v25
	v_add_f32_e32 v28, v28, v24
	s_waitcnt vmcnt(16)
	v_pk_fma_f32 v[26:27], v[18:19], 0.5, v[50:51] op_sel_hi:[1,0,1]
	v_pk_fma_f32 v[24:25], v[16:17], 0.5, v[48:49] op_sel_hi:[1,0,1]
	v_mul_f32_e32 v17, v27, v27
	v_mul_f32_e32 v16, v25, v25
	v_fmac_f32_e32 v16, v24, v24
	v_fmac_f32_e32 v17, v26, v26
	v_add_f32_e32 v16, v16, v17
	v_add_f32_e32 v18, v28, v16
	ds_bpermute_b32 v19, v177, v18
	v_cvt_pk_bf16_f32 v16, v20, v21
	v_cvt_pk_bf16_f32 v17, v22, v23
	global_store_dwordx4 v[60:61], v[20:23], off offset:512
	global_store_dwordx2 v[62:63], v[16:17], off offset:256
	s_waitcnt lgkmcnt(0)
	v_add_f32_e32 v16, v18, v19
	ds_bpermute_b32 v17, v178, v16
	v_cvt_pk_bf16_f32 v18, v24, v25
	v_cvt_pk_bf16_f32 v19, v26, v27
	global_store_dwordx4 v[60:61], v[24:27], off offset:576
	global_store_dwordx2 v[62:63], v[18:19], off offset:288
	s_mov_b32 vcc_lo, 0x11111111
	s_mov_b32 vcc_hi, 0x11111111
	s_and_saveexec_b64 s[54:55], vcc
	s_cbranch_execz .LBB0_267
	v_lshl_add_u64 v[18:19], v[80:81], 2, s[90:91]
	s_waitcnt lgkmcnt(0)
	v_add_f32_e32 v16, v16, v17
	global_atomic_add_f32 v[18:19], v16, off
.LBB0_267:
	s_or_b64 exec, exec, s[54:55]
	s_waitcnt vmcnt(11)
	v_pk_fma_f32 v[14:15], v[14:15], 0.5, v[46:47] op_sel_hi:[1,0,1]
	v_pk_fma_f32 v[12:13], v[12:13], 0.5, v[44:45] op_sel_hi:[1,0,1]
	s_waitcnt lgkmcnt(0)
	v_mul_f32_e32 v17, v15, v15
	v_mul_f32_e32 v16, v13, v13
	v_fmac_f32_e32 v16, v12, v12
	v_fmac_f32_e32 v17, v14, v14
	v_add_f32_e32 v20, v16, v17
	v_lshl_add_u64 v[16:17], s[6:7], 0, v[66:67]
	v_lshlrev_b64 v[18:19], 11, v[64:65]
	v_lshl_add_u64 v[16:17], v[156:157], 2, v[16:17]
	v_lshl_add_u64 v[18:19], s[10:11], 0, v[18:19]
	global_store_dwordx4 v[16:17], v[12:15], off
	v_lshl_add_u64 v[18:19], v[156:157], 1, v[18:19]
	s_waitcnt vmcnt(11)
	v_pk_fma_f32 v[8:9], v[8:9], 0.5, v[40:41] op_sel_hi:[1,0,1]
	v_cvt_pk_bf16_f32 v12, v12, v13
	v_cvt_pk_bf16_f32 v13, v14, v15
	global_store_dwordx2 v[18:19], v[12:13], off
	v_pk_fma_f32 v[10:11], v[10:11], 0.5, v[42:43] op_sel_hi:[1,0,1]
	v_mul_f32_e32 v12, v9, v9
	v_fmac_f32_e32 v12, v8, v8
	v_mul_f32_e32 v13, v11, v11
	global_store_dwordx4 v[16:17], v[8:11], off offset:64
	s_waitcnt vmcnt(12)
	v_pk_fma_f32 v[6:7], v[6:7], 0.5, v[38:39] op_sel_hi:[1,0,1]
	v_pk_fma_f32 v[4:5], v[4:5], 0.5, v[36:37] op_sel_hi:[1,0,1]
	v_cvt_pk_bf16_f32 v8, v8, v9
	v_cvt_pk_bf16_f32 v9, v10, v11
	v_fmac_f32_e32 v13, v10, v10
	global_store_dwordx2 v[18:19], v[8:9], off offset:32
	v_mul_f32_e32 v8, v5, v5
	v_mul_f32_e32 v9, v7, v7
	v_add_f32_e32 v12, v12, v13
	v_fmac_f32_e32 v8, v4, v4
	v_fmac_f32_e32 v9, v6, v6
	v_add_f32_e32 v12, v20, v12
	v_add_f32_e32 v8, v8, v9
	v_add_f32_e32 v12, v12, v8
	s_waitcnt vmcnt(12)
	v_pk_fma_f32 v[10:11], v[2:3], 0.5, v[34:35] op_sel_hi:[1,0,1]
	v_pk_fma_f32 v[8:9], v[0:1], 0.5, v[32:33] op_sel_hi:[1,0,1]
	v_mul_f32_e32 v1, v11, v11
	v_mul_f32_e32 v0, v9, v9
	v_fmac_f32_e32 v0, v8, v8
	v_fmac_f32_e32 v1, v10, v10
	v_add_f32_e32 v0, v0, v1
	v_add_f32_e32 v2, v12, v0
	ds_bpermute_b32 v3, v177, v2
	v_cvt_pk_bf16_f32 v0, v4, v5
	v_cvt_pk_bf16_f32 v1, v6, v7
	global_store_dwordx4 v[16:17], v[4:7], off offset:512
	global_store_dwordx2 v[18:19], v[0:1], off offset:256
	s_waitcnt lgkmcnt(0)
	v_add_f32_e32 v0, v2, v3
	ds_bpermute_b32 v1, v178, v0
	v_cvt_pk_bf16_f32 v2, v8, v9
	v_cvt_pk_bf16_f32 v3, v10, v11
	global_store_dwordx4 v[16:17], v[8:11], off offset:576
	global_store_dwordx2 v[18:19], v[2:3], off offset:288
	s_mov_b32 vcc_lo, 0x11111111
	s_mov_b32 vcc_hi, 0x11111111
	s_and_saveexec_b64 s[54:55], vcc
	s_cbranch_execz .LBB0_269
	v_lshl_add_u64 v[2:3], v[64:65], 2, s[90:91]
	s_waitcnt lgkmcnt(0)
	v_add_f32_e32 v0, v0, v1
	global_atomic_add_f32 v[2:3], v0, off

.LBB0_1187:
	ds_read_b128 v[128:131], v171
	ds_read_b128 v[132:135], v171 offset:1024
	ds_read_b128 v[136:139], v171 offset:2048
	ds_read_b128 v[140:143], v171 offset:3072
	ds_read_b128 v[156:159], v172
	ds_read_b128 v[160:163], v172 offset:1024
	ds_read_b128 v[164:167], v172 offset:2048
	ds_read_b128 v[176:179], v172 offset:3072
	s_add_u32 s24, s22, 0x100
	s_addc_u32 s25, s23, 0
	s_cmp_eq_u32 s57, 40
	s_cselect_b32 s31, s5, s25
	s_cselect_b32 s30, s4, s24
	s_cselect_b32 s27, s21, s56
	s_cselect_b32 s26, s20, s55
	v_lshl_add_u64 v[188:189], s[22:23], 0, v[150:151]
	s_add_i32 m0, s38, 0xc000
	ds_read_b128 v[180:183], v173
	ds_read_b128 v[184:187], v173 offset:1024
	ds_read_b128 v[192:195], v173 offset:2048
	ds_read_b128 v[196:199], v173 offset:3072
	ds_read_b128 v[200:203], v173 offset:4096
	ds_read_b128 v[204:207], v173 offset:5120
	ds_read_b128 v[208:211], v173 offset:6144
	ds_read_b128 v[212:215], v173 offset:7168
	global_load_lds_dwordx4 v[188:189], off
	v_lshl_add_u64 v[188:189], s[22:23], 0, v[148:149]
	s_add_i32 m0, s38, 0xe000
	s_nop 0
	global_load_lds_dwordx4 v[188:189], off
	s_waitcnt vmcnt(8)
	s_waitcnt lgkmcnt(0)
	s_barrier
	s_setprio 1
	s_waitcnt lgkmcnt(0)
	v_mfma_f32_16x16x32_bf16 v[124:127], v[128:131], v[180:183], v[124:127]
	v_mfma_f32_16x16x32_bf16 v[120:123], v[136:139], v[180:183], v[120:123]
	v_mfma_f32_16x16x32_bf16 v[108:111], v[128:131], v[192:195], v[108:111]
	v_mfma_f32_16x16x32_bf16 v[104:107], v[136:139], v[192:195], v[104:107]
	v_mfma_f32_16x16x32_bf16 v[92:95], v[128:131], v[200:203], v[92:95]
	v_mfma_f32_16x16x32_bf16 v[88:91], v[136:139], v[200:203], v[88:91]
	v_mfma_f32_16x16x32_bf16 v[76:79], v[128:131], v[208:211], v[76:79]
	v_mfma_f32_16x16x32_bf16 v[72:75], v[136:139], v[208:211], v[72:75]
	v_mfma_f32_16x16x32_bf16 v[124:127], v[132:135], v[184:187], v[124:127]
	v_mfma_f32_16x16x32_bf16 v[120:123], v[140:143], v[184:187], v[120:123]
	v_mfma_f32_16x16x32_bf16 v[108:111], v[132:135], v[196:199], v[108:111]
	v_mfma_f32_16x16x32_bf16 v[104:107], v[140:143], v[196:199], v[104:107]
	v_mfma_f32_16x16x32_bf16 v[92:95], v[132:135], v[204:207], v[92:95]
	v_mfma_f32_16x16x32_bf16 v[88:91], v[140:143], v[204:207], v[88:91]
	v_mfma_f32_16x16x32_bf16 v[76:79], v[132:135], v[212:215], v[76:79]
	v_mfma_f32_16x16x32_bf16 v[72:75], v[140:143], v[212:215], v[72:75]
	s_setprio 0
	s_setprio 1
	v_mfma_f32_16x16x32_bf16 v[116:119], v[156:159], v[180:183], v[116:119]
	v_mfma_f32_16x16x32_bf16 v[112:115], v[164:167], v[180:183], v[112:115]
	v_mfma_f32_16x16x32_bf16 v[100:103], v[156:159], v[192:195], v[100:103]
	v_mfma_f32_16x16x32_bf16 v[96:99], v[164:167], v[192:195], v[96:99]
	v_mfma_f32_16x16x32_bf16 v[84:87], v[156:159], v[200:203], v[84:87]
	v_mfma_f32_16x16x32_bf16 v[80:83], v[164:167], v[200:203], v[80:83]
	v_mfma_f32_16x16x32_bf16 v[68:71], v[156:159], v[208:211], v[68:71]
	v_mfma_f32_16x16x32_bf16 v[64:67], v[164:167], v[208:211], v[64:67]
	v_mfma_f32_16x16x32_bf16 v[116:119], v[160:163], v[184:187], v[116:119]
	v_mfma_f32_16x16x32_bf16 v[112:115], v[176:179], v[184:187], v[112:115]
	v_mfma_f32_16x16x32_bf16 v[100:103], v[160:163], v[196:199], v[100:103]
	v_mfma_f32_16x16x32_bf16 v[96:99], v[176:179], v[196:199], v[96:99]
	v_mfma_f32_16x16x32_bf16 v[84:87], v[160:163], v[204:207], v[84:87]
	v_mfma_f32_16x16x32_bf16 v[80:83], v[176:179], v[204:207], v[80:83]
	v_mfma_f32_16x16x32_bf16 v[68:71], v[160:163], v[212:215], v[68:71]
	v_mfma_f32_16x16x32_bf16 v[64:67], v[176:179], v[212:215], v[64:67]
	s_setprio 0
	s_barrier
	s_add_i32 s22, s49, s37
	v_lshl_add_u64 v[188:189], s[26:27], 0, v[144:145]
	s_mov_b32 m0, s22
	ds_read_b128 v[180:183], v173 offset:16384
	ds_read_b128 v[184:187], v173 offset:17408
	ds_read_b128 v[192:195], v173 offset:18432
	ds_read_b128 v[196:199], v173 offset:19456
	ds_read_b128 v[200:203], v173 offset:20480
	ds_read_b128 v[204:207], v173 offset:21504
	ds_read_b128 v[208:211], v173 offset:22528
	ds_read_b128 v[212:215], v173 offset:23552
	global_load_lds_dwordx4 v[188:189], off
	s_add_i32 m0, s22, 0x2000
	s_add_u32 s22, s26, 0xb0000
	v_lshl_add_u64 v[216:217], s[26:27], 0, v[146:147]
	s_addc_u32 s23, s27, 0
	s_add_i32 s58, s50, s37
	global_load_lds_dwordx4 v[216:217], off
	v_lshl_add_u64 v[218:219], s[22:23], 0, v[144:145]
	s_mov_b32 m0, s58
	v_lshl_add_u64 v[220:221], s[30:31], 0, v[146:147]
	global_load_lds_dwordx4 v[218:219], off
	v_lshl_add_u64 v[218:219], s[22:23], 0, v[146:147]
	s_add_i32 m0, s58, 0x2000
	s_nop 0
	global_load_lds_dwordx4 v[218:219], off
	v_lshl_add_u64 v[218:219], s[30:31], 0, v[144:145]
	s_mov_b32 m0, s38
	s_nop 0
	global_load_lds_dwordx4 v[218:219], off
	s_mov_b32 m0, s39
	s_nop 0
	global_load_lds_dwordx4 v[220:221], off
	s_waitcnt vmcnt(8)
	s_waitcnt lgkmcnt(0)
	s_barrier
	s_setprio 1
	s_waitcnt lgkmcnt(0)
	v_mfma_f32_16x16x32_bf16 v[60:63], v[128:131], v[180:183], v[60:63]
	v_mfma_f32_16x16x32_bf16 v[56:59], v[136:139], v[180:183], v[56:59]
	v_mfma_f32_16x16x32_bf16 v[44:47], v[128:131], v[192:195], v[44:47]
	v_mfma_f32_16x16x32_bf16 v[40:43], v[136:139], v[192:195], v[40:43]
	v_mfma_f32_16x16x32_bf16 v[28:31], v[128:131], v[200:203], v[28:31]
	v_mfma_f32_16x16x32_bf16 v[24:27], v[136:139], v[200:203], v[24:27]
	v_mfma_f32_16x16x32_bf16 v[12:15], v[128:131], v[208:211], v[12:15]
	v_mfma_f32_16x16x32_bf16 v[8:11], v[136:139], v[208:211], v[8:11]
	v_mfma_f32_16x16x32_bf16 v[60:63], v[132:135], v[184:187], v[60:63]
	v_mfma_f32_16x16x32_bf16 v[56:59], v[140:143], v[184:187], v[56:59]
	v_mfma_f32_16x16x32_bf16 v[44:47], v[132:135], v[196:199], v[44:47]
	v_mfma_f32_16x16x32_bf16 v[40:43], v[140:143], v[196:199], v[40:43]
	v_mfma_f32_16x16x32_bf16 v[28:31], v[132:135], v[204:207], v[28:31]
	v_mfma_f32_16x16x32_bf16 v[24:27], v[140:143], v[204:207], v[24:27]
	v_mfma_f32_16x16x32_bf16 v[12:15], v[132:135], v[212:215], v[12:15]
	v_mfma_f32_16x16x32_bf16 v[8:11], v[140:143], v[212:215], v[8:11]
	s_setprio 0
	s_setprio 1
	v_mfma_f32_16x16x32_bf16 v[52:55], v[156:159], v[180:183], v[52:55]
	v_mfma_f32_16x16x32_bf16 v[48:51], v[164:167], v[180:183], v[48:51]
	v_mfma_f32_16x16x32_bf16 v[36:39], v[156:159], v[192:195], v[36:39]
	v_mfma_f32_16x16x32_bf16 v[32:35], v[164:167], v[192:195], v[32:35]
	v_mfma_f32_16x16x32_bf16 v[20:23], v[156:159], v[200:203], v[20:23]
	v_mfma_f32_16x16x32_bf16 v[16:19], v[164:167], v[200:203], v[16:19]
	v_mfma_f32_16x16x32_bf16 v[4:7], v[156:159], v[208:211], v[4:7]
	v_mfma_f32_16x16x32_bf16 v[0:3], v[164:167], v[208:211], v[0:3]
	v_mfma_f32_16x16x32_bf16 v[52:55], v[160:163], v[184:187], v[52:55]
	v_mfma_f32_16x16x32_bf16 v[48:51], v[176:179], v[184:187], v[48:51]
	v_mfma_f32_16x16x32_bf16 v[36:39], v[160:163], v[196:199], v[36:39]
	v_mfma_f32_16x16x32_bf16 v[32:35], v[176:179], v[196:199], v[32:35]
	v_mfma_f32_16x16x32_bf16 v[20:23], v[160:163], v[204:207], v[20:23]
	v_mfma_f32_16x16x32_bf16 v[16:19], v[176:179], v[204:207], v[16:19]
	v_mfma_f32_16x16x32_bf16 v[4:7], v[160:163], v[212:215], v[4:7]
	v_mfma_f32_16x16x32_bf16 v[0:3], v[176:179], v[212:215], v[0:3]
	s_setprio 0
	s_barrier
	s_add_i32 s58, 0, 0x18000
	s_add_i32 s59, 0, 0x1c000
	v_add_u32_e32 v140, s58, v169
	v_add_u32_e32 v175, s59, v169
	ds_read_b128 v[128:131], v140
	ds_read_b128 v[132:135], v140 offset:1024
	ds_read_b128 v[136:139], v140 offset:2048
	ds_read_b128 v[140:143], v140 offset:3072
	ds_read_b128 v[156:159], v175
	ds_read_b128 v[160:163], v175 offset:1024
	ds_read_b128 v[164:167], v175 offset:2048
	ds_read_b128 v[176:179], v175 offset:3072
	s_add_u32 s22, s30, 0xb0000
	s_addc_u32 s23, s31, 0
	s_mov_b32 m0, s40
	v_lshl_add_u64 v[222:223], s[22:23], 0, v[144:145]
	ds_read_b128 v[180:183], v173 offset:32768
	ds_read_b128 v[184:187], v173 offset:33792
	ds_read_b128 v[192:195], v173 offset:34816
	ds_read_b128 v[196:199], v173 offset:35840
	ds_read_b128 v[200:203], v173 offset:36864
	ds_read_b128 v[204:207], v173 offset:37888
	ds_read_b128 v[208:211], v173 offset:38912
	ds_read_b128 v[212:215], v173 offset:39936
	global_load_lds_dwordx4 v[222:223], off
	v_lshl_add_u64 v[222:223], s[22:23], 0, v[146:147]
	s_mov_b32 m0, s41
	s_nop 0
	global_load_lds_dwordx4 v[222:223], off
	s_waitcnt vmcnt(8)
	s_waitcnt lgkmcnt(0)
	s_barrier
	s_setprio 1
	s_waitcnt lgkmcnt(0)
	v_mfma_f32_16x16x32_bf16 v[124:127], v[128:131], v[180:183], v[124:127]
	v_mfma_f32_16x16x32_bf16 v[120:123], v[136:139], v[180:183], v[120:123]
	v_mfma_f32_16x16x32_bf16 v[108:111], v[128:131], v[192:195], v[108:111]
	v_mfma_f32_16x16x32_bf16 v[104:107], v[136:139], v[192:195], v[104:107]
	v_mfma_f32_16x16x32_bf16 v[92:95], v[128:131], v[200:203], v[92:95]
	v_mfma_f32_16x16x32_bf16 v[88:91], v[136:139], v[200:203], v[88:91]
	v_mfma_f32_16x16x32_bf16 v[76:79], v[128:131], v[208:211], v[76:79]
	v_mfma_f32_16x16x32_bf16 v[72:75], v[136:139], v[208:211], v[72:75]
	v_mfma_f32_16x16x32_bf16 v[124:127], v[132:135], v[184:187], v[124:127]
	v_mfma_f32_16x16x32_bf16 v[120:123], v[140:143], v[184:187], v[120:123]
	v_mfma_f32_16x16x32_bf16 v[108:111], v[132:135], v[196:199], v[108:111]
	v_mfma_f32_16x16x32_bf16 v[104:107], v[140:143], v[196:199], v[104:107]
	v_mfma_f32_16x16x32_bf16 v[92:95], v[132:135], v[204:207], v[92:95]
	v_mfma_f32_16x16x32_bf16 v[88:91], v[140:143], v[204:207], v[88:91]
	v_mfma_f32_16x16x32_bf16 v[76:79], v[132:135], v[212:215], v[76:79]
	v_mfma_f32_16x16x32_bf16 v[72:75], v[140:143], v[212:215], v[72:75]
	s_setprio 0
	s_setprio 1
	v_mfma_f32_16x16x32_bf16 v[116:119], v[156:159], v[180:183], v[116:119]
	v_mfma_f32_16x16x32_bf16 v[112:115], v[164:167], v[180:183], v[112:115]
	v_mfma_f32_16x16x32_bf16 v[100:103], v[156:159], v[192:195], v[100:103]
	v_mfma_f32_16x16x32_bf16 v[96:99], v[164:167], v[192:195], v[96:99]
	v_mfma_f32_16x16x32_bf16 v[84:87], v[156:159], v[200:203], v[84:87]
	v_mfma_f32_16x16x32_bf16 v[80:83], v[164:167], v[200:203], v[80:83]
	v_mfma_f32_16x16x32_bf16 v[68:71], v[156:159], v[208:211], v[68:71]
	v_mfma_f32_16x16x32_bf16 v[64:67], v[164:167], v[208:211], v[64:67]
	v_mfma_f32_16x16x32_bf16 v[116:119], v[160:163], v[184:187], v[116:119]
	v_mfma_f32_16x16x32_bf16 v[112:115], v[176:179], v[184:187], v[112:115]
	v_mfma_f32_16x16x32_bf16 v[100:103], v[160:163], v[196:199], v[100:103]
	v_mfma_f32_16x16x32_bf16 v[96:99], v[176:179], v[196:199], v[96:99]
	v_mfma_f32_16x16x32_bf16 v[84:87], v[160:163], v[204:207], v[84:87]
	v_mfma_f32_16x16x32_bf16 v[80:83], v[176:179], v[204:207], v[80:83]
	v_mfma_f32_16x16x32_bf16 v[68:71], v[160:163], v[212:215], v[68:71]
	v_mfma_f32_16x16x32_bf16 v[64:67], v[176:179], v[212:215], v[64:67]
	s_setprio 0
	s_barrier
	s_add_i32 s22, s58, s37
	v_lshl_add_u64 v[188:189], v[188:189], 0, s[16:17]
	s_mov_b32 m0, s22
	ds_read_b128 v[180:183], v173 offset:49152
	ds_read_b128 v[184:187], v173 offset:50176
	ds_read_b128 v[192:195], v173 offset:51200
	ds_read_b128 v[196:199], v173 offset:52224
	ds_read_b128 v[200:203], v173 offset:53248
	ds_read_b128 v[204:207], v173 offset:54272
	ds_read_b128 v[208:211], v173 offset:55296
	ds_read_b128 v[212:215], v173 offset:56320
	global_load_lds_dwordx4 v[188:189], off
	s_add_i32 m0, s22, 0x2000
	s_add_u32 s22, s26, 0xb0080
	v_lshl_add_u64 v[188:189], v[216:217], 0, s[16:17]
	s_addc_u32 s23, s27, 0
	s_add_i32 s26, s59, s37
	global_load_lds_dwordx4 v[188:189], off
	v_lshl_add_u64 v[188:189], s[22:23], 0, v[144:145]
	s_mov_b32 m0, s26
	s_nop 0
	global_load_lds_dwordx4 v[188:189], off
	v_lshl_add_u64 v[188:189], s[22:23], 0, v[146:147]
	s_add_i32 m0, s26, 0x2000
	s_nop 0
	global_load_lds_dwordx4 v[188:189], off
	v_lshl_add_u64 v[188:189], v[218:219], 0, s[16:17]
	s_mov_b32 m0, s43
	s_nop 0
	global_load_lds_dwordx4 v[188:189], off
	v_lshl_add_u64 v[188:189], v[220:221], 0, s[16:17]
	s_mov_b32 m0, s44
	s_nop 0
	global_load_lds_dwordx4 v[188:189], off
	s_waitcnt vmcnt(8)
	s_waitcnt lgkmcnt(0)
	s_barrier
	s_setprio 1
	s_waitcnt lgkmcnt(0)
	v_mfma_f32_16x16x32_bf16 v[60:63], v[128:131], v[180:183], v[60:63]
	v_mfma_f32_16x16x32_bf16 v[56:59], v[136:139], v[180:183], v[56:59]
	v_mfma_f32_16x16x32_bf16 v[44:47], v[128:131], v[192:195], v[44:47]
	v_mfma_f32_16x16x32_bf16 v[40:43], v[136:139], v[192:195], v[40:43]
	v_mfma_f32_16x16x32_bf16 v[28:31], v[128:131], v[200:203], v[28:31]
	v_mfma_f32_16x16x32_bf16 v[24:27], v[136:139], v[200:203], v[24:27]
	v_mfma_f32_16x16x32_bf16 v[12:15], v[128:131], v[208:211], v[12:15]
	v_mfma_f32_16x16x32_bf16 v[8:11], v[136:139], v[208:211], v[8:11]
	v_mfma_f32_16x16x32_bf16 v[60:63], v[132:135], v[184:187], v[60:63]
	v_mfma_f32_16x16x32_bf16 v[56:59], v[140:143], v[184:187], v[56:59]
	v_mfma_f32_16x16x32_bf16 v[44:47], v[132:135], v[196:199], v[44:47]
	v_mfma_f32_16x16x32_bf16 v[40:43], v[140:143], v[196:199], v[40:43]
	v_mfma_f32_16x16x32_bf16 v[28:31], v[132:135], v[204:207], v[28:31]
	v_mfma_f32_16x16x32_bf16 v[24:27], v[140:143], v[204:207], v[24:27]
	v_mfma_f32_16x16x32_bf16 v[12:15], v[132:135], v[212:215], v[12:15]
	v_mfma_f32_16x16x32_bf16 v[8:11], v[140:143], v[212:215], v[8:11]
	s_setprio 0
	s_setprio 1
	v_mfma_f32_16x16x32_bf16 v[52:55], v[156:159], v[180:183], v[52:55]
	v_mfma_f32_16x16x32_bf16 v[48:51], v[164:167], v[180:183], v[48:51]
	v_mfma_f32_16x16x32_bf16 v[36:39], v[156:159], v[192:195], v[36:39]
	v_mfma_f32_16x16x32_bf16 v[32:35], v[164:167], v[192:195], v[32:35]
	v_mfma_f32_16x16x32_bf16 v[20:23], v[156:159], v[200:203], v[20:23]
	v_mfma_f32_16x16x32_bf16 v[16:19], v[164:167], v[200:203], v[16:19]
	v_mfma_f32_16x16x32_bf16 v[4:7], v[156:159], v[208:211], v[4:7]
	v_mfma_f32_16x16x32_bf16 v[0:3], v[164:167], v[208:211], v[0:3]
	v_mfma_f32_16x16x32_bf16 v[52:55], v[160:163], v[184:187], v[52:55]
	v_mfma_f32_16x16x32_bf16 v[48:51], v[176:179], v[184:187], v[48:51]
	v_mfma_f32_16x16x32_bf16 v[36:39], v[160:163], v[196:199], v[36:39]
	v_mfma_f32_16x16x32_bf16 v[32:35], v[176:179], v[196:199], v[32:35]
	v_mfma_f32_16x16x32_bf16 v[20:23], v[160:163], v[204:207], v[20:23]
	v_mfma_f32_16x16x32_bf16 v[16:19], v[176:179], v[204:207], v[16:19]
	v_mfma_f32_16x16x32_bf16 v[4:7], v[160:163], v[212:215], v[4:7]
	v_mfma_f32_16x16x32_bf16 v[0:3], v[176:179], v[212:215], v[0:3]
	s_setprio 0
	s_barrier
	s_add_i32 s57, s57, 2
	s_add_u32 s55, s55, 0x100
	s_addc_u32 s56, s56, 0
	s_cmp_gt_u32 s57, 41
	s_mov_b64 s[22:23], s[24:25]
	s_cbranch_scc0 .LBB0_1187
	v_mbcnt_lo_u32_b32 v235, -1, 0
	v_mbcnt_hi_u32_b32 v235, -1, v235
	v_lshrrev_b32_e32 v236, 2, v235
	v_and_b32_e32 v237, 3, v235
	v_lshl_add_u32 v232, v237, 4, v236
	v_lshlrev_b32_e32 v232, 2, v232
	v_and_b32_e32 v233, -16, v168
	v_or_b32_e32 v233, v233, v236
	v_lshlrev_b32_e32 v237, 2, v237
	v_and_b32_e32 v234, -13, v170
	v_or_b32_e32 v234, v234, v237
	ds_bpermute_b32 v127, v232, v127
	ds_bpermute_b32 v126, v232, v126
	ds_bpermute_b32 v125, v232, v125
	ds_bpermute_b32 v124, v232, v124
	ds_bpermute_b32 v123, v232, v123
	ds_bpermute_b32 v122, v232, v122
	ds_bpermute_b32 v121, v232, v121
	ds_bpermute_b32 v120, v232, v120
	ds_bpermute_b32 v119, v232, v119
	ds_bpermute_b32 v118, v232, v118
	ds_bpermute_b32 v117, v232, v117
	ds_bpermute_b32 v116, v232, v116
	ds_bpermute_b32 v115, v232, v115
	ds_bpermute_b32 v114, v232, v114
	ds_bpermute_b32 v113, v232, v113
	ds_bpermute_b32 v112, v232, v112
	ds_bpermute_b32 v111, v232, v111
	ds_bpermute_b32 v110, v232, v110
	ds_bpermute_b32 v109, v232, v109
	ds_bpermute_b32 v108, v232, v108
	ds_bpermute_b32 v107, v232, v107
	ds_bpermute_b32 v106, v232, v106
	ds_bpermute_b32 v105, v232, v105
	ds_bpermute_b32 v104, v232, v104
	ds_bpermute_b32 v103, v232, v103
	ds_bpermute_b32 v102, v232, v102
	ds_bpermute_b32 v101, v232, v101
	ds_bpermute_b32 v100, v232, v100
	ds_bpermute_b32 v99, v232, v99
	ds_bpermute_b32 v98, v232, v98
	ds_bpermute_b32 v97, v232, v97
	ds_bpermute_b32 v96, v232, v96
	ds_bpermute_b32 v95, v232, v95
	ds_bpermute_b32 v94, v232, v94
	ds_bpermute_b32 v93, v232, v93
	ds_bpermute_b32 v92, v232, v92
	ds_bpermute_b32 v91, v232, v91
	ds_bpermute_b32 v90, v232, v90
	ds_bpermute_b32 v89, v232, v89
	ds_bpermute_b32 v88, v232, v88
	ds_bpermute_b32 v87, v232, v87
	ds_bpermute_b32 v86, v232, v86
	ds_bpermute_b32 v85, v232, v85
	ds_bpermute_b32 v84, v232, v84
	ds_bpermute_b32 v83, v232, v83
	ds_bpermute_b32 v82, v232, v82
	ds_bpermute_b32 v81, v232, v81
	ds_bpermute_b32 v80, v232, v80
	ds_bpermute_b32 v79, v232, v79
	ds_bpermute_b32 v78, v232, v78
	ds_bpermute_b32 v77, v232, v77
	ds_bpermute_b32 v76, v232, v76
	ds_bpermute_b32 v75, v232, v75
	ds_bpermute_b32 v74, v232, v74
	ds_bpermute_b32 v73, v232, v73
	ds_bpermute_b32 v72, v232, v72
	ds_bpermute_b32 v71, v232, v71
	ds_bpermute_b32 v70, v232, v70
	ds_bpermute_b32 v69, v232, v69
	ds_bpermute_b32 v68, v232, v68
	ds_bpermute_b32 v67, v232, v67
	ds_bpermute_b32 v66, v232, v66
	ds_bpermute_b32 v65, v232, v65
	ds_bpermute_b32 v64, v232, v64
	ds_bpermute_b32 v63, v232, v63
	ds_bpermute_b32 v62, v232, v62
	ds_bpermute_b32 v61, v232, v61
	ds_bpermute_b32 v60, v232, v60
	ds_bpermute_b32 v59, v232, v59
	ds_bpermute_b32 v58, v232, v58
	ds_bpermute_b32 v57, v232, v57
	ds_bpermute_b32 v56, v232, v56
	ds_bpermute_b32 v55, v232, v55
	ds_bpermute_b32 v54, v232, v54
	ds_bpermute_b32 v53, v232, v53
	ds_bpermute_b32 v52, v232, v52
	ds_bpermute_b32 v51, v232, v51
	ds_bpermute_b32 v50, v232, v50
	ds_bpermute_b32 v49, v232, v49
	ds_bpermute_b32 v48, v232, v48
	ds_bpermute_b32 v47, v232, v47
	ds_bpermute_b32 v46, v232, v46
	ds_bpermute_b32 v45, v232, v45
	ds_bpermute_b32 v44, v232, v44
	ds_bpermute_b32 v43, v232, v43
	ds_bpermute_b32 v42, v232, v42
	ds_bpermute_b32 v41, v232, v41
	ds_bpermute_b32 v40, v232, v40
	ds_bpermute_b32 v39, v232, v39
	ds_bpermute_b32 v38, v232, v38
	ds_bpermute_b32 v37, v232, v37
	ds_bpermute_b32 v36, v232, v36
	ds_bpermute_b32 v35, v232, v35
	ds_bpermute_b32 v34, v232, v34
	ds_bpermute_b32 v33, v232, v33
	ds_bpermute_b32 v32, v232, v32
	ds_bpermute_b32 v31, v232, v31
	ds_bpermute_b32 v30, v232, v30
	ds_bpermute_b32 v29, v232, v29
	ds_bpermute_b32 v28, v232, v28
	ds_bpermute_b32 v27, v232, v27
	ds_bpermute_b32 v26, v232, v26
	ds_bpermute_b32 v25, v232, v25
	ds_bpermute_b32 v24, v232, v24
	ds_bpermute_b32 v23, v232, v23
	ds_bpermute_b32 v22, v232, v22
	ds_bpermute_b32 v21, v232, v21
	ds_bpermute_b32 v20, v232, v20
	ds_bpermute_b32 v19, v232, v19
	ds_bpermute_b32 v18, v232, v18
	ds_bpermute_b32 v17, v232, v17
	ds_bpermute_b32 v16, v232, v16
	ds_bpermute_b32 v15, v232, v15
	ds_bpermute_b32 v14, v232, v14
	ds_bpermute_b32 v13, v232, v13
	ds_bpermute_b32 v12, v232, v12
	ds_bpermute_b32 v11, v232, v11
	ds_bpermute_b32 v10, v232, v10
	ds_bpermute_b32 v9, v232, v9
	ds_bpermute_b32 v8, v232, v8
	ds_bpermute_b32 v7, v232, v7
	ds_bpermute_b32 v6, v232, v6
	ds_bpermute_b32 v5, v232, v5
	ds_bpermute_b32 v4, v232, v4
	ds_bpermute_b32 v3, v232, v3
	ds_bpermute_b32 v2, v232, v2
	ds_bpermute_b32 v1, v232, v1
	ds_bpermute_b32 v0, v232, v0
	s_waitcnt lgkmcnt(0)
	v_lshl_add_u32 v158, s54, 8, v233
	v_lshl_or_b32 v156, s53, 8, v234
	v_ashrrev_i32_e32 v159, 31, v158
	v_lshlrev_b64 v[128:129], 12, v[158:159]
	v_ashrrev_i32_e32 v157, 31, v156
	v_lshl_add_u64 v[128:129], s[8:9], 0, v[128:129]
	v_lshlrev_b64 v[130:131], 2, v[156:157]
	v_lshl_add_u64 v[188:189], v[128:129], 0, v[130:131]
	global_load_dwordx4 v[164:167], v[188:189], off
	global_load_dwordx4 v[176:179], v[188:189], off offset:64
	global_load_dwordx4 v[180:183], v[188:189], off offset:512
	global_load_dwordx4 v[184:187], v[188:189], off offset:576
	v_or_b32_e32 v160, 16, v158
	v_ashrrev_i32_e32 v161, 31, v160
	v_lshlrev_b64 v[128:129], 12, v[160:161]
	v_lshl_add_u64 v[128:129], s[8:9], 0, v[128:129]
	v_lshl_add_u64 v[162:163], v[128:129], 0, v[130:131]
	global_load_dwordx4 v[140:143], v[162:163], off
	global_load_dwordx4 v[136:139], v[162:163], off offset:64
	global_load_dwordx4 v[132:135], v[162:163], off offset:512
	global_load_dwordx4 v[128:131], v[162:163], off offset:576
	v_lshlrev_b64 v[192:193], 11, v[158:159]
	v_lshl_add_u64 v[192:193], s[12:13], 0, v[192:193]
	v_and_b32_e32 v191, 64, v174
	v_lshl_add_u64 v[192:193], v[156:157], 1, v[192:193]
	v_xor_b32_e32 v175, 1, v174
	v_add_u32_e32 v191, 64, v191
	v_cmp_lt_i32_e32 vcc, v175, v191
	v_xor_b32_e32 v194, 2, v174
	s_waitcnt lgkmcnt(0)
	s_cmp_eq_u64 s[18:19], 0
	s_cbranch_scc1 .LBB0_1190
	s_barrier
.LBB0_1190:
	s_waitcnt vmcnt(7)
	v_pk_fma_f32 v[126:127], v[126:127], 0.5, v[166:167] op_sel_hi:[1,0,1]
	v_pk_fma_f32 v[124:125], v[124:125], 0.5, v[164:165] op_sel_hi:[1,0,1]
	s_waitcnt vmcnt(6)
	v_pk_fma_f32 v[122:123], v[122:123], 0.5, v[178:179] op_sel_hi:[1,0,1]
	v_pk_fma_f32 v[120:121], v[120:121], 0.5, v[176:177] op_sel_hi:[1,0,1]
	s_waitcnt vmcnt(5)
	v_pk_fma_f32 v[118:119], v[118:119], 0.5, v[182:183] op_sel_hi:[1,0,1]
	v_pk_fma_f32 v[116:117], v[116:117], 0.5, v[180:181] op_sel_hi:[1,0,1]
	s_waitcnt vmcnt(4)
	v_pk_fma_f32 v[164:165], v[112:113], 0.5, v[184:185] op_sel_hi:[1,0,1]
	v_mul_f32_e32 v178, v125, v125
	v_mul_f32_e32 v179, v127, v127
	global_store_dwordx4 v[188:189], v[124:127], off
	v_cvt_pk_bf16_f32 v112, v124, v125
	v_cvt_pk_bf16_f32 v113, v126, v127
	v_mul_f32_e32 v125, v121, v121
	v_mul_f32_e32 v127, v123, v123
	v_pk_fma_f32 v[166:167], v[114:115], 0.5, v[186:187] op_sel_hi:[1,0,1]
	v_mul_f32_e32 v180, v117, v117
	v_mul_f32_e32 v181, v119, v119
	v_fmac_f32_e32 v178, v124, v124
	v_fmac_f32_e32 v179, v126, v126
	v_fmac_f32_e32 v125, v120, v120
	v_fmac_f32_e32 v127, v122, v122
	v_mul_f32_e32 v182, v165, v165
	v_mul_f32_e32 v183, v167, v167
	global_store_dwordx2 v[192:193], v[112:113], off
	v_fmac_f32_e32 v180, v116, v116
	v_fmac_f32_e32 v181, v118, v118
	v_add_f32_e32 v112, v178, v179
	v_add_f32_e32 v113, v125, v127
	v_fmac_f32_e32 v182, v164, v164
	v_fmac_f32_e32 v183, v166, v166
	v_add_f32_e32 v124, v180, v181
	v_add_f32_e32 v112, v112, v113
	v_cndmask_b32_e32 v175, v174, v175, vcc
	v_add_f32_e32 v125, v182, v183
	v_add_f32_e32 v112, v112, v124
	v_lshlrev_b32_e32 v175, 2, v175
	v_add_f32_e32 v112, v112, v125
	ds_bpermute_b32 v113, v175, v112
	v_cmp_lt_i32_e32 vcc, v194, v191
	v_cvt_pk_bf16_f32 v176, v116, v117
	v_cvt_pk_bf16_f32 v114, v120, v121
	v_cndmask_b32_e32 v191, v174, v194, vcc
	v_cvt_pk_bf16_f32 v115, v122, v123
	v_cvt_pk_bf16_f32 v177, v118, v119
	global_store_dwordx4 v[188:189], v[120:123], off offset:64
	global_store_dwordx2 v[192:193], v[114:115], off offset:32
	global_store_dwordx4 v[188:189], v[116:119], off offset:512
	global_store_dwordx2 v[192:193], v[176:177], off offset:256
	s_waitcnt lgkmcnt(0)
	v_add_f32_e32 v112, v112, v113
	v_lshlrev_b32_e32 v176, 2, v191
	ds_bpermute_b32 v113, v176, v112
	v_cvt_pk_bf16_f32 v114, v164, v165
	v_cvt_pk_bf16_f32 v115, v166, v167
	global_store_dwordx4 v[188:189], v[164:167], off offset:576
	global_store_dwordx2 v[192:193], v[114:115], off offset:288
	s_mov_b32 vcc_lo, 0x11111111
	s_mov_b32 vcc_hi, 0x11111111
	s_and_saveexec_b64 s[22:23], vcc
	s_cbranch_execz .LBB0_1192
	v_lshl_add_u64 v[114:115], v[158:159], 2, s[14:15]
	s_waitcnt lgkmcnt(0)
	v_add_f32_e32 v112, v112, v113
	global_atomic_add_f32 v[114:115], v112, off
.LBB0_1192:
	s_or_b64 exec, exec, s[22:23]
	v_or_b32_e32 v164, 32, v158
	v_ashrrev_i32_e32 v165, 31, v164
	s_waitcnt lgkmcnt(0)
	v_lshlrev_b64 v[112:113], 12, v[164:165]
	v_lshl_add_u64 v[112:113], s[8:9], 0, v[112:113]
	v_lshl_add_u64 v[166:167], v[156:157], 2, v[112:113]
	global_load_dwordx4 v[124:127], v[166:167], off
	global_load_dwordx4 v[120:123], v[166:167], off offset:64
	global_load_dwordx4 v[116:119], v[166:167], off offset:512
	global_load_dwordx4 v[112:115], v[166:167], off offset:576
	s_waitcnt vmcnt(15)
	v_pk_fma_f32 v[110:111], v[110:111], 0.5, v[142:143] op_sel_hi:[1,0,1]
	v_pk_fma_f32 v[108:109], v[108:109], 0.5, v[140:141] op_sel_hi:[1,0,1]
	v_mul_f32_e32 v141, v111, v111
	v_mul_f32_e32 v140, v109, v109
	v_fmac_f32_e32 v140, v108, v108
	v_fmac_f32_e32 v141, v110, v110
	v_add_f32_e32 v142, v140, v141
	v_lshlrev_b64 v[140:141], 11, v[160:161]
	v_lshl_add_u64 v[140:141], s[12:13], 0, v[140:141]
	global_store_dwordx4 v[162:163], v[108:111], off
	v_lshl_add_u64 v[140:141], v[156:157], 1, v[140:141]
	s_waitcnt vmcnt(15)
	v_pk_fma_f32 v[104:105], v[104:105], 0.5, v[136:137] op_sel_hi:[1,0,1]
	v_cvt_pk_bf16_f32 v108, v108, v109
	v_cvt_pk_bf16_f32 v109, v110, v111
	global_store_dwordx2 v[140:141], v[108:109], off
	v_pk_fma_f32 v[106:107], v[106:107], 0.5, v[138:139] op_sel_hi:[1,0,1]
	v_mul_f32_e32 v108, v105, v105
	v_fmac_f32_e32 v108, v104, v104
	v_mul_f32_e32 v109, v107, v107
	global_store_dwordx4 v[162:163], v[104:107], off offset:64
	s_waitcnt vmcnt(16)
	v_pk_fma_f32 v[102:103], v[102:103], 0.5, v[134:135] op_sel_hi:[1,0,1]
	v_pk_fma_f32 v[100:101], v[100:101], 0.5, v[132:133] op_sel_hi:[1,0,1]
	v_cvt_pk_bf16_f32 v104, v104, v105
	v_cvt_pk_bf16_f32 v105, v106, v107
	v_fmac_f32_e32 v109, v106, v106
	global_store_dwordx2 v[140:141], v[104:105], off offset:32
	v_mul_f32_e32 v104, v101, v101
	v_mul_f32_e32 v105, v103, v103
	v_add_f32_e32 v108, v108, v109
	v_fmac_f32_e32 v104, v100, v100
	v_fmac_f32_e32 v105, v102, v102
	v_add_f32_e32 v108, v142, v108
	v_add_f32_e32 v104, v104, v105
	v_add_f32_e32 v108, v108, v104
	s_waitcnt vmcnt(16)
	v_pk_fma_f32 v[106:107], v[98:99], 0.5, v[130:131] op_sel_hi:[1,0,1]
	v_pk_fma_f32 v[104:105], v[96:97], 0.5, v[128:129] op_sel_hi:[1,0,1]
	v_mul_f32_e32 v97, v107, v107
	v_mul_f32_e32 v96, v105, v105
	v_fmac_f32_e32 v96, v104, v104
	v_fmac_f32_e32 v97, v106, v106
	v_add_f32_e32 v96, v96, v97
	v_add_f32_e32 v98, v108, v96
	ds_bpermute_b32 v99, v175, v98
	v_cvt_pk_bf16_f32 v96, v100, v101
	v_cvt_pk_bf16_f32 v97, v102, v103
	global_store_dwordx4 v[162:163], v[100:103], off offset:512
	global_store_dwordx2 v[140:141], v[96:97], off offset:256
	s_waitcnt lgkmcnt(0)
	v_add_f32_e32 v96, v98, v99
	ds_bpermute_b32 v97, v176, v96
	v_cvt_pk_bf16_f32 v98, v104, v105
	v_cvt_pk_bf16_f32 v99, v106, v107
	global_store_dwordx4 v[162:163], v[104:107], off offset:576
	global_store_dwordx2 v[140:141], v[98:99], off offset:288
	s_mov_b32 vcc_lo, 0x11111111
	s_mov_b32 vcc_hi, 0x11111111
	s_and_saveexec_b64 s[22:23], vcc
	s_cbranch_execz .LBB0_1194
	v_lshl_add_u64 v[98:99], v[160:161], 2, s[14:15]
	s_waitcnt lgkmcnt(0)
	v_add_f32_e32 v96, v96, v97
	global_atomic_add_f32 v[98:99], v96, off
.LBB0_1194:
	s_or_b64 exec, exec, s[22:23]
	v_or_b32_e32 v128, 48, v158
	v_ashrrev_i32_e32 v129, 31, v128
	s_waitcnt lgkmcnt(0)
	v_lshlrev_b64 v[96:97], 12, v[128:129]
	v_lshl_add_u64 v[96:97], s[8:9], 0, v[96:97]
	v_lshl_add_u64 v[130:131], v[156:157], 2, v[96:97]
	global_load_dwordx4 v[108:111], v[130:131], off
	global_load_dwordx4 v[104:107], v[130:131], off offset:64
	global_load_dwordx4 v[100:103], v[130:131], off offset:512
	global_load_dwordx4 v[96:99], v[130:131], off offset:576
	s_waitcnt vmcnt(15)
	v_pk_fma_f32 v[94:95], v[94:95], 0.5, v[126:127] op_sel_hi:[1,0,1]
	v_pk_fma_f32 v[92:93], v[92:93], 0.5, v[124:125] op_sel_hi:[1,0,1]
	v_mul_f32_e32 v125, v95, v95
	v_mul_f32_e32 v124, v93, v93
	v_fmac_f32_e32 v124, v92, v92
	v_fmac_f32_e32 v125, v94, v94
	v_add_f32_e32 v126, v124, v125
	v_lshlrev_b64 v[124:125], 11, v[164:165]
	v_lshl_add_u64 v[124:125], s[12:13], 0, v[124:125]
	global_store_dwordx4 v[166:167], v[92:95], off
	v_lshl_add_u64 v[124:125], v[156:157], 1, v[124:125]
	s_waitcnt vmcnt(15)
	v_pk_fma_f32 v[88:89], v[88:89], 0.5, v[120:121] op_sel_hi:[1,0,1]
	v_cvt_pk_bf16_f32 v92, v92, v93
	v_cvt_pk_bf16_f32 v93, v94, v95
	global_store_dwordx2 v[124:125], v[92:93], off
	v_pk_fma_f32 v[90:91], v[90:91], 0.5, v[122:123] op_sel_hi:[1,0,1]
	v_mul_f32_e32 v92, v89, v89
	v_fmac_f32_e32 v92, v88, v88
	v_mul_f32_e32 v93, v91, v91
	global_store_dwordx4 v[166:167], v[88:91], off offset:64
	s_waitcnt vmcnt(16)
	v_pk_fma_f32 v[86:87], v[86:87], 0.5, v[118:119] op_sel_hi:[1,0,1]
	v_pk_fma_f32 v[84:85], v[84:85], 0.5, v[116:117] op_sel_hi:[1,0,1]
	v_cvt_pk_bf16_f32 v88, v88, v89
	v_cvt_pk_bf16_f32 v89, v90, v91
	v_fmac_f32_e32 v93, v90, v90
	global_store_dwordx2 v[124:125], v[88:89], off offset:32
	v_mul_f32_e32 v88, v85, v85
	v_mul_f32_e32 v89, v87, v87
	v_add_f32_e32 v92, v92, v93
	v_fmac_f32_e32 v88, v84, v84
	v_fmac_f32_e32 v89, v86, v86
	v_add_f32_e32 v92, v126, v92
	v_add_f32_e32 v88, v88, v89
	v_add_f32_e32 v92, v92, v88
	s_waitcnt vmcnt(16)
	v_pk_fma_f32 v[90:91], v[82:83], 0.5, v[114:115] op_sel_hi:[1,0,1]
	v_pk_fma_f32 v[88:89], v[80:81], 0.5, v[112:113] op_sel_hi:[1,0,1]
	v_mul_f32_e32 v81, v91, v91
	v_mul_f32_e32 v80, v89, v89
	v_fmac_f32_e32 v80, v88, v88
	v_fmac_f32_e32 v81, v90, v90
	v_add_f32_e32 v80, v80, v81
	v_add_f32_e32 v82, v92, v80
	ds_bpermute_b32 v83, v175, v82
	v_cvt_pk_bf16_f32 v80, v84, v85
	v_cvt_pk_bf16_f32 v81, v86, v87
	global_store_dwordx4 v[166:167], v[84:87], off offset:512
	global_store_dwordx2 v[124:125], v[80:81], off offset:256
	s_waitcnt lgkmcnt(0)
	v_add_f32_e32 v80, v82, v83
	ds_bpermute_b32 v81, v176, v80
	v_cvt_pk_bf16_f32 v82, v88, v89
	v_cvt_pk_bf16_f32 v83, v90, v91
	global_store_dwordx4 v[166:167], v[88:91], off offset:576
	global_store_dwordx2 v[124:125], v[82:83], off offset:288
	s_mov_b32 vcc_lo, 0x11111111
	s_mov_b32 vcc_hi, 0x11111111
	s_and_saveexec_b64 s[22:23], vcc
	s_cbranch_execz .LBB0_1196
	v_lshl_add_u64 v[82:83], v[164:165], 2, s[14:15]
	s_waitcnt lgkmcnt(0)
	v_add_f32_e32 v80, v80, v81
	global_atomic_add_f32 v[82:83], v80, off
.LBB0_1196:
	s_or_b64 exec, exec, s[22:23]
	v_add_u32_e32 v112, 0x80, v158
	v_ashrrev_i32_e32 v113, 31, v112
	s_waitcnt lgkmcnt(0)
	v_lshlrev_b64 v[80:81], 12, v[112:113]
	v_lshl_add_u64 v[80:81], s[8:9], 0, v[80:81]
	v_lshl_add_u64 v[114:115], v[156:157], 2, v[80:81]
	global_load_dwordx4 v[92:95], v[114:115], off
	global_load_dwordx4 v[88:91], v[114:115], off offset:64
	global_load_dwordx4 v[84:87], v[114:115], off offset:512
	global_load_dwordx4 v[80:83], v[114:115], off offset:576
	s_waitcnt vmcnt(15)
	v_pk_fma_f32 v[78:79], v[78:79], 0.5, v[110:111] op_sel_hi:[1,0,1]
	v_pk_fma_f32 v[76:77], v[76:77], 0.5, v[108:109] op_sel_hi:[1,0,1]
	v_mul_f32_e32 v109, v79, v79
	v_mul_f32_e32 v108, v77, v77
	v_fmac_f32_e32 v108, v76, v76
	v_fmac_f32_e32 v109, v78, v78
	v_add_f32_e32 v110, v108, v109
	v_lshlrev_b64 v[108:109], 11, v[128:129]
	v_lshl_add_u64 v[108:109], s[12:13], 0, v[108:109]
	global_store_dwordx4 v[130:131], v[76:79], off
	v_lshl_add_u64 v[108:109], v[156:157], 1, v[108:109]
	s_waitcnt vmcnt(15)
	v_pk_fma_f32 v[72:73], v[72:73], 0.5, v[104:105] op_sel_hi:[1,0,1]
	v_cvt_pk_bf16_f32 v76, v76, v77
	v_cvt_pk_bf16_f32 v77, v78, v79
	global_store_dwordx2 v[108:109], v[76:77], off
	v_pk_fma_f32 v[74:75], v[74:75], 0.5, v[106:107] op_sel_hi:[1,0,1]
	v_mul_f32_e32 v76, v73, v73
	v_fmac_f32_e32 v76, v72, v72
	v_mul_f32_e32 v77, v75, v75
	global_store_dwordx4 v[130:131], v[72:75], off offset:64
	s_waitcnt vmcnt(16)
	v_pk_fma_f32 v[70:71], v[70:71], 0.5, v[102:103] op_sel_hi:[1,0,1]
	v_pk_fma_f32 v[68:69], v[68:69], 0.5, v[100:101] op_sel_hi:[1,0,1]
	v_cvt_pk_bf16_f32 v72, v72, v73
	v_cvt_pk_bf16_f32 v73, v74, v75
	v_fmac_f32_e32 v77, v74, v74
	global_store_dwordx2 v[108:109], v[72:73], off offset:32
	v_mul_f32_e32 v72, v69, v69
	v_mul_f32_e32 v73, v71, v71
	v_add_f32_e32 v76, v76, v77
	v_fmac_f32_e32 v72, v68, v68
	v_fmac_f32_e32 v73, v70, v70
	v_add_f32_e32 v76, v110, v76
	v_add_f32_e32 v72, v72, v73
	v_add_f32_e32 v76, v76, v72
	s_waitcnt vmcnt(16)
	v_pk_fma_f32 v[74:75], v[66:67], 0.5, v[98:99] op_sel_hi:[1,0,1]
	v_pk_fma_f32 v[72:73], v[64:65], 0.5, v[96:97] op_sel_hi:[1,0,1]
	v_mul_f32_e32 v65, v75, v75
	v_mul_f32_e32 v64, v73, v73
	v_fmac_f32_e32 v64, v72, v72
	v_fmac_f32_e32 v65, v74, v74
	v_add_f32_e32 v64, v64, v65
	v_add_f32_e32 v66, v76, v64
	ds_bpermute_b32 v67, v175, v66
	v_cvt_pk_bf16_f32 v64, v68, v69
	v_cvt_pk_bf16_f32 v65, v70, v71
	global_store_dwordx4 v[130:131], v[68:71], off offset:512
	global_store_dwordx2 v[108:109], v[64:65], off offset:256
	s_waitcnt lgkmcnt(0)
	v_add_f32_e32 v64, v66, v67
	ds_bpermute_b32 v65, v176, v64
	v_cvt_pk_bf16_f32 v66, v72, v73
	v_cvt_pk_bf16_f32 v67, v74, v75
	global_store_dwordx4 v[130:131], v[72:75], off offset:576
	global_store_dwordx2 v[108:109], v[66:67], off offset:288
	s_mov_b32 vcc_lo, 0x11111111
	s_mov_b32 vcc_hi, 0x11111111
	s_and_saveexec_b64 s[22:23], vcc
	s_cbranch_execz .LBB0_1198
	v_lshl_add_u64 v[66:67], v[128:129], 2, s[14:15]
	s_waitcnt lgkmcnt(0)
	v_add_f32_e32 v64, v64, v65
	global_atomic_add_f32 v[66:67], v64, off
.LBB0_1198:
	s_or_b64 exec, exec, s[22:23]
	v_or_b32_e32 v96, 16, v112
	v_ashrrev_i32_e32 v97, 31, v96
	s_waitcnt lgkmcnt(0)
	v_lshlrev_b64 v[64:65], 12, v[96:97]
	v_lshl_add_u64 v[64:65], s[8:9], 0, v[64:65]
	v_lshl_add_u64 v[98:99], v[156:157], 2, v[64:65]
	global_load_dwordx4 v[76:79], v[98:99], off
	global_load_dwordx4 v[72:75], v[98:99], off offset:64
	global_load_dwordx4 v[68:71], v[98:99], off offset:512
	global_load_dwordx4 v[64:67], v[98:99], off offset:576
	s_waitcnt vmcnt(15)
	v_pk_fma_f32 v[62:63], v[62:63], 0.5, v[94:95] op_sel_hi:[1,0,1]
	v_pk_fma_f32 v[60:61], v[60:61], 0.5, v[92:93] op_sel_hi:[1,0,1]
	v_mul_f32_e32 v93, v63, v63
	v_mul_f32_e32 v92, v61, v61
	v_fmac_f32_e32 v92, v60, v60
	v_fmac_f32_e32 v93, v62, v62
	v_add_f32_e32 v94, v92, v93
	v_lshlrev_b64 v[92:93], 11, v[112:113]
	v_lshl_add_u64 v[92:93], s[12:13], 0, v[92:93]
	global_store_dwordx4 v[114:115], v[60:63], off
	v_lshl_add_u64 v[92:93], v[156:157], 1, v[92:93]
	s_waitcnt vmcnt(15)
	v_pk_fma_f32 v[56:57], v[56:57], 0.5, v[88:89] op_sel_hi:[1,0,1]
	v_cvt_pk_bf16_f32 v60, v60, v61
	v_cvt_pk_bf16_f32 v61, v62, v63
	global_store_dwordx2 v[92:93], v[60:61], off
	v_pk_fma_f32 v[58:59], v[58:59], 0.5, v[90:91] op_sel_hi:[1,0,1]
	v_mul_f32_e32 v60, v57, v57
	v_fmac_f32_e32 v60, v56, v56
	v_mul_f32_e32 v61, v59, v59
	global_store_dwordx4 v[114:115], v[56:59], off offset:64
	s_waitcnt vmcnt(16)
	v_pk_fma_f32 v[54:55], v[54:55], 0.5, v[86:87] op_sel_hi:[1,0,1]
	v_pk_fma_f32 v[52:53], v[52:53], 0.5, v[84:85] op_sel_hi:[1,0,1]
	v_cvt_pk_bf16_f32 v56, v56, v57
	v_cvt_pk_bf16_f32 v57, v58, v59
	v_fmac_f32_e32 v61, v58, v58
	global_store_dwordx2 v[92:93], v[56:57], off offset:32
	v_mul_f32_e32 v56, v53, v53
	v_mul_f32_e32 v57, v55, v55
	v_add_f32_e32 v60, v60, v61
	v_fmac_f32_e32 v56, v52, v52
	v_fmac_f32_e32 v57, v54, v54
	v_add_f32_e32 v60, v94, v60
	v_add_f32_e32 v56, v56, v57
	v_add_f32_e32 v60, v60, v56
	s_waitcnt vmcnt(16)
	v_pk_fma_f32 v[58:59], v[50:51], 0.5, v[82:83] op_sel_hi:[1,0,1]
	v_pk_fma_f32 v[56:57], v[48:49], 0.5, v[80:81] op_sel_hi:[1,0,1]
	v_mul_f32_e32 v49, v59, v59
	v_mul_f32_e32 v48, v57, v57
	v_fmac_f32_e32 v48, v56, v56
	v_fmac_f32_e32 v49, v58, v58
	v_add_f32_e32 v48, v48, v49
	v_add_f32_e32 v50, v60, v48
	ds_bpermute_b32 v51, v175, v50
	v_cvt_pk_bf16_f32 v48, v52, v53
	v_cvt_pk_bf16_f32 v49, v54, v55
	global_store_dwordx4 v[114:115], v[52:55], off offset:512
	global_store_dwordx2 v[92:93], v[48:49], off offset:256
	s_waitcnt lgkmcnt(0)
	v_add_f32_e32 v48, v50, v51
	ds_bpermute_b32 v49, v176, v48
	v_cvt_pk_bf16_f32 v50, v56, v57
	v_cvt_pk_bf16_f32 v51, v58, v59
	global_store_dwordx4 v[114:115], v[56:59], off offset:576
	global_store_dwordx2 v[92:93], v[50:51], off offset:288
	s_mov_b32 vcc_lo, 0x11111111
	s_mov_b32 vcc_hi, 0x11111111
	s_and_saveexec_b64 s[22:23], vcc
	s_cbranch_execz .LBB0_1200
	v_lshl_add_u64 v[50:51], v[112:113], 2, s[14:15]
	s_waitcnt lgkmcnt(0)
	v_add_f32_e32 v48, v48, v49
	global_atomic_add_f32 v[50:51], v48, off
.LBB0_1200:
	s_or_b64 exec, exec, s[22:23]
	v_or_b32_e32 v80, 32, v112
	v_ashrrev_i32_e32 v81, 31, v80
	s_waitcnt lgkmcnt(0)
	v_lshlrev_b64 v[48:49], 12, v[80:81]
	v_lshl_add_u64 v[48:49], s[8:9], 0, v[48:49]
	v_lshl_add_u64 v[82:83], v[156:157], 2, v[48:49]
	global_load_dwordx4 v[60:63], v[82:83], off
	global_load_dwordx4 v[56:59], v[82:83], off offset:64
	global_load_dwordx4 v[52:55], v[82:83], off offset:512
	global_load_dwordx4 v[48:51], v[82:83], off offset:576
	s_waitcnt vmcnt(15)
	v_pk_fma_f32 v[46:47], v[46:47], 0.5, v[78:79] op_sel_hi:[1,0,1]
	v_pk_fma_f32 v[44:45], v[44:45], 0.5, v[76:77] op_sel_hi:[1,0,1]
	v_mul_f32_e32 v77, v47, v47
	v_mul_f32_e32 v76, v45, v45
	v_fmac_f32_e32 v76, v44, v44
	v_fmac_f32_e32 v77, v46, v46
	v_add_f32_e32 v78, v76, v77
	v_lshlrev_b64 v[76:77], 11, v[96:97]
	v_lshl_add_u64 v[76:77], s[12:13], 0, v[76:77]
	global_store_dwordx4 v[98:99], v[44:47], off
	v_lshl_add_u64 v[76:77], v[156:157], 1, v[76:77]
	s_waitcnt vmcnt(15)
	v_pk_fma_f32 v[40:41], v[40:41], 0.5, v[72:73] op_sel_hi:[1,0,1]
	v_cvt_pk_bf16_f32 v44, v44, v45
	v_cvt_pk_bf16_f32 v45, v46, v47
	global_store_dwordx2 v[76:77], v[44:45], off
	v_pk_fma_f32 v[42:43], v[42:43], 0.5, v[74:75] op_sel_hi:[1,0,1]
	v_mul_f32_e32 v44, v41, v41
	v_fmac_f32_e32 v44, v40, v40
	v_mul_f32_e32 v45, v43, v43
	global_store_dwordx4 v[98:99], v[40:43], off offset:64
	s_waitcnt vmcnt(16)
	v_pk_fma_f32 v[38:39], v[38:39], 0.5, v[70:71] op_sel_hi:[1,0,1]
	v_pk_fma_f32 v[36:37], v[36:37], 0.5, v[68:69] op_sel_hi:[1,0,1]
	v_cvt_pk_bf16_f32 v40, v40, v41
	v_cvt_pk_bf16_f32 v41, v42, v43
	v_fmac_f32_e32 v45, v42, v42
	global_store_dwordx2 v[76:77], v[40:41], off offset:32
	v_mul_f32_e32 v40, v37, v37
	v_mul_f32_e32 v41, v39, v39
	v_add_f32_e32 v44, v44, v45
	v_fmac_f32_e32 v40, v36, v36
	v_fmac_f32_e32 v41, v38, v38
	v_add_f32_e32 v44, v78, v44
	v_add_f32_e32 v40, v40, v41
	v_add_f32_e32 v44, v44, v40
	s_waitcnt vmcnt(16)
	v_pk_fma_f32 v[42:43], v[34:35], 0.5, v[66:67] op_sel_hi:[1,0,1]
	v_pk_fma_f32 v[40:41], v[32:33], 0.5, v[64:65] op_sel_hi:[1,0,1]
	v_mul_f32_e32 v33, v43, v43
	v_mul_f32_e32 v32, v41, v41
	v_fmac_f32_e32 v32, v40, v40
	v_fmac_f32_e32 v33, v42, v42
	v_add_f32_e32 v32, v32, v33
	v_add_f32_e32 v34, v44, v32
	ds_bpermute_b32 v35, v175, v34
	v_cvt_pk_bf16_f32 v32, v36, v37
	v_cvt_pk_bf16_f32 v33, v38, v39
	global_store_dwordx4 v[98:99], v[36:39], off offset:512
	global_store_dwordx2 v[76:77], v[32:33], off offset:256
	s_waitcnt lgkmcnt(0)
	v_add_f32_e32 v32, v34, v35
	ds_bpermute_b32 v33, v176, v32
	v_cvt_pk_bf16_f32 v34, v40, v41
	v_cvt_pk_bf16_f32 v35, v42, v43
	global_store_dwordx4 v[98:99], v[40:43], off offset:576
	global_store_dwordx2 v[76:77], v[34:35], off offset:288
	s_mov_b32 vcc_lo, 0x11111111
	s_mov_b32 vcc_hi, 0x11111111
	s_and_saveexec_b64 s[22:23], vcc
	s_cbranch_execz .LBB0_1202
	v_lshl_add_u64 v[34:35], v[96:97], 2, s[14:15]
	s_waitcnt lgkmcnt(0)
	v_add_f32_e32 v32, v32, v33
	global_atomic_add_f32 v[34:35], v32, off
.LBB0_1202:
	s_or_b64 exec, exec, s[22:23]
	v_or_b32_e32 v64, 48, v112
	v_ashrrev_i32_e32 v65, 31, v64
	s_waitcnt lgkmcnt(0)
	v_lshlrev_b64 v[32:33], 12, v[64:65]
	v_lshl_add_u64 v[32:33], s[8:9], 0, v[32:33]
	v_lshl_add_u64 v[66:67], v[156:157], 2, v[32:33]
	global_load_dwordx4 v[44:47], v[66:67], off
	global_load_dwordx4 v[40:43], v[66:67], off offset:64
	global_load_dwordx4 v[36:39], v[66:67], off offset:512
	global_load_dwordx4 v[32:35], v[66:67], off offset:576
	s_waitcnt vmcnt(15)
	v_pk_fma_f32 v[30:31], v[30:31], 0.5, v[62:63] op_sel_hi:[1,0,1]
	v_pk_fma_f32 v[28:29], v[28:29], 0.5, v[60:61] op_sel_hi:[1,0,1]
	v_mul_f32_e32 v61, v31, v31
	v_mul_f32_e32 v60, v29, v29
	v_fmac_f32_e32 v60, v28, v28
	v_fmac_f32_e32 v61, v30, v30
	v_add_f32_e32 v62, v60, v61
	v_lshlrev_b64 v[60:61], 11, v[80:81]
	v_lshl_add_u64 v[60:61], s[12:13], 0, v[60:61]
	global_store_dwordx4 v[82:83], v[28:31], off
	v_lshl_add_u64 v[60:61], v[156:157], 1, v[60:61]
	s_waitcnt vmcnt(15)
	v_pk_fma_f32 v[24:25], v[24:25], 0.5, v[56:57] op_sel_hi:[1,0,1]
	v_cvt_pk_bf16_f32 v28, v28, v29
	v_cvt_pk_bf16_f32 v29, v30, v31
	global_store_dwordx2 v[60:61], v[28:29], off
	v_pk_fma_f32 v[26:27], v[26:27], 0.5, v[58:59] op_sel_hi:[1,0,1]
	v_mul_f32_e32 v28, v25, v25
	v_fmac_f32_e32 v28, v24, v24
	v_mul_f32_e32 v29, v27, v27
	global_store_dwordx4 v[82:83], v[24:27], off offset:64
	s_waitcnt vmcnt(16)
	v_pk_fma_f32 v[22:23], v[22:23], 0.5, v[54:55] op_sel_hi:[1,0,1]
	v_pk_fma_f32 v[20:21], v[20:21], 0.5, v[52:53] op_sel_hi:[1,0,1]
	v_cvt_pk_bf16_f32 v24, v24, v25
	v_cvt_pk_bf16_f32 v25, v26, v27
	v_fmac_f32_e32 v29, v26, v26
	global_store_dwordx2 v[60:61], v[24:25], off offset:32
	v_mul_f32_e32 v24, v21, v21
	v_mul_f32_e32 v25, v23, v23
	v_add_f32_e32 v28, v28, v29
	v_fmac_f32_e32 v24, v20, v20
	v_fmac_f32_e32 v25, v22, v22
	v_add_f32_e32 v28, v62, v28
	v_add_f32_e32 v24, v24, v25
	v_add_f32_e32 v28, v28, v24
	s_waitcnt vmcnt(16)
	v_pk_fma_f32 v[26:27], v[18:19], 0.5, v[50:51] op_sel_hi:[1,0,1]
	v_pk_fma_f32 v[24:25], v[16:17], 0.5, v[48:49] op_sel_hi:[1,0,1]
	v_mul_f32_e32 v17, v27, v27
	v_mul_f32_e32 v16, v25, v25
	v_fmac_f32_e32 v16, v24, v24
	v_fmac_f32_e32 v17, v26, v26
	v_add_f32_e32 v16, v16, v17
	v_add_f32_e32 v18, v28, v16
	ds_bpermute_b32 v19, v175, v18
	v_cvt_pk_bf16_f32 v16, v20, v21
	v_cvt_pk_bf16_f32 v17, v22, v23
	global_store_dwordx4 v[82:83], v[20:23], off offset:512
	global_store_dwordx2 v[60:61], v[16:17], off offset:256
	s_waitcnt lgkmcnt(0)
	v_add_f32_e32 v16, v18, v19
	ds_bpermute_b32 v17, v176, v16
	v_cvt_pk_bf16_f32 v18, v24, v25
	v_cvt_pk_bf16_f32 v19, v26, v27
	global_store_dwordx4 v[82:83], v[24:27], off offset:576
	global_store_dwordx2 v[60:61], v[18:19], off offset:288
	s_mov_b32 vcc_lo, 0x11111111
	s_mov_b32 vcc_hi, 0x11111111
	s_and_saveexec_b64 s[22:23], vcc
	s_cbranch_execz .LBB0_1204
	v_lshl_add_u64 v[18:19], v[80:81], 2, s[14:15]
	s_waitcnt lgkmcnt(0)
	v_add_f32_e32 v16, v16, v17
	global_atomic_add_f32 v[18:19], v16, off
.LBB0_1204:
	s_or_b64 exec, exec, s[22:23]
	s_waitcnt vmcnt(11)
	v_pk_fma_f32 v[14:15], v[14:15], 0.5, v[46:47] op_sel_hi:[1,0,1]
	v_pk_fma_f32 v[12:13], v[12:13], 0.5, v[44:45] op_sel_hi:[1,0,1]
	s_waitcnt lgkmcnt(0)
	v_mul_f32_e32 v17, v15, v15
	v_mul_f32_e32 v16, v13, v13
	v_fmac_f32_e32 v16, v12, v12
	v_fmac_f32_e32 v17, v14, v14
	v_add_f32_e32 v18, v16, v17
	v_lshlrev_b64 v[16:17], 11, v[64:65]
	v_lshl_add_u64 v[16:17], s[12:13], 0, v[16:17]
	global_store_dwordx4 v[66:67], v[12:15], off
	v_lshl_add_u64 v[16:17], v[156:157], 1, v[16:17]
	s_waitcnt vmcnt(11)
	v_pk_fma_f32 v[8:9], v[8:9], 0.5, v[40:41] op_sel_hi:[1,0,1]
	v_cvt_pk_bf16_f32 v12, v12, v13
	v_cvt_pk_bf16_f32 v13, v14, v15
	global_store_dwordx2 v[16:17], v[12:13], off
	v_pk_fma_f32 v[10:11], v[10:11], 0.5, v[42:43] op_sel_hi:[1,0,1]
	v_mul_f32_e32 v12, v9, v9
	v_fmac_f32_e32 v12, v8, v8
	v_mul_f32_e32 v13, v11, v11
	global_store_dwordx4 v[66:67], v[8:11], off offset:64
	s_waitcnt vmcnt(12)
	v_pk_fma_f32 v[6:7], v[6:7], 0.5, v[38:39] op_sel_hi:[1,0,1]
	v_pk_fma_f32 v[4:5], v[4:5], 0.5, v[36:37] op_sel_hi:[1,0,1]
	v_cvt_pk_bf16_f32 v8, v8, v9
	v_cvt_pk_bf16_f32 v9, v10, v11
	v_fmac_f32_e32 v13, v10, v10
	global_store_dwordx2 v[16:17], v[8:9], off offset:32
	v_mul_f32_e32 v8, v5, v5
	v_mul_f32_e32 v9, v7, v7
	v_add_f32_e32 v12, v12, v13
	v_fmac_f32_e32 v8, v4, v4
	v_fmac_f32_e32 v9, v6, v6
	v_add_f32_e32 v12, v18, v12
	v_add_f32_e32 v8, v8, v9
	v_add_f32_e32 v12, v12, v8
	s_waitcnt vmcnt(12)
	v_pk_fma_f32 v[10:11], v[2:3], 0.5, v[34:35] op_sel_hi:[1,0,1]
	v_pk_fma_f32 v[8:9], v[0:1], 0.5, v[32:33] op_sel_hi:[1,0,1]
	v_mul_f32_e32 v1, v11, v11
	v_mul_f32_e32 v0, v9, v9
	v_fmac_f32_e32 v0, v8, v8
	v_fmac_f32_e32 v1, v10, v10
	v_add_f32_e32 v0, v0, v1
	v_add_f32_e32 v2, v12, v0
	ds_bpermute_b32 v3, v175, v2
	v_cvt_pk_bf16_f32 v0, v4, v5
	v_cvt_pk_bf16_f32 v1, v6, v7
	global_store_dwordx4 v[66:67], v[4:7], off offset:512
	global_store_dwordx2 v[16:17], v[0:1], off offset:256
	s_waitcnt lgkmcnt(0)
	v_add_f32_e32 v0, v2, v3
	ds_bpermute_b32 v1, v176, v0
	v_cvt_pk_bf16_f32 v2, v8, v9
	v_cvt_pk_bf16_f32 v3, v10, v11
	global_store_dwordx4 v[66:67], v[8:11], off offset:576
	global_store_dwordx2 v[16:17], v[2:3], off offset:288
	s_mov_b32 vcc_lo, 0x11111111
	s_mov_b32 vcc_hi, 0x11111111
	s_and_saveexec_b64 s[22:23], vcc
	s_cbranch_execz .LBB0_1206
	v_lshl_add_u64 v[2:3], v[64:65], 2, s[14:15]
	s_waitcnt lgkmcnt(0)
	v_add_f32_e32 v0, v0, v1
	global_atomic_add_f32 v[2:3], v0, off

.LBB0_1307:
	ds_read_b128 v[128:131], v194
	ds_read_b128 v[132:135], v194 offset:1024
	ds_read_b128 v[136:139], v194 offset:2048
	ds_read_b128 v[140:143], v194 offset:3072
	ds_read_b128 v[144:147], v195
	ds_read_b128 v[160:163], v195 offset:1024
	ds_read_b128 v[164:167], v195 offset:2048
	ds_read_b128 v[168:171], v195 offset:3072
	s_add_u32 s36, s0, 0xfffc0080
	s_addc_u32 s37, s1, -1
	s_cmp_eq_u32 s60, 12
	s_cselect_b32 s39, s23, s37
	s_cselect_b32 s38, s33, s36
	s_cselect_b32 s37, s21, s59
	s_cselect_b32 s36, s57, s58
	v_lshl_add_u64 v[188:189], s[0:1], 0, v[154:155]
	s_add_i32 m0, s31, 0xc000
	ds_read_b128 v[172:175], v196
	ds_read_b128 v[176:179], v196 offset:1024
	ds_read_b128 v[180:183], v196 offset:2048
	ds_read_b128 v[184:187], v196 offset:3072
	ds_read_b128 v[200:203], v196 offset:4096
	ds_read_b128 v[204:207], v196 offset:5120
	ds_read_b128 v[208:211], v196 offset:6144
	ds_read_b128 v[212:215], v196 offset:7168
	global_load_lds_dwordx4 v[188:189], off
	v_lshl_add_u64 v[188:189], s[0:1], 0, v[152:153]
	s_add_i32 m0, s31, 0xe000
	s_nop 0
	global_load_lds_dwordx4 v[188:189], off
	s_waitcnt vmcnt(8)
	s_waitcnt lgkmcnt(0)
	s_barrier
	s_setprio 1
	s_waitcnt lgkmcnt(0)
	v_mfma_f32_16x16x32_bf16 v[124:127], v[128:131], v[172:175], v[124:127]
	v_mfma_f32_16x16x32_bf16 v[120:123], v[136:139], v[172:175], v[120:123]
	v_mfma_f32_16x16x32_bf16 v[108:111], v[128:131], v[180:183], v[108:111]
	v_mfma_f32_16x16x32_bf16 v[104:107], v[136:139], v[180:183], v[104:107]
	v_mfma_f32_16x16x32_bf16 v[92:95], v[128:131], v[200:203], v[92:95]
	v_mfma_f32_16x16x32_bf16 v[88:91], v[136:139], v[200:203], v[88:91]
	v_mfma_f32_16x16x32_bf16 v[76:79], v[128:131], v[208:211], v[76:79]
	v_mfma_f32_16x16x32_bf16 v[72:75], v[136:139], v[208:211], v[72:75]
	v_mfma_f32_16x16x32_bf16 v[124:127], v[132:135], v[176:179], v[124:127]
	v_mfma_f32_16x16x32_bf16 v[120:123], v[140:143], v[176:179], v[120:123]
	v_mfma_f32_16x16x32_bf16 v[108:111], v[132:135], v[184:187], v[108:111]
	v_mfma_f32_16x16x32_bf16 v[104:107], v[140:143], v[184:187], v[104:107]
	v_mfma_f32_16x16x32_bf16 v[92:95], v[132:135], v[204:207], v[92:95]
	v_mfma_f32_16x16x32_bf16 v[88:91], v[140:143], v[204:207], v[88:91]
	v_mfma_f32_16x16x32_bf16 v[76:79], v[132:135], v[212:215], v[76:79]
	v_mfma_f32_16x16x32_bf16 v[72:75], v[140:143], v[212:215], v[72:75]
	s_setprio 0
	s_setprio 1
	v_mfma_f32_16x16x32_bf16 v[116:119], v[144:147], v[172:175], v[116:119]
	v_mfma_f32_16x16x32_bf16 v[112:115], v[164:167], v[172:175], v[112:115]
	v_mfma_f32_16x16x32_bf16 v[100:103], v[144:147], v[180:183], v[100:103]
	v_mfma_f32_16x16x32_bf16 v[96:99], v[164:167], v[180:183], v[96:99]
	v_mfma_f32_16x16x32_bf16 v[84:87], v[144:147], v[200:203], v[84:87]
	v_mfma_f32_16x16x32_bf16 v[80:83], v[164:167], v[200:203], v[80:83]
	v_mfma_f32_16x16x32_bf16 v[68:71], v[144:147], v[208:211], v[68:71]
	v_mfma_f32_16x16x32_bf16 v[64:67], v[164:167], v[208:211], v[64:67]
	v_mfma_f32_16x16x32_bf16 v[116:119], v[160:163], v[176:179], v[116:119]
	v_mfma_f32_16x16x32_bf16 v[112:115], v[168:171], v[176:179], v[112:115]
	v_mfma_f32_16x16x32_bf16 v[100:103], v[160:163], v[184:187], v[100:103]
	v_mfma_f32_16x16x32_bf16 v[96:99], v[168:171], v[184:187], v[96:99]
	v_mfma_f32_16x16x32_bf16 v[84:87], v[160:163], v[204:207], v[84:87]
	v_mfma_f32_16x16x32_bf16 v[80:83], v[168:171], v[204:207], v[80:83]
	v_mfma_f32_16x16x32_bf16 v[68:71], v[160:163], v[212:215], v[68:71]
	v_mfma_f32_16x16x32_bf16 v[64:67], v[168:171], v[212:215], v[64:67]
	s_setprio 0
	s_barrier
	s_add_i32 s61, s54, s42
	v_lshl_add_u64 v[188:189], s[36:37], 0, v[148:149]
	s_mov_b32 m0, s61
	ds_read_b128 v[172:175], v196 offset:16384
	ds_read_b128 v[176:179], v196 offset:17408
	ds_read_b128 v[180:183], v196 offset:18432
	ds_read_b128 v[184:187], v196 offset:19456
	ds_read_b128 v[200:203], v196 offset:20480
	ds_read_b128 v[204:207], v196 offset:21504
	ds_read_b128 v[208:211], v196 offset:22528
	ds_read_b128 v[212:215], v196 offset:23552
	global_load_lds_dwordx4 v[188:189], off
	s_add_i32 m0, s61, 0x2000
	s_add_u32 s62, s36, 0x40000
	v_lshl_add_u64 v[216:217], s[36:37], 0, v[150:151]
	s_addc_u32 s63, s37, 0
	s_add_i32 s61, s55, s42
	global_load_lds_dwordx4 v[216:217], off
	v_lshl_add_u64 v[218:219], s[62:63], 0, v[148:149]
	s_mov_b32 m0, s61
	v_lshl_add_u64 v[220:221], s[38:39], 0, v[150:151]
	global_load_lds_dwordx4 v[218:219], off
	v_lshl_add_u64 v[218:219], s[62:63], 0, v[150:151]
	s_add_i32 m0, s61, 0x2000
	s_nop 0
	global_load_lds_dwordx4 v[218:219], off
	v_lshl_add_u64 v[218:219], s[38:39], 0, v[148:149]
	s_mov_b32 m0, s31
	s_nop 0
	global_load_lds_dwordx4 v[218:219], off
	s_mov_b32 m0, s35
	s_nop 0
	global_load_lds_dwordx4 v[220:221], off
	s_waitcnt vmcnt(8)
	s_waitcnt lgkmcnt(0)
	s_barrier
	s_setprio 1
	s_waitcnt lgkmcnt(0)
	v_mfma_f32_16x16x32_bf16 v[60:63], v[128:131], v[172:175], v[60:63]
	v_mfma_f32_16x16x32_bf16 v[56:59], v[136:139], v[172:175], v[56:59]
	v_mfma_f32_16x16x32_bf16 v[44:47], v[128:131], v[180:183], v[44:47]
	v_mfma_f32_16x16x32_bf16 v[40:43], v[136:139], v[180:183], v[40:43]
	v_mfma_f32_16x16x32_bf16 v[28:31], v[128:131], v[200:203], v[28:31]
	v_mfma_f32_16x16x32_bf16 v[24:27], v[136:139], v[200:203], v[24:27]
	v_mfma_f32_16x16x32_bf16 v[12:15], v[128:131], v[208:211], v[12:15]
	v_mfma_f32_16x16x32_bf16 v[8:11], v[136:139], v[208:211], v[8:11]
	v_mfma_f32_16x16x32_bf16 v[60:63], v[132:135], v[176:179], v[60:63]
	v_mfma_f32_16x16x32_bf16 v[56:59], v[140:143], v[176:179], v[56:59]
	v_mfma_f32_16x16x32_bf16 v[44:47], v[132:135], v[184:187], v[44:47]
	v_mfma_f32_16x16x32_bf16 v[40:43], v[140:143], v[184:187], v[40:43]
	v_mfma_f32_16x16x32_bf16 v[28:31], v[132:135], v[204:207], v[28:31]
	v_mfma_f32_16x16x32_bf16 v[24:27], v[140:143], v[204:207], v[24:27]
	v_mfma_f32_16x16x32_bf16 v[12:15], v[132:135], v[212:215], v[12:15]
	v_mfma_f32_16x16x32_bf16 v[8:11], v[140:143], v[212:215], v[8:11]
	s_setprio 0
	s_setprio 1
	v_mfma_f32_16x16x32_bf16 v[52:55], v[144:147], v[172:175], v[52:55]
	v_mfma_f32_16x16x32_bf16 v[48:51], v[164:167], v[172:175], v[48:51]
	v_mfma_f32_16x16x32_bf16 v[36:39], v[144:147], v[180:183], v[36:39]
	v_mfma_f32_16x16x32_bf16 v[32:35], v[164:167], v[180:183], v[32:35]
	v_mfma_f32_16x16x32_bf16 v[20:23], v[144:147], v[200:203], v[20:23]
	v_mfma_f32_16x16x32_bf16 v[16:19], v[164:167], v[200:203], v[16:19]
	v_mfma_f32_16x16x32_bf16 v[4:7], v[144:147], v[208:211], v[4:7]
	v_mfma_f32_16x16x32_bf16 v[0:3], v[164:167], v[208:211], v[0:3]
	v_mfma_f32_16x16x32_bf16 v[52:55], v[160:163], v[176:179], v[52:55]
	v_mfma_f32_16x16x32_bf16 v[48:51], v[168:171], v[176:179], v[48:51]
	v_mfma_f32_16x16x32_bf16 v[36:39], v[160:163], v[184:187], v[36:39]
	v_mfma_f32_16x16x32_bf16 v[32:35], v[168:171], v[184:187], v[32:35]
	v_mfma_f32_16x16x32_bf16 v[20:23], v[160:163], v[204:207], v[20:23]
	v_mfma_f32_16x16x32_bf16 v[16:19], v[168:171], v[204:207], v[16:19]
	v_mfma_f32_16x16x32_bf16 v[4:7], v[160:163], v[212:215], v[4:7]
	v_mfma_f32_16x16x32_bf16 v[0:3], v[168:171], v[212:215], v[0:3]
	s_setprio 0
	s_barrier
	s_add_i32 s61, 0, 0x18000
	s_add_i32 s62, 0, 0x1c000
	v_add_u32_e32 v140, s61, v192
	v_add_u32_e32 v168, s62, v192
	ds_read_b128 v[128:131], v140
	ds_read_b128 v[132:135], v140 offset:1024
	ds_read_b128 v[136:139], v140 offset:2048
	ds_read_b128 v[140:143], v140 offset:3072
	ds_read_b128 v[144:147], v168
	ds_read_b128 v[160:163], v168 offset:1024
	ds_read_b128 v[164:167], v168 offset:2048
	ds_read_b128 v[168:171], v168 offset:3072
	s_add_u32 s38, s38, 0x40000
	s_addc_u32 s39, s39, 0
	s_mov_b32 m0, s45
	v_lshl_add_u64 v[222:223], s[38:39], 0, v[148:149]
	ds_read_b128 v[172:175], v196 offset:32768
	ds_read_b128 v[176:179], v196 offset:33792
	ds_read_b128 v[180:183], v196 offset:34816
	ds_read_b128 v[184:187], v196 offset:35840
	ds_read_b128 v[200:203], v196 offset:36864
	ds_read_b128 v[204:207], v196 offset:37888
	ds_read_b128 v[208:211], v196 offset:38912
	ds_read_b128 v[212:215], v196 offset:39936
	global_load_lds_dwordx4 v[222:223], off
	v_lshl_add_u64 v[222:223], s[38:39], 0, v[150:151]
	s_mov_b32 m0, s46
	s_nop 0
	global_load_lds_dwordx4 v[222:223], off
	s_waitcnt vmcnt(8)
	s_waitcnt lgkmcnt(0)
	s_barrier
	s_setprio 1
	s_waitcnt lgkmcnt(0)
	v_mfma_f32_16x16x32_bf16 v[124:127], v[128:131], v[172:175], v[124:127]
	v_mfma_f32_16x16x32_bf16 v[120:123], v[136:139], v[172:175], v[120:123]
	v_mfma_f32_16x16x32_bf16 v[108:111], v[128:131], v[180:183], v[108:111]
	v_mfma_f32_16x16x32_bf16 v[104:107], v[136:139], v[180:183], v[104:107]
	v_mfma_f32_16x16x32_bf16 v[92:95], v[128:131], v[200:203], v[92:95]
	v_mfma_f32_16x16x32_bf16 v[88:91], v[136:139], v[200:203], v[88:91]
	v_mfma_f32_16x16x32_bf16 v[76:79], v[128:131], v[208:211], v[76:79]
	v_mfma_f32_16x16x32_bf16 v[72:75], v[136:139], v[208:211], v[72:75]
	v_mfma_f32_16x16x32_bf16 v[124:127], v[132:135], v[176:179], v[124:127]
	v_mfma_f32_16x16x32_bf16 v[120:123], v[140:143], v[176:179], v[120:123]
	v_mfma_f32_16x16x32_bf16 v[108:111], v[132:135], v[184:187], v[108:111]
	v_mfma_f32_16x16x32_bf16 v[104:107], v[140:143], v[184:187], v[104:107]
	v_mfma_f32_16x16x32_bf16 v[92:95], v[132:135], v[204:207], v[92:95]
	v_mfma_f32_16x16x32_bf16 v[88:91], v[140:143], v[204:207], v[88:91]
	v_mfma_f32_16x16x32_bf16 v[76:79], v[132:135], v[212:215], v[76:79]
	v_mfma_f32_16x16x32_bf16 v[72:75], v[140:143], v[212:215], v[72:75]
	s_setprio 0
	s_setprio 1
	v_mfma_f32_16x16x32_bf16 v[116:119], v[144:147], v[172:175], v[116:119]
	v_mfma_f32_16x16x32_bf16 v[112:115], v[164:167], v[172:175], v[112:115]
	v_mfma_f32_16x16x32_bf16 v[100:103], v[144:147], v[180:183], v[100:103]
	v_mfma_f32_16x16x32_bf16 v[96:99], v[164:167], v[180:183], v[96:99]
	v_mfma_f32_16x16x32_bf16 v[84:87], v[144:147], v[200:203], v[84:87]
	v_mfma_f32_16x16x32_bf16 v[80:83], v[164:167], v[200:203], v[80:83]
	v_mfma_f32_16x16x32_bf16 v[68:71], v[144:147], v[208:211], v[68:71]
	v_mfma_f32_16x16x32_bf16 v[64:67], v[164:167], v[208:211], v[64:67]
	v_mfma_f32_16x16x32_bf16 v[116:119], v[160:163], v[176:179], v[116:119]
	v_mfma_f32_16x16x32_bf16 v[112:115], v[168:171], v[176:179], v[112:115]
	v_mfma_f32_16x16x32_bf16 v[100:103], v[160:163], v[184:187], v[100:103]
	v_mfma_f32_16x16x32_bf16 v[96:99], v[168:171], v[184:187], v[96:99]
	v_mfma_f32_16x16x32_bf16 v[84:87], v[160:163], v[204:207], v[84:87]
	v_mfma_f32_16x16x32_bf16 v[80:83], v[168:171], v[204:207], v[80:83]
	v_mfma_f32_16x16x32_bf16 v[68:71], v[160:163], v[212:215], v[68:71]
	v_mfma_f32_16x16x32_bf16 v[64:67], v[168:171], v[212:215], v[64:67]
	s_setprio 0
	s_barrier
	s_add_i32 s38, s61, s42
	v_lshl_add_u64 v[188:189], v[188:189], 0, s[16:17]
	s_mov_b32 m0, s38
	ds_read_b128 v[172:175], v196 offset:49152
	ds_read_b128 v[176:179], v196 offset:50176
	ds_read_b128 v[180:183], v196 offset:51200
	ds_read_b128 v[184:187], v196 offset:52224
	ds_read_b128 v[200:203], v196 offset:53248
	ds_read_b128 v[204:207], v196 offset:54272
	ds_read_b128 v[208:211], v196 offset:55296
	ds_read_b128 v[212:215], v196 offset:56320
	global_load_lds_dwordx4 v[188:189], off
	s_add_i32 m0, s38, 0x2000
	s_add_u32 s36, s36, 0x40080
	v_lshl_add_u64 v[188:189], v[216:217], 0, s[16:17]
	s_addc_u32 s37, s37, 0
	s_add_i32 s38, s62, s42
	global_load_lds_dwordx4 v[188:189], off
	v_lshl_add_u64 v[188:189], s[36:37], 0, v[148:149]
	s_mov_b32 m0, s38
	s_nop 0
	global_load_lds_dwordx4 v[188:189], off
	v_lshl_add_u64 v[188:189], s[36:37], 0, v[150:151]
	s_add_i32 m0, s38, 0x2000
	s_nop 0
	global_load_lds_dwordx4 v[188:189], off
	v_lshl_add_u64 v[188:189], v[218:219], 0, s[16:17]
	s_mov_b32 m0, s48
	s_nop 0
	global_load_lds_dwordx4 v[188:189], off
	v_lshl_add_u64 v[188:189], v[220:221], 0, s[16:17]
	s_mov_b32 m0, s49
	s_nop 0
	global_load_lds_dwordx4 v[188:189], off
	s_waitcnt vmcnt(8)
	s_waitcnt lgkmcnt(0)
	s_barrier
	s_setprio 1
	s_waitcnt lgkmcnt(0)
	v_mfma_f32_16x16x32_bf16 v[60:63], v[128:131], v[172:175], v[60:63]
	v_mfma_f32_16x16x32_bf16 v[56:59], v[136:139], v[172:175], v[56:59]
	v_mfma_f32_16x16x32_bf16 v[44:47], v[128:131], v[180:183], v[44:47]
	v_mfma_f32_16x16x32_bf16 v[40:43], v[136:139], v[180:183], v[40:43]
	v_mfma_f32_16x16x32_bf16 v[28:31], v[128:131], v[200:203], v[28:31]
	v_mfma_f32_16x16x32_bf16 v[24:27], v[136:139], v[200:203], v[24:27]
	v_mfma_f32_16x16x32_bf16 v[12:15], v[128:131], v[208:211], v[12:15]
	v_mfma_f32_16x16x32_bf16 v[8:11], v[136:139], v[208:211], v[8:11]
	v_mfma_f32_16x16x32_bf16 v[60:63], v[132:135], v[176:179], v[60:63]
	v_mfma_f32_16x16x32_bf16 v[56:59], v[140:143], v[176:179], v[56:59]
	v_mfma_f32_16x16x32_bf16 v[44:47], v[132:135], v[184:187], v[44:47]
	v_mfma_f32_16x16x32_bf16 v[40:43], v[140:143], v[184:187], v[40:43]
	v_mfma_f32_16x16x32_bf16 v[28:31], v[132:135], v[204:207], v[28:31]
	v_mfma_f32_16x16x32_bf16 v[24:27], v[140:143], v[204:207], v[24:27]
	v_mfma_f32_16x16x32_bf16 v[12:15], v[132:135], v[212:215], v[12:15]
	v_mfma_f32_16x16x32_bf16 v[8:11], v[140:143], v[212:215], v[8:11]
	s_setprio 0
	s_setprio 1
	v_mfma_f32_16x16x32_bf16 v[52:55], v[144:147], v[172:175], v[52:55]
	v_mfma_f32_16x16x32_bf16 v[48:51], v[164:167], v[172:175], v[48:51]
	v_mfma_f32_16x16x32_bf16 v[36:39], v[144:147], v[180:183], v[36:39]
	v_mfma_f32_16x16x32_bf16 v[32:35], v[164:167], v[180:183], v[32:35]
	v_mfma_f32_16x16x32_bf16 v[20:23], v[144:147], v[200:203], v[20:23]
	v_mfma_f32_16x16x32_bf16 v[16:19], v[164:167], v[200:203], v[16:19]
	v_mfma_f32_16x16x32_bf16 v[4:7], v[144:147], v[208:211], v[4:7]
	v_mfma_f32_16x16x32_bf16 v[0:3], v[164:167], v[208:211], v[0:3]
	v_mfma_f32_16x16x32_bf16 v[52:55], v[160:163], v[176:179], v[52:55]
	v_mfma_f32_16x16x32_bf16 v[48:51], v[168:171], v[176:179], v[48:51]
	v_mfma_f32_16x16x32_bf16 v[36:39], v[160:163], v[184:187], v[36:39]
	v_mfma_f32_16x16x32_bf16 v[32:35], v[168:171], v[184:187], v[32:35]
	v_mfma_f32_16x16x32_bf16 v[20:23], v[160:163], v[204:207], v[20:23]
	v_mfma_f32_16x16x32_bf16 v[16:19], v[168:171], v[204:207], v[16:19]
	v_mfma_f32_16x16x32_bf16 v[4:7], v[160:163], v[212:215], v[4:7]
	v_mfma_f32_16x16x32_bf16 v[0:3], v[168:171], v[212:215], v[0:3]
	s_setprio 0
	s_barrier
	s_add_i32 s60, s60, 2
	s_add_u32 s58, s58, 0x100
	s_addc_u32 s59, s59, 0
	s_add_u32 s0, s0, 0x100
	s_addc_u32 s1, s1, 0
	s_cmp_gt_u32 s60, 13
	s_cbranch_scc0 .LBB0_1307
	v_mbcnt_lo_u32_b32 v235, -1, 0
	v_mbcnt_hi_u32_b32 v235, -1, v235
	v_lshrrev_b32_e32 v236, 2, v235
	v_and_b32_e32 v237, 3, v235
	v_lshl_add_u32 v232, v237, 4, v236
	v_lshlrev_b32_e32 v232, 2, v232
	v_and_b32_e32 v233, -16, v191
	v_or_b32_e32 v233, v233, v236
	v_lshlrev_b32_e32 v237, 2, v237
	v_and_b32_e32 v234, -13, v193
	v_or_b32_e32 v234, v234, v237
	ds_bpermute_b32 v127, v232, v127
	ds_bpermute_b32 v126, v232, v126
	ds_bpermute_b32 v125, v232, v125
	ds_bpermute_b32 v124, v232, v124
	ds_bpermute_b32 v123, v232, v123
	ds_bpermute_b32 v122, v232, v122
	ds_bpermute_b32 v121, v232, v121
	ds_bpermute_b32 v120, v232, v120
	ds_bpermute_b32 v119, v232, v119
	ds_bpermute_b32 v118, v232, v118
	ds_bpermute_b32 v117, v232, v117
	ds_bpermute_b32 v116, v232, v116
	ds_bpermute_b32 v115, v232, v115
	ds_bpermute_b32 v114, v232, v114
	ds_bpermute_b32 v113, v232, v113
	ds_bpermute_b32 v112, v232, v112
	ds_bpermute_b32 v111, v232, v111
	ds_bpermute_b32 v110, v232, v110
	ds_bpermute_b32 v109, v232, v109
	ds_bpermute_b32 v108, v232, v108
	ds_bpermute_b32 v107, v232, v107
	ds_bpermute_b32 v106, v232, v106
	ds_bpermute_b32 v105, v232, v105
	ds_bpermute_b32 v104, v232, v104
	ds_bpermute_b32 v103, v232, v103
	ds_bpermute_b32 v102, v232, v102
	ds_bpermute_b32 v101, v232, v101
	ds_bpermute_b32 v100, v232, v100
	ds_bpermute_b32 v99, v232, v99
	ds_bpermute_b32 v98, v232, v98
	ds_bpermute_b32 v97, v232, v97
	ds_bpermute_b32 v96, v232, v96
	ds_bpermute_b32 v95, v232, v95
	ds_bpermute_b32 v94, v232, v94
	ds_bpermute_b32 v93, v232, v93
	ds_bpermute_b32 v92, v232, v92
	ds_bpermute_b32 v91, v232, v91
	ds_bpermute_b32 v90, v232, v90
	ds_bpermute_b32 v89, v232, v89
	ds_bpermute_b32 v88, v232, v88
	ds_bpermute_b32 v87, v232, v87
	ds_bpermute_b32 v86, v232, v86
	ds_bpermute_b32 v85, v232, v85
	ds_bpermute_b32 v84, v232, v84
	ds_bpermute_b32 v83, v232, v83
	ds_bpermute_b32 v82, v232, v82
	ds_bpermute_b32 v81, v232, v81
	ds_bpermute_b32 v80, v232, v80
	ds_bpermute_b32 v79, v232, v79
	ds_bpermute_b32 v78, v232, v78
	ds_bpermute_b32 v77, v232, v77
	ds_bpermute_b32 v76, v232, v76
	ds_bpermute_b32 v75, v232, v75
	ds_bpermute_b32 v74, v232, v74
	ds_bpermute_b32 v73, v232, v73
	ds_bpermute_b32 v72, v232, v72
	ds_bpermute_b32 v71, v232, v71
	ds_bpermute_b32 v70, v232, v70
	ds_bpermute_b32 v69, v232, v69
	ds_bpermute_b32 v68, v232, v68
	ds_bpermute_b32 v67, v232, v67
	ds_bpermute_b32 v66, v232, v66
	ds_bpermute_b32 v65, v232, v65
	ds_bpermute_b32 v64, v232, v64
	ds_bpermute_b32 v63, v232, v63
	ds_bpermute_b32 v62, v232, v62
	ds_bpermute_b32 v61, v232, v61
	ds_bpermute_b32 v60, v232, v60
	ds_bpermute_b32 v59, v232, v59
	ds_bpermute_b32 v58, v232, v58
	ds_bpermute_b32 v57, v232, v57
	ds_bpermute_b32 v56, v232, v56
	ds_bpermute_b32 v55, v232, v55
	ds_bpermute_b32 v54, v232, v54
	ds_bpermute_b32 v53, v232, v53
	ds_bpermute_b32 v52, v232, v52
	ds_bpermute_b32 v51, v232, v51
	ds_bpermute_b32 v50, v232, v50
	ds_bpermute_b32 v49, v232, v49
	ds_bpermute_b32 v48, v232, v48
	ds_bpermute_b32 v47, v232, v47
	ds_bpermute_b32 v46, v232, v46
	ds_bpermute_b32 v45, v232, v45
	ds_bpermute_b32 v44, v232, v44
	ds_bpermute_b32 v43, v232, v43
	ds_bpermute_b32 v42, v232, v42
	ds_bpermute_b32 v41, v232, v41
	ds_bpermute_b32 v40, v232, v40
	ds_bpermute_b32 v39, v232, v39
	ds_bpermute_b32 v38, v232, v38
	ds_bpermute_b32 v37, v232, v37
	ds_bpermute_b32 v36, v232, v36
	ds_bpermute_b32 v35, v232, v35
	ds_bpermute_b32 v34, v232, v34
	ds_bpermute_b32 v33, v232, v33
	ds_bpermute_b32 v32, v232, v32
	ds_bpermute_b32 v31, v232, v31
	ds_bpermute_b32 v30, v232, v30
	ds_bpermute_b32 v29, v232, v29
	ds_bpermute_b32 v28, v232, v28
	ds_bpermute_b32 v27, v232, v27
	ds_bpermute_b32 v26, v232, v26
	ds_bpermute_b32 v25, v232, v25
	ds_bpermute_b32 v24, v232, v24
	ds_bpermute_b32 v23, v232, v23
	ds_bpermute_b32 v22, v232, v22
	ds_bpermute_b32 v21, v232, v21
	ds_bpermute_b32 v20, v232, v20
	ds_bpermute_b32 v19, v232, v19
	ds_bpermute_b32 v18, v232, v18
	ds_bpermute_b32 v17, v232, v17
	ds_bpermute_b32 v16, v232, v16
	ds_bpermute_b32 v15, v232, v15
	ds_bpermute_b32 v14, v232, v14
	ds_bpermute_b32 v13, v232, v13
	ds_bpermute_b32 v12, v232, v12
	ds_bpermute_b32 v11, v232, v11
	ds_bpermute_b32 v10, v232, v10
	ds_bpermute_b32 v9, v232, v9
	ds_bpermute_b32 v8, v232, v8
	ds_bpermute_b32 v7, v232, v7
	ds_bpermute_b32 v6, v232, v6
	ds_bpermute_b32 v5, v232, v5
	ds_bpermute_b32 v4, v232, v4
	ds_bpermute_b32 v3, v232, v3
	ds_bpermute_b32 v2, v232, v2
	ds_bpermute_b32 v1, v232, v1
	ds_bpermute_b32 v0, v232, v0
	s_waitcnt lgkmcnt(0)
	v_lshl_add_u32 v164, s30, 8, v233
	v_ashrrev_i32_e32 v165, 31, v164
	v_lshl_add_u64 v[162:163], v[164:165], 2, s[14:15]
	global_load_dword v181, v[162:163], off
	v_lshl_or_b32 v160, s34, 8, v234
	v_lshlrev_b64 v[128:129], 11, v[164:165]
	v_ashrrev_i32_e32 v161, 31, v160
	v_lshl_add_u64 v[128:129], s[8:9], 0, v[128:129]
	v_lshlrev_b64 v[130:131], 1, v[160:161]
	v_lshl_add_u64 v[172:173], v[128:129], 0, v[130:131]
	v_lshlrev_b64 v[128:129], 12, v[164:165]
	v_lshlrev_b64 v[132:133], 2, v[160:161]
	v_lshl_add_u64 v[128:129], s[6:7], 0, v[128:129]
	global_load_dwordx2 v[184:185], v[172:173], off
	global_load_dwordx2 v[188:189], v[172:173], off offset:32
	v_lshl_add_u64 v[176:177], v[128:129], 0, v[132:133]
	global_load_dwordx4 v[200:203], v[176:177], off
	global_load_dwordx4 v[204:207], v[176:177], off offset:64
	v_or_b32_e32 v166, 16, v164
	v_ashrrev_i32_e32 v167, 31, v166
	v_lshl_add_u64 v[136:137], v[166:167], 2, s[14:15]
	global_load_dword v180, v[136:137], off
	global_load_dwordx4 v[208:211], v[176:177], off offset:512
	global_load_dwordx4 v[144:147], v[176:177], off offset:576
	global_load_dwordx2 v[212:213], v[172:173], off offset:256
	global_load_dwordx2 v[214:215], v[172:173], off offset:288
	v_lshlrev_b64 v[128:129], 12, v[166:167]
	v_lshlrev_b64 v[134:135], 11, v[166:167]
	v_lshl_add_u64 v[128:129], s[6:7], 0, v[128:129]
	v_lshl_add_u64 v[134:135], s[8:9], 0, v[134:135]
	v_lshl_add_u64 v[170:171], v[128:129], 0, v[132:133]
	v_lshl_add_u64 v[168:169], v[134:135], 0, v[130:131]
	global_load_dwordx4 v[140:143], v[170:171], off
	global_load_dwordx4 v[136:139], v[170:171], off offset:64
	global_load_dwordx4 v[132:135], v[170:171], off offset:512
	global_load_dwordx4 v[128:131], v[170:171], off offset:576
	global_load_dwordx2 v[186:187], v[168:169], off
	global_load_dwordx2 v[182:183], v[168:169], off offset:32
	global_load_dwordx2 v[178:179], v[168:169], off offset:256
	global_load_dwordx2 v[174:175], v[168:169], off offset:288
	s_waitcnt lgkmcnt(0)
	s_and_b64 vcc, exec, s[18:19]
	s_cbranch_vccz .LBB0_1310
	s_barrier
.LBB0_1310:
	s_waitcnt vmcnt(17)
	v_fmamk_f32 v181, v181, 0x3a800000, v197
	v_mul_f32_e32 v199, 0x4b800000, v181
	v_cmp_gt_f32_e32 vcc, s56, v181
	s_waitcnt vmcnt(16)
	v_lshlrev_b32_e32 v216, 16, v184
	s_nop 0
	v_cndmask_b32_e32 v181, v181, v199, vcc
	v_rsq_f32_e32 v181, v181
	v_and_b32_e32 v217, 0xffff0000, v184
	v_lshlrev_b32_e32 v184, 16, v185
	v_and_b32_e32 v185, 0xffff0000, v185
	v_mul_f32_e32 v199, 0x45800000, v181
	v_cndmask_b32_e32 v220, v181, v199, vcc
	v_pk_mul_f32 v[126:127], v[126:127], v[220:221] op_sel_hi:[1,0]
	v_pk_mul_f32 v[124:125], v[124:125], v[220:221] op_sel_hi:[1,0]
	v_pk_mul_f32 v[122:123], v[122:123], v[220:221] op_sel_hi:[1,0]
	v_pk_mul_f32 v[120:121], v[120:121], v[220:221] op_sel_hi:[1,0]
	v_mul_f32_e32 v124, 0xbfb8aa3b, v124
	v_mul_f32_e32 v125, 0xbfb8aa3b, v125
	v_mul_f32_e32 v126, 0xbfb8aa3b, v126
	v_mul_f32_e32 v127, 0xbfb8aa3b, v127
	v_mul_f32_e32 v120, 0xbfb8aa3b, v120
	v_mul_f32_e32 v121, 0xbfb8aa3b, v121
	v_mul_f32_e32 v122, 0xbfb8aa3b, v122
	v_mul_f32_e32 v123, 0xbfb8aa3b, v123
	v_exp_f32_e32 v124, v124
	v_exp_f32_e32 v125, v125
	v_exp_f32_e32 v126, v126
	v_exp_f32_e32 v127, v127
	v_exp_f32_e32 v120, v120
	v_exp_f32_e32 v121, v121
	v_exp_f32_e32 v122, v122
	v_exp_f32_e32 v123, v123
	v_add_f32_e32 v124, 1.0, v124
	v_add_f32_e32 v125, 1.0, v125
	v_add_f32_e32 v126, 1.0, v126
	v_add_f32_e32 v127, 1.0, v127
	v_add_f32_e32 v181, 1.0, v120
	v_add_f32_e32 v199, 1.0, v121
	v_add_f32_e32 v221, 1.0, v122
	v_add_f32_e32 v222, 1.0, v123
	v_rcp_f32_e32 v120, v124
	v_rcp_f32_e32 v121, v125
	v_rcp_f32_e32 v122, v126
	v_rcp_f32_e32 v123, v127
	v_rcp_f32_e32 v124, v181
	v_rcp_f32_e32 v125, v199
	v_rcp_f32_e32 v126, v221
	v_rcp_f32_e32 v127, v222
	s_waitcnt vmcnt(14)
	v_pk_fma_f32 v[120:121], v[120:121], v[216:217], v[200:201]
	v_pk_fma_f32 v[122:123], v[122:123], v[184:185], v[202:203]
	v_pk_mul_f32 v[116:117], v[116:117], v[220:221] op_sel_hi:[1,0]
	v_lshlrev_b32_e32 v218, 16, v188
	v_and_b32_e32 v219, 0xffff0000, v188
	v_lshlrev_b32_e32 v188, 16, v189
	v_and_b32_e32 v189, 0xffff0000, v189
	v_pk_mul_f32 v[184:185], v[120:121], v[120:121]
	global_store_dwordx4 v[176:177], v[120:123], off
	v_mul_f32_e32 v116, 0xbfb8aa3b, v116
	s_waitcnt vmcnt(14)
	v_pk_fma_f32 v[124:125], v[124:125], v[218:219], v[204:205]
	v_cvt_pk_bf16_f32 v120, v120, v121
	v_cvt_pk_bf16_f32 v121, v122, v123
	v_pk_fma_f32 v[126:127], v[126:127], v[188:189], v[206:207]
	global_store_dwordx2 v[172:173], v[120:121], off
	global_store_dwordx4 v[176:177], v[124:127], off offset:64
	v_exp_f32_e32 v120, v116
	v_mul_f32_e32 v116, 0xbfb8aa3b, v117
	v_exp_f32_e32 v121, v116
	v_pk_mul_f32 v[116:117], v[118:119], v[220:221] op_sel_hi:[1,0]
	v_add_f32_e32 v118, 1.0, v120
	v_mul_f32_e32 v116, 0xbfb8aa3b, v116
	v_exp_f32_e32 v116, v116
	v_mul_f32_e32 v117, 0xbfb8aa3b, v117
	v_add_f32_e32 v119, 1.0, v121
	v_exp_f32_e32 v117, v117
	v_rcp_f32_e32 v118, v118
	v_rcp_f32_e32 v119, v119
	v_pk_mul_f32 v[188:189], v[122:123], v[122:123]
	v_cvt_pk_bf16_f32 v122, v124, v125
	v_cvt_pk_bf16_f32 v123, v126, v127
	v_add_f32_e32 v116, 1.0, v116
	v_pk_mul_f32 v[112:113], v[112:113], v[220:221] op_sel_hi:[1,0]
	global_store_dwordx2 v[172:173], v[122:123], off offset:32
	s_waitcnt vmcnt(13)
	v_lshlrev_b32_e32 v120, 16, v212
	v_and_b32_e32 v121, 0xffff0000, v212
	v_rcp_f32_e32 v122, v116
	v_add_f32_e32 v116, 1.0, v117
	v_mul_f32_e32 v112, 0xbfb8aa3b, v112
	v_rcp_f32_e32 v123, v116
	v_pk_fma_f32 v[116:117], v[118:119], v[120:121], v[208:209]
	v_exp_f32_e32 v120, v112
	v_mul_f32_e32 v112, 0xbfb8aa3b, v113
	v_exp_f32_e32 v121, v112
	v_pk_mul_f32 v[112:113], v[114:115], v[220:221] op_sel_hi:[1,0]
	v_add_f32_e32 v114, 1.0, v120
	v_mul_f32_e32 v112, 0xbfb8aa3b, v112
	v_mul_f32_e32 v113, 0xbfb8aa3b, v113
	v_exp_f32_e32 v112, v112
	v_exp_f32_e32 v113, v113
	v_add_f32_e32 v115, 1.0, v121
	v_rcp_f32_e32 v114, v114
	v_rcp_f32_e32 v115, v115
	v_add_f32_e32 v112, 1.0, v112
	v_add_f32_e32 v113, 1.0, v113
	v_rcp_f32_e32 v112, v112
	v_rcp_f32_e32 v113, v113
	v_pk_mul_f32 v[200:201], v[124:125], v[124:125]
	v_pk_mul_f32 v[202:203], v[126:127], v[126:127]
	v_lshlrev_b32_e32 v118, 16, v213
	v_and_b32_e32 v119, 0xffff0000, v213
	s_waitcnt vmcnt(12)
	v_lshlrev_b32_e32 v120, 16, v214
	v_and_b32_e32 v121, 0xffff0000, v214
	v_pk_fma_f32 v[118:119], v[122:123], v[118:119], v[210:211]
	v_pk_fma_f32 v[120:121], v[114:115], v[120:121], v[144:145]
	v_lshlrev_b32_e32 v114, 16, v215
	v_and_b32_e32 v115, 0xffff0000, v215
	v_add_f32_e32 v144, v202, v203
	v_add_f32_e32 v145, v200, v201
	v_pk_mul_f32 v[124:125], v[116:117], v[116:117]
	v_pk_mul_f32 v[126:127], v[118:119], v[118:119]
	v_pk_fma_f32 v[122:123], v[112:113], v[114:115], v[146:147]
	v_add_f32_e32 v144, v145, v144
	v_add_f32_e32 v145, v188, v189
	v_add_f32_e32 v146, v184, v185
	v_pk_mul_f32 v[112:113], v[120:121], v[120:121]
	v_pk_mul_f32 v[114:115], v[122:123], v[122:123]
	v_add_f32_e32 v145, v146, v145
	v_add_f32_e32 v126, v126, v127
	v_add_f32_e32 v124, v124, v125
	v_add_f32_e32 v144, v145, v144
	v_add_f32_e32 v124, v124, v126
	v_add_f32_e32 v114, v114, v115
	v_add_f32_e32 v112, v112, v113
	v_add_f32_e32 v124, v124, v144
	v_add_f32_e32 v112, v112, v114
	v_and_b32_e32 v113, 64, v198
	v_add_f32_e32 v114, v112, v124
	v_xor_b32_e32 v112, 1, v198
	v_add_u32_e32 v115, 64, v113
	v_cmp_lt_i32_e32 vcc, v112, v115
	v_cvt_pk_bf16_f32 v113, v118, v119
	global_store_dwordx4 v[176:177], v[116:119], off offset:512
	v_cndmask_b32_e32 v112, v198, v112, vcc
	v_lshlrev_b32_e32 v199, 2, v112
	ds_bpermute_b32 v124, v199, v114
	v_cvt_pk_bf16_f32 v112, v116, v117
	global_store_dwordx2 v[172:173], v[112:113], off offset:256
	v_xor_b32_e32 v113, 2, v198
	v_cmp_lt_i32_e32 vcc, v113, v115
	s_waitcnt lgkmcnt(0)
	v_add_f32_e32 v112, v114, v124
	v_cvt_pk_bf16_f32 v114, v120, v121
	v_cndmask_b32_e32 v113, v198, v113, vcc
	v_lshlrev_b32_e32 v200, 2, v113
	ds_bpermute_b32 v113, v200, v112
	v_cvt_pk_bf16_f32 v115, v122, v123
	global_store_dwordx4 v[176:177], v[120:123], off offset:576
	global_store_dwordx2 v[172:173], v[114:115], off offset:288
	s_mov_b32 vcc_lo, 0x11111111
	s_mov_b32 vcc_hi, 0x11111111
	s_and_saveexec_b64 s[0:1], vcc
	s_cbranch_execz .LBB0_1312
	v_lshl_add_u64 v[114:115], v[164:165], 2, s[12:13]
	s_waitcnt lgkmcnt(0)
	v_add_f32_e32 v112, v112, v113
	global_atomic_add_f32 v[114:115], v112, off
.LBB0_1312:
	s_or_b64 exec, exec, s[0:1]
	v_fmamk_f32 v112, v180, 0x3a800000, v197
	s_waitcnt lgkmcnt(0)
	v_mul_f32_e32 v113, 0x4b800000, v112
	v_cmp_gt_f32_e32 vcc, s56, v112
	v_or_b32_e32 v144, 32, v164
	v_ashrrev_i32_e32 v145, 31, v144
	v_cndmask_b32_e32 v112, v112, v113, vcc
	v_rsq_f32_e32 v112, v112
	v_lshlrev_b64 v[114:115], 11, v[144:145]
	v_lshl_add_u64 v[114:115], s[8:9], 0, v[114:115]
	v_mul_f32_e32 v113, 0x45800000, v112
	v_cndmask_b32_e32 v202, v112, v113, vcc
	v_lshlrev_b64 v[112:113], 12, v[144:145]
	v_lshl_add_u64 v[112:113], s[6:7], 0, v[112:113]
	v_lshl_add_u64 v[172:173], v[160:161], 2, v[112:113]
	v_lshl_add_u64 v[146:147], v[160:161], 1, v[114:115]
	global_load_dwordx4 v[124:127], v[172:173], off
	global_load_dwordx4 v[120:123], v[172:173], off offset:64
	global_load_dwordx4 v[116:119], v[172:173], off offset:512
	global_load_dwordx4 v[112:115], v[172:173], off offset:576
	global_load_dwordx2 v[188:189], v[146:147], off
	global_load_dwordx2 v[184:185], v[146:147], off offset:32
	global_load_dwordx2 v[180:181], v[146:147], off offset:256
	global_load_dwordx2 v[176:177], v[146:147], off offset:288
	v_lshl_add_u64 v[204:205], v[144:145], 2, s[14:15]
	global_load_dword v165, v[204:205], off
	v_pk_mul_f32 v[108:109], v[108:109], v[202:203] op_sel_hi:[1,0]
	s_waitcnt vmcnt(20)
	v_lshlrev_b32_e32 v204, 16, v186
	v_mul_f32_e32 v108, 0xbfb8aa3b, v108
	v_exp_f32_e32 v201, v108
	v_mul_f32_e32 v108, 0xbfb8aa3b, v109
	v_exp_f32_e32 v203, v108
	v_and_b32_e32 v205, 0xffff0000, v186
	v_pk_mul_f32 v[108:109], v[110:111], v[202:203] op_sel_hi:[1,0]
	s_nop 0
	v_mul_f32_e32 v108, 0xbfb8aa3b, v108
	v_exp_f32_e32 v108, v108
	v_mul_f32_e32 v109, 0xbfb8aa3b, v109
	v_exp_f32_e32 v109, v109
	v_add_f32_e32 v110, 1.0, v201
	v_add_f32_e32 v111, 1.0, v203
	v_add_f32_e32 v108, 1.0, v108
	v_rcp_f32_e32 v110, v110
	v_rcp_f32_e32 v111, v111
	v_rcp_f32_e32 v206, v108
	v_add_f32_e32 v108, 1.0, v109
	v_rcp_f32_e32 v207, v108
	v_pk_fma_f32 v[108:109], v[110:111], v[204:205], v[140:141]
	v_lshlrev_b32_e32 v110, 16, v187
	v_and_b32_e32 v111, 0xffff0000, v187
	v_pk_fma_f32 v[110:111], v[206:207], v[110:111], v[142:143]
	v_pk_mul_f32 v[104:105], v[104:105], v[202:203] op_sel_hi:[1,0]
	v_pk_mul_f32 v[140:141], v[108:109], v[108:109]
	global_store_dwordx4 v[170:171], v[108:111], off
	v_mul_f32_e32 v104, 0xbfb8aa3b, v104
	v_pk_mul_f32 v[142:143], v[110:111], v[110:111]
	v_cvt_pk_bf16_f32 v108, v108, v109
	v_cvt_pk_bf16_f32 v109, v110, v111
	global_store_dwordx2 v[168:169], v[108:109], off
	v_exp_f32_e32 v108, v104
	v_mul_f32_e32 v104, 0xbfb8aa3b, v105
	v_exp_f32_e32 v109, v104
	v_pk_mul_f32 v[104:105], v[106:107], v[202:203] op_sel_hi:[1,0]
	v_add_f32_e32 v106, 1.0, v108
	v_mul_f32_e32 v104, 0xbfb8aa3b, v104
	v_exp_f32_e32 v104, v104
	v_mul_f32_e32 v105, 0xbfb8aa3b, v105
	v_exp_f32_e32 v105, v105
	v_add_f32_e32 v107, 1.0, v109
	v_add_f32_e32 v104, 1.0, v104
	v_rcp_f32_e32 v106, v106
	v_rcp_f32_e32 v107, v107
	v_rcp_f32_e32 v110, v104
	v_add_f32_e32 v104, 1.0, v105
	v_rcp_f32_e32 v111, v104
	s_waitcnt vmcnt(21)
	v_lshlrev_b32_e32 v108, 16, v182
	v_and_b32_e32 v109, 0xffff0000, v182
	v_pk_fma_f32 v[104:105], v[106:107], v[108:109], v[136:137]
	v_lshlrev_b32_e32 v106, 16, v183
	v_and_b32_e32 v107, 0xffff0000, v183
	v_pk_fma_f32 v[106:107], v[110:111], v[106:107], v[138:139]
	v_pk_mul_f32 v[100:101], v[100:101], v[202:203] op_sel_hi:[1,0]
	v_pk_mul_f32 v[108:109], v[104:105], v[104:105]
	global_store_dwordx4 v[170:171], v[104:107], off offset:64
	v_mul_f32_e32 v100, 0xbfb8aa3b, v100
	v_pk_mul_f32 v[96:97], v[96:97], v[202:203] op_sel_hi:[1,0]
	v_cvt_pk_bf16_f32 v104, v104, v105
	v_cvt_pk_bf16_f32 v105, v106, v107
	global_store_dwordx2 v[168:169], v[104:105], off offset:32
	v_exp_f32_e32 v104, v100
	v_mul_f32_e32 v100, 0xbfb8aa3b, v101
	v_exp_f32_e32 v105, v100
	v_pk_mul_f32 v[100:101], v[102:103], v[202:203] op_sel_hi:[1,0]
	v_add_f32_e32 v102, 1.0, v104
	v_mul_f32_e32 v100, 0xbfb8aa3b, v100
	v_exp_f32_e32 v100, v100
	v_mul_f32_e32 v101, 0xbfb8aa3b, v101
	v_add_f32_e32 v103, 1.0, v105
	v_exp_f32_e32 v101, v101
	v_rcp_f32_e32 v102, v102
	v_rcp_f32_e32 v103, v103
	v_add_f32_e32 v100, 1.0, v100
	v_pk_mul_f32 v[110:111], v[106:107], v[106:107]
	s_waitcnt vmcnt(22)
	v_lshlrev_b32_e32 v104, 16, v178
	v_and_b32_e32 v105, 0xffff0000, v178
	v_rcp_f32_e32 v106, v100
	v_add_f32_e32 v100, 1.0, v101
	v_mul_f32_e32 v96, 0xbfb8aa3b, v96
	v_rcp_f32_e32 v107, v100
	v_pk_fma_f32 v[100:101], v[102:103], v[104:105], v[132:133]
	v_exp_f32_e32 v104, v96
	v_mul_f32_e32 v96, 0xbfb8aa3b, v97
	v_exp_f32_e32 v105, v96
	v_pk_mul_f32 v[96:97], v[98:99], v[202:203] op_sel_hi:[1,0]
	v_add_f32_e32 v98, 1.0, v104
	v_mul_f32_e32 v96, 0xbfb8aa3b, v96
	v_mul_f32_e32 v97, 0xbfb8aa3b, v97
	v_exp_f32_e32 v96, v96
	v_exp_f32_e32 v97, v97
	v_add_f32_e32 v99, 1.0, v105
	v_rcp_f32_e32 v98, v98
	v_rcp_f32_e32 v99, v99
	v_add_f32_e32 v96, 1.0, v96
	v_add_f32_e32 v97, 1.0, v97
	v_rcp_f32_e32 v96, v96
	v_rcp_f32_e32 v97, v97
	v_lshlrev_b32_e32 v102, 16, v179
	v_and_b32_e32 v103, 0xffff0000, v179
	s_waitcnt vmcnt(21)
	v_lshlrev_b32_e32 v104, 16, v174
	v_and_b32_e32 v105, 0xffff0000, v174
	v_add_f32_e32 v110, v110, v111
	v_add_f32_e32 v108, v108, v109
	v_pk_fma_f32 v[102:103], v[106:107], v[102:103], v[134:135]
	v_pk_fma_f32 v[104:105], v[98:99], v[104:105], v[128:129]
	v_lshlrev_b32_e32 v98, 16, v175
	v_and_b32_e32 v99, 0xffff0000, v175
	v_add_f32_e32 v108, v108, v110
	v_add_f32_e32 v109, v142, v143
	v_add_f32_e32 v110, v140, v141
	v_pk_mul_f32 v[132:133], v[100:101], v[100:101]
	v_pk_mul_f32 v[134:135], v[102:103], v[102:103]
	v_pk_fma_f32 v[106:107], v[96:97], v[98:99], v[130:131]
	v_add_f32_e32 v109, v110, v109
	v_pk_mul_f32 v[96:97], v[104:105], v[104:105]
	v_pk_mul_f32 v[98:99], v[106:107], v[106:107]
	v_add_f32_e32 v108, v109, v108
	v_add_f32_e32 v109, v134, v135
	v_add_f32_e32 v110, v132, v133
	v_add_f32_e32 v109, v110, v109
	v_add_f32_e32 v98, v98, v99
	v_add_f32_e32 v96, v96, v97
	v_add_f32_e32 v108, v109, v108
	v_add_f32_e32 v96, v96, v98
	v_add_f32_e32 v98, v96, v108
	ds_bpermute_b32 v99, v199, v98
	v_cvt_pk_bf16_f32 v96, v100, v101
	v_cvt_pk_bf16_f32 v97, v102, v103
	global_store_dwordx4 v[170:171], v[100:103], off offset:512
	global_store_dwordx2 v[168:169], v[96:97], off offset:256
	s_waitcnt lgkmcnt(0)
	v_add_f32_e32 v96, v98, v99
	ds_bpermute_b32 v97, v200, v96
	v_cvt_pk_bf16_f32 v98, v104, v105
	v_cvt_pk_bf16_f32 v99, v106, v107
	global_store_dwordx4 v[170:171], v[104:107], off offset:576
	global_store_dwordx2 v[168:169], v[98:99], off offset:288
	s_mov_b32 vcc_lo, 0x11111111
	s_mov_b32 vcc_hi, 0x11111111
	s_and_saveexec_b64 s[0:1], vcc
	s_cbranch_execz .LBB0_1314
	v_lshl_add_u64 v[98:99], v[166:167], 2, s[12:13]
	s_waitcnt lgkmcnt(0)
	v_add_f32_e32 v96, v96, v97
	global_atomic_add_f32 v[98:99], v96, off
.LBB0_1314:
	s_or_b64 exec, exec, s[0:1]
	s_waitcnt vmcnt(8)
	v_fmamk_f32 v96, v165, 0x3a800000, v197
	s_waitcnt lgkmcnt(0)
	v_mul_f32_e32 v97, 0x4b800000, v96
	v_cmp_gt_f32_e32 vcc, s56, v96
	v_or_b32_e32 v128, 48, v164
	v_ashrrev_i32_e32 v129, 31, v128
	v_cndmask_b32_e32 v96, v96, v97, vcc
	v_rsq_f32_e32 v96, v96
	v_lshlrev_b64 v[98:99], 11, v[128:129]
	v_lshl_add_u64 v[98:99], s[8:9], 0, v[98:99]
	v_mul_f32_e32 v97, 0x45800000, v96
	v_cndmask_b32_e32 v166, v96, v97, vcc
	v_lshlrev_b64 v[96:97], 12, v[128:129]
	v_lshl_add_u64 v[96:97], s[6:7], 0, v[96:97]
	v_lshl_add_u64 v[132:133], v[160:161], 2, v[96:97]
	v_lshl_add_u64 v[130:131], v[160:161], 1, v[98:99]
	global_load_dwordx4 v[108:111], v[132:133], off
	global_load_dwordx4 v[104:107], v[132:133], off offset:64
	global_load_dwordx4 v[100:103], v[132:133], off offset:512
	global_load_dwordx4 v[96:99], v[132:133], off offset:576
	global_load_dwordx2 v[140:141], v[130:131], off
	global_load_dwordx2 v[138:139], v[130:131], off offset:32
	global_load_dwordx2 v[136:137], v[130:131], off offset:256
	global_load_dwordx2 v[134:135], v[130:131], off offset:288
	v_lshl_add_u64 v[142:143], v[128:129], 2, s[14:15]
	global_load_dword v142, v[142:143], off
	v_pk_mul_f32 v[92:93], v[92:93], v[166:167] op_sel_hi:[1,0]
	v_lshlrev_b32_e32 v168, 16, v188
	v_mul_f32_e32 v92, 0xbfb8aa3b, v92
	v_exp_f32_e32 v143, v92
	v_mul_f32_e32 v92, 0xbfb8aa3b, v93
	v_exp_f32_e32 v165, v92
	v_pk_mul_f32 v[92:93], v[94:95], v[166:167] op_sel_hi:[1,0]
	v_add_f32_e32 v94, 1.0, v143
	v_mul_f32_e32 v92, 0xbfb8aa3b, v92
	v_exp_f32_e32 v92, v92
	v_mul_f32_e32 v93, 0xbfb8aa3b, v93
	v_exp_f32_e32 v93, v93
	v_add_f32_e32 v95, 1.0, v165
	v_add_f32_e32 v92, 1.0, v92
	v_rcp_f32_e32 v94, v94
	v_rcp_f32_e32 v95, v95
	v_rcp_f32_e32 v170, v92
	v_add_f32_e32 v92, 1.0, v93
	v_rcp_f32_e32 v171, v92
	v_and_b32_e32 v169, 0xffff0000, v188
	v_pk_fma_f32 v[92:93], v[94:95], v[168:169], v[124:125]
	v_lshlrev_b32_e32 v94, 16, v189
	v_and_b32_e32 v95, 0xffff0000, v189
	v_pk_fma_f32 v[94:95], v[170:171], v[94:95], v[126:127]
	v_pk_mul_f32 v[88:89], v[88:89], v[166:167] op_sel_hi:[1,0]
	v_pk_mul_f32 v[124:125], v[92:93], v[92:93]
	global_store_dwordx4 v[172:173], v[92:95], off
	v_mul_f32_e32 v88, 0xbfb8aa3b, v88
	v_pk_mul_f32 v[126:127], v[94:95], v[94:95]
	v_cvt_pk_bf16_f32 v92, v92, v93
	v_cvt_pk_bf16_f32 v93, v94, v95
	global_store_dwordx2 v[146:147], v[92:93], off
	v_exp_f32_e32 v92, v88
	v_mul_f32_e32 v88, 0xbfb8aa3b, v89
	v_exp_f32_e32 v93, v88
	v_pk_mul_f32 v[88:89], v[90:91], v[166:167] op_sel_hi:[1,0]
	v_add_f32_e32 v90, 1.0, v92
	v_mul_f32_e32 v88, 0xbfb8aa3b, v88
	v_exp_f32_e32 v88, v88
	v_mul_f32_e32 v89, 0xbfb8aa3b, v89
	v_exp_f32_e32 v89, v89
	v_add_f32_e32 v91, 1.0, v93
	v_add_f32_e32 v88, 1.0, v88
	v_rcp_f32_e32 v90, v90
	v_rcp_f32_e32 v91, v91
	v_rcp_f32_e32 v94, v88
	v_add_f32_e32 v88, 1.0, v89
	v_rcp_f32_e32 v95, v88
	v_lshlrev_b32_e32 v92, 16, v184
	v_and_b32_e32 v93, 0xffff0000, v184
	v_pk_fma_f32 v[88:89], v[90:91], v[92:93], v[120:121]
	v_lshlrev_b32_e32 v90, 16, v185
	v_and_b32_e32 v91, 0xffff0000, v185
	v_pk_fma_f32 v[90:91], v[94:95], v[90:91], v[122:123]
	v_pk_mul_f32 v[84:85], v[84:85], v[166:167] op_sel_hi:[1,0]
	v_pk_mul_f32 v[92:93], v[88:89], v[88:89]
	global_store_dwordx4 v[172:173], v[88:91], off offset:64
	v_mul_f32_e32 v84, 0xbfb8aa3b, v84
	v_pk_mul_f32 v[80:81], v[80:81], v[166:167] op_sel_hi:[1,0]
	v_cvt_pk_bf16_f32 v88, v88, v89
	v_cvt_pk_bf16_f32 v89, v90, v91
	global_store_dwordx2 v[146:147], v[88:89], off offset:32
	v_exp_f32_e32 v88, v84
	v_mul_f32_e32 v84, 0xbfb8aa3b, v85
	v_exp_f32_e32 v89, v84
	v_pk_mul_f32 v[84:85], v[86:87], v[166:167] op_sel_hi:[1,0]
	v_add_f32_e32 v86, 1.0, v88
	v_mul_f32_e32 v84, 0xbfb8aa3b, v84
	v_exp_f32_e32 v84, v84
	v_mul_f32_e32 v85, 0xbfb8aa3b, v85
	v_add_f32_e32 v87, 1.0, v89
	v_exp_f32_e32 v85, v85
	v_rcp_f32_e32 v86, v86
	v_rcp_f32_e32 v87, v87
	v_add_f32_e32 v84, 1.0, v84
	v_pk_mul_f32 v[94:95], v[90:91], v[90:91]
	v_lshlrev_b32_e32 v88, 16, v180
	v_and_b32_e32 v89, 0xffff0000, v180
	v_rcp_f32_e32 v90, v84
	v_add_f32_e32 v84, 1.0, v85
	v_mul_f32_e32 v80, 0xbfb8aa3b, v80
	v_rcp_f32_e32 v91, v84
	v_pk_fma_f32 v[84:85], v[86:87], v[88:89], v[116:117]
	v_exp_f32_e32 v88, v80
	v_mul_f32_e32 v80, 0xbfb8aa3b, v81
	v_exp_f32_e32 v89, v80
	v_pk_mul_f32 v[80:81], v[82:83], v[166:167] op_sel_hi:[1,0]
	v_add_f32_e32 v82, 1.0, v88
	v_mul_f32_e32 v80, 0xbfb8aa3b, v80
	v_mul_f32_e32 v81, 0xbfb8aa3b, v81
	v_exp_f32_e32 v80, v80
	v_exp_f32_e32 v81, v81
	v_add_f32_e32 v83, 1.0, v89
	v_rcp_f32_e32 v82, v82
	v_rcp_f32_e32 v83, v83
	v_add_f32_e32 v80, 1.0, v80
	v_add_f32_e32 v81, 1.0, v81
	v_rcp_f32_e32 v80, v80
	v_rcp_f32_e32 v81, v81
	v_lshlrev_b32_e32 v86, 16, v181
	v_and_b32_e32 v87, 0xffff0000, v181
	v_lshlrev_b32_e32 v88, 16, v176
	v_and_b32_e32 v89, 0xffff0000, v176
	v_add_f32_e32 v94, v94, v95
	v_add_f32_e32 v92, v92, v93
	v_pk_fma_f32 v[86:87], v[90:91], v[86:87], v[118:119]
	v_pk_fma_f32 v[88:89], v[82:83], v[88:89], v[112:113]
	v_lshlrev_b32_e32 v82, 16, v177
	v_and_b32_e32 v83, 0xffff0000, v177
	v_add_f32_e32 v92, v92, v94
	v_add_f32_e32 v93, v126, v127
	v_add_f32_e32 v94, v124, v125
	v_pk_mul_f32 v[116:117], v[84:85], v[84:85]
	v_pk_mul_f32 v[118:119], v[86:87], v[86:87]
	v_pk_fma_f32 v[90:91], v[80:81], v[82:83], v[114:115]
	v_add_f32_e32 v93, v94, v93
	v_pk_mul_f32 v[80:81], v[88:89], v[88:89]
	v_pk_mul_f32 v[82:83], v[90:91], v[90:91]
	v_add_f32_e32 v92, v93, v92
	v_add_f32_e32 v93, v118, v119
	v_add_f32_e32 v94, v116, v117
	v_add_f32_e32 v93, v94, v93
	v_add_f32_e32 v82, v82, v83
	v_add_f32_e32 v80, v80, v81
	v_add_f32_e32 v92, v93, v92
	v_add_f32_e32 v80, v80, v82
	v_add_f32_e32 v82, v80, v92
	ds_bpermute_b32 v83, v199, v82
	v_cvt_pk_bf16_f32 v80, v84, v85
	v_cvt_pk_bf16_f32 v81, v86, v87
	global_store_dwordx4 v[172:173], v[84:87], off offset:512
	global_store_dwordx2 v[146:147], v[80:81], off offset:256
	s_waitcnt lgkmcnt(0)
	v_add_f32_e32 v80, v82, v83
	ds_bpermute_b32 v81, v200, v80
	v_cvt_pk_bf16_f32 v82, v88, v89
	v_cvt_pk_bf16_f32 v83, v90, v91
	global_store_dwordx4 v[172:173], v[88:91], off offset:576
	global_store_dwordx2 v[146:147], v[82:83], off offset:288
	s_mov_b32 vcc_lo, 0x11111111
	s_mov_b32 vcc_hi, 0x11111111
	s_and_saveexec_b64 s[0:1], vcc
	s_cbranch_execz .LBB0_1316
	v_lshl_add_u64 v[82:83], v[144:145], 2, s[12:13]
	s_waitcnt lgkmcnt(0)
	v_add_f32_e32 v80, v80, v81
	global_atomic_add_f32 v[82:83], v80, off
.LBB0_1316:
	s_or_b64 exec, exec, s[0:1]
	s_waitcnt vmcnt(8)
	v_fmamk_f32 v80, v142, 0x3a800000, v197
	s_waitcnt lgkmcnt(0)
	v_mul_f32_e32 v81, 0x4b800000, v80
	v_cmp_gt_f32_e32 vcc, s56, v80
	v_add_u32_e32 v112, 0x80, v164
	v_ashrrev_i32_e32 v113, 31, v112
	v_cndmask_b32_e32 v80, v80, v81, vcc
	v_rsq_f32_e32 v80, v80
	v_lshlrev_b64 v[82:83], 11, v[112:113]
	v_lshl_add_u64 v[82:83], s[8:9], 0, v[82:83]
	v_mul_f32_e32 v81, 0x45800000, v80
	v_cndmask_b32_e32 v142, v80, v81, vcc
	v_lshlrev_b64 v[80:81], 12, v[112:113]
	v_lshl_add_u64 v[80:81], s[6:7], 0, v[80:81]
	v_lshl_add_u64 v[116:117], v[160:161], 2, v[80:81]
	v_lshl_add_u64 v[114:115], v[160:161], 1, v[82:83]
	global_load_dwordx4 v[92:95], v[116:117], off
	global_load_dwordx4 v[88:91], v[116:117], off offset:64
	global_load_dwordx4 v[84:87], v[116:117], off offset:512
	global_load_dwordx4 v[80:83], v[116:117], off offset:576
	global_load_dwordx2 v[124:125], v[114:115], off
	global_load_dwordx2 v[122:123], v[114:115], off offset:32
	global_load_dwordx2 v[120:121], v[114:115], off offset:256
	global_load_dwordx2 v[118:119], v[114:115], off offset:288
	global_load_dword v126, v[162:163], off offset:512
	v_pk_mul_f32 v[76:77], v[76:77], v[142:143] op_sel_hi:[1,0]
	v_lshlrev_b32_e32 v144, 16, v140
	v_mul_f32_e32 v76, 0xbfb8aa3b, v76
	v_exp_f32_e32 v127, v76
	v_mul_f32_e32 v76, 0xbfb8aa3b, v77
	v_exp_f32_e32 v143, v76
	v_and_b32_e32 v145, 0xffff0000, v140
	v_pk_mul_f32 v[76:77], v[78:79], v[142:143] op_sel_hi:[1,0]
	s_nop 0
	v_mul_f32_e32 v76, 0xbfb8aa3b, v76
	v_exp_f32_e32 v76, v76
	v_mul_f32_e32 v77, 0xbfb8aa3b, v77
	v_exp_f32_e32 v77, v77
	v_add_f32_e32 v78, 1.0, v127
	v_add_f32_e32 v79, 1.0, v143
	v_add_f32_e32 v76, 1.0, v76
	v_rcp_f32_e32 v78, v78
	v_rcp_f32_e32 v79, v79
	v_rcp_f32_e32 v146, v76
	v_add_f32_e32 v76, 1.0, v77
	v_rcp_f32_e32 v147, v76
	v_pk_fma_f32 v[76:77], v[78:79], v[144:145], v[108:109]
	v_lshlrev_b32_e32 v78, 16, v141
	v_and_b32_e32 v79, 0xffff0000, v141
	v_pk_fma_f32 v[78:79], v[146:147], v[78:79], v[110:111]
	v_pk_mul_f32 v[72:73], v[72:73], v[142:143] op_sel_hi:[1,0]
	v_pk_mul_f32 v[108:109], v[76:77], v[76:77]
	global_store_dwordx4 v[132:133], v[76:79], off
	v_mul_f32_e32 v72, 0xbfb8aa3b, v72
	v_pk_mul_f32 v[110:111], v[78:79], v[78:79]
	v_cvt_pk_bf16_f32 v76, v76, v77
	v_cvt_pk_bf16_f32 v77, v78, v79
	global_store_dwordx2 v[130:131], v[76:77], off
	v_exp_f32_e32 v76, v72
	v_mul_f32_e32 v72, 0xbfb8aa3b, v73
	v_exp_f32_e32 v77, v72
	v_pk_mul_f32 v[72:73], v[74:75], v[142:143] op_sel_hi:[1,0]
	v_add_f32_e32 v74, 1.0, v76
	v_mul_f32_e32 v72, 0xbfb8aa3b, v72
	v_exp_f32_e32 v72, v72
	v_mul_f32_e32 v73, 0xbfb8aa3b, v73
	v_exp_f32_e32 v73, v73
	v_add_f32_e32 v75, 1.0, v77
	v_add_f32_e32 v72, 1.0, v72
	v_rcp_f32_e32 v74, v74
	v_rcp_f32_e32 v75, v75
	v_rcp_f32_e32 v78, v72
	v_add_f32_e32 v72, 1.0, v73
	v_rcp_f32_e32 v79, v72
	v_lshlrev_b32_e32 v76, 16, v138
	v_and_b32_e32 v77, 0xffff0000, v138
	v_pk_fma_f32 v[72:73], v[74:75], v[76:77], v[104:105]
	v_lshlrev_b32_e32 v74, 16, v139
	v_and_b32_e32 v75, 0xffff0000, v139
	v_pk_fma_f32 v[74:75], v[78:79], v[74:75], v[106:107]
	v_pk_mul_f32 v[68:69], v[68:69], v[142:143] op_sel_hi:[1,0]
	v_pk_mul_f32 v[76:77], v[72:73], v[72:73]
	global_store_dwordx4 v[132:133], v[72:75], off offset:64
	v_mul_f32_e32 v68, 0xbfb8aa3b, v68
	v_pk_mul_f32 v[64:65], v[64:65], v[142:143] op_sel_hi:[1,0]
	v_cvt_pk_bf16_f32 v72, v72, v73
	v_cvt_pk_bf16_f32 v73, v74, v75
	global_store_dwordx2 v[130:131], v[72:73], off offset:32
	v_exp_f32_e32 v72, v68
	v_mul_f32_e32 v68, 0xbfb8aa3b, v69
	v_exp_f32_e32 v73, v68
	v_pk_mul_f32 v[68:69], v[70:71], v[142:143] op_sel_hi:[1,0]
	v_add_f32_e32 v70, 1.0, v72
	v_mul_f32_e32 v68, 0xbfb8aa3b, v68
	v_exp_f32_e32 v68, v68
	v_mul_f32_e32 v69, 0xbfb8aa3b, v69
	v_add_f32_e32 v71, 1.0, v73
	v_exp_f32_e32 v69, v69
	v_rcp_f32_e32 v70, v70
	v_rcp_f32_e32 v71, v71
	v_add_f32_e32 v68, 1.0, v68
	v_pk_mul_f32 v[78:79], v[74:75], v[74:75]
	v_lshlrev_b32_e32 v72, 16, v136
	v_and_b32_e32 v73, 0xffff0000, v136
	v_rcp_f32_e32 v74, v68
	v_add_f32_e32 v68, 1.0, v69
	v_mul_f32_e32 v64, 0xbfb8aa3b, v64
	v_rcp_f32_e32 v75, v68
	v_pk_fma_f32 v[68:69], v[70:71], v[72:73], v[100:101]
	v_exp_f32_e32 v72, v64
	v_mul_f32_e32 v64, 0xbfb8aa3b, v65
	v_exp_f32_e32 v73, v64
	v_pk_mul_f32 v[64:65], v[66:67], v[142:143] op_sel_hi:[1,0]
	v_add_f32_e32 v66, 1.0, v72
	v_mul_f32_e32 v64, 0xbfb8aa3b, v64
	v_mul_f32_e32 v65, 0xbfb8aa3b, v65
	v_exp_f32_e32 v64, v64
	v_exp_f32_e32 v65, v65
	v_add_f32_e32 v67, 1.0, v73
	v_rcp_f32_e32 v66, v66
	v_rcp_f32_e32 v67, v67
	v_add_f32_e32 v64, 1.0, v64
	v_add_f32_e32 v65, 1.0, v65
	v_rcp_f32_e32 v64, v64
	v_rcp_f32_e32 v65, v65
	v_lshlrev_b32_e32 v70, 16, v137
	v_and_b32_e32 v71, 0xffff0000, v137
	v_lshlrev_b32_e32 v72, 16, v134
	v_and_b32_e32 v73, 0xffff0000, v134
	v_add_f32_e32 v78, v78, v79
	v_add_f32_e32 v76, v76, v77
	v_pk_fma_f32 v[70:71], v[74:75], v[70:71], v[102:103]
	v_pk_fma_f32 v[72:73], v[66:67], v[72:73], v[96:97]
	v_lshlrev_b32_e32 v66, 16, v135
	v_and_b32_e32 v67, 0xffff0000, v135
	v_add_f32_e32 v76, v76, v78
	v_add_f32_e32 v77, v110, v111
	v_add_f32_e32 v78, v108, v109
	v_pk_mul_f32 v[100:101], v[68:69], v[68:69]
	v_pk_mul_f32 v[102:103], v[70:71], v[70:71]
	v_pk_fma_f32 v[74:75], v[64:65], v[66:67], v[98:99]
	v_add_f32_e32 v77, v78, v77
	v_pk_mul_f32 v[64:65], v[72:73], v[72:73]
	v_pk_mul_f32 v[66:67], v[74:75], v[74:75]
	v_add_f32_e32 v76, v77, v76
	v_add_f32_e32 v77, v102, v103
	v_add_f32_e32 v78, v100, v101
	v_add_f32_e32 v77, v78, v77
	v_add_f32_e32 v66, v66, v67
	v_add_f32_e32 v64, v64, v65
	v_add_f32_e32 v76, v77, v76
	v_add_f32_e32 v64, v64, v66
	v_add_f32_e32 v66, v64, v76
	ds_bpermute_b32 v67, v199, v66
	v_cvt_pk_bf16_f32 v64, v68, v69
	v_cvt_pk_bf16_f32 v65, v70, v71
	global_store_dwordx4 v[132:133], v[68:71], off offset:512
	global_store_dwordx2 v[130:131], v[64:65], off offset:256
	s_waitcnt lgkmcnt(0)
	v_add_f32_e32 v64, v66, v67
	ds_bpermute_b32 v65, v200, v64
	v_cvt_pk_bf16_f32 v66, v72, v73
	v_cvt_pk_bf16_f32 v67, v74, v75
	global_store_dwordx4 v[132:133], v[72:75], off offset:576
	global_store_dwordx2 v[130:131], v[66:67], off offset:288
	s_mov_b32 vcc_lo, 0x11111111
	s_mov_b32 vcc_hi, 0x11111111
	s_and_saveexec_b64 s[0:1], vcc
	s_cbranch_execz .LBB0_1318
	v_lshl_add_u64 v[66:67], v[128:129], 2, s[12:13]
	s_waitcnt lgkmcnt(0)
	v_add_f32_e32 v64, v64, v65
	global_atomic_add_f32 v[66:67], v64, off
.LBB0_1318:
	s_or_b64 exec, exec, s[0:1]
	s_waitcnt vmcnt(8)
	v_fmamk_f32 v64, v126, 0x3a800000, v197
	s_waitcnt lgkmcnt(0)
	v_mul_f32_e32 v65, 0x4b800000, v64
	v_cmp_gt_f32_e32 vcc, s56, v64
	v_or_b32_e32 v96, 16, v112
	v_ashrrev_i32_e32 v97, 31, v96
	v_cndmask_b32_e32 v64, v64, v65, vcc
	v_rsq_f32_e32 v64, v64
	v_lshlrev_b64 v[66:67], 11, v[96:97]
	v_lshl_add_u64 v[66:67], s[8:9], 0, v[66:67]
	v_mul_f32_e32 v65, 0x45800000, v64
	v_cndmask_b32_e32 v126, v64, v65, vcc
	v_lshlrev_b64 v[64:65], 12, v[96:97]
	v_lshl_add_u64 v[64:65], s[6:7], 0, v[64:65]
	v_lshl_add_u64 v[100:101], v[160:161], 2, v[64:65]
	v_lshl_add_u64 v[98:99], v[160:161], 1, v[66:67]
	global_load_dwordx4 v[76:79], v[100:101], off
	global_load_dwordx4 v[72:75], v[100:101], off offset:64
	global_load_dwordx4 v[68:71], v[100:101], off offset:512
	global_load_dwordx4 v[64:67], v[100:101], off offset:576
	global_load_dwordx2 v[108:109], v[98:99], off
	global_load_dwordx2 v[106:107], v[98:99], off offset:32
	global_load_dwordx2 v[104:105], v[98:99], off offset:256
	global_load_dwordx2 v[102:103], v[98:99], off offset:288
	v_lshl_add_u64 v[110:111], v[96:97], 2, s[14:15]
	global_load_dword v110, v[110:111], off
	v_pk_mul_f32 v[60:61], v[60:61], v[126:127] op_sel_hi:[1,0]
	v_lshlrev_b32_e32 v128, 16, v124
	v_mul_f32_e32 v60, 0xbfb8aa3b, v60
	v_exp_f32_e32 v111, v60
	v_mul_f32_e32 v60, 0xbfb8aa3b, v61
	v_exp_f32_e32 v127, v60
	v_and_b32_e32 v129, 0xffff0000, v124
	v_pk_mul_f32 v[60:61], v[62:63], v[126:127] op_sel_hi:[1,0]
	s_nop 0
	v_mul_f32_e32 v60, 0xbfb8aa3b, v60
	v_exp_f32_e32 v60, v60
	v_mul_f32_e32 v61, 0xbfb8aa3b, v61
	v_exp_f32_e32 v61, v61
	v_add_f32_e32 v62, 1.0, v111
	v_add_f32_e32 v63, 1.0, v127
	v_add_f32_e32 v60, 1.0, v60
	v_rcp_f32_e32 v62, v62
	v_rcp_f32_e32 v63, v63
	v_rcp_f32_e32 v130, v60
	v_add_f32_e32 v60, 1.0, v61
	v_rcp_f32_e32 v131, v60
	v_pk_fma_f32 v[60:61], v[62:63], v[128:129], v[92:93]
	v_lshlrev_b32_e32 v62, 16, v125
	v_and_b32_e32 v63, 0xffff0000, v125
	v_pk_fma_f32 v[62:63], v[130:131], v[62:63], v[94:95]
	v_pk_mul_f32 v[56:57], v[56:57], v[126:127] op_sel_hi:[1,0]
	v_pk_mul_f32 v[92:93], v[60:61], v[60:61]
	global_store_dwordx4 v[116:117], v[60:63], off
	v_mul_f32_e32 v56, 0xbfb8aa3b, v56
	v_pk_mul_f32 v[94:95], v[62:63], v[62:63]
	v_cvt_pk_bf16_f32 v60, v60, v61
	v_cvt_pk_bf16_f32 v61, v62, v63
	global_store_dwordx2 v[114:115], v[60:61], off
	v_exp_f32_e32 v60, v56
	v_mul_f32_e32 v56, 0xbfb8aa3b, v57
	v_exp_f32_e32 v61, v56
	v_pk_mul_f32 v[56:57], v[58:59], v[126:127] op_sel_hi:[1,0]
	v_add_f32_e32 v58, 1.0, v60
	v_mul_f32_e32 v56, 0xbfb8aa3b, v56
	v_exp_f32_e32 v56, v56
	v_mul_f32_e32 v57, 0xbfb8aa3b, v57
	v_exp_f32_e32 v57, v57
	v_add_f32_e32 v59, 1.0, v61
	v_add_f32_e32 v56, 1.0, v56
	v_rcp_f32_e32 v58, v58
	v_rcp_f32_e32 v59, v59
	v_rcp_f32_e32 v62, v56
	v_add_f32_e32 v56, 1.0, v57
	v_rcp_f32_e32 v63, v56
	v_lshlrev_b32_e32 v60, 16, v122
	v_and_b32_e32 v61, 0xffff0000, v122
	v_pk_fma_f32 v[56:57], v[58:59], v[60:61], v[88:89]
	v_lshlrev_b32_e32 v58, 16, v123
	v_and_b32_e32 v59, 0xffff0000, v123
	v_pk_fma_f32 v[58:59], v[62:63], v[58:59], v[90:91]
	v_pk_mul_f32 v[52:53], v[52:53], v[126:127] op_sel_hi:[1,0]
	v_pk_mul_f32 v[60:61], v[56:57], v[56:57]
	global_store_dwordx4 v[116:117], v[56:59], off offset:64
	v_mul_f32_e32 v52, 0xbfb8aa3b, v52
	v_pk_mul_f32 v[48:49], v[48:49], v[126:127] op_sel_hi:[1,0]
	v_cvt_pk_bf16_f32 v56, v56, v57
	v_cvt_pk_bf16_f32 v57, v58, v59
	global_store_dwordx2 v[114:115], v[56:57], off offset:32
	v_exp_f32_e32 v56, v52
	v_mul_f32_e32 v52, 0xbfb8aa3b, v53
	v_exp_f32_e32 v57, v52
	v_pk_mul_f32 v[52:53], v[54:55], v[126:127] op_sel_hi:[1,0]
	v_add_f32_e32 v54, 1.0, v56
	v_mul_f32_e32 v52, 0xbfb8aa3b, v52
	v_exp_f32_e32 v52, v52
	v_mul_f32_e32 v53, 0xbfb8aa3b, v53
	v_add_f32_e32 v55, 1.0, v57
	v_exp_f32_e32 v53, v53
	v_rcp_f32_e32 v54, v54
	v_rcp_f32_e32 v55, v55
	v_add_f32_e32 v52, 1.0, v52
	v_pk_mul_f32 v[62:63], v[58:59], v[58:59]
	v_lshlrev_b32_e32 v56, 16, v120
	v_and_b32_e32 v57, 0xffff0000, v120
	v_rcp_f32_e32 v58, v52
	v_add_f32_e32 v52, 1.0, v53
	v_mul_f32_e32 v48, 0xbfb8aa3b, v48
	v_rcp_f32_e32 v59, v52
	v_pk_fma_f32 v[52:53], v[54:55], v[56:57], v[84:85]
	v_exp_f32_e32 v56, v48
	v_mul_f32_e32 v48, 0xbfb8aa3b, v49
	v_exp_f32_e32 v57, v48
	v_pk_mul_f32 v[48:49], v[50:51], v[126:127] op_sel_hi:[1,0]
	v_add_f32_e32 v50, 1.0, v56
	v_mul_f32_e32 v48, 0xbfb8aa3b, v48
	v_mul_f32_e32 v49, 0xbfb8aa3b, v49
	v_exp_f32_e32 v48, v48
	v_exp_f32_e32 v49, v49
	v_add_f32_e32 v51, 1.0, v57
	v_rcp_f32_e32 v50, v50
	v_rcp_f32_e32 v51, v51
	v_add_f32_e32 v48, 1.0, v48
	v_add_f32_e32 v49, 1.0, v49
	v_rcp_f32_e32 v48, v48
	v_rcp_f32_e32 v49, v49
	v_lshlrev_b32_e32 v54, 16, v121
	v_and_b32_e32 v55, 0xffff0000, v121
	v_lshlrev_b32_e32 v56, 16, v118
	v_and_b32_e32 v57, 0xffff0000, v118
	v_add_f32_e32 v62, v62, v63
	v_add_f32_e32 v60, v60, v61
	v_pk_fma_f32 v[54:55], v[58:59], v[54:55], v[86:87]
	v_pk_fma_f32 v[56:57], v[50:51], v[56:57], v[80:81]
	v_lshlrev_b32_e32 v50, 16, v119
	v_and_b32_e32 v51, 0xffff0000, v119
	v_add_f32_e32 v60, v60, v62
	v_add_f32_e32 v61, v94, v95
	v_add_f32_e32 v62, v92, v93
	v_pk_mul_f32 v[84:85], v[52:53], v[52:53]
	v_pk_mul_f32 v[86:87], v[54:55], v[54:55]
	v_pk_fma_f32 v[58:59], v[48:49], v[50:51], v[82:83]
	v_add_f32_e32 v61, v62, v61
	v_pk_mul_f32 v[48:49], v[56:57], v[56:57]
	v_pk_mul_f32 v[50:51], v[58:59], v[58:59]
	v_add_f32_e32 v60, v61, v60
	v_add_f32_e32 v61, v86, v87
	v_add_f32_e32 v62, v84, v85
	v_add_f32_e32 v61, v62, v61
	v_add_f32_e32 v50, v50, v51
	v_add_f32_e32 v48, v48, v49
	v_add_f32_e32 v60, v61, v60
	v_add_f32_e32 v48, v48, v50
	v_add_f32_e32 v50, v48, v60
	ds_bpermute_b32 v51, v199, v50
	v_cvt_pk_bf16_f32 v48, v52, v53
	v_cvt_pk_bf16_f32 v49, v54, v55
	global_store_dwordx4 v[116:117], v[52:55], off offset:512
	global_store_dwordx2 v[114:115], v[48:49], off offset:256
	s_waitcnt lgkmcnt(0)
	v_add_f32_e32 v48, v50, v51
	ds_bpermute_b32 v49, v200, v48
	v_cvt_pk_bf16_f32 v50, v56, v57
	v_cvt_pk_bf16_f32 v51, v58, v59
	global_store_dwordx4 v[116:117], v[56:59], off offset:576
	global_store_dwordx2 v[114:115], v[50:51], off offset:288
	s_mov_b32 vcc_lo, 0x11111111
	s_mov_b32 vcc_hi, 0x11111111
	s_and_saveexec_b64 s[0:1], vcc
	s_cbranch_execz .LBB0_1320
	v_lshl_add_u64 v[50:51], v[112:113], 2, s[12:13]
	s_waitcnt lgkmcnt(0)
	v_add_f32_e32 v48, v48, v49
	global_atomic_add_f32 v[50:51], v48, off
.LBB0_1320:
	s_or_b64 exec, exec, s[0:1]
	s_waitcnt vmcnt(8)
	v_fmamk_f32 v48, v110, 0x3a800000, v197
	s_waitcnt lgkmcnt(0)
	v_mul_f32_e32 v49, 0x4b800000, v48
	v_cmp_gt_f32_e32 vcc, s56, v48
	v_or_b32_e32 v80, 32, v112
	v_ashrrev_i32_e32 v81, 31, v80
	v_cndmask_b32_e32 v48, v48, v49, vcc
	v_rsq_f32_e32 v48, v48
	v_lshlrev_b64 v[50:51], 11, v[80:81]
	v_lshl_add_u64 v[50:51], s[8:9], 0, v[50:51]
	v_mul_f32_e32 v49, 0x45800000, v48
	v_cndmask_b32_e32 v110, v48, v49, vcc
	v_lshlrev_b64 v[48:49], 12, v[80:81]
	v_lshl_add_u64 v[48:49], s[6:7], 0, v[48:49]
	v_lshl_add_u64 v[84:85], v[160:161], 2, v[48:49]
	v_lshl_add_u64 v[82:83], v[160:161], 1, v[50:51]
	global_load_dwordx4 v[60:63], v[84:85], off
	global_load_dwordx4 v[56:59], v[84:85], off offset:64
	global_load_dwordx4 v[52:55], v[84:85], off offset:512
	global_load_dwordx4 v[48:51], v[84:85], off offset:576
	global_load_dwordx2 v[92:93], v[82:83], off
	global_load_dwordx2 v[90:91], v[82:83], off offset:32
	global_load_dwordx2 v[88:89], v[82:83], off offset:256
	global_load_dwordx2 v[86:87], v[82:83], off offset:288
	v_lshl_add_u64 v[94:95], v[80:81], 2, s[14:15]
	global_load_dword v94, v[94:95], off
	v_pk_mul_f32 v[44:45], v[44:45], v[110:111] op_sel_hi:[1,0]
	v_lshlrev_b32_e32 v114, 16, v108
	v_mul_f32_e32 v44, 0xbfb8aa3b, v44
	v_exp_f32_e32 v95, v44
	v_mul_f32_e32 v44, 0xbfb8aa3b, v45
	v_exp_f32_e32 v111, v44
	v_and_b32_e32 v115, 0xffff0000, v108
	v_pk_mul_f32 v[44:45], v[46:47], v[110:111] op_sel_hi:[1,0]
	s_nop 0
	v_mul_f32_e32 v44, 0xbfb8aa3b, v44
	v_exp_f32_e32 v44, v44
	v_mul_f32_e32 v45, 0xbfb8aa3b, v45
	v_exp_f32_e32 v45, v45
	v_add_f32_e32 v46, 1.0, v95
	v_add_f32_e32 v47, 1.0, v111
	v_add_f32_e32 v44, 1.0, v44
	v_rcp_f32_e32 v46, v46
	v_rcp_f32_e32 v47, v47
	v_rcp_f32_e32 v116, v44
	v_add_f32_e32 v44, 1.0, v45
	v_rcp_f32_e32 v117, v44
	v_pk_fma_f32 v[44:45], v[46:47], v[114:115], v[76:77]
	v_lshlrev_b32_e32 v46, 16, v109
	v_and_b32_e32 v47, 0xffff0000, v109
	v_pk_fma_f32 v[46:47], v[116:117], v[46:47], v[78:79]
	v_pk_mul_f32 v[40:41], v[40:41], v[110:111] op_sel_hi:[1,0]
	v_pk_mul_f32 v[76:77], v[44:45], v[44:45]
	global_store_dwordx4 v[100:101], v[44:47], off
	v_mul_f32_e32 v40, 0xbfb8aa3b, v40
	v_pk_mul_f32 v[78:79], v[46:47], v[46:47]
	v_cvt_pk_bf16_f32 v44, v44, v45
	v_cvt_pk_bf16_f32 v45, v46, v47
	global_store_dwordx2 v[98:99], v[44:45], off
	v_exp_f32_e32 v44, v40
	v_mul_f32_e32 v40, 0xbfb8aa3b, v41
	v_exp_f32_e32 v45, v40
	v_pk_mul_f32 v[40:41], v[42:43], v[110:111] op_sel_hi:[1,0]
	v_add_f32_e32 v42, 1.0, v44
	v_mul_f32_e32 v40, 0xbfb8aa3b, v40
	v_exp_f32_e32 v40, v40
	v_mul_f32_e32 v41, 0xbfb8aa3b, v41
	v_exp_f32_e32 v41, v41
	v_add_f32_e32 v43, 1.0, v45
	v_add_f32_e32 v40, 1.0, v40
	v_rcp_f32_e32 v42, v42
	v_rcp_f32_e32 v43, v43
	v_rcp_f32_e32 v46, v40
	v_add_f32_e32 v40, 1.0, v41
	v_rcp_f32_e32 v47, v40
	v_lshlrev_b32_e32 v44, 16, v106
	v_and_b32_e32 v45, 0xffff0000, v106
	v_pk_fma_f32 v[40:41], v[42:43], v[44:45], v[72:73]
	v_lshlrev_b32_e32 v42, 16, v107
	v_and_b32_e32 v43, 0xffff0000, v107
	v_pk_fma_f32 v[42:43], v[46:47], v[42:43], v[74:75]
	v_pk_mul_f32 v[36:37], v[36:37], v[110:111] op_sel_hi:[1,0]
	v_pk_mul_f32 v[44:45], v[40:41], v[40:41]
	global_store_dwordx4 v[100:101], v[40:43], off offset:64
	v_mul_f32_e32 v36, 0xbfb8aa3b, v36
	v_pk_mul_f32 v[32:33], v[32:33], v[110:111] op_sel_hi:[1,0]
	v_cvt_pk_bf16_f32 v40, v40, v41
	v_cvt_pk_bf16_f32 v41, v42, v43
	global_store_dwordx2 v[98:99], v[40:41], off offset:32
	v_exp_f32_e32 v40, v36
	v_mul_f32_e32 v36, 0xbfb8aa3b, v37
	v_exp_f32_e32 v41, v36
	v_pk_mul_f32 v[36:37], v[38:39], v[110:111] op_sel_hi:[1,0]
	v_add_f32_e32 v38, 1.0, v40
	v_mul_f32_e32 v36, 0xbfb8aa3b, v36
	v_exp_f32_e32 v36, v36
	v_mul_f32_e32 v37, 0xbfb8aa3b, v37
	v_add_f32_e32 v39, 1.0, v41
	v_exp_f32_e32 v37, v37
	v_rcp_f32_e32 v38, v38
	v_rcp_f32_e32 v39, v39
	v_add_f32_e32 v36, 1.0, v36
	v_pk_mul_f32 v[46:47], v[42:43], v[42:43]
	v_lshlrev_b32_e32 v40, 16, v104
	v_and_b32_e32 v41, 0xffff0000, v104
	v_rcp_f32_e32 v42, v36
	v_add_f32_e32 v36, 1.0, v37
	v_mul_f32_e32 v32, 0xbfb8aa3b, v32
	v_rcp_f32_e32 v43, v36
	v_pk_fma_f32 v[36:37], v[38:39], v[40:41], v[68:69]
	v_exp_f32_e32 v40, v32
	v_mul_f32_e32 v32, 0xbfb8aa3b, v33
	v_exp_f32_e32 v41, v32
	v_pk_mul_f32 v[32:33], v[34:35], v[110:111] op_sel_hi:[1,0]
	v_add_f32_e32 v34, 1.0, v40
	v_mul_f32_e32 v32, 0xbfb8aa3b, v32
	v_mul_f32_e32 v33, 0xbfb8aa3b, v33
	v_exp_f32_e32 v32, v32
	v_exp_f32_e32 v33, v33
	v_add_f32_e32 v35, 1.0, v41
	v_rcp_f32_e32 v34, v34
	v_rcp_f32_e32 v35, v35
	v_add_f32_e32 v32, 1.0, v32
	v_add_f32_e32 v33, 1.0, v33
	v_rcp_f32_e32 v32, v32
	v_rcp_f32_e32 v33, v33
	v_lshlrev_b32_e32 v38, 16, v105
	v_and_b32_e32 v39, 0xffff0000, v105
	v_lshlrev_b32_e32 v40, 16, v102
	v_and_b32_e32 v41, 0xffff0000, v102
	v_add_f32_e32 v46, v46, v47
	v_add_f32_e32 v44, v44, v45
	v_pk_fma_f32 v[38:39], v[42:43], v[38:39], v[70:71]
	v_pk_fma_f32 v[40:41], v[34:35], v[40:41], v[64:65]
	v_lshlrev_b32_e32 v34, 16, v103
	v_and_b32_e32 v35, 0xffff0000, v103
	v_add_f32_e32 v44, v44, v46
	v_add_f32_e32 v45, v78, v79
	v_add_f32_e32 v46, v76, v77
	v_pk_mul_f32 v[68:69], v[36:37], v[36:37]
	v_pk_mul_f32 v[70:71], v[38:39], v[38:39]
	v_pk_fma_f32 v[42:43], v[32:33], v[34:35], v[66:67]
	v_add_f32_e32 v45, v46, v45
	v_pk_mul_f32 v[32:33], v[40:41], v[40:41]
	v_pk_mul_f32 v[34:35], v[42:43], v[42:43]
	v_add_f32_e32 v44, v45, v44
	v_add_f32_e32 v45, v70, v71
	v_add_f32_e32 v46, v68, v69
	v_add_f32_e32 v45, v46, v45
	v_add_f32_e32 v34, v34, v35
	v_add_f32_e32 v32, v32, v33
	v_add_f32_e32 v44, v45, v44
	v_add_f32_e32 v32, v32, v34
	v_add_f32_e32 v34, v32, v44
	ds_bpermute_b32 v35, v199, v34
	v_cvt_pk_bf16_f32 v32, v36, v37
	v_cvt_pk_bf16_f32 v33, v38, v39
	global_store_dwordx4 v[100:101], v[36:39], off offset:512
	global_store_dwordx2 v[98:99], v[32:33], off offset:256
	s_waitcnt lgkmcnt(0)
	v_add_f32_e32 v32, v34, v35
	ds_bpermute_b32 v33, v200, v32
	v_cvt_pk_bf16_f32 v34, v40, v41
	v_cvt_pk_bf16_f32 v35, v42, v43
	global_store_dwordx4 v[100:101], v[40:43], off offset:576
	global_store_dwordx2 v[98:99], v[34:35], off offset:288
	s_mov_b32 vcc_lo, 0x11111111
	s_mov_b32 vcc_hi, 0x11111111
	s_and_saveexec_b64 s[0:1], vcc
	s_cbranch_execz .LBB0_1322
	v_lshl_add_u64 v[34:35], v[96:97], 2, s[12:13]
	s_waitcnt lgkmcnt(0)
	v_add_f32_e32 v32, v32, v33
	global_atomic_add_f32 v[34:35], v32, off
.LBB0_1322:
	s_or_b64 exec, exec, s[0:1]
	s_waitcnt vmcnt(8)
	v_fmamk_f32 v32, v94, 0x3a800000, v197
	s_waitcnt lgkmcnt(0)
	v_mul_f32_e32 v33, 0x4b800000, v32
	v_cmp_gt_f32_e32 vcc, s56, v32
	v_or_b32_e32 v64, 48, v112
	v_ashrrev_i32_e32 v65, 31, v64
	v_cndmask_b32_e32 v32, v32, v33, vcc
	v_rsq_f32_e32 v32, v32
	v_lshlrev_b64 v[34:35], 11, v[64:65]
	v_lshl_add_u64 v[34:35], s[8:9], 0, v[34:35]
	v_mul_f32_e32 v33, 0x45800000, v32
	v_cndmask_b32_e32 v94, v32, v33, vcc
	v_lshlrev_b64 v[32:33], 12, v[64:65]
	v_lshl_add_u64 v[32:33], s[6:7], 0, v[32:33]
	v_lshl_add_u64 v[68:69], v[160:161], 2, v[32:33]
	v_lshl_add_u64 v[66:67], v[160:161], 1, v[34:35]
	global_load_dwordx4 v[44:47], v[68:69], off
	global_load_dwordx4 v[40:43], v[68:69], off offset:64
	global_load_dwordx4 v[36:39], v[68:69], off offset:512
	global_load_dwordx4 v[32:35], v[68:69], off offset:576
	global_load_dwordx2 v[76:77], v[66:67], off
	global_load_dwordx2 v[74:75], v[66:67], off offset:32
	global_load_dwordx2 v[72:73], v[66:67], off offset:256
	global_load_dwordx2 v[70:71], v[66:67], off offset:288
	v_lshl_add_u64 v[78:79], v[64:65], 2, s[14:15]
	global_load_dword v78, v[78:79], off
	v_pk_mul_f32 v[28:29], v[28:29], v[94:95] op_sel_hi:[1,0]
	v_lshlrev_b32_e32 v96, 16, v92
	v_mul_f32_e32 v28, 0xbfb8aa3b, v28
	v_exp_f32_e32 v79, v28
	v_mul_f32_e32 v28, 0xbfb8aa3b, v29
	v_exp_f32_e32 v95, v28
	v_and_b32_e32 v97, 0xffff0000, v92
	v_pk_mul_f32 v[28:29], v[30:31], v[94:95] op_sel_hi:[1,0]
	s_nop 0
	v_mul_f32_e32 v28, 0xbfb8aa3b, v28
	v_exp_f32_e32 v28, v28
	v_mul_f32_e32 v29, 0xbfb8aa3b, v29
	v_exp_f32_e32 v29, v29
	v_add_f32_e32 v30, 1.0, v79
	v_add_f32_e32 v31, 1.0, v95
	v_add_f32_e32 v28, 1.0, v28
	v_rcp_f32_e32 v30, v30
	v_rcp_f32_e32 v31, v31
	v_rcp_f32_e32 v98, v28
	v_add_f32_e32 v28, 1.0, v29
	v_rcp_f32_e32 v99, v28
	v_pk_fma_f32 v[28:29], v[30:31], v[96:97], v[60:61]
	v_lshlrev_b32_e32 v30, 16, v93
	v_and_b32_e32 v31, 0xffff0000, v93
	v_pk_fma_f32 v[30:31], v[98:99], v[30:31], v[62:63]
	v_pk_mul_f32 v[24:25], v[24:25], v[94:95] op_sel_hi:[1,0]
	v_pk_mul_f32 v[60:61], v[28:29], v[28:29]
	global_store_dwordx4 v[84:85], v[28:31], off
	v_mul_f32_e32 v24, 0xbfb8aa3b, v24
	v_pk_mul_f32 v[62:63], v[30:31], v[30:31]
	v_cvt_pk_bf16_f32 v28, v28, v29
	v_cvt_pk_bf16_f32 v29, v30, v31
	global_store_dwordx2 v[82:83], v[28:29], off
	v_exp_f32_e32 v28, v24
	v_mul_f32_e32 v24, 0xbfb8aa3b, v25
	v_exp_f32_e32 v29, v24
	v_pk_mul_f32 v[24:25], v[26:27], v[94:95] op_sel_hi:[1,0]
	v_add_f32_e32 v26, 1.0, v28
	v_mul_f32_e32 v24, 0xbfb8aa3b, v24
	v_exp_f32_e32 v24, v24
	v_mul_f32_e32 v25, 0xbfb8aa3b, v25
	v_exp_f32_e32 v25, v25
	v_add_f32_e32 v27, 1.0, v29
	v_add_f32_e32 v24, 1.0, v24
	v_rcp_f32_e32 v26, v26
	v_rcp_f32_e32 v27, v27
	v_rcp_f32_e32 v30, v24
	v_add_f32_e32 v24, 1.0, v25
	v_rcp_f32_e32 v31, v24
	v_lshlrev_b32_e32 v28, 16, v90
	v_and_b32_e32 v29, 0xffff0000, v90
	v_pk_fma_f32 v[24:25], v[26:27], v[28:29], v[56:57]
	v_lshlrev_b32_e32 v26, 16, v91
	v_and_b32_e32 v27, 0xffff0000, v91
	v_pk_fma_f32 v[26:27], v[30:31], v[26:27], v[58:59]
	v_pk_mul_f32 v[20:21], v[20:21], v[94:95] op_sel_hi:[1,0]
	v_pk_mul_f32 v[28:29], v[24:25], v[24:25]
	global_store_dwordx4 v[84:85], v[24:27], off offset:64
	v_mul_f32_e32 v20, 0xbfb8aa3b, v20
	v_pk_mul_f32 v[16:17], v[16:17], v[94:95] op_sel_hi:[1,0]
	v_cvt_pk_bf16_f32 v24, v24, v25
	v_cvt_pk_bf16_f32 v25, v26, v27
	global_store_dwordx2 v[82:83], v[24:25], off offset:32
	v_exp_f32_e32 v24, v20
	v_mul_f32_e32 v20, 0xbfb8aa3b, v21
	v_exp_f32_e32 v25, v20
	v_pk_mul_f32 v[20:21], v[22:23], v[94:95] op_sel_hi:[1,0]
	v_add_f32_e32 v22, 1.0, v24
	v_mul_f32_e32 v20, 0xbfb8aa3b, v20
	v_exp_f32_e32 v20, v20
	v_mul_f32_e32 v21, 0xbfb8aa3b, v21
	v_add_f32_e32 v23, 1.0, v25
	v_exp_f32_e32 v21, v21
	v_rcp_f32_e32 v22, v22
	v_rcp_f32_e32 v23, v23
	v_add_f32_e32 v20, 1.0, v20
	v_pk_mul_f32 v[30:31], v[26:27], v[26:27]
	v_lshlrev_b32_e32 v24, 16, v88
	v_and_b32_e32 v25, 0xffff0000, v88
	v_rcp_f32_e32 v26, v20
	v_add_f32_e32 v20, 1.0, v21
	v_mul_f32_e32 v16, 0xbfb8aa3b, v16
	v_rcp_f32_e32 v27, v20
	v_pk_fma_f32 v[20:21], v[22:23], v[24:25], v[52:53]
	v_exp_f32_e32 v24, v16
	v_mul_f32_e32 v16, 0xbfb8aa3b, v17
	v_exp_f32_e32 v25, v16
	v_pk_mul_f32 v[16:17], v[18:19], v[94:95] op_sel_hi:[1,0]
	v_add_f32_e32 v18, 1.0, v24
	v_mul_f32_e32 v16, 0xbfb8aa3b, v16
	v_mul_f32_e32 v17, 0xbfb8aa3b, v17
	v_exp_f32_e32 v16, v16
	v_exp_f32_e32 v17, v17
	v_add_f32_e32 v19, 1.0, v25
	v_rcp_f32_e32 v18, v18
	v_rcp_f32_e32 v19, v19
	v_add_f32_e32 v16, 1.0, v16
	v_add_f32_e32 v17, 1.0, v17
	v_rcp_f32_e32 v16, v16
	v_rcp_f32_e32 v17, v17
	v_lshlrev_b32_e32 v22, 16, v89
	v_and_b32_e32 v23, 0xffff0000, v89
	v_lshlrev_b32_e32 v24, 16, v86
	v_and_b32_e32 v25, 0xffff0000, v86
	v_add_f32_e32 v30, v30, v31
	v_add_f32_e32 v28, v28, v29
	v_pk_fma_f32 v[22:23], v[26:27], v[22:23], v[54:55]
	v_pk_fma_f32 v[24:25], v[18:19], v[24:25], v[48:49]
	v_lshlrev_b32_e32 v18, 16, v87
	v_and_b32_e32 v19, 0xffff0000, v87
	v_add_f32_e32 v28, v28, v30
	v_add_f32_e32 v29, v62, v63
	v_add_f32_e32 v30, v60, v61
	v_pk_mul_f32 v[52:53], v[20:21], v[20:21]
	v_pk_mul_f32 v[54:55], v[22:23], v[22:23]
	v_pk_fma_f32 v[26:27], v[16:17], v[18:19], v[50:51]
	v_add_f32_e32 v29, v30, v29
	v_pk_mul_f32 v[16:17], v[24:25], v[24:25]
	v_pk_mul_f32 v[18:19], v[26:27], v[26:27]
	v_add_f32_e32 v28, v29, v28
	v_add_f32_e32 v29, v54, v55
	v_add_f32_e32 v30, v52, v53
	v_add_f32_e32 v29, v30, v29
	v_add_f32_e32 v18, v18, v19
	v_add_f32_e32 v16, v16, v17
	v_add_f32_e32 v28, v29, v28
	v_add_f32_e32 v16, v16, v18
	v_add_f32_e32 v18, v16, v28
	ds_bpermute_b32 v19, v199, v18
	v_cvt_pk_bf16_f32 v16, v20, v21
	v_cvt_pk_bf16_f32 v17, v22, v23
	global_store_dwordx4 v[84:85], v[20:23], off offset:512
	global_store_dwordx2 v[82:83], v[16:17], off offset:256
	s_waitcnt lgkmcnt(0)
	v_add_f32_e32 v16, v18, v19
	ds_bpermute_b32 v17, v200, v16
	v_cvt_pk_bf16_f32 v18, v24, v25
	v_cvt_pk_bf16_f32 v19, v26, v27
	global_store_dwordx4 v[84:85], v[24:27], off offset:576
	global_store_dwordx2 v[82:83], v[18:19], off offset:288
	s_mov_b32 vcc_lo, 0x11111111
	s_mov_b32 vcc_hi, 0x11111111
	s_and_saveexec_b64 s[0:1], vcc
	s_cbranch_execz .LBB0_1324
	v_lshl_add_u64 v[18:19], v[80:81], 2, s[12:13]
	s_waitcnt lgkmcnt(0)
	v_add_f32_e32 v16, v16, v17
	global_atomic_add_f32 v[18:19], v16, off
.LBB0_1324:
	s_or_b64 exec, exec, s[0:1]
	s_waitcnt vmcnt(8)
	v_fmamk_f32 v16, v78, 0x3a800000, v197
	s_waitcnt lgkmcnt(0)
	v_mul_f32_e32 v17, 0x4b800000, v16
	v_cmp_gt_f32_e32 vcc, s56, v16
	v_and_b32_e32 v19, 0xffff0000, v76
	s_nop 0
	v_cndmask_b32_e32 v16, v16, v17, vcc
	v_rsq_f32_e32 v16, v16
	s_nop 0
	v_mul_f32_e32 v17, 0x45800000, v16
	v_cndmask_b32_e32 v16, v16, v17, vcc
	v_pk_mul_f32 v[12:13], v[12:13], v[16:17] op_sel_hi:[1,0]
	s_nop 0
	v_mul_f32_e32 v12, 0xbfb8aa3b, v12
	v_exp_f32_e32 v17, v12
	v_mul_f32_e32 v12, 0xbfb8aa3b, v13
	v_exp_f32_e32 v18, v12
	v_pk_mul_f32 v[12:13], v[14:15], v[16:17] op_sel_hi:[1,0]
	s_nop 0
	v_mul_f32_e32 v12, 0xbfb8aa3b, v12
	v_exp_f32_e32 v12, v12
	v_mul_f32_e32 v13, 0xbfb8aa3b, v13
	v_exp_f32_e32 v13, v13
	v_add_f32_e32 v14, 1.0, v17
	v_add_f32_e32 v15, 1.0, v18
	v_add_f32_e32 v12, 1.0, v12
	v_rcp_f32_e32 v14, v14
	v_rcp_f32_e32 v15, v15
	v_rcp_f32_e32 v20, v12
	v_add_f32_e32 v12, 1.0, v13
	v_rcp_f32_e32 v21, v12
	v_lshlrev_b32_e32 v18, 16, v76
	v_pk_fma_f32 v[12:13], v[14:15], v[18:19], v[44:45]
	v_lshlrev_b32_e32 v14, 16, v77
	v_and_b32_e32 v15, 0xffff0000, v77
	v_pk_fma_f32 v[14:15], v[20:21], v[14:15], v[46:47]
	v_pk_mul_f32 v[8:9], v[8:9], v[16:17] op_sel_hi:[1,0]
	v_pk_mul_f32 v[18:19], v[12:13], v[12:13]
	global_store_dwordx4 v[68:69], v[12:15], off
	v_mul_f32_e32 v8, 0xbfb8aa3b, v8
	v_pk_mul_f32 v[20:21], v[14:15], v[14:15]
	v_cvt_pk_bf16_f32 v12, v12, v13
	v_cvt_pk_bf16_f32 v13, v14, v15
	global_store_dwordx2 v[66:67], v[12:13], off
	v_exp_f32_e32 v12, v8
	v_mul_f32_e32 v8, 0xbfb8aa3b, v9
	v_exp_f32_e32 v13, v8
	v_pk_mul_f32 v[8:9], v[10:11], v[16:17] op_sel_hi:[1,0]
	v_add_f32_e32 v10, 1.0, v12
	v_mul_f32_e32 v8, 0xbfb8aa3b, v8
	v_exp_f32_e32 v8, v8
	v_mul_f32_e32 v9, 0xbfb8aa3b, v9
	v_exp_f32_e32 v9, v9
	v_add_f32_e32 v11, 1.0, v13
	v_add_f32_e32 v8, 1.0, v8
	v_rcp_f32_e32 v10, v10
	v_rcp_f32_e32 v11, v11
	v_rcp_f32_e32 v14, v8
	v_add_f32_e32 v8, 1.0, v9
	v_rcp_f32_e32 v15, v8
	v_lshlrev_b32_e32 v12, 16, v74
	v_and_b32_e32 v13, 0xffff0000, v74
	v_pk_fma_f32 v[8:9], v[10:11], v[12:13], v[40:41]
	v_lshlrev_b32_e32 v10, 16, v75
	v_and_b32_e32 v11, 0xffff0000, v75
	v_pk_fma_f32 v[10:11], v[14:15], v[10:11], v[42:43]
	v_pk_mul_f32 v[4:5], v[4:5], v[16:17] op_sel_hi:[1,0]
	v_pk_mul_f32 v[12:13], v[8:9], v[8:9]
	global_store_dwordx4 v[68:69], v[8:11], off offset:64
	v_mul_f32_e32 v4, 0xbfb8aa3b, v4
	v_pk_mul_f32 v[0:1], v[0:1], v[16:17] op_sel_hi:[1,0]
	v_cvt_pk_bf16_f32 v8, v8, v9
	v_cvt_pk_bf16_f32 v9, v10, v11
	global_store_dwordx2 v[66:67], v[8:9], off offset:32
	v_exp_f32_e32 v8, v4
	v_mul_f32_e32 v4, 0xbfb8aa3b, v5
	v_exp_f32_e32 v9, v4
	v_pk_mul_f32 v[4:5], v[6:7], v[16:17] op_sel_hi:[1,0]
	v_add_f32_e32 v6, 1.0, v8
	v_mul_f32_e32 v4, 0xbfb8aa3b, v4
	v_exp_f32_e32 v4, v4
	v_mul_f32_e32 v5, 0xbfb8aa3b, v5
	v_add_f32_e32 v7, 1.0, v9
	v_exp_f32_e32 v5, v5
	v_rcp_f32_e32 v6, v6
	v_rcp_f32_e32 v7, v7
	v_add_f32_e32 v4, 1.0, v4
	v_pk_mul_f32 v[14:15], v[10:11], v[10:11]
	v_lshlrev_b32_e32 v8, 16, v72
	v_and_b32_e32 v9, 0xffff0000, v72
	v_rcp_f32_e32 v10, v4
	v_add_f32_e32 v4, 1.0, v5
	v_mul_f32_e32 v0, 0xbfb8aa3b, v0
	v_rcp_f32_e32 v11, v4
	v_pk_fma_f32 v[4:5], v[6:7], v[8:9], v[36:37]
	v_exp_f32_e32 v8, v0
	v_mul_f32_e32 v0, 0xbfb8aa3b, v1
	v_exp_f32_e32 v9, v0
	v_pk_mul_f32 v[0:1], v[2:3], v[16:17] op_sel_hi:[1,0]
	v_add_f32_e32 v2, 1.0, v8
	v_mul_f32_e32 v0, 0xbfb8aa3b, v0
	v_mul_f32_e32 v1, 0xbfb8aa3b, v1
	v_exp_f32_e32 v0, v0
	v_exp_f32_e32 v1, v1
	v_add_f32_e32 v3, 1.0, v9
	v_rcp_f32_e32 v2, v2
	v_rcp_f32_e32 v3, v3
	v_add_f32_e32 v0, 1.0, v0
	v_add_f32_e32 v1, 1.0, v1
	v_rcp_f32_e32 v0, v0
	v_rcp_f32_e32 v1, v1
	v_lshlrev_b32_e32 v6, 16, v73
	v_and_b32_e32 v7, 0xffff0000, v73
	v_lshlrev_b32_e32 v8, 16, v70
	v_and_b32_e32 v9, 0xffff0000, v70
	v_add_f32_e32 v14, v14, v15
	v_add_f32_e32 v12, v12, v13
	v_pk_fma_f32 v[6:7], v[10:11], v[6:7], v[38:39]
	v_pk_fma_f32 v[8:9], v[2:3], v[8:9], v[32:33]
	v_lshlrev_b32_e32 v2, 16, v71
	v_and_b32_e32 v3, 0xffff0000, v71
	v_add_f32_e32 v12, v12, v14
	v_add_f32_e32 v13, v20, v21
	v_add_f32_e32 v14, v18, v19
	v_pk_mul_f32 v[22:23], v[4:5], v[4:5]
	v_pk_mul_f32 v[24:25], v[6:7], v[6:7]
	v_pk_fma_f32 v[10:11], v[0:1], v[2:3], v[34:35]
	v_add_f32_e32 v13, v14, v13
	v_pk_mul_f32 v[0:1], v[8:9], v[8:9]
	v_pk_mul_f32 v[2:3], v[10:11], v[10:11]
	v_add_f32_e32 v12, v13, v12
	v_add_f32_e32 v13, v24, v25
	v_add_f32_e32 v14, v22, v23
	v_add_f32_e32 v13, v14, v13
	v_add_f32_e32 v2, v2, v3
	v_add_f32_e32 v0, v0, v1
	v_add_f32_e32 v12, v13, v12
	v_add_f32_e32 v0, v0, v2
	v_add_f32_e32 v2, v0, v12
	ds_bpermute_b32 v3, v199, v2
	v_cvt_pk_bf16_f32 v0, v4, v5
	v_cvt_pk_bf16_f32 v1, v6, v7
	global_store_dwordx4 v[68:69], v[4:7], off offset:512
	global_store_dwordx2 v[66:67], v[0:1], off offset:256
	s_waitcnt lgkmcnt(0)
	v_add_f32_e32 v0, v2, v3
	ds_bpermute_b32 v1, v200, v0
	v_cvt_pk_bf16_f32 v2, v8, v9
	v_cvt_pk_bf16_f32 v3, v10, v11
	global_store_dwordx4 v[68:69], v[8:11], off offset:576
	global_store_dwordx2 v[66:67], v[2:3], off offset:288
	s_mov_b32 vcc_lo, 0x11111111
	s_mov_b32 vcc_hi, 0x11111111
	s_and_saveexec_b64 s[0:1], vcc
	s_cbranch_execz .LBB0_1326
	v_lshl_add_u64 v[2:3], v[64:65], 2, s[12:13]
	s_waitcnt lgkmcnt(0)
	v_add_f32_e32 v0, v0, v1
	global_atomic_add_f32 v[2:3], v0, off

.LBB0_1497:
	ds_read_b128 v[128:131], v171
	ds_read_b128 v[132:135], v171 offset:1024
	ds_read_b128 v[136:139], v171 offset:2048
	ds_read_b128 v[140:143], v171 offset:3072
	ds_read_b128 v[156:159], v172
	ds_read_b128 v[160:163], v172 offset:1024
	ds_read_b128 v[164:167], v172 offset:2048
	ds_read_b128 v[176:179], v172 offset:3072
	s_add_u32 s26, s24, 0x100
	s_addc_u32 s27, s25, 0
	s_cmp_eq_u32 s55, 40
	s_cselect_b32 s31, s7, s27
	s_cselect_b32 s30, s6, s26
	s_cselect_b32 s29, s23, s54
	s_cselect_b32 s28, s22, s53
	v_lshl_add_u64 v[188:189], s[24:25], 0, v[150:151]
	s_add_i32 m0, s36, 0xc000
	ds_read_b128 v[180:183], v173
	ds_read_b128 v[184:187], v173 offset:1024
	ds_read_b128 v[192:195], v173 offset:2048
	ds_read_b128 v[196:199], v173 offset:3072
	ds_read_b128 v[200:203], v173 offset:4096
	ds_read_b128 v[204:207], v173 offset:5120
	ds_read_b128 v[208:211], v173 offset:6144
	ds_read_b128 v[212:215], v173 offset:7168
	global_load_lds_dwordx4 v[188:189], off
	v_lshl_add_u64 v[188:189], s[24:25], 0, v[148:149]
	s_add_i32 m0, s36, 0xe000
	s_nop 0
	global_load_lds_dwordx4 v[188:189], off
	s_waitcnt vmcnt(8)
	s_waitcnt lgkmcnt(0)
	s_barrier
	s_setprio 1
	s_waitcnt lgkmcnt(0)
	v_mfma_f32_16x16x32_bf16 v[124:127], v[128:131], v[180:183], v[124:127]
	v_mfma_f32_16x16x32_bf16 v[120:123], v[136:139], v[180:183], v[120:123]
	v_mfma_f32_16x16x32_bf16 v[108:111], v[128:131], v[192:195], v[108:111]
	v_mfma_f32_16x16x32_bf16 v[104:107], v[136:139], v[192:195], v[104:107]
	v_mfma_f32_16x16x32_bf16 v[92:95], v[128:131], v[200:203], v[92:95]
	v_mfma_f32_16x16x32_bf16 v[88:91], v[136:139], v[200:203], v[88:91]
	v_mfma_f32_16x16x32_bf16 v[76:79], v[128:131], v[208:211], v[76:79]
	v_mfma_f32_16x16x32_bf16 v[72:75], v[136:139], v[208:211], v[72:75]
	v_mfma_f32_16x16x32_bf16 v[124:127], v[132:135], v[184:187], v[124:127]
	v_mfma_f32_16x16x32_bf16 v[120:123], v[140:143], v[184:187], v[120:123]
	v_mfma_f32_16x16x32_bf16 v[108:111], v[132:135], v[196:199], v[108:111]
	v_mfma_f32_16x16x32_bf16 v[104:107], v[140:143], v[196:199], v[104:107]
	v_mfma_f32_16x16x32_bf16 v[92:95], v[132:135], v[204:207], v[92:95]
	v_mfma_f32_16x16x32_bf16 v[88:91], v[140:143], v[204:207], v[88:91]
	v_mfma_f32_16x16x32_bf16 v[76:79], v[132:135], v[212:215], v[76:79]
	v_mfma_f32_16x16x32_bf16 v[72:75], v[140:143], v[212:215], v[72:75]
	s_setprio 0
	s_setprio 1
	v_mfma_f32_16x16x32_bf16 v[116:119], v[156:159], v[180:183], v[116:119]
	v_mfma_f32_16x16x32_bf16 v[112:115], v[164:167], v[180:183], v[112:115]
	v_mfma_f32_16x16x32_bf16 v[100:103], v[156:159], v[192:195], v[100:103]
	v_mfma_f32_16x16x32_bf16 v[96:99], v[164:167], v[192:195], v[96:99]
	v_mfma_f32_16x16x32_bf16 v[84:87], v[156:159], v[200:203], v[84:87]
	v_mfma_f32_16x16x32_bf16 v[80:83], v[164:167], v[200:203], v[80:83]
	v_mfma_f32_16x16x32_bf16 v[68:71], v[156:159], v[208:211], v[68:71]
	v_mfma_f32_16x16x32_bf16 v[64:67], v[164:167], v[208:211], v[64:67]
	v_mfma_f32_16x16x32_bf16 v[116:119], v[160:163], v[184:187], v[116:119]
	v_mfma_f32_16x16x32_bf16 v[112:115], v[176:179], v[184:187], v[112:115]
	v_mfma_f32_16x16x32_bf16 v[100:103], v[160:163], v[196:199], v[100:103]
	v_mfma_f32_16x16x32_bf16 v[96:99], v[176:179], v[196:199], v[96:99]
	v_mfma_f32_16x16x32_bf16 v[84:87], v[160:163], v[204:207], v[84:87]
	v_mfma_f32_16x16x32_bf16 v[80:83], v[176:179], v[204:207], v[80:83]
	v_mfma_f32_16x16x32_bf16 v[68:71], v[160:163], v[212:215], v[68:71]
	v_mfma_f32_16x16x32_bf16 v[64:67], v[176:179], v[212:215], v[64:67]
	s_setprio 0
	s_barrier
	s_add_i32 s24, s47, s35
	v_lshl_add_u64 v[188:189], s[28:29], 0, v[144:145]
	s_mov_b32 m0, s24
	ds_read_b128 v[180:183], v173 offset:16384
	ds_read_b128 v[184:187], v173 offset:17408
	ds_read_b128 v[192:195], v173 offset:18432
	ds_read_b128 v[196:199], v173 offset:19456
	ds_read_b128 v[200:203], v173 offset:20480
	ds_read_b128 v[204:207], v173 offset:21504
	ds_read_b128 v[208:211], v173 offset:22528
	ds_read_b128 v[212:215], v173 offset:23552
	global_load_lds_dwordx4 v[188:189], off
	s_add_i32 m0, s24, 0x2000
	s_add_u32 s24, s28, 0xb0000
	v_lshl_add_u64 v[216:217], s[28:29], 0, v[146:147]
	s_addc_u32 s25, s29, 0
	s_add_i32 s56, s48, s35
	global_load_lds_dwordx4 v[216:217], off
	v_lshl_add_u64 v[218:219], s[24:25], 0, v[144:145]
	s_mov_b32 m0, s56
	v_lshl_add_u64 v[220:221], s[30:31], 0, v[146:147]
	global_load_lds_dwordx4 v[218:219], off
	v_lshl_add_u64 v[218:219], s[24:25], 0, v[146:147]
	s_add_i32 m0, s56, 0x2000
	s_nop 0
	global_load_lds_dwordx4 v[218:219], off
	v_lshl_add_u64 v[218:219], s[30:31], 0, v[144:145]
	s_mov_b32 m0, s36
	s_nop 0
	global_load_lds_dwordx4 v[218:219], off
	s_mov_b32 m0, s37
	s_nop 0
	global_load_lds_dwordx4 v[220:221], off
	s_waitcnt vmcnt(8)
	s_waitcnt lgkmcnt(0)
	s_barrier
	s_setprio 1
	s_waitcnt lgkmcnt(0)
	v_mfma_f32_16x16x32_bf16 v[60:63], v[128:131], v[180:183], v[60:63]
	v_mfma_f32_16x16x32_bf16 v[56:59], v[136:139], v[180:183], v[56:59]
	v_mfma_f32_16x16x32_bf16 v[44:47], v[128:131], v[192:195], v[44:47]
	v_mfma_f32_16x16x32_bf16 v[40:43], v[136:139], v[192:195], v[40:43]
	v_mfma_f32_16x16x32_bf16 v[28:31], v[128:131], v[200:203], v[28:31]
	v_mfma_f32_16x16x32_bf16 v[24:27], v[136:139], v[200:203], v[24:27]
	v_mfma_f32_16x16x32_bf16 v[12:15], v[128:131], v[208:211], v[12:15]
	v_mfma_f32_16x16x32_bf16 v[8:11], v[136:139], v[208:211], v[8:11]
	v_mfma_f32_16x16x32_bf16 v[60:63], v[132:135], v[184:187], v[60:63]
	v_mfma_f32_16x16x32_bf16 v[56:59], v[140:143], v[184:187], v[56:59]
	v_mfma_f32_16x16x32_bf16 v[44:47], v[132:135], v[196:199], v[44:47]
	v_mfma_f32_16x16x32_bf16 v[40:43], v[140:143], v[196:199], v[40:43]
	v_mfma_f32_16x16x32_bf16 v[28:31], v[132:135], v[204:207], v[28:31]
	v_mfma_f32_16x16x32_bf16 v[24:27], v[140:143], v[204:207], v[24:27]
	v_mfma_f32_16x16x32_bf16 v[12:15], v[132:135], v[212:215], v[12:15]
	v_mfma_f32_16x16x32_bf16 v[8:11], v[140:143], v[212:215], v[8:11]
	s_setprio 0
	s_setprio 1
	v_mfma_f32_16x16x32_bf16 v[52:55], v[156:159], v[180:183], v[52:55]
	v_mfma_f32_16x16x32_bf16 v[48:51], v[164:167], v[180:183], v[48:51]
	v_mfma_f32_16x16x32_bf16 v[36:39], v[156:159], v[192:195], v[36:39]
	v_mfma_f32_16x16x32_bf16 v[32:35], v[164:167], v[192:195], v[32:35]
	v_mfma_f32_16x16x32_bf16 v[20:23], v[156:159], v[200:203], v[20:23]
	v_mfma_f32_16x16x32_bf16 v[16:19], v[164:167], v[200:203], v[16:19]
	v_mfma_f32_16x16x32_bf16 v[4:7], v[156:159], v[208:211], v[4:7]
	v_mfma_f32_16x16x32_bf16 v[0:3], v[164:167], v[208:211], v[0:3]
	v_mfma_f32_16x16x32_bf16 v[52:55], v[160:163], v[184:187], v[52:55]
	v_mfma_f32_16x16x32_bf16 v[48:51], v[176:179], v[184:187], v[48:51]
	v_mfma_f32_16x16x32_bf16 v[36:39], v[160:163], v[196:199], v[36:39]
	v_mfma_f32_16x16x32_bf16 v[32:35], v[176:179], v[196:199], v[32:35]
	v_mfma_f32_16x16x32_bf16 v[20:23], v[160:163], v[204:207], v[20:23]
	v_mfma_f32_16x16x32_bf16 v[16:19], v[176:179], v[204:207], v[16:19]
	v_mfma_f32_16x16x32_bf16 v[4:7], v[160:163], v[212:215], v[4:7]
	v_mfma_f32_16x16x32_bf16 v[0:3], v[176:179], v[212:215], v[0:3]
	s_setprio 0
	s_barrier
	s_add_i32 s56, 0, 0x18000
	s_add_i32 s57, 0, 0x1c000
	v_add_u32_e32 v140, s56, v169
	v_add_u32_e32 v175, s57, v169
	ds_read_b128 v[128:131], v140
	ds_read_b128 v[132:135], v140 offset:1024
	ds_read_b128 v[136:139], v140 offset:2048
	ds_read_b128 v[140:143], v140 offset:3072
	ds_read_b128 v[156:159], v175
	ds_read_b128 v[160:163], v175 offset:1024
	ds_read_b128 v[164:167], v175 offset:2048
	ds_read_b128 v[176:179], v175 offset:3072
	s_add_u32 s24, s30, 0xb0000
	s_addc_u32 s25, s31, 0
	s_mov_b32 m0, s38
	v_lshl_add_u64 v[222:223], s[24:25], 0, v[144:145]
	ds_read_b128 v[180:183], v173 offset:32768
	ds_read_b128 v[184:187], v173 offset:33792
	ds_read_b128 v[192:195], v173 offset:34816
	ds_read_b128 v[196:199], v173 offset:35840
	ds_read_b128 v[200:203], v173 offset:36864
	ds_read_b128 v[204:207], v173 offset:37888
	ds_read_b128 v[208:211], v173 offset:38912
	ds_read_b128 v[212:215], v173 offset:39936
	global_load_lds_dwordx4 v[222:223], off
	v_lshl_add_u64 v[222:223], s[24:25], 0, v[146:147]
	s_mov_b32 m0, s39
	s_nop 0
	global_load_lds_dwordx4 v[222:223], off
	s_waitcnt vmcnt(8)
	s_waitcnt lgkmcnt(0)
	s_barrier
	s_setprio 1
	s_waitcnt lgkmcnt(0)
	v_mfma_f32_16x16x32_bf16 v[124:127], v[128:131], v[180:183], v[124:127]
	v_mfma_f32_16x16x32_bf16 v[120:123], v[136:139], v[180:183], v[120:123]
	v_mfma_f32_16x16x32_bf16 v[108:111], v[128:131], v[192:195], v[108:111]
	v_mfma_f32_16x16x32_bf16 v[104:107], v[136:139], v[192:195], v[104:107]
	v_mfma_f32_16x16x32_bf16 v[92:95], v[128:131], v[200:203], v[92:95]
	v_mfma_f32_16x16x32_bf16 v[88:91], v[136:139], v[200:203], v[88:91]
	v_mfma_f32_16x16x32_bf16 v[76:79], v[128:131], v[208:211], v[76:79]
	v_mfma_f32_16x16x32_bf16 v[72:75], v[136:139], v[208:211], v[72:75]
	v_mfma_f32_16x16x32_bf16 v[124:127], v[132:135], v[184:187], v[124:127]
	v_mfma_f32_16x16x32_bf16 v[120:123], v[140:143], v[184:187], v[120:123]
	v_mfma_f32_16x16x32_bf16 v[108:111], v[132:135], v[196:199], v[108:111]
	v_mfma_f32_16x16x32_bf16 v[104:107], v[140:143], v[196:199], v[104:107]
	v_mfma_f32_16x16x32_bf16 v[92:95], v[132:135], v[204:207], v[92:95]
	v_mfma_f32_16x16x32_bf16 v[88:91], v[140:143], v[204:207], v[88:91]
	v_mfma_f32_16x16x32_bf16 v[76:79], v[132:135], v[212:215], v[76:79]
	v_mfma_f32_16x16x32_bf16 v[72:75], v[140:143], v[212:215], v[72:75]
	s_setprio 0
	s_setprio 1
	v_mfma_f32_16x16x32_bf16 v[116:119], v[156:159], v[180:183], v[116:119]
	v_mfma_f32_16x16x32_bf16 v[112:115], v[164:167], v[180:183], v[112:115]
	v_mfma_f32_16x16x32_bf16 v[100:103], v[156:159], v[192:195], v[100:103]
	v_mfma_f32_16x16x32_bf16 v[96:99], v[164:167], v[192:195], v[96:99]
	v_mfma_f32_16x16x32_bf16 v[84:87], v[156:159], v[200:203], v[84:87]
	v_mfma_f32_16x16x32_bf16 v[80:83], v[164:167], v[200:203], v[80:83]
	v_mfma_f32_16x16x32_bf16 v[68:71], v[156:159], v[208:211], v[68:71]
	v_mfma_f32_16x16x32_bf16 v[64:67], v[164:167], v[208:211], v[64:67]
	v_mfma_f32_16x16x32_bf16 v[116:119], v[160:163], v[184:187], v[116:119]
	v_mfma_f32_16x16x32_bf16 v[112:115], v[176:179], v[184:187], v[112:115]
	v_mfma_f32_16x16x32_bf16 v[100:103], v[160:163], v[196:199], v[100:103]
	v_mfma_f32_16x16x32_bf16 v[96:99], v[176:179], v[196:199], v[96:99]
	v_mfma_f32_16x16x32_bf16 v[84:87], v[160:163], v[204:207], v[84:87]
	v_mfma_f32_16x16x32_bf16 v[80:83], v[176:179], v[204:207], v[80:83]
	v_mfma_f32_16x16x32_bf16 v[68:71], v[160:163], v[212:215], v[68:71]
	v_mfma_f32_16x16x32_bf16 v[64:67], v[176:179], v[212:215], v[64:67]
	s_setprio 0
	s_barrier
	s_add_i32 s24, s56, s35
	v_lshl_add_u64 v[188:189], v[188:189], 0, s[18:19]
	s_mov_b32 m0, s24
	ds_read_b128 v[180:183], v173 offset:49152
	ds_read_b128 v[184:187], v173 offset:50176
	ds_read_b128 v[192:195], v173 offset:51200
	ds_read_b128 v[196:199], v173 offset:52224
	ds_read_b128 v[200:203], v173 offset:53248
	ds_read_b128 v[204:207], v173 offset:54272
	ds_read_b128 v[208:211], v173 offset:55296
	ds_read_b128 v[212:215], v173 offset:56320
	global_load_lds_dwordx4 v[188:189], off
	s_add_i32 m0, s24, 0x2000
	s_add_u32 s24, s28, 0xb0080
	v_lshl_add_u64 v[188:189], v[216:217], 0, s[18:19]
	s_addc_u32 s25, s29, 0
	s_add_i32 s28, s57, s35
	global_load_lds_dwordx4 v[188:189], off
	v_lshl_add_u64 v[188:189], s[24:25], 0, v[144:145]
	s_mov_b32 m0, s28
	s_nop 0
	global_load_lds_dwordx4 v[188:189], off
	v_lshl_add_u64 v[188:189], s[24:25], 0, v[146:147]
	s_add_i32 m0, s28, 0x2000
	s_nop 0
	global_load_lds_dwordx4 v[188:189], off
	v_lshl_add_u64 v[188:189], v[218:219], 0, s[18:19]
	s_mov_b32 m0, s41
	s_nop 0
	global_load_lds_dwordx4 v[188:189], off
	v_lshl_add_u64 v[188:189], v[220:221], 0, s[18:19]
	s_mov_b32 m0, s42
	s_nop 0
	global_load_lds_dwordx4 v[188:189], off
	s_waitcnt vmcnt(8)
	s_waitcnt lgkmcnt(0)
	s_barrier
	s_setprio 1
	s_waitcnt lgkmcnt(0)
	v_mfma_f32_16x16x32_bf16 v[60:63], v[128:131], v[180:183], v[60:63]
	v_mfma_f32_16x16x32_bf16 v[56:59], v[136:139], v[180:183], v[56:59]
	v_mfma_f32_16x16x32_bf16 v[44:47], v[128:131], v[192:195], v[44:47]
	v_mfma_f32_16x16x32_bf16 v[40:43], v[136:139], v[192:195], v[40:43]
	v_mfma_f32_16x16x32_bf16 v[28:31], v[128:131], v[200:203], v[28:31]
	v_mfma_f32_16x16x32_bf16 v[24:27], v[136:139], v[200:203], v[24:27]
	v_mfma_f32_16x16x32_bf16 v[12:15], v[128:131], v[208:211], v[12:15]
	v_mfma_f32_16x16x32_bf16 v[8:11], v[136:139], v[208:211], v[8:11]
	v_mfma_f32_16x16x32_bf16 v[60:63], v[132:135], v[184:187], v[60:63]
	v_mfma_f32_16x16x32_bf16 v[56:59], v[140:143], v[184:187], v[56:59]
	v_mfma_f32_16x16x32_bf16 v[44:47], v[132:135], v[196:199], v[44:47]
	v_mfma_f32_16x16x32_bf16 v[40:43], v[140:143], v[196:199], v[40:43]
	v_mfma_f32_16x16x32_bf16 v[28:31], v[132:135], v[204:207], v[28:31]
	v_mfma_f32_16x16x32_bf16 v[24:27], v[140:143], v[204:207], v[24:27]
	v_mfma_f32_16x16x32_bf16 v[12:15], v[132:135], v[212:215], v[12:15]
	v_mfma_f32_16x16x32_bf16 v[8:11], v[140:143], v[212:215], v[8:11]
	s_setprio 0
	s_setprio 1
	v_mfma_f32_16x16x32_bf16 v[52:55], v[156:159], v[180:183], v[52:55]
	v_mfma_f32_16x16x32_bf16 v[48:51], v[164:167], v[180:183], v[48:51]
	v_mfma_f32_16x16x32_bf16 v[36:39], v[156:159], v[192:195], v[36:39]
	v_mfma_f32_16x16x32_bf16 v[32:35], v[164:167], v[192:195], v[32:35]
	v_mfma_f32_16x16x32_bf16 v[20:23], v[156:159], v[200:203], v[20:23]
	v_mfma_f32_16x16x32_bf16 v[16:19], v[164:167], v[200:203], v[16:19]
	v_mfma_f32_16x16x32_bf16 v[4:7], v[156:159], v[208:211], v[4:7]
	v_mfma_f32_16x16x32_bf16 v[0:3], v[164:167], v[208:211], v[0:3]
	v_mfma_f32_16x16x32_bf16 v[52:55], v[160:163], v[184:187], v[52:55]
	v_mfma_f32_16x16x32_bf16 v[48:51], v[176:179], v[184:187], v[48:51]
	v_mfma_f32_16x16x32_bf16 v[36:39], v[160:163], v[196:199], v[36:39]
	v_mfma_f32_16x16x32_bf16 v[32:35], v[176:179], v[196:199], v[32:35]
	v_mfma_f32_16x16x32_bf16 v[20:23], v[160:163], v[204:207], v[20:23]
	v_mfma_f32_16x16x32_bf16 v[16:19], v[176:179], v[204:207], v[16:19]
	v_mfma_f32_16x16x32_bf16 v[4:7], v[160:163], v[212:215], v[4:7]
	v_mfma_f32_16x16x32_bf16 v[0:3], v[176:179], v[212:215], v[0:3]
	s_setprio 0
	s_barrier
	s_add_i32 s55, s55, 2
	s_add_u32 s53, s53, 0x100
	s_addc_u32 s54, s54, 0
	s_cmp_gt_u32 s55, 41
	s_mov_b64 s[24:25], s[26:27]
	s_cbranch_scc0 .LBB0_1497
	v_mbcnt_lo_u32_b32 v235, -1, 0
	v_mbcnt_hi_u32_b32 v235, -1, v235
	v_lshrrev_b32_e32 v236, 2, v235
	v_and_b32_e32 v237, 3, v235
	v_lshl_add_u32 v232, v237, 4, v236
	v_lshlrev_b32_e32 v232, 2, v232
	v_and_b32_e32 v233, -16, v168
	v_or_b32_e32 v233, v233, v236
	v_lshlrev_b32_e32 v237, 2, v237
	v_and_b32_e32 v234, -13, v170
	v_or_b32_e32 v234, v234, v237
	ds_bpermute_b32 v127, v232, v127
	ds_bpermute_b32 v126, v232, v126
	ds_bpermute_b32 v125, v232, v125
	ds_bpermute_b32 v124, v232, v124
	ds_bpermute_b32 v123, v232, v123
	ds_bpermute_b32 v122, v232, v122
	ds_bpermute_b32 v121, v232, v121
	ds_bpermute_b32 v120, v232, v120
	ds_bpermute_b32 v119, v232, v119
	ds_bpermute_b32 v118, v232, v118
	ds_bpermute_b32 v117, v232, v117
	ds_bpermute_b32 v116, v232, v116
	ds_bpermute_b32 v115, v232, v115
	ds_bpermute_b32 v114, v232, v114
	ds_bpermute_b32 v113, v232, v113
	ds_bpermute_b32 v112, v232, v112
	ds_bpermute_b32 v111, v232, v111
	ds_bpermute_b32 v110, v232, v110
	ds_bpermute_b32 v109, v232, v109
	ds_bpermute_b32 v108, v232, v108
	ds_bpermute_b32 v107, v232, v107
	ds_bpermute_b32 v106, v232, v106
	ds_bpermute_b32 v105, v232, v105
	ds_bpermute_b32 v104, v232, v104
	ds_bpermute_b32 v103, v232, v103
	ds_bpermute_b32 v102, v232, v102
	ds_bpermute_b32 v101, v232, v101
	ds_bpermute_b32 v100, v232, v100
	ds_bpermute_b32 v99, v232, v99
	ds_bpermute_b32 v98, v232, v98
	ds_bpermute_b32 v97, v232, v97
	ds_bpermute_b32 v96, v232, v96
	ds_bpermute_b32 v95, v232, v95
	ds_bpermute_b32 v94, v232, v94
	ds_bpermute_b32 v93, v232, v93
	ds_bpermute_b32 v92, v232, v92
	ds_bpermute_b32 v91, v232, v91
	ds_bpermute_b32 v90, v232, v90
	ds_bpermute_b32 v89, v232, v89
	ds_bpermute_b32 v88, v232, v88
	ds_bpermute_b32 v87, v232, v87
	ds_bpermute_b32 v86, v232, v86
	ds_bpermute_b32 v85, v232, v85
	ds_bpermute_b32 v84, v232, v84
	ds_bpermute_b32 v83, v232, v83
	ds_bpermute_b32 v82, v232, v82
	ds_bpermute_b32 v81, v232, v81
	ds_bpermute_b32 v80, v232, v80
	ds_bpermute_b32 v79, v232, v79
	ds_bpermute_b32 v78, v232, v78
	ds_bpermute_b32 v77, v232, v77
	ds_bpermute_b32 v76, v232, v76
	ds_bpermute_b32 v75, v232, v75
	ds_bpermute_b32 v74, v232, v74
	ds_bpermute_b32 v73, v232, v73
	ds_bpermute_b32 v72, v232, v72
	ds_bpermute_b32 v71, v232, v71
	ds_bpermute_b32 v70, v232, v70
	ds_bpermute_b32 v69, v232, v69
	ds_bpermute_b32 v68, v232, v68
	ds_bpermute_b32 v67, v232, v67
	ds_bpermute_b32 v66, v232, v66
	ds_bpermute_b32 v65, v232, v65
	ds_bpermute_b32 v64, v232, v64
	ds_bpermute_b32 v63, v232, v63
	ds_bpermute_b32 v62, v232, v62
	ds_bpermute_b32 v61, v232, v61
	ds_bpermute_b32 v60, v232, v60
	ds_bpermute_b32 v59, v232, v59
	ds_bpermute_b32 v58, v232, v58
	ds_bpermute_b32 v57, v232, v57
	ds_bpermute_b32 v56, v232, v56
	ds_bpermute_b32 v55, v232, v55
	ds_bpermute_b32 v54, v232, v54
	ds_bpermute_b32 v53, v232, v53
	ds_bpermute_b32 v52, v232, v52
	ds_bpermute_b32 v51, v232, v51
	ds_bpermute_b32 v50, v232, v50
	ds_bpermute_b32 v49, v232, v49
	ds_bpermute_b32 v48, v232, v48
	ds_bpermute_b32 v47, v232, v47
	ds_bpermute_b32 v46, v232, v46
	ds_bpermute_b32 v45, v232, v45
	ds_bpermute_b32 v44, v232, v44
	ds_bpermute_b32 v43, v232, v43
	ds_bpermute_b32 v42, v232, v42
	ds_bpermute_b32 v41, v232, v41
	ds_bpermute_b32 v40, v232, v40
	ds_bpermute_b32 v39, v232, v39
	ds_bpermute_b32 v38, v232, v38
	ds_bpermute_b32 v37, v232, v37
	ds_bpermute_b32 v36, v232, v36
	ds_bpermute_b32 v35, v232, v35
	ds_bpermute_b32 v34, v232, v34
	ds_bpermute_b32 v33, v232, v33
	ds_bpermute_b32 v32, v232, v32
	ds_bpermute_b32 v31, v232, v31
	ds_bpermute_b32 v30, v232, v30
	ds_bpermute_b32 v29, v232, v29
	ds_bpermute_b32 v28, v232, v28
	ds_bpermute_b32 v27, v232, v27
	ds_bpermute_b32 v26, v232, v26
	ds_bpermute_b32 v25, v232, v25
	ds_bpermute_b32 v24, v232, v24
	ds_bpermute_b32 v23, v232, v23
	ds_bpermute_b32 v22, v232, v22
	ds_bpermute_b32 v21, v232, v21
	ds_bpermute_b32 v20, v232, v20
	ds_bpermute_b32 v19, v232, v19
	ds_bpermute_b32 v18, v232, v18
	ds_bpermute_b32 v17, v232, v17
	ds_bpermute_b32 v16, v232, v16
	ds_bpermute_b32 v15, v232, v15
	ds_bpermute_b32 v14, v232, v14
	ds_bpermute_b32 v13, v232, v13
	ds_bpermute_b32 v12, v232, v12
	ds_bpermute_b32 v11, v232, v11
	ds_bpermute_b32 v10, v232, v10
	ds_bpermute_b32 v9, v232, v9
	ds_bpermute_b32 v8, v232, v8
	ds_bpermute_b32 v7, v232, v7
	ds_bpermute_b32 v6, v232, v6
	ds_bpermute_b32 v5, v232, v5
	ds_bpermute_b32 v4, v232, v4
	ds_bpermute_b32 v3, v232, v3
	ds_bpermute_b32 v2, v232, v2
	ds_bpermute_b32 v1, v232, v1
	ds_bpermute_b32 v0, v232, v0
	s_waitcnt lgkmcnt(0)
	v_lshl_add_u32 v158, s52, 8, v233
	v_lshl_or_b32 v156, s51, 8, v234
	v_ashrrev_i32_e32 v159, 31, v158
	v_lshlrev_b64 v[128:129], 12, v[158:159]
	v_ashrrev_i32_e32 v157, 31, v156
	v_lshl_add_u64 v[128:129], s[10:11], 0, v[128:129]
	v_lshlrev_b64 v[130:131], 2, v[156:157]
	v_lshl_add_u64 v[188:189], v[128:129], 0, v[130:131]
	global_load_dwordx4 v[164:167], v[188:189], off
	global_load_dwordx4 v[176:179], v[188:189], off offset:64
	global_load_dwordx4 v[180:183], v[188:189], off offset:512
	global_load_dwordx4 v[184:187], v[188:189], off offset:576
	v_or_b32_e32 v160, 16, v158
	v_ashrrev_i32_e32 v161, 31, v160
	v_lshlrev_b64 v[128:129], 12, v[160:161]
	v_lshl_add_u64 v[128:129], s[10:11], 0, v[128:129]
	v_lshl_add_u64 v[162:163], v[128:129], 0, v[130:131]
	global_load_dwordx4 v[140:143], v[162:163], off
	global_load_dwordx4 v[136:139], v[162:163], off offset:64
	global_load_dwordx4 v[132:135], v[162:163], off offset:512
	global_load_dwordx4 v[128:131], v[162:163], off offset:576
	v_lshlrev_b64 v[192:193], 11, v[158:159]
	v_lshl_add_u64 v[192:193], s[14:15], 0, v[192:193]
	v_and_b32_e32 v191, 64, v174
	v_lshl_add_u64 v[192:193], v[156:157], 1, v[192:193]
	v_xor_b32_e32 v175, 1, v174
	v_add_u32_e32 v191, 64, v191
	v_cmp_lt_i32_e32 vcc, v175, v191
	v_xor_b32_e32 v194, 2, v174
	s_waitcnt lgkmcnt(0)
	s_cmp_eq_u64 s[20:21], 0
	s_cbranch_scc1 .LBB0_1500
	s_barrier
.LBB0_1500:
	s_waitcnt vmcnt(7)
	v_pk_fma_f32 v[126:127], v[126:127], 0.5, v[166:167] op_sel_hi:[1,0,1]
	v_pk_fma_f32 v[124:125], v[124:125], 0.5, v[164:165] op_sel_hi:[1,0,1]
	s_waitcnt vmcnt(6)
	v_pk_fma_f32 v[122:123], v[122:123], 0.5, v[178:179] op_sel_hi:[1,0,1]
	v_pk_fma_f32 v[120:121], v[120:121], 0.5, v[176:177] op_sel_hi:[1,0,1]
	s_waitcnt vmcnt(5)
	v_pk_fma_f32 v[118:119], v[118:119], 0.5, v[182:183] op_sel_hi:[1,0,1]
	v_pk_fma_f32 v[116:117], v[116:117], 0.5, v[180:181] op_sel_hi:[1,0,1]
	s_waitcnt vmcnt(4)
	v_pk_fma_f32 v[164:165], v[112:113], 0.5, v[184:185] op_sel_hi:[1,0,1]
	v_mul_f32_e32 v178, v125, v125
	v_mul_f32_e32 v179, v127, v127
	global_store_dwordx4 v[188:189], v[124:127], off
	v_cvt_pk_bf16_f32 v112, v124, v125
	v_cvt_pk_bf16_f32 v113, v126, v127
	v_mul_f32_e32 v125, v121, v121
	v_mul_f32_e32 v127, v123, v123
	v_pk_fma_f32 v[166:167], v[114:115], 0.5, v[186:187] op_sel_hi:[1,0,1]
	v_mul_f32_e32 v180, v117, v117
	v_mul_f32_e32 v181, v119, v119
	v_fmac_f32_e32 v178, v124, v124
	v_fmac_f32_e32 v179, v126, v126
	v_fmac_f32_e32 v125, v120, v120
	v_fmac_f32_e32 v127, v122, v122
	v_mul_f32_e32 v182, v165, v165
	v_mul_f32_e32 v183, v167, v167
	global_store_dwordx2 v[192:193], v[112:113], off
	v_fmac_f32_e32 v180, v116, v116
	v_fmac_f32_e32 v181, v118, v118
	v_add_f32_e32 v112, v178, v179
	v_add_f32_e32 v113, v125, v127
	v_fmac_f32_e32 v182, v164, v164
	v_fmac_f32_e32 v183, v166, v166
	v_add_f32_e32 v124, v180, v181
	v_add_f32_e32 v112, v112, v113
	v_cndmask_b32_e32 v175, v174, v175, vcc
	v_add_f32_e32 v125, v182, v183
	v_add_f32_e32 v112, v112, v124
	v_lshlrev_b32_e32 v175, 2, v175
	v_add_f32_e32 v112, v112, v125
	ds_bpermute_b32 v113, v175, v112
	v_cmp_lt_i32_e32 vcc, v194, v191
	v_cvt_pk_bf16_f32 v176, v116, v117
	v_cvt_pk_bf16_f32 v114, v120, v121
	v_cndmask_b32_e32 v191, v174, v194, vcc
	v_cvt_pk_bf16_f32 v115, v122, v123
	v_cvt_pk_bf16_f32 v177, v118, v119
	global_store_dwordx4 v[188:189], v[120:123], off offset:64
	global_store_dwordx2 v[192:193], v[114:115], off offset:32
	global_store_dwordx4 v[188:189], v[116:119], off offset:512
	global_store_dwordx2 v[192:193], v[176:177], off offset:256
	s_waitcnt lgkmcnt(0)
	v_add_f32_e32 v112, v112, v113
	v_lshlrev_b32_e32 v176, 2, v191
	ds_bpermute_b32 v113, v176, v112
	v_cvt_pk_bf16_f32 v114, v164, v165
	v_cvt_pk_bf16_f32 v115, v166, v167
	global_store_dwordx4 v[188:189], v[164:167], off offset:576
	global_store_dwordx2 v[192:193], v[114:115], off offset:288
	s_mov_b32 vcc_lo, 0x11111111
	s_mov_b32 vcc_hi, 0x11111111
	s_and_saveexec_b64 s[24:25], vcc
	s_cbranch_execz .LBB0_1502
	v_lshl_add_u64 v[114:115], v[158:159], 2, s[16:17]
	s_waitcnt lgkmcnt(0)
	v_add_f32_e32 v112, v112, v113
	global_atomic_add_f32 v[114:115], v112, off
.LBB0_1502:
	s_or_b64 exec, exec, s[24:25]
	v_or_b32_e32 v164, 32, v158
	v_ashrrev_i32_e32 v165, 31, v164
	s_waitcnt lgkmcnt(0)
	v_lshlrev_b64 v[112:113], 12, v[164:165]
	v_lshl_add_u64 v[112:113], s[10:11], 0, v[112:113]
	v_lshl_add_u64 v[166:167], v[156:157], 2, v[112:113]
	global_load_dwordx4 v[124:127], v[166:167], off
	global_load_dwordx4 v[120:123], v[166:167], off offset:64
	global_load_dwordx4 v[116:119], v[166:167], off offset:512
	global_load_dwordx4 v[112:115], v[166:167], off offset:576
	s_waitcnt vmcnt(15)
	v_pk_fma_f32 v[110:111], v[110:111], 0.5, v[142:143] op_sel_hi:[1,0,1]
	v_pk_fma_f32 v[108:109], v[108:109], 0.5, v[140:141] op_sel_hi:[1,0,1]
	v_mul_f32_e32 v141, v111, v111
	v_mul_f32_e32 v140, v109, v109
	v_fmac_f32_e32 v140, v108, v108
	v_fmac_f32_e32 v141, v110, v110
	v_add_f32_e32 v142, v140, v141
	v_lshlrev_b64 v[140:141], 11, v[160:161]
	v_lshl_add_u64 v[140:141], s[14:15], 0, v[140:141]
	global_store_dwordx4 v[162:163], v[108:111], off
	v_lshl_add_u64 v[140:141], v[156:157], 1, v[140:141]
	s_waitcnt vmcnt(15)
	v_pk_fma_f32 v[104:105], v[104:105], 0.5, v[136:137] op_sel_hi:[1,0,1]
	v_cvt_pk_bf16_f32 v108, v108, v109
	v_cvt_pk_bf16_f32 v109, v110, v111
	global_store_dwordx2 v[140:141], v[108:109], off
	v_pk_fma_f32 v[106:107], v[106:107], 0.5, v[138:139] op_sel_hi:[1,0,1]
	v_mul_f32_e32 v108, v105, v105
	v_fmac_f32_e32 v108, v104, v104
	v_mul_f32_e32 v109, v107, v107
	global_store_dwordx4 v[162:163], v[104:107], off offset:64
	s_waitcnt vmcnt(16)
	v_pk_fma_f32 v[102:103], v[102:103], 0.5, v[134:135] op_sel_hi:[1,0,1]
	v_pk_fma_f32 v[100:101], v[100:101], 0.5, v[132:133] op_sel_hi:[1,0,1]
	v_cvt_pk_bf16_f32 v104, v104, v105
	v_cvt_pk_bf16_f32 v105, v106, v107
	v_fmac_f32_e32 v109, v106, v106
	global_store_dwordx2 v[140:141], v[104:105], off offset:32
	v_mul_f32_e32 v104, v101, v101
	v_mul_f32_e32 v105, v103, v103
	v_add_f32_e32 v108, v108, v109
	v_fmac_f32_e32 v104, v100, v100
	v_fmac_f32_e32 v105, v102, v102
	v_add_f32_e32 v108, v142, v108
	v_add_f32_e32 v104, v104, v105
	v_add_f32_e32 v108, v108, v104
	s_waitcnt vmcnt(16)
	v_pk_fma_f32 v[106:107], v[98:99], 0.5, v[130:131] op_sel_hi:[1,0,1]
	v_pk_fma_f32 v[104:105], v[96:97], 0.5, v[128:129] op_sel_hi:[1,0,1]
	v_mul_f32_e32 v97, v107, v107
	v_mul_f32_e32 v96, v105, v105
	v_fmac_f32_e32 v96, v104, v104
	v_fmac_f32_e32 v97, v106, v106
	v_add_f32_e32 v96, v96, v97
	v_add_f32_e32 v98, v108, v96
	ds_bpermute_b32 v99, v175, v98
	v_cvt_pk_bf16_f32 v96, v100, v101
	v_cvt_pk_bf16_f32 v97, v102, v103
	global_store_dwordx4 v[162:163], v[100:103], off offset:512
	global_store_dwordx2 v[140:141], v[96:97], off offset:256
	s_waitcnt lgkmcnt(0)
	v_add_f32_e32 v96, v98, v99
	ds_bpermute_b32 v97, v176, v96
	v_cvt_pk_bf16_f32 v98, v104, v105
	v_cvt_pk_bf16_f32 v99, v106, v107
	global_store_dwordx4 v[162:163], v[104:107], off offset:576
	global_store_dwordx2 v[140:141], v[98:99], off offset:288
	s_mov_b32 vcc_lo, 0x11111111
	s_mov_b32 vcc_hi, 0x11111111
	s_and_saveexec_b64 s[24:25], vcc
	s_cbranch_execz .LBB0_1504
	v_lshl_add_u64 v[98:99], v[160:161], 2, s[16:17]
	s_waitcnt lgkmcnt(0)
	v_add_f32_e32 v96, v96, v97
	global_atomic_add_f32 v[98:99], v96, off
.LBB0_1504:
	s_or_b64 exec, exec, s[24:25]
	v_or_b32_e32 v128, 48, v158
	v_ashrrev_i32_e32 v129, 31, v128
	s_waitcnt lgkmcnt(0)
	v_lshlrev_b64 v[96:97], 12, v[128:129]
	v_lshl_add_u64 v[96:97], s[10:11], 0, v[96:97]
	v_lshl_add_u64 v[130:131], v[156:157], 2, v[96:97]
	global_load_dwordx4 v[108:111], v[130:131], off
	global_load_dwordx4 v[104:107], v[130:131], off offset:64
	global_load_dwordx4 v[100:103], v[130:131], off offset:512
	global_load_dwordx4 v[96:99], v[130:131], off offset:576
	s_waitcnt vmcnt(15)
	v_pk_fma_f32 v[94:95], v[94:95], 0.5, v[126:127] op_sel_hi:[1,0,1]
	v_pk_fma_f32 v[92:93], v[92:93], 0.5, v[124:125] op_sel_hi:[1,0,1]
	v_mul_f32_e32 v125, v95, v95
	v_mul_f32_e32 v124, v93, v93
	v_fmac_f32_e32 v124, v92, v92
	v_fmac_f32_e32 v125, v94, v94
	v_add_f32_e32 v126, v124, v125
	v_lshlrev_b64 v[124:125], 11, v[164:165]
	v_lshl_add_u64 v[124:125], s[14:15], 0, v[124:125]
	global_store_dwordx4 v[166:167], v[92:95], off
	v_lshl_add_u64 v[124:125], v[156:157], 1, v[124:125]
	s_waitcnt vmcnt(15)
	v_pk_fma_f32 v[88:89], v[88:89], 0.5, v[120:121] op_sel_hi:[1,0,1]
	v_cvt_pk_bf16_f32 v92, v92, v93
	v_cvt_pk_bf16_f32 v93, v94, v95
	global_store_dwordx2 v[124:125], v[92:93], off
	v_pk_fma_f32 v[90:91], v[90:91], 0.5, v[122:123] op_sel_hi:[1,0,1]
	v_mul_f32_e32 v92, v89, v89
	v_fmac_f32_e32 v92, v88, v88
	v_mul_f32_e32 v93, v91, v91
	global_store_dwordx4 v[166:167], v[88:91], off offset:64
	s_waitcnt vmcnt(16)
	v_pk_fma_f32 v[86:87], v[86:87], 0.5, v[118:119] op_sel_hi:[1,0,1]
	v_pk_fma_f32 v[84:85], v[84:85], 0.5, v[116:117] op_sel_hi:[1,0,1]
	v_cvt_pk_bf16_f32 v88, v88, v89
	v_cvt_pk_bf16_f32 v89, v90, v91
	v_fmac_f32_e32 v93, v90, v90
	global_store_dwordx2 v[124:125], v[88:89], off offset:32
	v_mul_f32_e32 v88, v85, v85
	v_mul_f32_e32 v89, v87, v87
	v_add_f32_e32 v92, v92, v93
	v_fmac_f32_e32 v88, v84, v84
	v_fmac_f32_e32 v89, v86, v86
	v_add_f32_e32 v92, v126, v92
	v_add_f32_e32 v88, v88, v89
	v_add_f32_e32 v92, v92, v88
	s_waitcnt vmcnt(16)
	v_pk_fma_f32 v[90:91], v[82:83], 0.5, v[114:115] op_sel_hi:[1,0,1]
	v_pk_fma_f32 v[88:89], v[80:81], 0.5, v[112:113] op_sel_hi:[1,0,1]
	v_mul_f32_e32 v81, v91, v91
	v_mul_f32_e32 v80, v89, v89
	v_fmac_f32_e32 v80, v88, v88
	v_fmac_f32_e32 v81, v90, v90
	v_add_f32_e32 v80, v80, v81
	v_add_f32_e32 v82, v92, v80
	ds_bpermute_b32 v83, v175, v82
	v_cvt_pk_bf16_f32 v80, v84, v85
	v_cvt_pk_bf16_f32 v81, v86, v87
	global_store_dwordx4 v[166:167], v[84:87], off offset:512
	global_store_dwordx2 v[124:125], v[80:81], off offset:256
	s_waitcnt lgkmcnt(0)
	v_add_f32_e32 v80, v82, v83
	ds_bpermute_b32 v81, v176, v80
	v_cvt_pk_bf16_f32 v82, v88, v89
	v_cvt_pk_bf16_f32 v83, v90, v91
	global_store_dwordx4 v[166:167], v[88:91], off offset:576
	global_store_dwordx2 v[124:125], v[82:83], off offset:288
	s_mov_b32 vcc_lo, 0x11111111
	s_mov_b32 vcc_hi, 0x11111111
	s_and_saveexec_b64 s[24:25], vcc
	s_cbranch_execz .LBB0_1506
	v_lshl_add_u64 v[82:83], v[164:165], 2, s[16:17]
	s_waitcnt lgkmcnt(0)
	v_add_f32_e32 v80, v80, v81
	global_atomic_add_f32 v[82:83], v80, off
.LBB0_1506:
	s_or_b64 exec, exec, s[24:25]
	v_add_u32_e32 v112, 0x80, v158
	v_ashrrev_i32_e32 v113, 31, v112
	s_waitcnt lgkmcnt(0)
	v_lshlrev_b64 v[80:81], 12, v[112:113]
	v_lshl_add_u64 v[80:81], s[10:11], 0, v[80:81]
	v_lshl_add_u64 v[114:115], v[156:157], 2, v[80:81]
	global_load_dwordx4 v[92:95], v[114:115], off
	global_load_dwordx4 v[88:91], v[114:115], off offset:64
	global_load_dwordx4 v[84:87], v[114:115], off offset:512
	global_load_dwordx4 v[80:83], v[114:115], off offset:576
	s_waitcnt vmcnt(15)
	v_pk_fma_f32 v[78:79], v[78:79], 0.5, v[110:111] op_sel_hi:[1,0,1]
	v_pk_fma_f32 v[76:77], v[76:77], 0.5, v[108:109] op_sel_hi:[1,0,1]
	v_mul_f32_e32 v109, v79, v79
	v_mul_f32_e32 v108, v77, v77
	v_fmac_f32_e32 v108, v76, v76
	v_fmac_f32_e32 v109, v78, v78
	v_add_f32_e32 v110, v108, v109
	v_lshlrev_b64 v[108:109], 11, v[128:129]
	v_lshl_add_u64 v[108:109], s[14:15], 0, v[108:109]
	global_store_dwordx4 v[130:131], v[76:79], off
	v_lshl_add_u64 v[108:109], v[156:157], 1, v[108:109]
	s_waitcnt vmcnt(15)
	v_pk_fma_f32 v[72:73], v[72:73], 0.5, v[104:105] op_sel_hi:[1,0,1]
	v_cvt_pk_bf16_f32 v76, v76, v77
	v_cvt_pk_bf16_f32 v77, v78, v79
	global_store_dwordx2 v[108:109], v[76:77], off
	v_pk_fma_f32 v[74:75], v[74:75], 0.5, v[106:107] op_sel_hi:[1,0,1]
	v_mul_f32_e32 v76, v73, v73
	v_fmac_f32_e32 v76, v72, v72
	v_mul_f32_e32 v77, v75, v75
	global_store_dwordx4 v[130:131], v[72:75], off offset:64
	s_waitcnt vmcnt(16)
	v_pk_fma_f32 v[70:71], v[70:71], 0.5, v[102:103] op_sel_hi:[1,0,1]
	v_pk_fma_f32 v[68:69], v[68:69], 0.5, v[100:101] op_sel_hi:[1,0,1]
	v_cvt_pk_bf16_f32 v72, v72, v73
	v_cvt_pk_bf16_f32 v73, v74, v75
	v_fmac_f32_e32 v77, v74, v74
	global_store_dwordx2 v[108:109], v[72:73], off offset:32
	v_mul_f32_e32 v72, v69, v69
	v_mul_f32_e32 v73, v71, v71
	v_add_f32_e32 v76, v76, v77
	v_fmac_f32_e32 v72, v68, v68
	v_fmac_f32_e32 v73, v70, v70
	v_add_f32_e32 v76, v110, v76
	v_add_f32_e32 v72, v72, v73
	v_add_f32_e32 v76, v76, v72
	s_waitcnt vmcnt(16)
	v_pk_fma_f32 v[74:75], v[66:67], 0.5, v[98:99] op_sel_hi:[1,0,1]
	v_pk_fma_f32 v[72:73], v[64:65], 0.5, v[96:97] op_sel_hi:[1,0,1]
	v_mul_f32_e32 v65, v75, v75
	v_mul_f32_e32 v64, v73, v73
	v_fmac_f32_e32 v64, v72, v72
	v_fmac_f32_e32 v65, v74, v74
	v_add_f32_e32 v64, v64, v65
	v_add_f32_e32 v66, v76, v64
	ds_bpermute_b32 v67, v175, v66
	v_cvt_pk_bf16_f32 v64, v68, v69
	v_cvt_pk_bf16_f32 v65, v70, v71
	global_store_dwordx4 v[130:131], v[68:71], off offset:512
	global_store_dwordx2 v[108:109], v[64:65], off offset:256
	s_waitcnt lgkmcnt(0)
	v_add_f32_e32 v64, v66, v67
	ds_bpermute_b32 v65, v176, v64
	v_cvt_pk_bf16_f32 v66, v72, v73
	v_cvt_pk_bf16_f32 v67, v74, v75
	global_store_dwordx4 v[130:131], v[72:75], off offset:576
	global_store_dwordx2 v[108:109], v[66:67], off offset:288
	s_mov_b32 vcc_lo, 0x11111111
	s_mov_b32 vcc_hi, 0x11111111
	s_and_saveexec_b64 s[24:25], vcc
	s_cbranch_execz .LBB0_1508
	v_lshl_add_u64 v[66:67], v[128:129], 2, s[16:17]
	s_waitcnt lgkmcnt(0)
	v_add_f32_e32 v64, v64, v65
	global_atomic_add_f32 v[66:67], v64, off
.LBB0_1508:
	s_or_b64 exec, exec, s[24:25]
	v_or_b32_e32 v96, 16, v112
	v_ashrrev_i32_e32 v97, 31, v96
	s_waitcnt lgkmcnt(0)
	v_lshlrev_b64 v[64:65], 12, v[96:97]
	v_lshl_add_u64 v[64:65], s[10:11], 0, v[64:65]
	v_lshl_add_u64 v[98:99], v[156:157], 2, v[64:65]
	global_load_dwordx4 v[76:79], v[98:99], off
	global_load_dwordx4 v[72:75], v[98:99], off offset:64
	global_load_dwordx4 v[68:71], v[98:99], off offset:512
	global_load_dwordx4 v[64:67], v[98:99], off offset:576
	s_waitcnt vmcnt(15)
	v_pk_fma_f32 v[62:63], v[62:63], 0.5, v[94:95] op_sel_hi:[1,0,1]
	v_pk_fma_f32 v[60:61], v[60:61], 0.5, v[92:93] op_sel_hi:[1,0,1]
	v_mul_f32_e32 v93, v63, v63
	v_mul_f32_e32 v92, v61, v61
	v_fmac_f32_e32 v92, v60, v60
	v_fmac_f32_e32 v93, v62, v62
	v_add_f32_e32 v94, v92, v93
	v_lshlrev_b64 v[92:93], 11, v[112:113]
	v_lshl_add_u64 v[92:93], s[14:15], 0, v[92:93]
	global_store_dwordx4 v[114:115], v[60:63], off
	v_lshl_add_u64 v[92:93], v[156:157], 1, v[92:93]
	s_waitcnt vmcnt(15)
	v_pk_fma_f32 v[56:57], v[56:57], 0.5, v[88:89] op_sel_hi:[1,0,1]
	v_cvt_pk_bf16_f32 v60, v60, v61
	v_cvt_pk_bf16_f32 v61, v62, v63
	global_store_dwordx2 v[92:93], v[60:61], off
	v_pk_fma_f32 v[58:59], v[58:59], 0.5, v[90:91] op_sel_hi:[1,0,1]
	v_mul_f32_e32 v60, v57, v57
	v_fmac_f32_e32 v60, v56, v56
	v_mul_f32_e32 v61, v59, v59
	global_store_dwordx4 v[114:115], v[56:59], off offset:64
	s_waitcnt vmcnt(16)
	v_pk_fma_f32 v[54:55], v[54:55], 0.5, v[86:87] op_sel_hi:[1,0,1]
	v_pk_fma_f32 v[52:53], v[52:53], 0.5, v[84:85] op_sel_hi:[1,0,1]
	v_cvt_pk_bf16_f32 v56, v56, v57
	v_cvt_pk_bf16_f32 v57, v58, v59
	v_fmac_f32_e32 v61, v58, v58
	global_store_dwordx2 v[92:93], v[56:57], off offset:32
	v_mul_f32_e32 v56, v53, v53
	v_mul_f32_e32 v57, v55, v55
	v_add_f32_e32 v60, v60, v61
	v_fmac_f32_e32 v56, v52, v52
	v_fmac_f32_e32 v57, v54, v54
	v_add_f32_e32 v60, v94, v60
	v_add_f32_e32 v56, v56, v57
	v_add_f32_e32 v60, v60, v56
	s_waitcnt vmcnt(16)
	v_pk_fma_f32 v[58:59], v[50:51], 0.5, v[82:83] op_sel_hi:[1,0,1]
	v_pk_fma_f32 v[56:57], v[48:49], 0.5, v[80:81] op_sel_hi:[1,0,1]
	v_mul_f32_e32 v49, v59, v59
	v_mul_f32_e32 v48, v57, v57
	v_fmac_f32_e32 v48, v56, v56
	v_fmac_f32_e32 v49, v58, v58
	v_add_f32_e32 v48, v48, v49
	v_add_f32_e32 v50, v60, v48
	ds_bpermute_b32 v51, v175, v50
	v_cvt_pk_bf16_f32 v48, v52, v53
	v_cvt_pk_bf16_f32 v49, v54, v55
	global_store_dwordx4 v[114:115], v[52:55], off offset:512
	global_store_dwordx2 v[92:93], v[48:49], off offset:256
	s_waitcnt lgkmcnt(0)
	v_add_f32_e32 v48, v50, v51
	ds_bpermute_b32 v49, v176, v48
	v_cvt_pk_bf16_f32 v50, v56, v57
	v_cvt_pk_bf16_f32 v51, v58, v59
	global_store_dwordx4 v[114:115], v[56:59], off offset:576
	global_store_dwordx2 v[92:93], v[50:51], off offset:288
	s_mov_b32 vcc_lo, 0x11111111
	s_mov_b32 vcc_hi, 0x11111111
	s_and_saveexec_b64 s[24:25], vcc
	s_cbranch_execz .LBB0_1510
	v_lshl_add_u64 v[50:51], v[112:113], 2, s[16:17]
	s_waitcnt lgkmcnt(0)
	v_add_f32_e32 v48, v48, v49
	global_atomic_add_f32 v[50:51], v48, off
.LBB0_1510:
	s_or_b64 exec, exec, s[24:25]
	v_or_b32_e32 v80, 32, v112
	v_ashrrev_i32_e32 v81, 31, v80
	s_waitcnt lgkmcnt(0)
	v_lshlrev_b64 v[48:49], 12, v[80:81]
	v_lshl_add_u64 v[48:49], s[10:11], 0, v[48:49]
	v_lshl_add_u64 v[82:83], v[156:157], 2, v[48:49]
	global_load_dwordx4 v[60:63], v[82:83], off
	global_load_dwordx4 v[56:59], v[82:83], off offset:64
	global_load_dwordx4 v[52:55], v[82:83], off offset:512
	global_load_dwordx4 v[48:51], v[82:83], off offset:576
	s_waitcnt vmcnt(15)
	v_pk_fma_f32 v[46:47], v[46:47], 0.5, v[78:79] op_sel_hi:[1,0,1]
	v_pk_fma_f32 v[44:45], v[44:45], 0.5, v[76:77] op_sel_hi:[1,0,1]
	v_mul_f32_e32 v77, v47, v47
	v_mul_f32_e32 v76, v45, v45
	v_fmac_f32_e32 v76, v44, v44
	v_fmac_f32_e32 v77, v46, v46
	v_add_f32_e32 v78, v76, v77
	v_lshlrev_b64 v[76:77], 11, v[96:97]
	v_lshl_add_u64 v[76:77], s[14:15], 0, v[76:77]
	global_store_dwordx4 v[98:99], v[44:47], off
	v_lshl_add_u64 v[76:77], v[156:157], 1, v[76:77]
	s_waitcnt vmcnt(15)
	v_pk_fma_f32 v[40:41], v[40:41], 0.5, v[72:73] op_sel_hi:[1,0,1]
	v_cvt_pk_bf16_f32 v44, v44, v45
	v_cvt_pk_bf16_f32 v45, v46, v47
	global_store_dwordx2 v[76:77], v[44:45], off
	v_pk_fma_f32 v[42:43], v[42:43], 0.5, v[74:75] op_sel_hi:[1,0,1]
	v_mul_f32_e32 v44, v41, v41
	v_fmac_f32_e32 v44, v40, v40
	v_mul_f32_e32 v45, v43, v43
	global_store_dwordx4 v[98:99], v[40:43], off offset:64
	s_waitcnt vmcnt(16)
	v_pk_fma_f32 v[38:39], v[38:39], 0.5, v[70:71] op_sel_hi:[1,0,1]
	v_pk_fma_f32 v[36:37], v[36:37], 0.5, v[68:69] op_sel_hi:[1,0,1]
	v_cvt_pk_bf16_f32 v40, v40, v41
	v_cvt_pk_bf16_f32 v41, v42, v43
	v_fmac_f32_e32 v45, v42, v42
	global_store_dwordx2 v[76:77], v[40:41], off offset:32
	v_mul_f32_e32 v40, v37, v37
	v_mul_f32_e32 v41, v39, v39
	v_add_f32_e32 v44, v44, v45
	v_fmac_f32_e32 v40, v36, v36
	v_fmac_f32_e32 v41, v38, v38
	v_add_f32_e32 v44, v78, v44
	v_add_f32_e32 v40, v40, v41
	v_add_f32_e32 v44, v44, v40
	s_waitcnt vmcnt(16)
	v_pk_fma_f32 v[42:43], v[34:35], 0.5, v[66:67] op_sel_hi:[1,0,1]
	v_pk_fma_f32 v[40:41], v[32:33], 0.5, v[64:65] op_sel_hi:[1,0,1]
	v_mul_f32_e32 v33, v43, v43
	v_mul_f32_e32 v32, v41, v41
	v_fmac_f32_e32 v32, v40, v40
	v_fmac_f32_e32 v33, v42, v42
	v_add_f32_e32 v32, v32, v33
	v_add_f32_e32 v34, v44, v32
	ds_bpermute_b32 v35, v175, v34
	v_cvt_pk_bf16_f32 v32, v36, v37
	v_cvt_pk_bf16_f32 v33, v38, v39
	global_store_dwordx4 v[98:99], v[36:39], off offset:512
	global_store_dwordx2 v[76:77], v[32:33], off offset:256
	s_waitcnt lgkmcnt(0)
	v_add_f32_e32 v32, v34, v35
	ds_bpermute_b32 v33, v176, v32
	v_cvt_pk_bf16_f32 v34, v40, v41
	v_cvt_pk_bf16_f32 v35, v42, v43
	global_store_dwordx4 v[98:99], v[40:43], off offset:576
	global_store_dwordx2 v[76:77], v[34:35], off offset:288
	s_mov_b32 vcc_lo, 0x11111111
	s_mov_b32 vcc_hi, 0x11111111
	s_and_saveexec_b64 s[24:25], vcc
	s_cbranch_execz .LBB0_1512
	v_lshl_add_u64 v[34:35], v[96:97], 2, s[16:17]
	s_waitcnt lgkmcnt(0)
	v_add_f32_e32 v32, v32, v33
	global_atomic_add_f32 v[34:35], v32, off
.LBB0_1512:
	s_or_b64 exec, exec, s[24:25]
	v_or_b32_e32 v64, 48, v112
	v_ashrrev_i32_e32 v65, 31, v64
	s_waitcnt lgkmcnt(0)
	v_lshlrev_b64 v[32:33], 12, v[64:65]
	v_lshl_add_u64 v[32:33], s[10:11], 0, v[32:33]
	v_lshl_add_u64 v[66:67], v[156:157], 2, v[32:33]
	global_load_dwordx4 v[44:47], v[66:67], off
	global_load_dwordx4 v[40:43], v[66:67], off offset:64
	global_load_dwordx4 v[36:39], v[66:67], off offset:512
	global_load_dwordx4 v[32:35], v[66:67], off offset:576
	s_waitcnt vmcnt(15)
	v_pk_fma_f32 v[30:31], v[30:31], 0.5, v[62:63] op_sel_hi:[1,0,1]
	v_pk_fma_f32 v[28:29], v[28:29], 0.5, v[60:61] op_sel_hi:[1,0,1]
	v_mul_f32_e32 v61, v31, v31
	v_mul_f32_e32 v60, v29, v29
	v_fmac_f32_e32 v60, v28, v28
	v_fmac_f32_e32 v61, v30, v30
	v_add_f32_e32 v62, v60, v61
	v_lshlrev_b64 v[60:61], 11, v[80:81]
	v_lshl_add_u64 v[60:61], s[14:15], 0, v[60:61]
	global_store_dwordx4 v[82:83], v[28:31], off
	v_lshl_add_u64 v[60:61], v[156:157], 1, v[60:61]
	s_waitcnt vmcnt(15)
	v_pk_fma_f32 v[24:25], v[24:25], 0.5, v[56:57] op_sel_hi:[1,0,1]
	v_cvt_pk_bf16_f32 v28, v28, v29
	v_cvt_pk_bf16_f32 v29, v30, v31
	global_store_dwordx2 v[60:61], v[28:29], off
	v_pk_fma_f32 v[26:27], v[26:27], 0.5, v[58:59] op_sel_hi:[1,0,1]
	v_mul_f32_e32 v28, v25, v25
	v_fmac_f32_e32 v28, v24, v24
	v_mul_f32_e32 v29, v27, v27
	global_store_dwordx4 v[82:83], v[24:27], off offset:64
	s_waitcnt vmcnt(16)
	v_pk_fma_f32 v[22:23], v[22:23], 0.5, v[54:55] op_sel_hi:[1,0,1]
	v_pk_fma_f32 v[20:21], v[20:21], 0.5, v[52:53] op_sel_hi:[1,0,1]
	v_cvt_pk_bf16_f32 v24, v24, v25
	v_cvt_pk_bf16_f32 v25, v26, v27
	v_fmac_f32_e32 v29, v26, v26
	global_store_dwordx2 v[60:61], v[24:25], off offset:32
	v_mul_f32_e32 v24, v21, v21
	v_mul_f32_e32 v25, v23, v23
	v_add_f32_e32 v28, v28, v29
	v_fmac_f32_e32 v24, v20, v20
	v_fmac_f32_e32 v25, v22, v22
	v_add_f32_e32 v28, v62, v28
	v_add_f32_e32 v24, v24, v25
	v_add_f32_e32 v28, v28, v24
	s_waitcnt vmcnt(16)
	v_pk_fma_f32 v[26:27], v[18:19], 0.5, v[50:51] op_sel_hi:[1,0,1]
	v_pk_fma_f32 v[24:25], v[16:17], 0.5, v[48:49] op_sel_hi:[1,0,1]
	v_mul_f32_e32 v17, v27, v27
	v_mul_f32_e32 v16, v25, v25
	v_fmac_f32_e32 v16, v24, v24
	v_fmac_f32_e32 v17, v26, v26
	v_add_f32_e32 v16, v16, v17
	v_add_f32_e32 v18, v28, v16
	ds_bpermute_b32 v19, v175, v18
	v_cvt_pk_bf16_f32 v16, v20, v21
	v_cvt_pk_bf16_f32 v17, v22, v23
	global_store_dwordx4 v[82:83], v[20:23], off offset:512
	global_store_dwordx2 v[60:61], v[16:17], off offset:256
	s_waitcnt lgkmcnt(0)
	v_add_f32_e32 v16, v18, v19
	ds_bpermute_b32 v17, v176, v16
	v_cvt_pk_bf16_f32 v18, v24, v25
	v_cvt_pk_bf16_f32 v19, v26, v27
	global_store_dwordx4 v[82:83], v[24:27], off offset:576
	global_store_dwordx2 v[60:61], v[18:19], off offset:288
	s_mov_b32 vcc_lo, 0x11111111
	s_mov_b32 vcc_hi, 0x11111111
	s_and_saveexec_b64 s[24:25], vcc
	s_cbranch_execz .LBB0_1514
	v_lshl_add_u64 v[18:19], v[80:81], 2, s[16:17]
	s_waitcnt lgkmcnt(0)
	v_add_f32_e32 v16, v16, v17
	global_atomic_add_f32 v[18:19], v16, off
.LBB0_1514:
	s_or_b64 exec, exec, s[24:25]
	s_waitcnt vmcnt(11)
	v_pk_fma_f32 v[14:15], v[14:15], 0.5, v[46:47] op_sel_hi:[1,0,1]
	v_pk_fma_f32 v[12:13], v[12:13], 0.5, v[44:45] op_sel_hi:[1,0,1]
	s_waitcnt lgkmcnt(0)
	v_mul_f32_e32 v17, v15, v15
	v_mul_f32_e32 v16, v13, v13
	v_fmac_f32_e32 v16, v12, v12
	v_fmac_f32_e32 v17, v14, v14
	v_add_f32_e32 v18, v16, v17
	v_lshlrev_b64 v[16:17], 11, v[64:65]
	v_lshl_add_u64 v[16:17], s[14:15], 0, v[16:17]
	global_store_dwordx4 v[66:67], v[12:15], off
	v_lshl_add_u64 v[16:17], v[156:157], 1, v[16:17]
	s_waitcnt vmcnt(11)
	v_pk_fma_f32 v[8:9], v[8:9], 0.5, v[40:41] op_sel_hi:[1,0,1]
	v_cvt_pk_bf16_f32 v12, v12, v13
	v_cvt_pk_bf16_f32 v13, v14, v15
	global_store_dwordx2 v[16:17], v[12:13], off
	v_pk_fma_f32 v[10:11], v[10:11], 0.5, v[42:43] op_sel_hi:[1,0,1]
	v_mul_f32_e32 v12, v9, v9
	v_fmac_f32_e32 v12, v8, v8
	v_mul_f32_e32 v13, v11, v11
	global_store_dwordx4 v[66:67], v[8:11], off offset:64
	s_waitcnt vmcnt(12)
	v_pk_fma_f32 v[6:7], v[6:7], 0.5, v[38:39] op_sel_hi:[1,0,1]
	v_pk_fma_f32 v[4:5], v[4:5], 0.5, v[36:37] op_sel_hi:[1,0,1]
	v_cvt_pk_bf16_f32 v8, v8, v9
	v_cvt_pk_bf16_f32 v9, v10, v11
	v_fmac_f32_e32 v13, v10, v10
	global_store_dwordx2 v[16:17], v[8:9], off offset:32
	v_mul_f32_e32 v8, v5, v5
	v_mul_f32_e32 v9, v7, v7
	v_add_f32_e32 v12, v12, v13
	v_fmac_f32_e32 v8, v4, v4
	v_fmac_f32_e32 v9, v6, v6
	v_add_f32_e32 v12, v18, v12
	v_add_f32_e32 v8, v8, v9
	v_add_f32_e32 v12, v12, v8
	s_waitcnt vmcnt(12)
	v_pk_fma_f32 v[10:11], v[2:3], 0.5, v[34:35] op_sel_hi:[1,0,1]
	v_pk_fma_f32 v[8:9], v[0:1], 0.5, v[32:33] op_sel_hi:[1,0,1]
	v_mul_f32_e32 v1, v11, v11
	v_mul_f32_e32 v0, v9, v9
	v_fmac_f32_e32 v0, v8, v8
	v_fmac_f32_e32 v1, v10, v10
	v_add_f32_e32 v0, v0, v1
	v_add_f32_e32 v2, v12, v0
	ds_bpermute_b32 v3, v175, v2
	v_cvt_pk_bf16_f32 v0, v4, v5
	v_cvt_pk_bf16_f32 v1, v6, v7
	global_store_dwordx4 v[66:67], v[4:7], off offset:512
	global_store_dwordx2 v[16:17], v[0:1], off offset:256
	s_waitcnt lgkmcnt(0)
	v_add_f32_e32 v0, v2, v3
	ds_bpermute_b32 v1, v176, v0
	v_cvt_pk_bf16_f32 v2, v8, v9
	v_cvt_pk_bf16_f32 v3, v10, v11
	global_store_dwordx4 v[66:67], v[8:11], off offset:576
	global_store_dwordx2 v[16:17], v[2:3], off offset:288
	s_mov_b32 vcc_lo, 0x11111111
	s_mov_b32 vcc_hi, 0x11111111
	s_and_saveexec_b64 s[24:25], vcc
	s_cbranch_execz .LBB0_1516
	v_lshl_add_u64 v[2:3], v[64:65], 2, s[16:17]
	s_waitcnt lgkmcnt(0)
	v_add_f32_e32 v0, v0, v1
	global_atomic_add_f32 v[2:3], v0, off

.LBB0_1810:
	ds_read_b128 v[128:131], v171
	ds_read_b128 v[132:135], v171 offset:1024
	ds_read_b128 v[136:139], v171 offset:2048
	ds_read_b128 v[140:143], v171 offset:3072
	ds_read_b128 v[156:159], v172
	ds_read_b128 v[160:163], v172 offset:1024
	ds_read_b128 v[164:167], v172 offset:2048
	ds_read_b128 v[176:179], v172 offset:3072
	s_add_u32 s30, s28, 0x100
	s_addc_u32 s31, s29, 0
	s_cmp_eq_u32 s57, 12
	s_cselect_b32 s37, s19, s31
	s_cselect_b32 s36, s25, s30
	s_cselect_b32 s35, s17, s56
	s_cselect_b32 s34, s54, s55
	v_lshl_add_u64 v[188:189], s[28:29], 0, v[150:151]
	s_add_i32 m0, s27, 0xc000
	ds_read_b128 v[180:183], v173
	ds_read_b128 v[184:187], v173 offset:1024
	ds_read_b128 v[192:195], v173 offset:2048
	ds_read_b128 v[196:199], v173 offset:3072
	ds_read_b128 v[200:203], v173 offset:4096
	ds_read_b128 v[204:207], v173 offset:5120
	ds_read_b128 v[208:211], v173 offset:6144
	ds_read_b128 v[212:215], v173 offset:7168
	global_load_lds_dwordx4 v[188:189], off
	v_lshl_add_u64 v[188:189], s[28:29], 0, v[148:149]
	s_add_i32 m0, s27, 0xe000
	s_nop 0
	global_load_lds_dwordx4 v[188:189], off
	s_waitcnt vmcnt(8)
	s_waitcnt lgkmcnt(0)
	s_barrier
	s_setprio 1
	s_waitcnt lgkmcnt(0)
	v_mfma_f32_16x16x32_bf16 v[124:127], v[128:131], v[180:183], v[124:127]
	v_mfma_f32_16x16x32_bf16 v[120:123], v[136:139], v[180:183], v[120:123]
	v_mfma_f32_16x16x32_bf16 v[108:111], v[128:131], v[192:195], v[108:111]
	v_mfma_f32_16x16x32_bf16 v[104:107], v[136:139], v[192:195], v[104:107]
	v_mfma_f32_16x16x32_bf16 v[92:95], v[128:131], v[200:203], v[92:95]
	v_mfma_f32_16x16x32_bf16 v[88:91], v[136:139], v[200:203], v[88:91]
	v_mfma_f32_16x16x32_bf16 v[76:79], v[128:131], v[208:211], v[76:79]
	v_mfma_f32_16x16x32_bf16 v[72:75], v[136:139], v[208:211], v[72:75]
	v_mfma_f32_16x16x32_bf16 v[124:127], v[132:135], v[184:187], v[124:127]
	v_mfma_f32_16x16x32_bf16 v[120:123], v[140:143], v[184:187], v[120:123]
	v_mfma_f32_16x16x32_bf16 v[108:111], v[132:135], v[196:199], v[108:111]
	v_mfma_f32_16x16x32_bf16 v[104:107], v[140:143], v[196:199], v[104:107]
	v_mfma_f32_16x16x32_bf16 v[92:95], v[132:135], v[204:207], v[92:95]
	v_mfma_f32_16x16x32_bf16 v[88:91], v[140:143], v[204:207], v[88:91]
	v_mfma_f32_16x16x32_bf16 v[76:79], v[132:135], v[212:215], v[76:79]
	v_mfma_f32_16x16x32_bf16 v[72:75], v[140:143], v[212:215], v[72:75]
	s_setprio 0
	s_setprio 1
	v_mfma_f32_16x16x32_bf16 v[116:119], v[156:159], v[180:183], v[116:119]
	v_mfma_f32_16x16x32_bf16 v[112:115], v[164:167], v[180:183], v[112:115]
	v_mfma_f32_16x16x32_bf16 v[100:103], v[156:159], v[192:195], v[100:103]
	v_mfma_f32_16x16x32_bf16 v[96:99], v[164:167], v[192:195], v[96:99]
	v_mfma_f32_16x16x32_bf16 v[84:87], v[156:159], v[200:203], v[84:87]
	v_mfma_f32_16x16x32_bf16 v[80:83], v[164:167], v[200:203], v[80:83]
	v_mfma_f32_16x16x32_bf16 v[68:71], v[156:159], v[208:211], v[68:71]
	v_mfma_f32_16x16x32_bf16 v[64:67], v[164:167], v[208:211], v[64:67]
	v_mfma_f32_16x16x32_bf16 v[116:119], v[160:163], v[184:187], v[116:119]
	v_mfma_f32_16x16x32_bf16 v[112:115], v[176:179], v[184:187], v[112:115]
	v_mfma_f32_16x16x32_bf16 v[100:103], v[160:163], v[196:199], v[100:103]
	v_mfma_f32_16x16x32_bf16 v[96:99], v[176:179], v[196:199], v[96:99]
	v_mfma_f32_16x16x32_bf16 v[84:87], v[160:163], v[204:207], v[84:87]
	v_mfma_f32_16x16x32_bf16 v[80:83], v[176:179], v[204:207], v[80:83]
	v_mfma_f32_16x16x32_bf16 v[68:71], v[160:163], v[212:215], v[68:71]
	v_mfma_f32_16x16x32_bf16 v[64:67], v[176:179], v[212:215], v[64:67]
	s_setprio 0
	s_barrier
	s_add_i32 s28, s52, s41
	v_lshl_add_u64 v[188:189], s[34:35], 0, v[144:145]
	s_mov_b32 m0, s28
	ds_read_b128 v[180:183], v173 offset:16384
	ds_read_b128 v[184:187], v173 offset:17408
	ds_read_b128 v[192:195], v173 offset:18432
	ds_read_b128 v[196:199], v173 offset:19456
	ds_read_b128 v[200:203], v173 offset:20480
	ds_read_b128 v[204:207], v173 offset:21504
	ds_read_b128 v[208:211], v173 offset:22528
	ds_read_b128 v[212:215], v173 offset:23552
	global_load_lds_dwordx4 v[188:189], off
	s_add_i32 m0, s28, 0x2000
	s_add_u32 s28, s34, 0x40000
	v_lshl_add_u64 v[216:217], s[34:35], 0, v[146:147]
	s_addc_u32 s29, s35, 0
	s_add_i32 s58, s53, s41
	global_load_lds_dwordx4 v[216:217], off
	v_lshl_add_u64 v[218:219], s[28:29], 0, v[144:145]
	s_mov_b32 m0, s58
	v_lshl_add_u64 v[220:221], s[36:37], 0, v[146:147]
	global_load_lds_dwordx4 v[218:219], off
	v_lshl_add_u64 v[218:219], s[28:29], 0, v[146:147]
	s_add_i32 m0, s58, 0x2000
	s_nop 0
	global_load_lds_dwordx4 v[218:219], off
	v_lshl_add_u64 v[218:219], s[36:37], 0, v[144:145]
	s_mov_b32 m0, s27
	s_nop 0
	global_load_lds_dwordx4 v[218:219], off
	s_mov_b32 m0, s42
	s_nop 0
	global_load_lds_dwordx4 v[220:221], off
	s_waitcnt vmcnt(8)
	s_waitcnt lgkmcnt(0)
	s_barrier
	s_setprio 1
	s_waitcnt lgkmcnt(0)
	v_mfma_f32_16x16x32_bf16 v[60:63], v[128:131], v[180:183], v[60:63]
	v_mfma_f32_16x16x32_bf16 v[56:59], v[136:139], v[180:183], v[56:59]
	v_mfma_f32_16x16x32_bf16 v[44:47], v[128:131], v[192:195], v[44:47]
	v_mfma_f32_16x16x32_bf16 v[40:43], v[136:139], v[192:195], v[40:43]
	v_mfma_f32_16x16x32_bf16 v[28:31], v[128:131], v[200:203], v[28:31]
	v_mfma_f32_16x16x32_bf16 v[24:27], v[136:139], v[200:203], v[24:27]
	v_mfma_f32_16x16x32_bf16 v[12:15], v[128:131], v[208:211], v[12:15]
	v_mfma_f32_16x16x32_bf16 v[8:11], v[136:139], v[208:211], v[8:11]
	v_mfma_f32_16x16x32_bf16 v[60:63], v[132:135], v[184:187], v[60:63]
	v_mfma_f32_16x16x32_bf16 v[56:59], v[140:143], v[184:187], v[56:59]
	v_mfma_f32_16x16x32_bf16 v[44:47], v[132:135], v[196:199], v[44:47]
	v_mfma_f32_16x16x32_bf16 v[40:43], v[140:143], v[196:199], v[40:43]
	v_mfma_f32_16x16x32_bf16 v[28:31], v[132:135], v[204:207], v[28:31]
	v_mfma_f32_16x16x32_bf16 v[24:27], v[140:143], v[204:207], v[24:27]
	v_mfma_f32_16x16x32_bf16 v[12:15], v[132:135], v[212:215], v[12:15]
	v_mfma_f32_16x16x32_bf16 v[8:11], v[140:143], v[212:215], v[8:11]
	s_setprio 0
	s_setprio 1
	v_mfma_f32_16x16x32_bf16 v[52:55], v[156:159], v[180:183], v[52:55]
	v_mfma_f32_16x16x32_bf16 v[48:51], v[164:167], v[180:183], v[48:51]
	v_mfma_f32_16x16x32_bf16 v[36:39], v[156:159], v[192:195], v[36:39]
	v_mfma_f32_16x16x32_bf16 v[32:35], v[164:167], v[192:195], v[32:35]
	v_mfma_f32_16x16x32_bf16 v[20:23], v[156:159], v[200:203], v[20:23]
	v_mfma_f32_16x16x32_bf16 v[16:19], v[164:167], v[200:203], v[16:19]
	v_mfma_f32_16x16x32_bf16 v[4:7], v[156:159], v[208:211], v[4:7]
	v_mfma_f32_16x16x32_bf16 v[0:3], v[164:167], v[208:211], v[0:3]
	v_mfma_f32_16x16x32_bf16 v[52:55], v[160:163], v[184:187], v[52:55]
	v_mfma_f32_16x16x32_bf16 v[48:51], v[176:179], v[184:187], v[48:51]
	v_mfma_f32_16x16x32_bf16 v[36:39], v[160:163], v[196:199], v[36:39]
	v_mfma_f32_16x16x32_bf16 v[32:35], v[176:179], v[196:199], v[32:35]
	v_mfma_f32_16x16x32_bf16 v[20:23], v[160:163], v[204:207], v[20:23]
	v_mfma_f32_16x16x32_bf16 v[16:19], v[176:179], v[204:207], v[16:19]
	v_mfma_f32_16x16x32_bf16 v[4:7], v[160:163], v[212:215], v[4:7]
	v_mfma_f32_16x16x32_bf16 v[0:3], v[176:179], v[212:215], v[0:3]
	s_setprio 0
	s_barrier
	s_add_i32 s58, 0, 0x18000
	s_add_i32 s59, 0, 0x1c000
	v_add_u32_e32 v140, s58, v169
	v_add_u32_e32 v175, s59, v169
	ds_read_b128 v[128:131], v140
	ds_read_b128 v[132:135], v140 offset:1024
	ds_read_b128 v[136:139], v140 offset:2048
	ds_read_b128 v[140:143], v140 offset:3072
	ds_read_b128 v[156:159], v175
	ds_read_b128 v[160:163], v175 offset:1024
	ds_read_b128 v[164:167], v175 offset:2048
	ds_read_b128 v[176:179], v175 offset:3072
	s_add_u32 s28, s36, 0x40000
	s_addc_u32 s29, s37, 0
	s_mov_b32 m0, s43
	v_lshl_add_u64 v[222:223], s[28:29], 0, v[144:145]
	ds_read_b128 v[180:183], v173 offset:32768
	ds_read_b128 v[184:187], v173 offset:33792
	ds_read_b128 v[192:195], v173 offset:34816
	ds_read_b128 v[196:199], v173 offset:35840
	ds_read_b128 v[200:203], v173 offset:36864
	ds_read_b128 v[204:207], v173 offset:37888
	ds_read_b128 v[208:211], v173 offset:38912
	ds_read_b128 v[212:215], v173 offset:39936
	global_load_lds_dwordx4 v[222:223], off
	v_lshl_add_u64 v[222:223], s[28:29], 0, v[146:147]
	s_mov_b32 m0, s44
	s_nop 0
	global_load_lds_dwordx4 v[222:223], off
	s_waitcnt vmcnt(8)
	s_waitcnt lgkmcnt(0)
	s_barrier
	s_setprio 1
	s_waitcnt lgkmcnt(0)
	v_mfma_f32_16x16x32_bf16 v[124:127], v[128:131], v[180:183], v[124:127]
	v_mfma_f32_16x16x32_bf16 v[120:123], v[136:139], v[180:183], v[120:123]
	v_mfma_f32_16x16x32_bf16 v[108:111], v[128:131], v[192:195], v[108:111]
	v_mfma_f32_16x16x32_bf16 v[104:107], v[136:139], v[192:195], v[104:107]
	v_mfma_f32_16x16x32_bf16 v[92:95], v[128:131], v[200:203], v[92:95]
	v_mfma_f32_16x16x32_bf16 v[88:91], v[136:139], v[200:203], v[88:91]
	v_mfma_f32_16x16x32_bf16 v[76:79], v[128:131], v[208:211], v[76:79]
	v_mfma_f32_16x16x32_bf16 v[72:75], v[136:139], v[208:211], v[72:75]
	v_mfma_f32_16x16x32_bf16 v[124:127], v[132:135], v[184:187], v[124:127]
	v_mfma_f32_16x16x32_bf16 v[120:123], v[140:143], v[184:187], v[120:123]
	v_mfma_f32_16x16x32_bf16 v[108:111], v[132:135], v[196:199], v[108:111]
	v_mfma_f32_16x16x32_bf16 v[104:107], v[140:143], v[196:199], v[104:107]
	v_mfma_f32_16x16x32_bf16 v[92:95], v[132:135], v[204:207], v[92:95]
	v_mfma_f32_16x16x32_bf16 v[88:91], v[140:143], v[204:207], v[88:91]
	v_mfma_f32_16x16x32_bf16 v[76:79], v[132:135], v[212:215], v[76:79]
	v_mfma_f32_16x16x32_bf16 v[72:75], v[140:143], v[212:215], v[72:75]
	s_setprio 0
	s_setprio 1
	v_mfma_f32_16x16x32_bf16 v[116:119], v[156:159], v[180:183], v[116:119]
	v_mfma_f32_16x16x32_bf16 v[112:115], v[164:167], v[180:183], v[112:115]
	v_mfma_f32_16x16x32_bf16 v[100:103], v[156:159], v[192:195], v[100:103]
	v_mfma_f32_16x16x32_bf16 v[96:99], v[164:167], v[192:195], v[96:99]
	v_mfma_f32_16x16x32_bf16 v[84:87], v[156:159], v[200:203], v[84:87]
	v_mfma_f32_16x16x32_bf16 v[80:83], v[164:167], v[200:203], v[80:83]
	v_mfma_f32_16x16x32_bf16 v[68:71], v[156:159], v[208:211], v[68:71]
	v_mfma_f32_16x16x32_bf16 v[64:67], v[164:167], v[208:211], v[64:67]
	v_mfma_f32_16x16x32_bf16 v[116:119], v[160:163], v[184:187], v[116:119]
	v_mfma_f32_16x16x32_bf16 v[112:115], v[176:179], v[184:187], v[112:115]
	v_mfma_f32_16x16x32_bf16 v[100:103], v[160:163], v[196:199], v[100:103]
	v_mfma_f32_16x16x32_bf16 v[96:99], v[176:179], v[196:199], v[96:99]
	v_mfma_f32_16x16x32_bf16 v[84:87], v[160:163], v[204:207], v[84:87]
	v_mfma_f32_16x16x32_bf16 v[80:83], v[176:179], v[204:207], v[80:83]
	v_mfma_f32_16x16x32_bf16 v[68:71], v[160:163], v[212:215], v[68:71]
	v_mfma_f32_16x16x32_bf16 v[64:67], v[176:179], v[212:215], v[64:67]
	s_setprio 0
	s_barrier
	s_add_i32 s28, s58, s41
	v_lshl_add_u64 v[188:189], v[188:189], 0, s[12:13]
	s_mov_b32 m0, s28
	ds_read_b128 v[180:183], v173 offset:49152
	ds_read_b128 v[184:187], v173 offset:50176
	ds_read_b128 v[192:195], v173 offset:51200
	ds_read_b128 v[196:199], v173 offset:52224
	ds_read_b128 v[200:203], v173 offset:53248
	ds_read_b128 v[204:207], v173 offset:54272
	ds_read_b128 v[208:211], v173 offset:55296
	ds_read_b128 v[212:215], v173 offset:56320
	global_load_lds_dwordx4 v[188:189], off
	s_add_i32 m0, s28, 0x2000
	s_add_u32 s28, s34, 0x40080
	v_lshl_add_u64 v[188:189], v[216:217], 0, s[12:13]
	s_addc_u32 s29, s35, 0
	s_add_i32 s34, s59, s41
	global_load_lds_dwordx4 v[188:189], off
	v_lshl_add_u64 v[188:189], s[28:29], 0, v[144:145]
	s_mov_b32 m0, s34
	s_nop 0
	global_load_lds_dwordx4 v[188:189], off
	v_lshl_add_u64 v[188:189], s[28:29], 0, v[146:147]
	s_add_i32 m0, s34, 0x2000
	s_nop 0
	global_load_lds_dwordx4 v[188:189], off
	v_lshl_add_u64 v[188:189], v[218:219], 0, s[12:13]
	s_mov_b32 m0, s46
	s_nop 0
	global_load_lds_dwordx4 v[188:189], off
	v_lshl_add_u64 v[188:189], v[220:221], 0, s[12:13]
	s_mov_b32 m0, s47
	s_nop 0
	global_load_lds_dwordx4 v[188:189], off
	s_waitcnt vmcnt(8)
	s_waitcnt lgkmcnt(0)
	s_barrier
	s_setprio 1
	s_waitcnt lgkmcnt(0)
	v_mfma_f32_16x16x32_bf16 v[60:63], v[128:131], v[180:183], v[60:63]
	v_mfma_f32_16x16x32_bf16 v[56:59], v[136:139], v[180:183], v[56:59]
	v_mfma_f32_16x16x32_bf16 v[44:47], v[128:131], v[192:195], v[44:47]
	v_mfma_f32_16x16x32_bf16 v[40:43], v[136:139], v[192:195], v[40:43]
	v_mfma_f32_16x16x32_bf16 v[28:31], v[128:131], v[200:203], v[28:31]
	v_mfma_f32_16x16x32_bf16 v[24:27], v[136:139], v[200:203], v[24:27]
	v_mfma_f32_16x16x32_bf16 v[12:15], v[128:131], v[208:211], v[12:15]
	v_mfma_f32_16x16x32_bf16 v[8:11], v[136:139], v[208:211], v[8:11]
	v_mfma_f32_16x16x32_bf16 v[60:63], v[132:135], v[184:187], v[60:63]
	v_mfma_f32_16x16x32_bf16 v[56:59], v[140:143], v[184:187], v[56:59]
	v_mfma_f32_16x16x32_bf16 v[44:47], v[132:135], v[196:199], v[44:47]
	v_mfma_f32_16x16x32_bf16 v[40:43], v[140:143], v[196:199], v[40:43]
	v_mfma_f32_16x16x32_bf16 v[28:31], v[132:135], v[204:207], v[28:31]
	v_mfma_f32_16x16x32_bf16 v[24:27], v[140:143], v[204:207], v[24:27]
	v_mfma_f32_16x16x32_bf16 v[12:15], v[132:135], v[212:215], v[12:15]
	v_mfma_f32_16x16x32_bf16 v[8:11], v[140:143], v[212:215], v[8:11]
	s_setprio 0
	s_setprio 1
	v_mfma_f32_16x16x32_bf16 v[52:55], v[156:159], v[180:183], v[52:55]
	v_mfma_f32_16x16x32_bf16 v[48:51], v[164:167], v[180:183], v[48:51]
	v_mfma_f32_16x16x32_bf16 v[36:39], v[156:159], v[192:195], v[36:39]
	v_mfma_f32_16x16x32_bf16 v[32:35], v[164:167], v[192:195], v[32:35]
	v_mfma_f32_16x16x32_bf16 v[20:23], v[156:159], v[200:203], v[20:23]
	v_mfma_f32_16x16x32_bf16 v[16:19], v[164:167], v[200:203], v[16:19]
	v_mfma_f32_16x16x32_bf16 v[4:7], v[156:159], v[208:211], v[4:7]
	v_mfma_f32_16x16x32_bf16 v[0:3], v[164:167], v[208:211], v[0:3]
	v_mfma_f32_16x16x32_bf16 v[52:55], v[160:163], v[184:187], v[52:55]
	v_mfma_f32_16x16x32_bf16 v[48:51], v[176:179], v[184:187], v[48:51]
	v_mfma_f32_16x16x32_bf16 v[36:39], v[160:163], v[196:199], v[36:39]
	v_mfma_f32_16x16x32_bf16 v[32:35], v[176:179], v[196:199], v[32:35]
	v_mfma_f32_16x16x32_bf16 v[20:23], v[160:163], v[204:207], v[20:23]
	v_mfma_f32_16x16x32_bf16 v[16:19], v[176:179], v[204:207], v[16:19]
	v_mfma_f32_16x16x32_bf16 v[4:7], v[160:163], v[212:215], v[4:7]
	v_mfma_f32_16x16x32_bf16 v[0:3], v[176:179], v[212:215], v[0:3]
	s_setprio 0
	s_barrier
	s_add_i32 s57, s57, 2
	s_add_u32 s55, s55, 0x100
	s_addc_u32 s56, s56, 0
	s_cmp_gt_u32 s57, 13
	s_mov_b64 s[28:29], s[30:31]
	s_cbranch_scc0 .LBB0_1810
	v_mbcnt_lo_u32_b32 v235, -1, 0
	v_mbcnt_hi_u32_b32 v235, -1, v235
	v_lshrrev_b32_e32 v236, 2, v235
	v_and_b32_e32 v237, 3, v235
	v_lshl_add_u32 v232, v237, 4, v236
	v_lshlrev_b32_e32 v232, 2, v232
	v_and_b32_e32 v233, -16, v168
	v_or_b32_e32 v233, v233, v236
	v_lshlrev_b32_e32 v237, 2, v237
	v_and_b32_e32 v234, -13, v170
	v_or_b32_e32 v234, v234, v237
	ds_bpermute_b32 v127, v232, v127
	ds_bpermute_b32 v126, v232, v126
	ds_bpermute_b32 v125, v232, v125
	ds_bpermute_b32 v124, v232, v124
	ds_bpermute_b32 v123, v232, v123
	ds_bpermute_b32 v122, v232, v122
	ds_bpermute_b32 v121, v232, v121
	ds_bpermute_b32 v120, v232, v120
	ds_bpermute_b32 v119, v232, v119
	ds_bpermute_b32 v118, v232, v118
	ds_bpermute_b32 v117, v232, v117
	ds_bpermute_b32 v116, v232, v116
	ds_bpermute_b32 v115, v232, v115
	ds_bpermute_b32 v114, v232, v114
	ds_bpermute_b32 v113, v232, v113
	ds_bpermute_b32 v112, v232, v112
	ds_bpermute_b32 v111, v232, v111
	ds_bpermute_b32 v110, v232, v110
	ds_bpermute_b32 v109, v232, v109
	ds_bpermute_b32 v108, v232, v108
	ds_bpermute_b32 v107, v232, v107
	ds_bpermute_b32 v106, v232, v106
	ds_bpermute_b32 v105, v232, v105
	ds_bpermute_b32 v104, v232, v104
	ds_bpermute_b32 v103, v232, v103
	ds_bpermute_b32 v102, v232, v102
	ds_bpermute_b32 v101, v232, v101
	ds_bpermute_b32 v100, v232, v100
	ds_bpermute_b32 v99, v232, v99
	ds_bpermute_b32 v98, v232, v98
	ds_bpermute_b32 v97, v232, v97
	ds_bpermute_b32 v96, v232, v96
	ds_bpermute_b32 v95, v232, v95
	ds_bpermute_b32 v94, v232, v94
	ds_bpermute_b32 v93, v232, v93
	ds_bpermute_b32 v92, v232, v92
	ds_bpermute_b32 v91, v232, v91
	ds_bpermute_b32 v90, v232, v90
	ds_bpermute_b32 v89, v232, v89
	ds_bpermute_b32 v88, v232, v88
	ds_bpermute_b32 v87, v232, v87
	ds_bpermute_b32 v86, v232, v86
	ds_bpermute_b32 v85, v232, v85
	ds_bpermute_b32 v84, v232, v84
	ds_bpermute_b32 v83, v232, v83
	ds_bpermute_b32 v82, v232, v82
	ds_bpermute_b32 v81, v232, v81
	ds_bpermute_b32 v80, v232, v80
	ds_bpermute_b32 v79, v232, v79
	ds_bpermute_b32 v78, v232, v78
	ds_bpermute_b32 v77, v232, v77
	ds_bpermute_b32 v76, v232, v76
	ds_bpermute_b32 v75, v232, v75
	ds_bpermute_b32 v74, v232, v74
	ds_bpermute_b32 v73, v232, v73
	ds_bpermute_b32 v72, v232, v72
	ds_bpermute_b32 v71, v232, v71
	ds_bpermute_b32 v70, v232, v70
	ds_bpermute_b32 v69, v232, v69
	ds_bpermute_b32 v68, v232, v68
	ds_bpermute_b32 v67, v232, v67
	ds_bpermute_b32 v66, v232, v66
	ds_bpermute_b32 v65, v232, v65
	ds_bpermute_b32 v64, v232, v64
	ds_bpermute_b32 v63, v232, v63
	ds_bpermute_b32 v62, v232, v62
	ds_bpermute_b32 v61, v232, v61
	ds_bpermute_b32 v60, v232, v60
	ds_bpermute_b32 v59, v232, v59
	ds_bpermute_b32 v58, v232, v58
	ds_bpermute_b32 v57, v232, v57
	ds_bpermute_b32 v56, v232, v56
	ds_bpermute_b32 v55, v232, v55
	ds_bpermute_b32 v54, v232, v54
	ds_bpermute_b32 v53, v232, v53
	ds_bpermute_b32 v52, v232, v52
	ds_bpermute_b32 v51, v232, v51
	ds_bpermute_b32 v50, v232, v50
	ds_bpermute_b32 v49, v232, v49
	ds_bpermute_b32 v48, v232, v48
	ds_bpermute_b32 v47, v232, v47
	ds_bpermute_b32 v46, v232, v46
	ds_bpermute_b32 v45, v232, v45
	ds_bpermute_b32 v44, v232, v44
	ds_bpermute_b32 v43, v232, v43
	ds_bpermute_b32 v42, v232, v42
	ds_bpermute_b32 v41, v232, v41
	ds_bpermute_b32 v40, v232, v40
	ds_bpermute_b32 v39, v232, v39
	ds_bpermute_b32 v38, v232, v38
	ds_bpermute_b32 v37, v232, v37
	ds_bpermute_b32 v36, v232, v36
	ds_bpermute_b32 v35, v232, v35
	ds_bpermute_b32 v34, v232, v34
	ds_bpermute_b32 v33, v232, v33
	ds_bpermute_b32 v32, v232, v32
	ds_bpermute_b32 v31, v232, v31
	ds_bpermute_b32 v30, v232, v30
	ds_bpermute_b32 v29, v232, v29
	ds_bpermute_b32 v28, v232, v28
	ds_bpermute_b32 v27, v232, v27
	ds_bpermute_b32 v26, v232, v26
	ds_bpermute_b32 v25, v232, v25
	ds_bpermute_b32 v24, v232, v24
	ds_bpermute_b32 v23, v232, v23
	ds_bpermute_b32 v22, v232, v22
	ds_bpermute_b32 v21, v232, v21
	ds_bpermute_b32 v20, v232, v20
	ds_bpermute_b32 v19, v232, v19
	ds_bpermute_b32 v18, v232, v18
	ds_bpermute_b32 v17, v232, v17
	ds_bpermute_b32 v16, v232, v16
	ds_bpermute_b32 v15, v232, v15
	ds_bpermute_b32 v14, v232, v14
	ds_bpermute_b32 v13, v232, v13
	ds_bpermute_b32 v12, v232, v12
	ds_bpermute_b32 v11, v232, v11
	ds_bpermute_b32 v10, v232, v10
	ds_bpermute_b32 v9, v232, v9
	ds_bpermute_b32 v8, v232, v8
	ds_bpermute_b32 v7, v232, v7
	ds_bpermute_b32 v6, v232, v6
	ds_bpermute_b32 v5, v232, v5
	ds_bpermute_b32 v4, v232, v4
	ds_bpermute_b32 v3, v232, v3
	ds_bpermute_b32 v2, v232, v2
	ds_bpermute_b32 v1, v232, v1
	ds_bpermute_b32 v0, v232, v0
	s_waitcnt lgkmcnt(0)
	v_lshl_add_u32 v158, s24, 8, v233
	v_lshl_or_b32 v156, s26, 8, v234
	v_ashrrev_i32_e32 v159, 31, v158
	v_lshlrev_b64 v[128:129], 12, v[158:159]
	v_ashrrev_i32_e32 v157, 31, v156
	v_lshl_add_u64 v[128:129], s[0:1], 0, v[128:129]
	v_lshlrev_b64 v[130:131], 2, v[156:157]
	v_lshl_add_u64 v[188:189], v[128:129], 0, v[130:131]
	global_load_dwordx4 v[164:167], v[188:189], off
	global_load_dwordx4 v[176:179], v[188:189], off offset:64
	global_load_dwordx4 v[180:183], v[188:189], off offset:512
	global_load_dwordx4 v[184:187], v[188:189], off offset:576
	v_or_b32_e32 v160, 16, v158
	v_ashrrev_i32_e32 v161, 31, v160
	v_lshlrev_b64 v[128:129], 12, v[160:161]
	v_lshl_add_u64 v[128:129], s[0:1], 0, v[128:129]
	v_lshl_add_u64 v[162:163], v[128:129], 0, v[130:131]
	global_load_dwordx4 v[140:143], v[162:163], off
	global_load_dwordx4 v[136:139], v[162:163], off offset:64
	global_load_dwordx4 v[132:135], v[162:163], off offset:512
	global_load_dwordx4 v[128:131], v[162:163], off offset:576
	v_lshlrev_b64 v[192:193], 11, v[158:159]
	v_lshl_add_u64 v[192:193], s[8:9], 0, v[192:193]
	v_and_b32_e32 v191, 64, v174
	v_lshl_add_u64 v[192:193], v[156:157], 1, v[192:193]
	v_xor_b32_e32 v175, 1, v174
	v_add_u32_e32 v191, 64, v191
	v_cmp_lt_i32_e32 vcc, v175, v191
	v_xor_b32_e32 v194, 2, v174
	s_waitcnt lgkmcnt(0)
	s_cmp_eq_u64 s[14:15], 0
	s_cbranch_scc1 .LBB0_1813
	s_barrier
.LBB0_1813:
	s_waitcnt vmcnt(7)
	v_pk_add_f32 v[126:127], v[126:127], v[166:167]
	v_pk_add_f32 v[124:125], v[124:125], v[164:165]
	s_waitcnt vmcnt(6)
	v_pk_add_f32 v[122:123], v[122:123], v[178:179]
	v_pk_add_f32 v[120:121], v[120:121], v[176:177]
	s_waitcnt vmcnt(5)
	v_pk_add_f32 v[118:119], v[118:119], v[182:183]
	v_pk_add_f32 v[116:117], v[116:117], v[180:181]
	s_waitcnt vmcnt(4)
	v_pk_add_f32 v[164:165], v[112:113], v[184:185]
	v_mul_f32_e32 v178, v125, v125
	v_mul_f32_e32 v179, v127, v127
	global_store_dwordx4 v[188:189], v[124:127], off
	v_cvt_pk_bf16_f32 v112, v124, v125
	v_cvt_pk_bf16_f32 v113, v126, v127
	v_mul_f32_e32 v125, v121, v121
	v_mul_f32_e32 v127, v123, v123
	v_pk_add_f32 v[166:167], v[114:115], v[186:187]
	v_mul_f32_e32 v180, v117, v117
	v_mul_f32_e32 v181, v119, v119
	v_fmac_f32_e32 v178, v124, v124
	v_fmac_f32_e32 v179, v126, v126
	v_fmac_f32_e32 v125, v120, v120
	v_fmac_f32_e32 v127, v122, v122
	v_mul_f32_e32 v182, v165, v165
	v_mul_f32_e32 v183, v167, v167
	global_store_dwordx2 v[192:193], v[112:113], off
	v_fmac_f32_e32 v180, v116, v116
	v_fmac_f32_e32 v181, v118, v118
	v_add_f32_e32 v112, v178, v179
	v_add_f32_e32 v113, v125, v127
	v_fmac_f32_e32 v182, v164, v164
	v_fmac_f32_e32 v183, v166, v166
	v_add_f32_e32 v124, v180, v181
	v_add_f32_e32 v112, v112, v113
	v_cndmask_b32_e32 v175, v174, v175, vcc
	v_add_f32_e32 v125, v182, v183
	v_add_f32_e32 v112, v112, v124
	v_lshlrev_b32_e32 v175, 2, v175
	v_add_f32_e32 v112, v112, v125
	ds_bpermute_b32 v113, v175, v112
	v_cmp_lt_i32_e32 vcc, v194, v191
	v_cvt_pk_bf16_f32 v176, v116, v117
	v_cvt_pk_bf16_f32 v114, v120, v121
	v_cndmask_b32_e32 v191, v174, v194, vcc
	v_cvt_pk_bf16_f32 v115, v122, v123
	v_cvt_pk_bf16_f32 v177, v118, v119
	global_store_dwordx4 v[188:189], v[120:123], off offset:64
	global_store_dwordx2 v[192:193], v[114:115], off offset:32
	global_store_dwordx4 v[188:189], v[116:119], off offset:512
	global_store_dwordx2 v[192:193], v[176:177], off offset:256
	s_waitcnt lgkmcnt(0)
	v_add_f32_e32 v112, v112, v113
	v_lshlrev_b32_e32 v176, 2, v191
	ds_bpermute_b32 v113, v176, v112
	v_cvt_pk_bf16_f32 v114, v164, v165
	v_cvt_pk_bf16_f32 v115, v166, v167
	global_store_dwordx4 v[188:189], v[164:167], off offset:576
	global_store_dwordx2 v[192:193], v[114:115], off offset:288
	s_mov_b32 vcc_lo, 0x11111111
	s_mov_b32 vcc_hi, 0x11111111
	s_and_saveexec_b64 s[24:25], vcc
	s_cbranch_execz .LBB0_1815
	v_lshl_add_u64 v[114:115], v[158:159], 2, s[10:11]
	s_waitcnt lgkmcnt(0)
	v_add_f32_e32 v112, v112, v113
	global_atomic_add_f32 v[114:115], v112, off
.LBB0_1815:
	s_or_b64 exec, exec, s[24:25]
	v_or_b32_e32 v164, 32, v158
	v_ashrrev_i32_e32 v165, 31, v164
	s_waitcnt lgkmcnt(0)
	v_lshlrev_b64 v[112:113], 12, v[164:165]
	v_lshl_add_u64 v[112:113], s[0:1], 0, v[112:113]
	v_lshl_add_u64 v[166:167], v[156:157], 2, v[112:113]
	global_load_dwordx4 v[124:127], v[166:167], off
	global_load_dwordx4 v[120:123], v[166:167], off offset:64
	global_load_dwordx4 v[116:119], v[166:167], off offset:512
	global_load_dwordx4 v[112:115], v[166:167], off offset:576
	s_waitcnt vmcnt(15)
	v_pk_add_f32 v[110:111], v[110:111], v[142:143]
	v_pk_add_f32 v[108:109], v[108:109], v[140:141]
	v_mul_f32_e32 v141, v111, v111
	v_mul_f32_e32 v140, v109, v109
	v_fmac_f32_e32 v140, v108, v108
	v_fmac_f32_e32 v141, v110, v110
	v_add_f32_e32 v142, v140, v141
	v_lshlrev_b64 v[140:141], 11, v[160:161]
	v_lshl_add_u64 v[140:141], s[8:9], 0, v[140:141]
	global_store_dwordx4 v[162:163], v[108:111], off
	v_lshl_add_u64 v[140:141], v[156:157], 1, v[140:141]
	s_waitcnt vmcnt(15)
	v_pk_add_f32 v[104:105], v[104:105], v[136:137]
	v_cvt_pk_bf16_f32 v108, v108, v109
	v_cvt_pk_bf16_f32 v109, v110, v111
	global_store_dwordx2 v[140:141], v[108:109], off
	v_pk_add_f32 v[106:107], v[106:107], v[138:139]
	v_mul_f32_e32 v108, v105, v105
	v_fmac_f32_e32 v108, v104, v104
	v_mul_f32_e32 v109, v107, v107
	global_store_dwordx4 v[162:163], v[104:107], off offset:64
	s_waitcnt vmcnt(16)
	v_pk_add_f32 v[102:103], v[102:103], v[134:135]
	v_pk_add_f32 v[100:101], v[100:101], v[132:133]
	v_cvt_pk_bf16_f32 v104, v104, v105
	v_cvt_pk_bf16_f32 v105, v106, v107
	v_fmac_f32_e32 v109, v106, v106
	global_store_dwordx2 v[140:141], v[104:105], off offset:32
	v_mul_f32_e32 v104, v101, v101
	v_mul_f32_e32 v105, v103, v103
	v_add_f32_e32 v108, v108, v109
	v_fmac_f32_e32 v104, v100, v100
	v_fmac_f32_e32 v105, v102, v102
	v_add_f32_e32 v108, v142, v108
	v_add_f32_e32 v104, v104, v105
	v_add_f32_e32 v108, v108, v104
	s_waitcnt vmcnt(16)
	v_pk_add_f32 v[106:107], v[98:99], v[130:131]
	v_pk_add_f32 v[104:105], v[96:97], v[128:129]
	v_mul_f32_e32 v97, v107, v107
	v_mul_f32_e32 v96, v105, v105
	v_fmac_f32_e32 v96, v104, v104
	v_fmac_f32_e32 v97, v106, v106
	v_add_f32_e32 v96, v96, v97
	v_add_f32_e32 v98, v108, v96
	ds_bpermute_b32 v99, v175, v98
	v_cvt_pk_bf16_f32 v96, v100, v101
	v_cvt_pk_bf16_f32 v97, v102, v103
	global_store_dwordx4 v[162:163], v[100:103], off offset:512
	global_store_dwordx2 v[140:141], v[96:97], off offset:256
	s_waitcnt lgkmcnt(0)
	v_add_f32_e32 v96, v98, v99
	ds_bpermute_b32 v97, v176, v96
	v_cvt_pk_bf16_f32 v98, v104, v105
	v_cvt_pk_bf16_f32 v99, v106, v107
	global_store_dwordx4 v[162:163], v[104:107], off offset:576
	global_store_dwordx2 v[140:141], v[98:99], off offset:288
	s_mov_b32 vcc_lo, 0x11111111
	s_mov_b32 vcc_hi, 0x11111111
	s_and_saveexec_b64 s[24:25], vcc
	s_cbranch_execz .LBB0_1817
	v_lshl_add_u64 v[98:99], v[160:161], 2, s[10:11]
	s_waitcnt lgkmcnt(0)
	v_add_f32_e32 v96, v96, v97
	global_atomic_add_f32 v[98:99], v96, off
.LBB0_1817:
	s_or_b64 exec, exec, s[24:25]
	v_or_b32_e32 v128, 48, v158
	v_ashrrev_i32_e32 v129, 31, v128
	s_waitcnt lgkmcnt(0)
	v_lshlrev_b64 v[96:97], 12, v[128:129]
	v_lshl_add_u64 v[96:97], s[0:1], 0, v[96:97]
	v_lshl_add_u64 v[130:131], v[156:157], 2, v[96:97]
	global_load_dwordx4 v[108:111], v[130:131], off
	global_load_dwordx4 v[104:107], v[130:131], off offset:64
	global_load_dwordx4 v[100:103], v[130:131], off offset:512
	global_load_dwordx4 v[96:99], v[130:131], off offset:576
	s_waitcnt vmcnt(15)
	v_pk_add_f32 v[94:95], v[94:95], v[126:127]
	v_pk_add_f32 v[92:93], v[92:93], v[124:125]
	v_mul_f32_e32 v125, v95, v95
	v_mul_f32_e32 v124, v93, v93
	v_fmac_f32_e32 v124, v92, v92
	v_fmac_f32_e32 v125, v94, v94
	v_add_f32_e32 v126, v124, v125
	v_lshlrev_b64 v[124:125], 11, v[164:165]
	v_lshl_add_u64 v[124:125], s[8:9], 0, v[124:125]
	global_store_dwordx4 v[166:167], v[92:95], off
	v_lshl_add_u64 v[124:125], v[156:157], 1, v[124:125]
	s_waitcnt vmcnt(15)
	v_pk_add_f32 v[88:89], v[88:89], v[120:121]
	v_cvt_pk_bf16_f32 v92, v92, v93
	v_cvt_pk_bf16_f32 v93, v94, v95
	global_store_dwordx2 v[124:125], v[92:93], off
	v_pk_add_f32 v[90:91], v[90:91], v[122:123]
	v_mul_f32_e32 v92, v89, v89
	v_fmac_f32_e32 v92, v88, v88
	v_mul_f32_e32 v93, v91, v91
	global_store_dwordx4 v[166:167], v[88:91], off offset:64
	s_waitcnt vmcnt(16)
	v_pk_add_f32 v[86:87], v[86:87], v[118:119]
	v_pk_add_f32 v[84:85], v[84:85], v[116:117]
	v_cvt_pk_bf16_f32 v88, v88, v89
	v_cvt_pk_bf16_f32 v89, v90, v91
	v_fmac_f32_e32 v93, v90, v90
	global_store_dwordx2 v[124:125], v[88:89], off offset:32
	v_mul_f32_e32 v88, v85, v85
	v_mul_f32_e32 v89, v87, v87
	v_add_f32_e32 v92, v92, v93
	v_fmac_f32_e32 v88, v84, v84
	v_fmac_f32_e32 v89, v86, v86
	v_add_f32_e32 v92, v126, v92
	v_add_f32_e32 v88, v88, v89
	v_add_f32_e32 v92, v92, v88
	s_waitcnt vmcnt(16)
	v_pk_add_f32 v[90:91], v[82:83], v[114:115]
	v_pk_add_f32 v[88:89], v[80:81], v[112:113]
	v_mul_f32_e32 v81, v91, v91
	v_mul_f32_e32 v80, v89, v89
	v_fmac_f32_e32 v80, v88, v88
	v_fmac_f32_e32 v81, v90, v90
	v_add_f32_e32 v80, v80, v81
	v_add_f32_e32 v82, v92, v80
	ds_bpermute_b32 v83, v175, v82
	v_cvt_pk_bf16_f32 v80, v84, v85
	v_cvt_pk_bf16_f32 v81, v86, v87
	global_store_dwordx4 v[166:167], v[84:87], off offset:512
	global_store_dwordx2 v[124:125], v[80:81], off offset:256
	s_waitcnt lgkmcnt(0)
	v_add_f32_e32 v80, v82, v83
	ds_bpermute_b32 v81, v176, v80
	v_cvt_pk_bf16_f32 v82, v88, v89
	v_cvt_pk_bf16_f32 v83, v90, v91
	global_store_dwordx4 v[166:167], v[88:91], off offset:576
	global_store_dwordx2 v[124:125], v[82:83], off offset:288
	s_mov_b32 vcc_lo, 0x11111111
	s_mov_b32 vcc_hi, 0x11111111
	s_and_saveexec_b64 s[24:25], vcc
	s_cbranch_execz .LBB0_1819
	v_lshl_add_u64 v[82:83], v[164:165], 2, s[10:11]
	s_waitcnt lgkmcnt(0)
	v_add_f32_e32 v80, v80, v81
	global_atomic_add_f32 v[82:83], v80, off
.LBB0_1819:
	s_or_b64 exec, exec, s[24:25]
	v_add_u32_e32 v112, 0x80, v158
	v_ashrrev_i32_e32 v113, 31, v112
	s_waitcnt lgkmcnt(0)
	v_lshlrev_b64 v[80:81], 12, v[112:113]
	v_lshl_add_u64 v[80:81], s[0:1], 0, v[80:81]
	v_lshl_add_u64 v[114:115], v[156:157], 2, v[80:81]
	global_load_dwordx4 v[92:95], v[114:115], off
	global_load_dwordx4 v[88:91], v[114:115], off offset:64
	global_load_dwordx4 v[84:87], v[114:115], off offset:512
	global_load_dwordx4 v[80:83], v[114:115], off offset:576
	s_waitcnt vmcnt(15)
	v_pk_add_f32 v[78:79], v[78:79], v[110:111]
	v_pk_add_f32 v[76:77], v[76:77], v[108:109]
	v_mul_f32_e32 v109, v79, v79
	v_mul_f32_e32 v108, v77, v77
	v_fmac_f32_e32 v108, v76, v76
	v_fmac_f32_e32 v109, v78, v78
	v_add_f32_e32 v110, v108, v109
	v_lshlrev_b64 v[108:109], 11, v[128:129]
	v_lshl_add_u64 v[108:109], s[8:9], 0, v[108:109]
	global_store_dwordx4 v[130:131], v[76:79], off
	v_lshl_add_u64 v[108:109], v[156:157], 1, v[108:109]
	s_waitcnt vmcnt(15)
	v_pk_add_f32 v[72:73], v[72:73], v[104:105]
	v_cvt_pk_bf16_f32 v76, v76, v77
	v_cvt_pk_bf16_f32 v77, v78, v79
	global_store_dwordx2 v[108:109], v[76:77], off
	v_pk_add_f32 v[74:75], v[74:75], v[106:107]
	v_mul_f32_e32 v76, v73, v73
	v_fmac_f32_e32 v76, v72, v72
	v_mul_f32_e32 v77, v75, v75
	global_store_dwordx4 v[130:131], v[72:75], off offset:64
	s_waitcnt vmcnt(16)
	v_pk_add_f32 v[70:71], v[70:71], v[102:103]
	v_pk_add_f32 v[68:69], v[68:69], v[100:101]
	v_cvt_pk_bf16_f32 v72, v72, v73
	v_cvt_pk_bf16_f32 v73, v74, v75
	v_fmac_f32_e32 v77, v74, v74
	global_store_dwordx2 v[108:109], v[72:73], off offset:32
	v_mul_f32_e32 v72, v69, v69
	v_mul_f32_e32 v73, v71, v71
	v_add_f32_e32 v76, v76, v77
	v_fmac_f32_e32 v72, v68, v68
	v_fmac_f32_e32 v73, v70, v70
	v_add_f32_e32 v76, v110, v76
	v_add_f32_e32 v72, v72, v73
	v_add_f32_e32 v76, v76, v72
	s_waitcnt vmcnt(16)
	v_pk_add_f32 v[74:75], v[66:67], v[98:99]
	v_pk_add_f32 v[72:73], v[64:65], v[96:97]
	v_mul_f32_e32 v65, v75, v75
	v_mul_f32_e32 v64, v73, v73
	v_fmac_f32_e32 v64, v72, v72
	v_fmac_f32_e32 v65, v74, v74
	v_add_f32_e32 v64, v64, v65
	v_add_f32_e32 v66, v76, v64
	ds_bpermute_b32 v67, v175, v66
	v_cvt_pk_bf16_f32 v64, v68, v69
	v_cvt_pk_bf16_f32 v65, v70, v71
	global_store_dwordx4 v[130:131], v[68:71], off offset:512
	global_store_dwordx2 v[108:109], v[64:65], off offset:256
	s_waitcnt lgkmcnt(0)
	v_add_f32_e32 v64, v66, v67
	ds_bpermute_b32 v65, v176, v64
	v_cvt_pk_bf16_f32 v66, v72, v73
	v_cvt_pk_bf16_f32 v67, v74, v75
	global_store_dwordx4 v[130:131], v[72:75], off offset:576
	global_store_dwordx2 v[108:109], v[66:67], off offset:288
	s_mov_b32 vcc_lo, 0x11111111
	s_mov_b32 vcc_hi, 0x11111111
	s_and_saveexec_b64 s[24:25], vcc
	s_cbranch_execz .LBB0_1821
	v_lshl_add_u64 v[66:67], v[128:129], 2, s[10:11]
	s_waitcnt lgkmcnt(0)
	v_add_f32_e32 v64, v64, v65
	global_atomic_add_f32 v[66:67], v64, off
.LBB0_1821:
	s_or_b64 exec, exec, s[24:25]
	v_or_b32_e32 v96, 16, v112
	v_ashrrev_i32_e32 v97, 31, v96
	s_waitcnt lgkmcnt(0)
	v_lshlrev_b64 v[64:65], 12, v[96:97]
	v_lshl_add_u64 v[64:65], s[0:1], 0, v[64:65]
	v_lshl_add_u64 v[98:99], v[156:157], 2, v[64:65]
	global_load_dwordx4 v[76:79], v[98:99], off
	global_load_dwordx4 v[72:75], v[98:99], off offset:64
	global_load_dwordx4 v[68:71], v[98:99], off offset:512
	global_load_dwordx4 v[64:67], v[98:99], off offset:576
	s_waitcnt vmcnt(15)
	v_pk_add_f32 v[62:63], v[62:63], v[94:95]
	v_pk_add_f32 v[60:61], v[60:61], v[92:93]
	v_mul_f32_e32 v93, v63, v63
	v_mul_f32_e32 v92, v61, v61
	v_fmac_f32_e32 v92, v60, v60
	v_fmac_f32_e32 v93, v62, v62
	v_add_f32_e32 v94, v92, v93
	v_lshlrev_b64 v[92:93], 11, v[112:113]
	v_lshl_add_u64 v[92:93], s[8:9], 0, v[92:93]
	global_store_dwordx4 v[114:115], v[60:63], off
	v_lshl_add_u64 v[92:93], v[156:157], 1, v[92:93]
	s_waitcnt vmcnt(15)
	v_pk_add_f32 v[56:57], v[56:57], v[88:89]
	v_cvt_pk_bf16_f32 v60, v60, v61
	v_cvt_pk_bf16_f32 v61, v62, v63
	global_store_dwordx2 v[92:93], v[60:61], off
	v_pk_add_f32 v[58:59], v[58:59], v[90:91]
	v_mul_f32_e32 v60, v57, v57
	v_fmac_f32_e32 v60, v56, v56
	v_mul_f32_e32 v61, v59, v59
	global_store_dwordx4 v[114:115], v[56:59], off offset:64
	s_waitcnt vmcnt(16)
	v_pk_add_f32 v[54:55], v[54:55], v[86:87]
	v_pk_add_f32 v[52:53], v[52:53], v[84:85]
	v_cvt_pk_bf16_f32 v56, v56, v57
	v_cvt_pk_bf16_f32 v57, v58, v59
	v_fmac_f32_e32 v61, v58, v58
	global_store_dwordx2 v[92:93], v[56:57], off offset:32
	v_mul_f32_e32 v56, v53, v53
	v_mul_f32_e32 v57, v55, v55
	v_add_f32_e32 v60, v60, v61
	v_fmac_f32_e32 v56, v52, v52
	v_fmac_f32_e32 v57, v54, v54
	v_add_f32_e32 v60, v94, v60
	v_add_f32_e32 v56, v56, v57
	v_add_f32_e32 v60, v60, v56
	s_waitcnt vmcnt(16)
	v_pk_add_f32 v[58:59], v[50:51], v[82:83]
	v_pk_add_f32 v[56:57], v[48:49], v[80:81]
	v_mul_f32_e32 v49, v59, v59
	v_mul_f32_e32 v48, v57, v57
	v_fmac_f32_e32 v48, v56, v56
	v_fmac_f32_e32 v49, v58, v58
	v_add_f32_e32 v48, v48, v49
	v_add_f32_e32 v50, v60, v48
	ds_bpermute_b32 v51, v175, v50
	v_cvt_pk_bf16_f32 v48, v52, v53
	v_cvt_pk_bf16_f32 v49, v54, v55
	global_store_dwordx4 v[114:115], v[52:55], off offset:512
	global_store_dwordx2 v[92:93], v[48:49], off offset:256
	s_waitcnt lgkmcnt(0)
	v_add_f32_e32 v48, v50, v51
	ds_bpermute_b32 v49, v176, v48
	v_cvt_pk_bf16_f32 v50, v56, v57
	v_cvt_pk_bf16_f32 v51, v58, v59
	global_store_dwordx4 v[114:115], v[56:59], off offset:576
	global_store_dwordx2 v[92:93], v[50:51], off offset:288
	s_mov_b32 vcc_lo, 0x11111111
	s_mov_b32 vcc_hi, 0x11111111
	s_and_saveexec_b64 s[24:25], vcc
	s_cbranch_execz .LBB0_1823
	v_lshl_add_u64 v[50:51], v[112:113], 2, s[10:11]
	s_waitcnt lgkmcnt(0)
	v_add_f32_e32 v48, v48, v49
	global_atomic_add_f32 v[50:51], v48, off
.LBB0_1823:
	s_or_b64 exec, exec, s[24:25]
	v_or_b32_e32 v80, 32, v112
	v_ashrrev_i32_e32 v81, 31, v80
	s_waitcnt lgkmcnt(0)
	v_lshlrev_b64 v[48:49], 12, v[80:81]
	v_lshl_add_u64 v[48:49], s[0:1], 0, v[48:49]
	v_lshl_add_u64 v[82:83], v[156:157], 2, v[48:49]
	global_load_dwordx4 v[60:63], v[82:83], off
	global_load_dwordx4 v[56:59], v[82:83], off offset:64
	global_load_dwordx4 v[52:55], v[82:83], off offset:512
	global_load_dwordx4 v[48:51], v[82:83], off offset:576
	s_waitcnt vmcnt(15)
	v_pk_add_f32 v[46:47], v[46:47], v[78:79]
	v_pk_add_f32 v[44:45], v[44:45], v[76:77]
	v_mul_f32_e32 v77, v47, v47
	v_mul_f32_e32 v76, v45, v45
	v_fmac_f32_e32 v76, v44, v44
	v_fmac_f32_e32 v77, v46, v46
	v_add_f32_e32 v78, v76, v77
	v_lshlrev_b64 v[76:77], 11, v[96:97]
	v_lshl_add_u64 v[76:77], s[8:9], 0, v[76:77]
	global_store_dwordx4 v[98:99], v[44:47], off
	v_lshl_add_u64 v[76:77], v[156:157], 1, v[76:77]
	s_waitcnt vmcnt(15)
	v_pk_add_f32 v[40:41], v[40:41], v[72:73]
	v_cvt_pk_bf16_f32 v44, v44, v45
	v_cvt_pk_bf16_f32 v45, v46, v47
	global_store_dwordx2 v[76:77], v[44:45], off
	v_pk_add_f32 v[42:43], v[42:43], v[74:75]
	v_mul_f32_e32 v44, v41, v41
	v_fmac_f32_e32 v44, v40, v40
	v_mul_f32_e32 v45, v43, v43
	global_store_dwordx4 v[98:99], v[40:43], off offset:64
	s_waitcnt vmcnt(16)
	v_pk_add_f32 v[38:39], v[38:39], v[70:71]
	v_pk_add_f32 v[36:37], v[36:37], v[68:69]
	v_cvt_pk_bf16_f32 v40, v40, v41
	v_cvt_pk_bf16_f32 v41, v42, v43
	v_fmac_f32_e32 v45, v42, v42
	global_store_dwordx2 v[76:77], v[40:41], off offset:32
	v_mul_f32_e32 v40, v37, v37
	v_mul_f32_e32 v41, v39, v39
	v_add_f32_e32 v44, v44, v45
	v_fmac_f32_e32 v40, v36, v36
	v_fmac_f32_e32 v41, v38, v38
	v_add_f32_e32 v44, v78, v44
	v_add_f32_e32 v40, v40, v41
	v_add_f32_e32 v44, v44, v40
	s_waitcnt vmcnt(16)
	v_pk_add_f32 v[42:43], v[34:35], v[66:67]
	v_pk_add_f32 v[40:41], v[32:33], v[64:65]
	v_mul_f32_e32 v33, v43, v43
	v_mul_f32_e32 v32, v41, v41
	v_fmac_f32_e32 v32, v40, v40
	v_fmac_f32_e32 v33, v42, v42
	v_add_f32_e32 v32, v32, v33
	v_add_f32_e32 v34, v44, v32
	ds_bpermute_b32 v35, v175, v34
	v_cvt_pk_bf16_f32 v32, v36, v37
	v_cvt_pk_bf16_f32 v33, v38, v39
	global_store_dwordx4 v[98:99], v[36:39], off offset:512
	global_store_dwordx2 v[76:77], v[32:33], off offset:256
	s_waitcnt lgkmcnt(0)
	v_add_f32_e32 v32, v34, v35
	ds_bpermute_b32 v33, v176, v32
	v_cvt_pk_bf16_f32 v34, v40, v41
	v_cvt_pk_bf16_f32 v35, v42, v43
	global_store_dwordx4 v[98:99], v[40:43], off offset:576
	global_store_dwordx2 v[76:77], v[34:35], off offset:288
	s_mov_b32 vcc_lo, 0x11111111
	s_mov_b32 vcc_hi, 0x11111111
	s_and_saveexec_b64 s[24:25], vcc
	s_cbranch_execz .LBB0_1825
	v_lshl_add_u64 v[34:35], v[96:97], 2, s[10:11]
	s_waitcnt lgkmcnt(0)
	v_add_f32_e32 v32, v32, v33
	global_atomic_add_f32 v[34:35], v32, off
.LBB0_1825:
	s_or_b64 exec, exec, s[24:25]
	v_or_b32_e32 v64, 48, v112
	v_ashrrev_i32_e32 v65, 31, v64
	s_waitcnt lgkmcnt(0)
	v_lshlrev_b64 v[32:33], 12, v[64:65]
	v_lshl_add_u64 v[32:33], s[0:1], 0, v[32:33]
	v_lshl_add_u64 v[66:67], v[156:157], 2, v[32:33]
	global_load_dwordx4 v[44:47], v[66:67], off
	global_load_dwordx4 v[40:43], v[66:67], off offset:64
	global_load_dwordx4 v[36:39], v[66:67], off offset:512
	global_load_dwordx4 v[32:35], v[66:67], off offset:576
	s_waitcnt vmcnt(15)
	v_pk_add_f32 v[30:31], v[30:31], v[62:63]
	v_pk_add_f32 v[28:29], v[28:29], v[60:61]
	v_mul_f32_e32 v61, v31, v31
	v_mul_f32_e32 v60, v29, v29
	v_fmac_f32_e32 v60, v28, v28
	v_fmac_f32_e32 v61, v30, v30
	v_add_f32_e32 v62, v60, v61
	v_lshlrev_b64 v[60:61], 11, v[80:81]
	v_lshl_add_u64 v[60:61], s[8:9], 0, v[60:61]
	global_store_dwordx4 v[82:83], v[28:31], off
	v_lshl_add_u64 v[60:61], v[156:157], 1, v[60:61]
	s_waitcnt vmcnt(15)
	v_pk_add_f32 v[24:25], v[24:25], v[56:57]
	v_cvt_pk_bf16_f32 v28, v28, v29
	v_cvt_pk_bf16_f32 v29, v30, v31
	global_store_dwordx2 v[60:61], v[28:29], off
	v_pk_add_f32 v[26:27], v[26:27], v[58:59]
	v_mul_f32_e32 v28, v25, v25
	v_fmac_f32_e32 v28, v24, v24
	v_mul_f32_e32 v29, v27, v27
	global_store_dwordx4 v[82:83], v[24:27], off offset:64
	s_waitcnt vmcnt(16)
	v_pk_add_f32 v[22:23], v[22:23], v[54:55]
	v_pk_add_f32 v[20:21], v[20:21], v[52:53]
	v_cvt_pk_bf16_f32 v24, v24, v25
	v_cvt_pk_bf16_f32 v25, v26, v27
	v_fmac_f32_e32 v29, v26, v26
	global_store_dwordx2 v[60:61], v[24:25], off offset:32
	v_mul_f32_e32 v24, v21, v21
	v_mul_f32_e32 v25, v23, v23
	v_add_f32_e32 v28, v28, v29
	v_fmac_f32_e32 v24, v20, v20
	v_fmac_f32_e32 v25, v22, v22
	v_add_f32_e32 v28, v62, v28
	v_add_f32_e32 v24, v24, v25
	v_add_f32_e32 v28, v28, v24
	s_waitcnt vmcnt(16)
	v_pk_add_f32 v[26:27], v[18:19], v[50:51]
	v_pk_add_f32 v[24:25], v[16:17], v[48:49]
	v_mul_f32_e32 v17, v27, v27
	v_mul_f32_e32 v16, v25, v25
	v_fmac_f32_e32 v16, v24, v24
	v_fmac_f32_e32 v17, v26, v26
	v_add_f32_e32 v16, v16, v17
	v_add_f32_e32 v18, v28, v16
	ds_bpermute_b32 v19, v175, v18
	v_cvt_pk_bf16_f32 v16, v20, v21
	v_cvt_pk_bf16_f32 v17, v22, v23
	global_store_dwordx4 v[82:83], v[20:23], off offset:512
	global_store_dwordx2 v[60:61], v[16:17], off offset:256
	s_waitcnt lgkmcnt(0)
	v_add_f32_e32 v16, v18, v19
	ds_bpermute_b32 v17, v176, v16
	v_cvt_pk_bf16_f32 v18, v24, v25
	v_cvt_pk_bf16_f32 v19, v26, v27
	global_store_dwordx4 v[82:83], v[24:27], off offset:576
	global_store_dwordx2 v[60:61], v[18:19], off offset:288
	s_mov_b32 vcc_lo, 0x11111111
	s_mov_b32 vcc_hi, 0x11111111
	s_and_saveexec_b64 s[24:25], vcc
	s_cbranch_execz .LBB0_1827
	v_lshl_add_u64 v[18:19], v[80:81], 2, s[10:11]
	s_waitcnt lgkmcnt(0)
	v_add_f32_e32 v16, v16, v17
	global_atomic_add_f32 v[18:19], v16, off
.LBB0_1827:
	s_or_b64 exec, exec, s[24:25]
	s_waitcnt vmcnt(11)
	v_pk_add_f32 v[14:15], v[14:15], v[46:47]
	v_pk_add_f32 v[12:13], v[12:13], v[44:45]
	s_waitcnt lgkmcnt(0)
	v_mul_f32_e32 v17, v15, v15
	v_mul_f32_e32 v16, v13, v13
	v_fmac_f32_e32 v16, v12, v12
	v_fmac_f32_e32 v17, v14, v14
	v_add_f32_e32 v18, v16, v17
	v_lshlrev_b64 v[16:17], 11, v[64:65]
	v_lshl_add_u64 v[16:17], s[8:9], 0, v[16:17]
	global_store_dwordx4 v[66:67], v[12:15], off
	v_lshl_add_u64 v[16:17], v[156:157], 1, v[16:17]
	s_waitcnt vmcnt(11)
	v_pk_add_f32 v[8:9], v[8:9], v[40:41]
	v_cvt_pk_bf16_f32 v12, v12, v13
	v_cvt_pk_bf16_f32 v13, v14, v15
	global_store_dwordx2 v[16:17], v[12:13], off
	v_pk_add_f32 v[10:11], v[10:11], v[42:43]
	v_mul_f32_e32 v12, v9, v9
	v_fmac_f32_e32 v12, v8, v8
	v_mul_f32_e32 v13, v11, v11
	global_store_dwordx4 v[66:67], v[8:11], off offset:64
	s_waitcnt vmcnt(12)
	v_pk_add_f32 v[6:7], v[6:7], v[38:39]
	v_pk_add_f32 v[4:5], v[4:5], v[36:37]
	v_cvt_pk_bf16_f32 v8, v8, v9
	v_cvt_pk_bf16_f32 v9, v10, v11
	v_fmac_f32_e32 v13, v10, v10
	global_store_dwordx2 v[16:17], v[8:9], off offset:32
	v_mul_f32_e32 v8, v5, v5
	v_mul_f32_e32 v9, v7, v7
	v_add_f32_e32 v12, v12, v13
	v_fmac_f32_e32 v8, v4, v4
	v_fmac_f32_e32 v9, v6, v6
	v_add_f32_e32 v12, v18, v12
	v_add_f32_e32 v8, v8, v9
	v_add_f32_e32 v12, v12, v8
	s_waitcnt vmcnt(12)
	v_pk_add_f32 v[10:11], v[2:3], v[34:35]
	v_pk_add_f32 v[8:9], v[0:1], v[32:33]
	v_mul_f32_e32 v1, v11, v11
	v_mul_f32_e32 v0, v9, v9
	v_fmac_f32_e32 v0, v8, v8
	v_fmac_f32_e32 v1, v10, v10
	v_add_f32_e32 v0, v0, v1
	v_add_f32_e32 v2, v12, v0
	ds_bpermute_b32 v3, v175, v2
	v_cvt_pk_bf16_f32 v0, v4, v5
	v_cvt_pk_bf16_f32 v1, v6, v7
	global_store_dwordx4 v[66:67], v[4:7], off offset:512
	global_store_dwordx2 v[16:17], v[0:1], off offset:256
	s_waitcnt lgkmcnt(0)
	v_add_f32_e32 v0, v2, v3
	ds_bpermute_b32 v1, v176, v0
	v_cvt_pk_bf16_f32 v2, v8, v9
	v_cvt_pk_bf16_f32 v3, v10, v11
	global_store_dwordx4 v[66:67], v[8:11], off offset:576
	global_store_dwordx2 v[16:17], v[2:3], off offset:288
	s_mov_b32 vcc_lo, 0x11111111
	s_mov_b32 vcc_hi, 0x11111111
	s_and_saveexec_b64 s[24:25], vcc
	s_cbranch_execz .LBB0_1829
	v_lshl_add_u64 v[2:3], v[64:65], 2, s[10:11]
	s_waitcnt lgkmcnt(0)
	v_add_f32_e32 v0, v0, v1
	global_atomic_add_f32 v[2:3], v0, off

.LBB0_1998:
	ds_read_b128 v[128:131], v171
	ds_read_b128 v[132:135], v171 offset:1024
	ds_read_b128 v[136:139], v171 offset:2048
	ds_read_b128 v[140:143], v171 offset:3072
	ds_read_b128 v[156:159], v172
	ds_read_b128 v[160:163], v172 offset:1024
	ds_read_b128 v[164:167], v172 offset:2048
	ds_read_b128 v[176:179], v172 offset:3072
	s_add_u32 s24, s22, 0x100
	s_addc_u32 s25, s23, 0
	s_cmp_eq_u32 s55, 40
	s_cselect_b32 s29, s7, s25
	s_cselect_b32 s28, s6, s24
	s_cselect_b32 s27, s21, s54
	s_cselect_b32 s26, s20, s53
	v_lshl_add_u64 v[188:189], s[22:23], 0, v[150:151]
	s_add_i32 m0, s36, 0xc000
	ds_read_b128 v[180:183], v173
	ds_read_b128 v[184:187], v173 offset:1024
	ds_read_b128 v[192:195], v173 offset:2048
	ds_read_b128 v[196:199], v173 offset:3072
	ds_read_b128 v[200:203], v173 offset:4096
	ds_read_b128 v[204:207], v173 offset:5120
	ds_read_b128 v[208:211], v173 offset:6144
	ds_read_b128 v[212:215], v173 offset:7168
	global_load_lds_dwordx4 v[188:189], off
	v_lshl_add_u64 v[188:189], s[22:23], 0, v[148:149]
	s_add_i32 m0, s36, 0xe000
	s_nop 0
	global_load_lds_dwordx4 v[188:189], off
	s_waitcnt vmcnt(8)
	s_waitcnt lgkmcnt(0)
	s_barrier
	s_setprio 1
	s_waitcnt lgkmcnt(0)
	v_mfma_f32_16x16x32_bf16 v[124:127], v[128:131], v[180:183], v[124:127]
	v_mfma_f32_16x16x32_bf16 v[120:123], v[136:139], v[180:183], v[120:123]
	v_mfma_f32_16x16x32_bf16 v[108:111], v[128:131], v[192:195], v[108:111]
	v_mfma_f32_16x16x32_bf16 v[104:107], v[136:139], v[192:195], v[104:107]
	v_mfma_f32_16x16x32_bf16 v[92:95], v[128:131], v[200:203], v[92:95]
	v_mfma_f32_16x16x32_bf16 v[88:91], v[136:139], v[200:203], v[88:91]
	v_mfma_f32_16x16x32_bf16 v[76:79], v[128:131], v[208:211], v[76:79]
	v_mfma_f32_16x16x32_bf16 v[72:75], v[136:139], v[208:211], v[72:75]
	v_mfma_f32_16x16x32_bf16 v[124:127], v[132:135], v[184:187], v[124:127]
	v_mfma_f32_16x16x32_bf16 v[120:123], v[140:143], v[184:187], v[120:123]
	v_mfma_f32_16x16x32_bf16 v[108:111], v[132:135], v[196:199], v[108:111]
	v_mfma_f32_16x16x32_bf16 v[104:107], v[140:143], v[196:199], v[104:107]
	v_mfma_f32_16x16x32_bf16 v[92:95], v[132:135], v[204:207], v[92:95]
	v_mfma_f32_16x16x32_bf16 v[88:91], v[140:143], v[204:207], v[88:91]
	v_mfma_f32_16x16x32_bf16 v[76:79], v[132:135], v[212:215], v[76:79]
	v_mfma_f32_16x16x32_bf16 v[72:75], v[140:143], v[212:215], v[72:75]
	s_setprio 0
	s_setprio 1
	v_mfma_f32_16x16x32_bf16 v[116:119], v[156:159], v[180:183], v[116:119]
	v_mfma_f32_16x16x32_bf16 v[112:115], v[164:167], v[180:183], v[112:115]
	v_mfma_f32_16x16x32_bf16 v[100:103], v[156:159], v[192:195], v[100:103]
	v_mfma_f32_16x16x32_bf16 v[96:99], v[164:167], v[192:195], v[96:99]
	v_mfma_f32_16x16x32_bf16 v[84:87], v[156:159], v[200:203], v[84:87]
	v_mfma_f32_16x16x32_bf16 v[80:83], v[164:167], v[200:203], v[80:83]
	v_mfma_f32_16x16x32_bf16 v[68:71], v[156:159], v[208:211], v[68:71]
	v_mfma_f32_16x16x32_bf16 v[64:67], v[164:167], v[208:211], v[64:67]
	v_mfma_f32_16x16x32_bf16 v[116:119], v[160:163], v[184:187], v[116:119]
	v_mfma_f32_16x16x32_bf16 v[112:115], v[176:179], v[184:187], v[112:115]
	v_mfma_f32_16x16x32_bf16 v[100:103], v[160:163], v[196:199], v[100:103]
	v_mfma_f32_16x16x32_bf16 v[96:99], v[176:179], v[196:199], v[96:99]
	v_mfma_f32_16x16x32_bf16 v[84:87], v[160:163], v[204:207], v[84:87]
	v_mfma_f32_16x16x32_bf16 v[80:83], v[176:179], v[204:207], v[80:83]
	v_mfma_f32_16x16x32_bf16 v[68:71], v[160:163], v[212:215], v[68:71]
	v_mfma_f32_16x16x32_bf16 v[64:67], v[176:179], v[212:215], v[64:67]
	s_setprio 0
	s_barrier
	s_add_i32 s22, s47, s35
	v_lshl_add_u64 v[188:189], s[26:27], 0, v[144:145]
	s_mov_b32 m0, s22
	ds_read_b128 v[180:183], v173 offset:16384
	ds_read_b128 v[184:187], v173 offset:17408
	ds_read_b128 v[192:195], v173 offset:18432
	ds_read_b128 v[196:199], v173 offset:19456
	ds_read_b128 v[200:203], v173 offset:20480
	ds_read_b128 v[204:207], v173 offset:21504
	ds_read_b128 v[208:211], v173 offset:22528
	ds_read_b128 v[212:215], v173 offset:23552
	global_load_lds_dwordx4 v[188:189], off
	s_add_i32 m0, s22, 0x2000
	s_add_u32 s22, s26, 0xb0000
	v_lshl_add_u64 v[216:217], s[26:27], 0, v[146:147]
	s_addc_u32 s23, s27, 0
	s_add_i32 s56, s48, s35
	global_load_lds_dwordx4 v[216:217], off
	v_lshl_add_u64 v[218:219], s[22:23], 0, v[144:145]
	s_mov_b32 m0, s56
	v_lshl_add_u64 v[220:221], s[28:29], 0, v[146:147]
	global_load_lds_dwordx4 v[218:219], off
	v_lshl_add_u64 v[218:219], s[22:23], 0, v[146:147]
	s_add_i32 m0, s56, 0x2000
	s_nop 0
	global_load_lds_dwordx4 v[218:219], off
	v_lshl_add_u64 v[218:219], s[28:29], 0, v[144:145]
	s_mov_b32 m0, s36
	s_nop 0
	global_load_lds_dwordx4 v[218:219], off
	s_mov_b32 m0, s37
	s_nop 0
	global_load_lds_dwordx4 v[220:221], off
	s_waitcnt vmcnt(8)
	s_waitcnt lgkmcnt(0)
	s_barrier
	s_setprio 1
	s_waitcnt lgkmcnt(0)
	v_mfma_f32_16x16x32_bf16 v[60:63], v[128:131], v[180:183], v[60:63]
	v_mfma_f32_16x16x32_bf16 v[56:59], v[136:139], v[180:183], v[56:59]
	v_mfma_f32_16x16x32_bf16 v[44:47], v[128:131], v[192:195], v[44:47]
	v_mfma_f32_16x16x32_bf16 v[40:43], v[136:139], v[192:195], v[40:43]
	v_mfma_f32_16x16x32_bf16 v[28:31], v[128:131], v[200:203], v[28:31]
	v_mfma_f32_16x16x32_bf16 v[24:27], v[136:139], v[200:203], v[24:27]
	v_mfma_f32_16x16x32_bf16 v[12:15], v[128:131], v[208:211], v[12:15]
	v_mfma_f32_16x16x32_bf16 v[8:11], v[136:139], v[208:211], v[8:11]
	v_mfma_f32_16x16x32_bf16 v[60:63], v[132:135], v[184:187], v[60:63]
	v_mfma_f32_16x16x32_bf16 v[56:59], v[140:143], v[184:187], v[56:59]
	v_mfma_f32_16x16x32_bf16 v[44:47], v[132:135], v[196:199], v[44:47]
	v_mfma_f32_16x16x32_bf16 v[40:43], v[140:143], v[196:199], v[40:43]
	v_mfma_f32_16x16x32_bf16 v[28:31], v[132:135], v[204:207], v[28:31]
	v_mfma_f32_16x16x32_bf16 v[24:27], v[140:143], v[204:207], v[24:27]
	v_mfma_f32_16x16x32_bf16 v[12:15], v[132:135], v[212:215], v[12:15]
	v_mfma_f32_16x16x32_bf16 v[8:11], v[140:143], v[212:215], v[8:11]
	s_setprio 0
	s_setprio 1
	v_mfma_f32_16x16x32_bf16 v[52:55], v[156:159], v[180:183], v[52:55]
	v_mfma_f32_16x16x32_bf16 v[48:51], v[164:167], v[180:183], v[48:51]
	v_mfma_f32_16x16x32_bf16 v[36:39], v[156:159], v[192:195], v[36:39]
	v_mfma_f32_16x16x32_bf16 v[32:35], v[164:167], v[192:195], v[32:35]
	v_mfma_f32_16x16x32_bf16 v[20:23], v[156:159], v[200:203], v[20:23]
	v_mfma_f32_16x16x32_bf16 v[16:19], v[164:167], v[200:203], v[16:19]
	v_mfma_f32_16x16x32_bf16 v[4:7], v[156:159], v[208:211], v[4:7]
	v_mfma_f32_16x16x32_bf16 v[0:3], v[164:167], v[208:211], v[0:3]
	v_mfma_f32_16x16x32_bf16 v[52:55], v[160:163], v[184:187], v[52:55]
	v_mfma_f32_16x16x32_bf16 v[48:51], v[176:179], v[184:187], v[48:51]
	v_mfma_f32_16x16x32_bf16 v[36:39], v[160:163], v[196:199], v[36:39]
	v_mfma_f32_16x16x32_bf16 v[32:35], v[176:179], v[196:199], v[32:35]
	v_mfma_f32_16x16x32_bf16 v[20:23], v[160:163], v[204:207], v[20:23]
	v_mfma_f32_16x16x32_bf16 v[16:19], v[176:179], v[204:207], v[16:19]
	v_mfma_f32_16x16x32_bf16 v[4:7], v[160:163], v[212:215], v[4:7]
	v_mfma_f32_16x16x32_bf16 v[0:3], v[176:179], v[212:215], v[0:3]
	s_setprio 0
	s_barrier
	s_add_i32 s56, 0, 0x18000
	s_add_i32 s57, 0, 0x1c000
	v_add_u32_e32 v140, s56, v169
	v_add_u32_e32 v175, s57, v169
	ds_read_b128 v[128:131], v140
	ds_read_b128 v[132:135], v140 offset:1024
	ds_read_b128 v[136:139], v140 offset:2048
	ds_read_b128 v[140:143], v140 offset:3072
	ds_read_b128 v[156:159], v175
	ds_read_b128 v[160:163], v175 offset:1024
	ds_read_b128 v[164:167], v175 offset:2048
	ds_read_b128 v[176:179], v175 offset:3072
	s_add_u32 s22, s28, 0xb0000
	s_addc_u32 s23, s29, 0
	s_mov_b32 m0, s38
	v_lshl_add_u64 v[222:223], s[22:23], 0, v[144:145]
	ds_read_b128 v[180:183], v173 offset:32768
	ds_read_b128 v[184:187], v173 offset:33792
	ds_read_b128 v[192:195], v173 offset:34816
	ds_read_b128 v[196:199], v173 offset:35840
	ds_read_b128 v[200:203], v173 offset:36864
	ds_read_b128 v[204:207], v173 offset:37888
	ds_read_b128 v[208:211], v173 offset:38912
	ds_read_b128 v[212:215], v173 offset:39936
	global_load_lds_dwordx4 v[222:223], off
	v_lshl_add_u64 v[222:223], s[22:23], 0, v[146:147]
	s_mov_b32 m0, s39
	s_nop 0
	global_load_lds_dwordx4 v[222:223], off
	s_waitcnt vmcnt(8)
	s_waitcnt lgkmcnt(0)
	s_barrier
	s_setprio 1
	s_waitcnt lgkmcnt(0)
	v_mfma_f32_16x16x32_bf16 v[124:127], v[128:131], v[180:183], v[124:127]
	v_mfma_f32_16x16x32_bf16 v[120:123], v[136:139], v[180:183], v[120:123]
	v_mfma_f32_16x16x32_bf16 v[108:111], v[128:131], v[192:195], v[108:111]
	v_mfma_f32_16x16x32_bf16 v[104:107], v[136:139], v[192:195], v[104:107]
	v_mfma_f32_16x16x32_bf16 v[92:95], v[128:131], v[200:203], v[92:95]
	v_mfma_f32_16x16x32_bf16 v[88:91], v[136:139], v[200:203], v[88:91]
	v_mfma_f32_16x16x32_bf16 v[76:79], v[128:131], v[208:211], v[76:79]
	v_mfma_f32_16x16x32_bf16 v[72:75], v[136:139], v[208:211], v[72:75]
	v_mfma_f32_16x16x32_bf16 v[124:127], v[132:135], v[184:187], v[124:127]
	v_mfma_f32_16x16x32_bf16 v[120:123], v[140:143], v[184:187], v[120:123]
	v_mfma_f32_16x16x32_bf16 v[108:111], v[132:135], v[196:199], v[108:111]
	v_mfma_f32_16x16x32_bf16 v[104:107], v[140:143], v[196:199], v[104:107]
	v_mfma_f32_16x16x32_bf16 v[92:95], v[132:135], v[204:207], v[92:95]
	v_mfma_f32_16x16x32_bf16 v[88:91], v[140:143], v[204:207], v[88:91]
	v_mfma_f32_16x16x32_bf16 v[76:79], v[132:135], v[212:215], v[76:79]
	v_mfma_f32_16x16x32_bf16 v[72:75], v[140:143], v[212:215], v[72:75]
	s_setprio 0
	s_setprio 1
	v_mfma_f32_16x16x32_bf16 v[116:119], v[156:159], v[180:183], v[116:119]
	v_mfma_f32_16x16x32_bf16 v[112:115], v[164:167], v[180:183], v[112:115]
	v_mfma_f32_16x16x32_bf16 v[100:103], v[156:159], v[192:195], v[100:103]
	v_mfma_f32_16x16x32_bf16 v[96:99], v[164:167], v[192:195], v[96:99]
	v_mfma_f32_16x16x32_bf16 v[84:87], v[156:159], v[200:203], v[84:87]
	v_mfma_f32_16x16x32_bf16 v[80:83], v[164:167], v[200:203], v[80:83]
	v_mfma_f32_16x16x32_bf16 v[68:71], v[156:159], v[208:211], v[68:71]
	v_mfma_f32_16x16x32_bf16 v[64:67], v[164:167], v[208:211], v[64:67]
	v_mfma_f32_16x16x32_bf16 v[116:119], v[160:163], v[184:187], v[116:119]
	v_mfma_f32_16x16x32_bf16 v[112:115], v[176:179], v[184:187], v[112:115]
	v_mfma_f32_16x16x32_bf16 v[100:103], v[160:163], v[196:199], v[100:103]
	v_mfma_f32_16x16x32_bf16 v[96:99], v[176:179], v[196:199], v[96:99]
	v_mfma_f32_16x16x32_bf16 v[84:87], v[160:163], v[204:207], v[84:87]
	v_mfma_f32_16x16x32_bf16 v[80:83], v[176:179], v[204:207], v[80:83]
	v_mfma_f32_16x16x32_bf16 v[68:71], v[160:163], v[212:215], v[68:71]
	v_mfma_f32_16x16x32_bf16 v[64:67], v[176:179], v[212:215], v[64:67]
	s_setprio 0
	s_barrier
	s_add_i32 s22, s56, s35
	v_lshl_add_u64 v[188:189], v[188:189], 0, s[16:17]
	s_mov_b32 m0, s22
	ds_read_b128 v[180:183], v173 offset:49152
	ds_read_b128 v[184:187], v173 offset:50176
	ds_read_b128 v[192:195], v173 offset:51200
	ds_read_b128 v[196:199], v173 offset:52224
	ds_read_b128 v[200:203], v173 offset:53248
	ds_read_b128 v[204:207], v173 offset:54272
	ds_read_b128 v[208:211], v173 offset:55296
	ds_read_b128 v[212:215], v173 offset:56320
	global_load_lds_dwordx4 v[188:189], off
	s_add_i32 m0, s22, 0x2000
	s_add_u32 s22, s26, 0xb0080
	v_lshl_add_u64 v[188:189], v[216:217], 0, s[16:17]
	s_addc_u32 s23, s27, 0
	s_add_i32 s26, s57, s35
	global_load_lds_dwordx4 v[188:189], off
	v_lshl_add_u64 v[188:189], s[22:23], 0, v[144:145]
	s_mov_b32 m0, s26
	s_nop 0
	global_load_lds_dwordx4 v[188:189], off
	v_lshl_add_u64 v[188:189], s[22:23], 0, v[146:147]
	s_add_i32 m0, s26, 0x2000
	s_nop 0
	global_load_lds_dwordx4 v[188:189], off
	v_lshl_add_u64 v[188:189], v[218:219], 0, s[16:17]
	s_mov_b32 m0, s41
	s_nop 0
	global_load_lds_dwordx4 v[188:189], off
	v_lshl_add_u64 v[188:189], v[220:221], 0, s[16:17]
	s_mov_b32 m0, s42
	s_nop 0
	global_load_lds_dwordx4 v[188:189], off
	s_waitcnt vmcnt(8)
	s_waitcnt lgkmcnt(0)
	s_barrier
	s_setprio 1
	s_waitcnt lgkmcnt(0)
	v_mfma_f32_16x16x32_bf16 v[60:63], v[128:131], v[180:183], v[60:63]
	v_mfma_f32_16x16x32_bf16 v[56:59], v[136:139], v[180:183], v[56:59]
	v_mfma_f32_16x16x32_bf16 v[44:47], v[128:131], v[192:195], v[44:47]
	v_mfma_f32_16x16x32_bf16 v[40:43], v[136:139], v[192:195], v[40:43]
	v_mfma_f32_16x16x32_bf16 v[28:31], v[128:131], v[200:203], v[28:31]
	v_mfma_f32_16x16x32_bf16 v[24:27], v[136:139], v[200:203], v[24:27]
	v_mfma_f32_16x16x32_bf16 v[12:15], v[128:131], v[208:211], v[12:15]
	v_mfma_f32_16x16x32_bf16 v[8:11], v[136:139], v[208:211], v[8:11]
	v_mfma_f32_16x16x32_bf16 v[60:63], v[132:135], v[184:187], v[60:63]
	v_mfma_f32_16x16x32_bf16 v[56:59], v[140:143], v[184:187], v[56:59]
	v_mfma_f32_16x16x32_bf16 v[44:47], v[132:135], v[196:199], v[44:47]
	v_mfma_f32_16x16x32_bf16 v[40:43], v[140:143], v[196:199], v[40:43]
	v_mfma_f32_16x16x32_bf16 v[28:31], v[132:135], v[204:207], v[28:31]
	v_mfma_f32_16x16x32_bf16 v[24:27], v[140:143], v[204:207], v[24:27]
	v_mfma_f32_16x16x32_bf16 v[12:15], v[132:135], v[212:215], v[12:15]
	v_mfma_f32_16x16x32_bf16 v[8:11], v[140:143], v[212:215], v[8:11]
	s_setprio 0
	s_setprio 1
	v_mfma_f32_16x16x32_bf16 v[52:55], v[156:159], v[180:183], v[52:55]
	v_mfma_f32_16x16x32_bf16 v[48:51], v[164:167], v[180:183], v[48:51]
	v_mfma_f32_16x16x32_bf16 v[36:39], v[156:159], v[192:195], v[36:39]
	v_mfma_f32_16x16x32_bf16 v[32:35], v[164:167], v[192:195], v[32:35]
	v_mfma_f32_16x16x32_bf16 v[20:23], v[156:159], v[200:203], v[20:23]
	v_mfma_f32_16x16x32_bf16 v[16:19], v[164:167], v[200:203], v[16:19]
	v_mfma_f32_16x16x32_bf16 v[4:7], v[156:159], v[208:211], v[4:7]
	v_mfma_f32_16x16x32_bf16 v[0:3], v[164:167], v[208:211], v[0:3]
	v_mfma_f32_16x16x32_bf16 v[52:55], v[160:163], v[184:187], v[52:55]
	v_mfma_f32_16x16x32_bf16 v[48:51], v[176:179], v[184:187], v[48:51]
	v_mfma_f32_16x16x32_bf16 v[36:39], v[160:163], v[196:199], v[36:39]
	v_mfma_f32_16x16x32_bf16 v[32:35], v[176:179], v[196:199], v[32:35]
	v_mfma_f32_16x16x32_bf16 v[20:23], v[160:163], v[204:207], v[20:23]
	v_mfma_f32_16x16x32_bf16 v[16:19], v[176:179], v[204:207], v[16:19]
	v_mfma_f32_16x16x32_bf16 v[4:7], v[160:163], v[212:215], v[4:7]
	v_mfma_f32_16x16x32_bf16 v[0:3], v[176:179], v[212:215], v[0:3]
	s_setprio 0
	s_barrier
	s_add_i32 s55, s55, 2
	s_add_u32 s53, s53, 0x100
	s_addc_u32 s54, s54, 0
	s_cmp_gt_u32 s55, 41
	s_mov_b64 s[22:23], s[24:25]
	s_cbranch_scc0 .LBB0_1998
	v_mbcnt_lo_u32_b32 v235, -1, 0
	v_mbcnt_hi_u32_b32 v235, -1, v235
	v_lshrrev_b32_e32 v236, 2, v235
	v_and_b32_e32 v237, 3, v235
	v_lshl_add_u32 v232, v237, 4, v236
	v_lshlrev_b32_e32 v232, 2, v232
	v_and_b32_e32 v233, -16, v168
	v_or_b32_e32 v233, v233, v236
	v_lshlrev_b32_e32 v237, 2, v237
	v_and_b32_e32 v234, -13, v170
	v_or_b32_e32 v234, v234, v237
	ds_bpermute_b32 v127, v232, v127
	ds_bpermute_b32 v126, v232, v126
	ds_bpermute_b32 v125, v232, v125
	ds_bpermute_b32 v124, v232, v124
	ds_bpermute_b32 v123, v232, v123
	ds_bpermute_b32 v122, v232, v122
	ds_bpermute_b32 v121, v232, v121
	ds_bpermute_b32 v120, v232, v120
	ds_bpermute_b32 v119, v232, v119
	ds_bpermute_b32 v118, v232, v118
	ds_bpermute_b32 v117, v232, v117
	ds_bpermute_b32 v116, v232, v116
	ds_bpermute_b32 v115, v232, v115
	ds_bpermute_b32 v114, v232, v114
	ds_bpermute_b32 v113, v232, v113
	ds_bpermute_b32 v112, v232, v112
	ds_bpermute_b32 v111, v232, v111
	ds_bpermute_b32 v110, v232, v110
	ds_bpermute_b32 v109, v232, v109
	ds_bpermute_b32 v108, v232, v108
	ds_bpermute_b32 v107, v232, v107
	ds_bpermute_b32 v106, v232, v106
	ds_bpermute_b32 v105, v232, v105
	ds_bpermute_b32 v104, v232, v104
	ds_bpermute_b32 v103, v232, v103
	ds_bpermute_b32 v102, v232, v102
	ds_bpermute_b32 v101, v232, v101
	ds_bpermute_b32 v100, v232, v100
	ds_bpermute_b32 v99, v232, v99
	ds_bpermute_b32 v98, v232, v98
	ds_bpermute_b32 v97, v232, v97
	ds_bpermute_b32 v96, v232, v96
	ds_bpermute_b32 v95, v232, v95
	ds_bpermute_b32 v94, v232, v94
	ds_bpermute_b32 v93, v232, v93
	ds_bpermute_b32 v92, v232, v92
	ds_bpermute_b32 v91, v232, v91
	ds_bpermute_b32 v90, v232, v90
	ds_bpermute_b32 v89, v232, v89
	ds_bpermute_b32 v88, v232, v88
	ds_bpermute_b32 v87, v232, v87
	ds_bpermute_b32 v86, v232, v86
	ds_bpermute_b32 v85, v232, v85
	ds_bpermute_b32 v84, v232, v84
	ds_bpermute_b32 v83, v232, v83
	ds_bpermute_b32 v82, v232, v82
	ds_bpermute_b32 v81, v232, v81
	ds_bpermute_b32 v80, v232, v80
	ds_bpermute_b32 v79, v232, v79
	ds_bpermute_b32 v78, v232, v78
	ds_bpermute_b32 v77, v232, v77
	ds_bpermute_b32 v76, v232, v76
	ds_bpermute_b32 v75, v232, v75
	ds_bpermute_b32 v74, v232, v74
	ds_bpermute_b32 v73, v232, v73
	ds_bpermute_b32 v72, v232, v72
	ds_bpermute_b32 v71, v232, v71
	ds_bpermute_b32 v70, v232, v70
	ds_bpermute_b32 v69, v232, v69
	ds_bpermute_b32 v68, v232, v68
	ds_bpermute_b32 v67, v232, v67
	ds_bpermute_b32 v66, v232, v66
	ds_bpermute_b32 v65, v232, v65
	ds_bpermute_b32 v64, v232, v64
	ds_bpermute_b32 v63, v232, v63
	ds_bpermute_b32 v62, v232, v62
	ds_bpermute_b32 v61, v232, v61
	ds_bpermute_b32 v60, v232, v60
	ds_bpermute_b32 v59, v232, v59
	ds_bpermute_b32 v58, v232, v58
	ds_bpermute_b32 v57, v232, v57
	ds_bpermute_b32 v56, v232, v56
	ds_bpermute_b32 v55, v232, v55
	ds_bpermute_b32 v54, v232, v54
	ds_bpermute_b32 v53, v232, v53
	ds_bpermute_b32 v52, v232, v52
	ds_bpermute_b32 v51, v232, v51
	ds_bpermute_b32 v50, v232, v50
	ds_bpermute_b32 v49, v232, v49
	ds_bpermute_b32 v48, v232, v48
	ds_bpermute_b32 v47, v232, v47
	ds_bpermute_b32 v46, v232, v46
	ds_bpermute_b32 v45, v232, v45
	ds_bpermute_b32 v44, v232, v44
	ds_bpermute_b32 v43, v232, v43
	ds_bpermute_b32 v42, v232, v42
	ds_bpermute_b32 v41, v232, v41
	ds_bpermute_b32 v40, v232, v40
	ds_bpermute_b32 v39, v232, v39
	ds_bpermute_b32 v38, v232, v38
	ds_bpermute_b32 v37, v232, v37
	ds_bpermute_b32 v36, v232, v36
	ds_bpermute_b32 v35, v232, v35
	ds_bpermute_b32 v34, v232, v34
	ds_bpermute_b32 v33, v232, v33
	ds_bpermute_b32 v32, v232, v32
	ds_bpermute_b32 v31, v232, v31
	ds_bpermute_b32 v30, v232, v30
	ds_bpermute_b32 v29, v232, v29
	ds_bpermute_b32 v28, v232, v28
	ds_bpermute_b32 v27, v232, v27
	ds_bpermute_b32 v26, v232, v26
	ds_bpermute_b32 v25, v232, v25
	ds_bpermute_b32 v24, v232, v24
	ds_bpermute_b32 v23, v232, v23
	ds_bpermute_b32 v22, v232, v22
	ds_bpermute_b32 v21, v232, v21
	ds_bpermute_b32 v20, v232, v20
	ds_bpermute_b32 v19, v232, v19
	ds_bpermute_b32 v18, v232, v18
	ds_bpermute_b32 v17, v232, v17
	ds_bpermute_b32 v16, v232, v16
	ds_bpermute_b32 v15, v232, v15
	ds_bpermute_b32 v14, v232, v14
	ds_bpermute_b32 v13, v232, v13
	ds_bpermute_b32 v12, v232, v12
	ds_bpermute_b32 v11, v232, v11
	ds_bpermute_b32 v10, v232, v10
	ds_bpermute_b32 v9, v232, v9
	ds_bpermute_b32 v8, v232, v8
	ds_bpermute_b32 v7, v232, v7
	ds_bpermute_b32 v6, v232, v6
	ds_bpermute_b32 v5, v232, v5
	ds_bpermute_b32 v4, v232, v4
	ds_bpermute_b32 v3, v232, v3
	ds_bpermute_b32 v2, v232, v2
	ds_bpermute_b32 v1, v232, v1
	ds_bpermute_b32 v0, v232, v0
	s_waitcnt lgkmcnt(0)
	v_lshl_add_u32 v158, s52, 8, v233
	v_lshl_or_b32 v156, s51, 8, v234
	v_ashrrev_i32_e32 v159, 31, v158
	v_lshlrev_b64 v[128:129], 12, v[158:159]
	v_ashrrev_i32_e32 v157, 31, v156
	v_lshl_add_u64 v[128:129], s[8:9], 0, v[128:129]
	v_lshlrev_b64 v[130:131], 2, v[156:157]
	v_lshl_add_u64 v[188:189], v[128:129], 0, v[130:131]
	global_load_dwordx4 v[164:167], v[188:189], off
	global_load_dwordx4 v[176:179], v[188:189], off offset:64
	global_load_dwordx4 v[180:183], v[188:189], off offset:512
	global_load_dwordx4 v[184:187], v[188:189], off offset:576
	v_or_b32_e32 v160, 16, v158
	v_ashrrev_i32_e32 v161, 31, v160
	v_lshlrev_b64 v[128:129], 12, v[160:161]
	v_lshl_add_u64 v[128:129], s[8:9], 0, v[128:129]
	v_lshl_add_u64 v[162:163], v[128:129], 0, v[130:131]
	global_load_dwordx4 v[140:143], v[162:163], off
	global_load_dwordx4 v[136:139], v[162:163], off offset:64
	global_load_dwordx4 v[132:135], v[162:163], off offset:512
	global_load_dwordx4 v[128:131], v[162:163], off offset:576
	v_lshlrev_b64 v[192:193], 11, v[158:159]
	v_lshl_add_u64 v[192:193], s[12:13], 0, v[192:193]
	v_and_b32_e32 v191, 64, v174
	v_lshl_add_u64 v[192:193], v[156:157], 1, v[192:193]
	v_xor_b32_e32 v175, 1, v174
	v_add_u32_e32 v191, 64, v191
	v_cmp_lt_i32_e32 vcc, v175, v191
	v_xor_b32_e32 v194, 2, v174
	s_waitcnt lgkmcnt(0)
	s_cmp_eq_u64 s[18:19], 0
	s_cbranch_scc1 .LBB0_2001
	s_barrier

.LBB0_2118:
	ds_read_b128 v[128:131], v189
	ds_read_b128 v[132:135], v189 offset:1024
	ds_read_b128 v[136:139], v189 offset:2048
	ds_read_b128 v[140:143], v189 offset:3072
	ds_read_b128 v[156:159], v191
	ds_read_b128 v[160:163], v191 offset:1024
	ds_read_b128 v[164:167], v191 offset:2048
	ds_read_b128 v[168:171], v191 offset:3072
	s_add_u32 s34, s30, 0xfffc0080
	s_addc_u32 s35, s31, -1
	s_cmp_eq_u32 s58, 12
	s_cselect_b32 s37, s21, s35
	s_cselect_b32 s36, s27, s34
	s_cselect_b32 s35, s19, s57
	s_cselect_b32 s34, s33, s56
	v_lshl_add_u64 v[184:185], s[30:31], 0, v[150:151]
	s_add_i32 m0, s29, 0xc000
	ds_read_b128 v[172:175], v192
	ds_read_b128 v[176:179], v192 offset:1024
	ds_read_b128 v[180:183], v192 offset:2048
	ds_read_b128 v[196:199], v192 offset:3072
	ds_read_b128 v[200:203], v192 offset:4096
	ds_read_b128 v[204:207], v192 offset:5120
	ds_read_b128 v[208:211], v192 offset:6144
	ds_read_b128 v[212:215], v192 offset:7168
	global_load_lds_dwordx4 v[184:185], off
	v_lshl_add_u64 v[184:185], s[30:31], 0, v[148:149]
	s_add_i32 m0, s29, 0xe000
	s_nop 0
	global_load_lds_dwordx4 v[184:185], off
	s_waitcnt vmcnt(8)
	s_waitcnt lgkmcnt(0)
	s_barrier
	s_setprio 1
	s_waitcnt lgkmcnt(0)
	v_mfma_f32_16x16x32_bf16 v[124:127], v[128:131], v[172:175], v[124:127]
	v_mfma_f32_16x16x32_bf16 v[120:123], v[136:139], v[172:175], v[120:123]
	v_mfma_f32_16x16x32_bf16 v[108:111], v[128:131], v[180:183], v[108:111]
	v_mfma_f32_16x16x32_bf16 v[104:107], v[136:139], v[180:183], v[104:107]
	v_mfma_f32_16x16x32_bf16 v[92:95], v[128:131], v[200:203], v[92:95]
	v_mfma_f32_16x16x32_bf16 v[88:91], v[136:139], v[200:203], v[88:91]
	v_mfma_f32_16x16x32_bf16 v[76:79], v[128:131], v[208:211], v[76:79]
	v_mfma_f32_16x16x32_bf16 v[72:75], v[136:139], v[208:211], v[72:75]
	v_mfma_f32_16x16x32_bf16 v[124:127], v[132:135], v[176:179], v[124:127]
	v_mfma_f32_16x16x32_bf16 v[120:123], v[140:143], v[176:179], v[120:123]
	v_mfma_f32_16x16x32_bf16 v[108:111], v[132:135], v[196:199], v[108:111]
	v_mfma_f32_16x16x32_bf16 v[104:107], v[140:143], v[196:199], v[104:107]
	v_mfma_f32_16x16x32_bf16 v[92:95], v[132:135], v[204:207], v[92:95]
	v_mfma_f32_16x16x32_bf16 v[88:91], v[140:143], v[204:207], v[88:91]
	v_mfma_f32_16x16x32_bf16 v[76:79], v[132:135], v[212:215], v[76:79]
	v_mfma_f32_16x16x32_bf16 v[72:75], v[140:143], v[212:215], v[72:75]
	s_setprio 0
	s_setprio 1
	v_mfma_f32_16x16x32_bf16 v[116:119], v[156:159], v[172:175], v[116:119]
	v_mfma_f32_16x16x32_bf16 v[112:115], v[164:167], v[172:175], v[112:115]
	v_mfma_f32_16x16x32_bf16 v[100:103], v[156:159], v[180:183], v[100:103]
	v_mfma_f32_16x16x32_bf16 v[96:99], v[164:167], v[180:183], v[96:99]
	v_mfma_f32_16x16x32_bf16 v[84:87], v[156:159], v[200:203], v[84:87]
	v_mfma_f32_16x16x32_bf16 v[80:83], v[164:167], v[200:203], v[80:83]
	v_mfma_f32_16x16x32_bf16 v[68:71], v[156:159], v[208:211], v[68:71]
	v_mfma_f32_16x16x32_bf16 v[64:67], v[164:167], v[208:211], v[64:67]
	v_mfma_f32_16x16x32_bf16 v[116:119], v[160:163], v[176:179], v[116:119]
	v_mfma_f32_16x16x32_bf16 v[112:115], v[168:171], v[176:179], v[112:115]
	v_mfma_f32_16x16x32_bf16 v[100:103], v[160:163], v[196:199], v[100:103]
	v_mfma_f32_16x16x32_bf16 v[96:99], v[168:171], v[196:199], v[96:99]
	v_mfma_f32_16x16x32_bf16 v[84:87], v[160:163], v[204:207], v[84:87]
	v_mfma_f32_16x16x32_bf16 v[80:83], v[168:171], v[204:207], v[80:83]
	v_mfma_f32_16x16x32_bf16 v[68:71], v[160:163], v[212:215], v[68:71]
	v_mfma_f32_16x16x32_bf16 v[64:67], v[168:171], v[212:215], v[64:67]
	s_setprio 0
	s_barrier
	s_add_i32 s59, s53, s40
	v_lshl_add_u64 v[184:185], s[34:35], 0, v[144:145]
	s_mov_b32 m0, s59
	ds_read_b128 v[172:175], v192 offset:16384
	ds_read_b128 v[176:179], v192 offset:17408
	ds_read_b128 v[180:183], v192 offset:18432
	ds_read_b128 v[196:199], v192 offset:19456
	ds_read_b128 v[200:203], v192 offset:20480
	ds_read_b128 v[204:207], v192 offset:21504
	ds_read_b128 v[208:211], v192 offset:22528
	ds_read_b128 v[212:215], v192 offset:23552
	global_load_lds_dwordx4 v[184:185], off
	s_add_i32 m0, s59, 0x2000
	s_add_u32 s60, s34, 0x40000
	v_lshl_add_u64 v[216:217], s[34:35], 0, v[146:147]
	s_addc_u32 s61, s35, 0
	s_add_i32 s59, s54, s40
	global_load_lds_dwordx4 v[216:217], off
	v_lshl_add_u64 v[218:219], s[60:61], 0, v[144:145]
	s_mov_b32 m0, s59
	v_lshl_add_u64 v[220:221], s[36:37], 0, v[146:147]
	global_load_lds_dwordx4 v[218:219], off
	v_lshl_add_u64 v[218:219], s[60:61], 0, v[146:147]
	s_add_i32 m0, s59, 0x2000
	s_nop 0
	global_load_lds_dwordx4 v[218:219], off
	v_lshl_add_u64 v[218:219], s[36:37], 0, v[144:145]
	s_mov_b32 m0, s29
	s_nop 0
	global_load_lds_dwordx4 v[218:219], off
	s_mov_b32 m0, s43
	s_nop 0
	global_load_lds_dwordx4 v[220:221], off
	s_waitcnt vmcnt(8)
	s_waitcnt lgkmcnt(0)
	s_barrier
	s_setprio 1
	s_waitcnt lgkmcnt(0)
	v_mfma_f32_16x16x32_bf16 v[60:63], v[128:131], v[172:175], v[60:63]
	v_mfma_f32_16x16x32_bf16 v[56:59], v[136:139], v[172:175], v[56:59]
	v_mfma_f32_16x16x32_bf16 v[44:47], v[128:131], v[180:183], v[44:47]
	v_mfma_f32_16x16x32_bf16 v[40:43], v[136:139], v[180:183], v[40:43]
	v_mfma_f32_16x16x32_bf16 v[28:31], v[128:131], v[200:203], v[28:31]
	v_mfma_f32_16x16x32_bf16 v[24:27], v[136:139], v[200:203], v[24:27]
	v_mfma_f32_16x16x32_bf16 v[12:15], v[128:131], v[208:211], v[12:15]
	v_mfma_f32_16x16x32_bf16 v[8:11], v[136:139], v[208:211], v[8:11]
	v_mfma_f32_16x16x32_bf16 v[60:63], v[132:135], v[176:179], v[60:63]
	v_mfma_f32_16x16x32_bf16 v[56:59], v[140:143], v[176:179], v[56:59]
	v_mfma_f32_16x16x32_bf16 v[44:47], v[132:135], v[196:199], v[44:47]
	v_mfma_f32_16x16x32_bf16 v[40:43], v[140:143], v[196:199], v[40:43]
	v_mfma_f32_16x16x32_bf16 v[28:31], v[132:135], v[204:207], v[28:31]
	v_mfma_f32_16x16x32_bf16 v[24:27], v[140:143], v[204:207], v[24:27]
	v_mfma_f32_16x16x32_bf16 v[12:15], v[132:135], v[212:215], v[12:15]
	v_mfma_f32_16x16x32_bf16 v[8:11], v[140:143], v[212:215], v[8:11]
	s_setprio 0
	s_setprio 1
	v_mfma_f32_16x16x32_bf16 v[52:55], v[156:159], v[172:175], v[52:55]
	v_mfma_f32_16x16x32_bf16 v[48:51], v[164:167], v[172:175], v[48:51]
	v_mfma_f32_16x16x32_bf16 v[36:39], v[156:159], v[180:183], v[36:39]
	v_mfma_f32_16x16x32_bf16 v[32:35], v[164:167], v[180:183], v[32:35]
	v_mfma_f32_16x16x32_bf16 v[20:23], v[156:159], v[200:203], v[20:23]
	v_mfma_f32_16x16x32_bf16 v[16:19], v[164:167], v[200:203], v[16:19]
	v_mfma_f32_16x16x32_bf16 v[4:7], v[156:159], v[208:211], v[4:7]
	v_mfma_f32_16x16x32_bf16 v[0:3], v[164:167], v[208:211], v[0:3]
	v_mfma_f32_16x16x32_bf16 v[52:55], v[160:163], v[176:179], v[52:55]
	v_mfma_f32_16x16x32_bf16 v[48:51], v[168:171], v[176:179], v[48:51]
	v_mfma_f32_16x16x32_bf16 v[36:39], v[160:163], v[196:199], v[36:39]
	v_mfma_f32_16x16x32_bf16 v[32:35], v[168:171], v[196:199], v[32:35]
	v_mfma_f32_16x16x32_bf16 v[20:23], v[160:163], v[204:207], v[20:23]
	v_mfma_f32_16x16x32_bf16 v[16:19], v[168:171], v[204:207], v[16:19]
	v_mfma_f32_16x16x32_bf16 v[4:7], v[160:163], v[212:215], v[4:7]
	v_mfma_f32_16x16x32_bf16 v[0:3], v[168:171], v[212:215], v[0:3]
	s_setprio 0
	s_barrier
	s_add_i32 s59, 0, 0x18000
	s_add_i32 s60, 0, 0x1c000
	v_add_u32_e32 v140, s59, v187
	v_add_u32_e32 v168, s60, v187
	ds_read_b128 v[128:131], v140
	ds_read_b128 v[132:135], v140 offset:1024
	ds_read_b128 v[136:139], v140 offset:2048
	ds_read_b128 v[140:143], v140 offset:3072
	ds_read_b128 v[156:159], v168
	ds_read_b128 v[160:163], v168 offset:1024
	ds_read_b128 v[164:167], v168 offset:2048
	ds_read_b128 v[168:171], v168 offset:3072
	s_add_u32 s36, s36, 0x40000
	s_addc_u32 s37, s37, 0
	s_mov_b32 m0, s44
	v_lshl_add_u64 v[222:223], s[36:37], 0, v[144:145]
	ds_read_b128 v[172:175], v192 offset:32768
	ds_read_b128 v[176:179], v192 offset:33792
	ds_read_b128 v[180:183], v192 offset:34816
	ds_read_b128 v[196:199], v192 offset:35840
	ds_read_b128 v[200:203], v192 offset:36864
	ds_read_b128 v[204:207], v192 offset:37888
	ds_read_b128 v[208:211], v192 offset:38912
	ds_read_b128 v[212:215], v192 offset:39936
	global_load_lds_dwordx4 v[222:223], off
	v_lshl_add_u64 v[222:223], s[36:37], 0, v[146:147]
	s_mov_b32 m0, s45
	s_nop 0
	global_load_lds_dwordx4 v[222:223], off
	s_waitcnt vmcnt(8)
	s_waitcnt lgkmcnt(0)
	s_barrier
	s_setprio 1
	s_waitcnt lgkmcnt(0)
	v_mfma_f32_16x16x32_bf16 v[124:127], v[128:131], v[172:175], v[124:127]
	v_mfma_f32_16x16x32_bf16 v[120:123], v[136:139], v[172:175], v[120:123]
	v_mfma_f32_16x16x32_bf16 v[108:111], v[128:131], v[180:183], v[108:111]
	v_mfma_f32_16x16x32_bf16 v[104:107], v[136:139], v[180:183], v[104:107]
	v_mfma_f32_16x16x32_bf16 v[92:95], v[128:131], v[200:203], v[92:95]
	v_mfma_f32_16x16x32_bf16 v[88:91], v[136:139], v[200:203], v[88:91]
	v_mfma_f32_16x16x32_bf16 v[76:79], v[128:131], v[208:211], v[76:79]
	v_mfma_f32_16x16x32_bf16 v[72:75], v[136:139], v[208:211], v[72:75]
	v_mfma_f32_16x16x32_bf16 v[124:127], v[132:135], v[176:179], v[124:127]
	v_mfma_f32_16x16x32_bf16 v[120:123], v[140:143], v[176:179], v[120:123]
	v_mfma_f32_16x16x32_bf16 v[108:111], v[132:135], v[196:199], v[108:111]
	v_mfma_f32_16x16x32_bf16 v[104:107], v[140:143], v[196:199], v[104:107]
	v_mfma_f32_16x16x32_bf16 v[92:95], v[132:135], v[204:207], v[92:95]
	v_mfma_f32_16x16x32_bf16 v[88:91], v[140:143], v[204:207], v[88:91]
	v_mfma_f32_16x16x32_bf16 v[76:79], v[132:135], v[212:215], v[76:79]
	v_mfma_f32_16x16x32_bf16 v[72:75], v[140:143], v[212:215], v[72:75]
	s_setprio 0
	s_setprio 1
	v_mfma_f32_16x16x32_bf16 v[116:119], v[156:159], v[172:175], v[116:119]
	v_mfma_f32_16x16x32_bf16 v[112:115], v[164:167], v[172:175], v[112:115]
	v_mfma_f32_16x16x32_bf16 v[100:103], v[156:159], v[180:183], v[100:103]
	v_mfma_f32_16x16x32_bf16 v[96:99], v[164:167], v[180:183], v[96:99]
	v_mfma_f32_16x16x32_bf16 v[84:87], v[156:159], v[200:203], v[84:87]
	v_mfma_f32_16x16x32_bf16 v[80:83], v[164:167], v[200:203], v[80:83]
	v_mfma_f32_16x16x32_bf16 v[68:71], v[156:159], v[208:211], v[68:71]
	v_mfma_f32_16x16x32_bf16 v[64:67], v[164:167], v[208:211], v[64:67]
	v_mfma_f32_16x16x32_bf16 v[116:119], v[160:163], v[176:179], v[116:119]
	v_mfma_f32_16x16x32_bf16 v[112:115], v[168:171], v[176:179], v[112:115]
	v_mfma_f32_16x16x32_bf16 v[100:103], v[160:163], v[196:199], v[100:103]
	v_mfma_f32_16x16x32_bf16 v[96:99], v[168:171], v[196:199], v[96:99]
	v_mfma_f32_16x16x32_bf16 v[84:87], v[160:163], v[204:207], v[84:87]
	v_mfma_f32_16x16x32_bf16 v[80:83], v[168:171], v[204:207], v[80:83]
	v_mfma_f32_16x16x32_bf16 v[68:71], v[160:163], v[212:215], v[68:71]
	v_mfma_f32_16x16x32_bf16 v[64:67], v[168:171], v[212:215], v[64:67]
	s_setprio 0
	s_barrier
	s_add_i32 s36, s59, s40
	v_lshl_add_u64 v[184:185], v[184:185], 0, s[14:15]
	s_mov_b32 m0, s36
	ds_read_b128 v[172:175], v192 offset:49152
	ds_read_b128 v[176:179], v192 offset:50176
	ds_read_b128 v[180:183], v192 offset:51200
	ds_read_b128 v[196:199], v192 offset:52224
	ds_read_b128 v[200:203], v192 offset:53248
	ds_read_b128 v[204:207], v192 offset:54272
	ds_read_b128 v[208:211], v192 offset:55296
	ds_read_b128 v[212:215], v192 offset:56320
	global_load_lds_dwordx4 v[184:185], off
	s_add_i32 m0, s36, 0x2000
	s_add_u32 s34, s34, 0x40080
	v_lshl_add_u64 v[184:185], v[216:217], 0, s[14:15]
	s_addc_u32 s35, s35, 0
	s_add_i32 s36, s60, s40
	global_load_lds_dwordx4 v[184:185], off
	v_lshl_add_u64 v[184:185], s[34:35], 0, v[144:145]
	s_mov_b32 m0, s36
	s_nop 0
	global_load_lds_dwordx4 v[184:185], off
	v_lshl_add_u64 v[184:185], s[34:35], 0, v[146:147]
	s_add_i32 m0, s36, 0x2000
	s_nop 0
	global_load_lds_dwordx4 v[184:185], off
	v_lshl_add_u64 v[184:185], v[218:219], 0, s[14:15]
	s_mov_b32 m0, s47
	s_nop 0
	global_load_lds_dwordx4 v[184:185], off
	v_lshl_add_u64 v[184:185], v[220:221], 0, s[14:15]
	s_mov_b32 m0, s48
	s_nop 0
	global_load_lds_dwordx4 v[184:185], off
	s_waitcnt vmcnt(8)
	s_waitcnt lgkmcnt(0)
	s_barrier
	s_setprio 1
	s_waitcnt lgkmcnt(0)
	v_mfma_f32_16x16x32_bf16 v[60:63], v[128:131], v[172:175], v[60:63]
	v_mfma_f32_16x16x32_bf16 v[56:59], v[136:139], v[172:175], v[56:59]
	v_mfma_f32_16x16x32_bf16 v[44:47], v[128:131], v[180:183], v[44:47]
	v_mfma_f32_16x16x32_bf16 v[40:43], v[136:139], v[180:183], v[40:43]
	v_mfma_f32_16x16x32_bf16 v[28:31], v[128:131], v[200:203], v[28:31]
	v_mfma_f32_16x16x32_bf16 v[24:27], v[136:139], v[200:203], v[24:27]
	v_mfma_f32_16x16x32_bf16 v[12:15], v[128:131], v[208:211], v[12:15]
	v_mfma_f32_16x16x32_bf16 v[8:11], v[136:139], v[208:211], v[8:11]
	v_mfma_f32_16x16x32_bf16 v[60:63], v[132:135], v[176:179], v[60:63]
	v_mfma_f32_16x16x32_bf16 v[56:59], v[140:143], v[176:179], v[56:59]
	v_mfma_f32_16x16x32_bf16 v[44:47], v[132:135], v[196:199], v[44:47]
	v_mfma_f32_16x16x32_bf16 v[40:43], v[140:143], v[196:199], v[40:43]
	v_mfma_f32_16x16x32_bf16 v[28:31], v[132:135], v[204:207], v[28:31]
	v_mfma_f32_16x16x32_bf16 v[24:27], v[140:143], v[204:207], v[24:27]
	v_mfma_f32_16x16x32_bf16 v[12:15], v[132:135], v[212:215], v[12:15]
	v_mfma_f32_16x16x32_bf16 v[8:11], v[140:143], v[212:215], v[8:11]
	s_setprio 0
	s_setprio 1
	v_mfma_f32_16x16x32_bf16 v[52:55], v[156:159], v[172:175], v[52:55]
	v_mfma_f32_16x16x32_bf16 v[48:51], v[164:167], v[172:175], v[48:51]
	v_mfma_f32_16x16x32_bf16 v[36:39], v[156:159], v[180:183], v[36:39]
	v_mfma_f32_16x16x32_bf16 v[32:35], v[164:167], v[180:183], v[32:35]
	v_mfma_f32_16x16x32_bf16 v[20:23], v[156:159], v[200:203], v[20:23]
	v_mfma_f32_16x16x32_bf16 v[16:19], v[164:167], v[200:203], v[16:19]
	v_mfma_f32_16x16x32_bf16 v[4:7], v[156:159], v[208:211], v[4:7]
	v_mfma_f32_16x16x32_bf16 v[0:3], v[164:167], v[208:211], v[0:3]
	v_mfma_f32_16x16x32_bf16 v[52:55], v[160:163], v[176:179], v[52:55]
	v_mfma_f32_16x16x32_bf16 v[48:51], v[168:171], v[176:179], v[48:51]
	v_mfma_f32_16x16x32_bf16 v[36:39], v[160:163], v[196:199], v[36:39]
	v_mfma_f32_16x16x32_bf16 v[32:35], v[168:171], v[196:199], v[32:35]
	v_mfma_f32_16x16x32_bf16 v[20:23], v[160:163], v[204:207], v[20:23]
	v_mfma_f32_16x16x32_bf16 v[16:19], v[168:171], v[204:207], v[16:19]
	v_mfma_f32_16x16x32_bf16 v[4:7], v[160:163], v[212:215], v[4:7]
	v_mfma_f32_16x16x32_bf16 v[0:3], v[168:171], v[212:215], v[0:3]
	s_setprio 0
	s_barrier
	s_add_i32 s58, s58, 2
	s_add_u32 s56, s56, 0x100
	s_addc_u32 s57, s57, 0
	s_add_u32 s30, s30, 0x100
	s_addc_u32 s31, s31, 0
	s_cmp_gt_u32 s58, 13
	s_cbranch_scc0 .LBB0_2118
	v_mbcnt_lo_u32_b32 v235, -1, 0
	v_mbcnt_hi_u32_b32 v235, -1, v235
	v_lshrrev_b32_e32 v236, 2, v235
	v_and_b32_e32 v237, 3, v235
	v_lshl_add_u32 v232, v237, 4, v236
	v_lshlrev_b32_e32 v232, 2, v232
	v_and_b32_e32 v233, -16, v186
	v_or_b32_e32 v233, v233, v236
	v_lshlrev_b32_e32 v237, 2, v237
	v_and_b32_e32 v234, -13, v188
	v_or_b32_e32 v234, v234, v237
	ds_bpermute_b32 v127, v232, v127
	ds_bpermute_b32 v126, v232, v126
	ds_bpermute_b32 v125, v232, v125
	ds_bpermute_b32 v124, v232, v124
	ds_bpermute_b32 v123, v232, v123
	ds_bpermute_b32 v122, v232, v122
	ds_bpermute_b32 v121, v232, v121
	ds_bpermute_b32 v120, v232, v120
	ds_bpermute_b32 v119, v232, v119
	ds_bpermute_b32 v118, v232, v118
	ds_bpermute_b32 v117, v232, v117
	ds_bpermute_b32 v116, v232, v116
	ds_bpermute_b32 v115, v232, v115
	ds_bpermute_b32 v114, v232, v114
	ds_bpermute_b32 v113, v232, v113
	ds_bpermute_b32 v112, v232, v112
	ds_bpermute_b32 v111, v232, v111
	ds_bpermute_b32 v110, v232, v110
	ds_bpermute_b32 v109, v232, v109
	ds_bpermute_b32 v108, v232, v108
	ds_bpermute_b32 v107, v232, v107
	ds_bpermute_b32 v106, v232, v106
	ds_bpermute_b32 v105, v232, v105
	ds_bpermute_b32 v104, v232, v104
	ds_bpermute_b32 v103, v232, v103
	ds_bpermute_b32 v102, v232, v102
	ds_bpermute_b32 v101, v232, v101
	ds_bpermute_b32 v100, v232, v100
	ds_bpermute_b32 v99, v232, v99
	ds_bpermute_b32 v98, v232, v98
	ds_bpermute_b32 v97, v232, v97
	ds_bpermute_b32 v96, v232, v96
	ds_bpermute_b32 v95, v232, v95
	ds_bpermute_b32 v94, v232, v94
	ds_bpermute_b32 v93, v232, v93
	ds_bpermute_b32 v92, v232, v92
	ds_bpermute_b32 v91, v232, v91
	ds_bpermute_b32 v90, v232, v90
	ds_bpermute_b32 v89, v232, v89
	ds_bpermute_b32 v88, v232, v88
	ds_bpermute_b32 v87, v232, v87
	ds_bpermute_b32 v86, v232, v86
	ds_bpermute_b32 v85, v232, v85
	ds_bpermute_b32 v84, v232, v84
	ds_bpermute_b32 v83, v232, v83
	ds_bpermute_b32 v82, v232, v82
	ds_bpermute_b32 v81, v232, v81
	ds_bpermute_b32 v80, v232, v80
	ds_bpermute_b32 v79, v232, v79
	ds_bpermute_b32 v78, v232, v78
	ds_bpermute_b32 v77, v232, v77
	ds_bpermute_b32 v76, v232, v76
	ds_bpermute_b32 v75, v232, v75
	ds_bpermute_b32 v74, v232, v74
	ds_bpermute_b32 v73, v232, v73
	ds_bpermute_b32 v72, v232, v72
	ds_bpermute_b32 v71, v232, v71
	ds_bpermute_b32 v70, v232, v70
	ds_bpermute_b32 v69, v232, v69
	ds_bpermute_b32 v68, v232, v68
	ds_bpermute_b32 v67, v232, v67
	ds_bpermute_b32 v66, v232, v66
	ds_bpermute_b32 v65, v232, v65
	ds_bpermute_b32 v64, v232, v64
	ds_bpermute_b32 v63, v232, v63
	ds_bpermute_b32 v62, v232, v62
	ds_bpermute_b32 v61, v232, v61
	ds_bpermute_b32 v60, v232, v60
	ds_bpermute_b32 v59, v232, v59
	ds_bpermute_b32 v58, v232, v58
	ds_bpermute_b32 v57, v232, v57
	ds_bpermute_b32 v56, v232, v56
	ds_bpermute_b32 v55, v232, v55
	ds_bpermute_b32 v54, v232, v54
	ds_bpermute_b32 v53, v232, v53
	ds_bpermute_b32 v52, v232, v52
	ds_bpermute_b32 v51, v232, v51
	ds_bpermute_b32 v50, v232, v50
	ds_bpermute_b32 v49, v232, v49
	ds_bpermute_b32 v48, v232, v48
	ds_bpermute_b32 v47, v232, v47
	ds_bpermute_b32 v46, v232, v46
	ds_bpermute_b32 v45, v232, v45
	ds_bpermute_b32 v44, v232, v44
	ds_bpermute_b32 v43, v232, v43
	ds_bpermute_b32 v42, v232, v42
	ds_bpermute_b32 v41, v232, v41
	ds_bpermute_b32 v40, v232, v40
	ds_bpermute_b32 v39, v232, v39
	ds_bpermute_b32 v38, v232, v38
	ds_bpermute_b32 v37, v232, v37
	ds_bpermute_b32 v36, v232, v36
	ds_bpermute_b32 v35, v232, v35
	ds_bpermute_b32 v34, v232, v34
	ds_bpermute_b32 v33, v232, v33
	ds_bpermute_b32 v32, v232, v32
	ds_bpermute_b32 v31, v232, v31
	ds_bpermute_b32 v30, v232, v30
	ds_bpermute_b32 v29, v232, v29
	ds_bpermute_b32 v28, v232, v28
	ds_bpermute_b32 v27, v232, v27
	ds_bpermute_b32 v26, v232, v26
	ds_bpermute_b32 v25, v232, v25
	ds_bpermute_b32 v24, v232, v24
	ds_bpermute_b32 v23, v232, v23
	ds_bpermute_b32 v22, v232, v22
	ds_bpermute_b32 v21, v232, v21
	ds_bpermute_b32 v20, v232, v20
	ds_bpermute_b32 v19, v232, v19
	ds_bpermute_b32 v18, v232, v18
	ds_bpermute_b32 v17, v232, v17
	ds_bpermute_b32 v16, v232, v16
	ds_bpermute_b32 v15, v232, v15
	ds_bpermute_b32 v14, v232, v14
	ds_bpermute_b32 v13, v232, v13
	ds_bpermute_b32 v12, v232, v12
	ds_bpermute_b32 v11, v232, v11
	ds_bpermute_b32 v10, v232, v10
	ds_bpermute_b32 v9, v232, v9
	ds_bpermute_b32 v8, v232, v8
	ds_bpermute_b32 v7, v232, v7
	ds_bpermute_b32 v6, v232, v6
	ds_bpermute_b32 v5, v232, v5
	ds_bpermute_b32 v4, v232, v4
	ds_bpermute_b32 v3, v232, v3
	ds_bpermute_b32 v2, v232, v2
	ds_bpermute_b32 v1, v232, v1
	ds_bpermute_b32 v0, v232, v0
	s_waitcnt lgkmcnt(0)
	v_lshl_add_u32 v160, s26, 8, v233
	v_ashrrev_i32_e32 v161, 31, v160
	v_lshl_add_u64 v[158:159], v[160:161], 2, s[12:13]
	global_load_dword v169, v[158:159], off
	v_lshl_or_b32 v156, s28, 8, v234
	v_lshlrev_b64 v[128:129], 11, v[160:161]
	v_ashrrev_i32_e32 v157, 31, v156
	v_lshlrev_b64 v[132:133], 12, v[160:161]
	v_lshl_add_u64 v[128:129], s[6:7], 0, v[128:129]
	v_lshlrev_b64 v[130:131], 1, v[156:157]
	v_lshlrev_b64 v[134:135], 2, v[156:157]
	v_lshl_add_u64 v[132:133], s[4:5], 0, v[132:133]
	v_lshl_add_u64 v[128:129], v[128:129], 0, v[130:131]
	v_lshl_add_u64 v[166:167], v[132:133], 0, v[134:135]
	global_load_dwordx2 v[172:173], v[128:129], off
	global_load_dwordx2 v[176:177], v[128:129], off offset:32
	global_load_dwordx4 v[196:199], v[166:167], off
	global_load_dwordx4 v[200:203], v[166:167], off offset:64
	v_or_b32_e32 v162, 16, v160
	v_ashrrev_i32_e32 v163, 31, v162
	v_lshl_add_u64 v[138:139], v[162:163], 2, s[12:13]
	global_load_dword v168, v[138:139], off
	global_load_dwordx4 v[204:207], v[166:167], off offset:512
	global_load_dwordx4 v[208:211], v[166:167], off offset:576
	global_load_dwordx2 v[180:181], v[128:129], off offset:256
	global_load_dwordx2 v[184:185], v[128:129], off offset:288
	v_lshlrev_b64 v[132:133], 12, v[162:163]
	v_lshlrev_b64 v[136:137], 11, v[162:163]
	v_lshl_add_u64 v[132:133], s[4:5], 0, v[132:133]
	v_lshl_add_u64 v[136:137], s[6:7], 0, v[136:137]
	v_lshl_add_u64 v[164:165], v[132:133], 0, v[134:135]
	v_lshl_add_u64 v[170:171], v[136:137], 0, v[130:131]
	global_load_dwordx4 v[140:143], v[164:165], off
	global_load_dwordx4 v[136:139], v[164:165], off offset:64
	global_load_dwordx4 v[132:135], v[164:165], off offset:512
	global_load_dwordx4 v[128:131], v[164:165], off offset:576
	global_load_dwordx2 v[182:183], v[170:171], off
	global_load_dwordx2 v[178:179], v[170:171], off offset:32
	global_load_dwordx2 v[174:175], v[170:171], off offset:256
	s_nop 0
	global_load_dwordx2 v[170:171], v[170:171], off offset:288
	s_waitcnt lgkmcnt(0)
	s_and_b64 vcc, exec, s[16:17]
	s_cbranch_vccz .LBB0_2121
	s_barrier
.LBB0_2121:
	s_waitcnt vmcnt(17)
	v_fmamk_f32 v169, v169, 0x3a800000, v193
	v_mul_f32_e32 v195, 0x4b800000, v169
	v_cmp_gt_f32_e32 vcc, s55, v169
	s_waitcnt vmcnt(16)
	v_lshlrev_b32_e32 v212, 16, v172
	s_nop 0
	v_cndmask_b32_e32 v169, v169, v195, vcc
	v_rsq_f32_e32 v169, v169
	v_and_b32_e32 v213, 0xffff0000, v172
	v_lshlrev_b32_e32 v172, 16, v173
	v_and_b32_e32 v173, 0xffff0000, v173
	v_mul_f32_e32 v195, 0x45800000, v169
	v_cndmask_b32_e32 v216, v169, v195, vcc
	v_pk_mul_f32 v[126:127], v[126:127], v[216:217] op_sel_hi:[1,0]
	v_pk_mul_f32 v[124:125], v[124:125], v[216:217] op_sel_hi:[1,0]
	v_pk_mul_f32 v[116:117], v[116:117], v[216:217] op_sel_hi:[1,0]
	v_pk_mul_f32 v[218:219], v[118:119], v[216:217] op_sel_hi:[1,0]
	v_mul_f32_e32 v119, 0xbfb8aa3b, v125
	v_mul_f32_e32 v125, 0xbfb8aa3b, v127
	v_mul_f32_e32 v117, 0xbfb8aa3b, v117
	v_mul_f32_e32 v118, 0xbfb8aa3b, v124
	v_mul_f32_e32 v124, 0xbfb8aa3b, v126
	v_exp_f32_e32 v119, v119
	v_exp_f32_e32 v125, v125
	v_exp_f32_e32 v127, v117
	v_exp_f32_e32 v118, v118
	v_exp_f32_e32 v124, v124
	v_mul_f32_e32 v116, 0xbfb8aa3b, v116
	v_add_f32_e32 v117, 1.0, v119
	v_add_f32_e32 v119, 1.0, v125
	v_add_f32_e32 v125, 1.0, v127
	v_mul_f32_e32 v127, 0xbfb8aa3b, v218
	v_exp_f32_e32 v126, v116
	v_add_f32_e32 v116, 1.0, v118
	v_add_f32_e32 v118, 1.0, v124
	v_exp_f32_e32 v169, v127
	v_mul_f32_e32 v127, 0xbfb8aa3b, v219
	v_rcp_f32_e32 v118, v118
	v_rcp_f32_e32 v119, v119
	v_exp_f32_e32 v195, v127
	v_add_f32_e32 v169, 1.0, v169
	v_pk_mul_f32 v[112:113], v[112:113], v[216:217] op_sel_hi:[1,0]
	s_waitcnt vmcnt(14)
	v_pk_fma_f32 v[118:119], v[118:119], v[172:173], v[198:199]
	v_rcp_f32_e32 v198, v169
	v_add_f32_e32 v169, 1.0, v195
	v_mul_f32_e32 v112, 0xbfb8aa3b, v112
	v_rcp_f32_e32 v199, v169
	v_exp_f32_e32 v169, v112
	v_mul_f32_e32 v112, 0xbfb8aa3b, v113
	v_pk_mul_f32 v[122:123], v[122:123], v[216:217] op_sel_hi:[1,0]
	v_pk_mul_f32 v[120:121], v[120:121], v[216:217] op_sel_hi:[1,0]
	v_exp_f32_e32 v195, v112
	v_pk_mul_f32 v[112:113], v[114:115], v[216:217] op_sel_hi:[1,0]
	v_mul_f32_e32 v120, 0xbfb8aa3b, v120
	v_mul_f32_e32 v121, 0xbfb8aa3b, v121
	v_mul_f32_e32 v122, 0xbfb8aa3b, v122
	v_mul_f32_e32 v123, 0xbfb8aa3b, v123
	v_mul_f32_e32 v112, 0xbfb8aa3b, v112
	v_mul_f32_e32 v113, 0xbfb8aa3b, v113
	v_exp_f32_e32 v120, v120
	v_exp_f32_e32 v121, v121
	v_exp_f32_e32 v122, v122
	v_exp_f32_e32 v123, v123
	v_exp_f32_e32 v112, v112
	v_exp_f32_e32 v113, v113
	v_add_f32_e32 v124, 1.0, v126
	v_rcp_f32_e32 v124, v124
	v_rcp_f32_e32 v125, v125
	v_add_f32_e32 v114, 1.0, v169
	v_add_f32_e32 v115, 1.0, v195
	v_add_f32_e32 v120, 1.0, v120
	v_add_f32_e32 v121, 1.0, v121
	v_add_f32_e32 v122, 1.0, v122
	v_add_f32_e32 v123, 1.0, v123
	v_rcp_f32_e32 v114, v114
	v_rcp_f32_e32 v115, v115
	v_add_f32_e32 v112, 1.0, v112
	v_add_f32_e32 v113, 1.0, v113
	v_rcp_f32_e32 v116, v116
	v_rcp_f32_e32 v117, v117
	v_rcp_f32_e32 v120, v120
	v_rcp_f32_e32 v121, v121
	v_rcp_f32_e32 v122, v122
	v_rcp_f32_e32 v123, v123
	s_waitcnt vmcnt(9)
	v_lshlrev_b32_e32 v126, 16, v180
	v_and_b32_e32 v127, 0xffff0000, v180
	v_rcp_f32_e32 v112, v112
	v_rcp_f32_e32 v113, v113
	v_pk_fma_f32 v[124:125], v[124:125], v[126:127], v[204:205]
	v_lshlrev_b32_e32 v126, 16, v181
	v_and_b32_e32 v127, 0xffff0000, v181
	v_pk_fma_f32 v[126:127], v[198:199], v[126:127], v[206:207]
	s_waitcnt vmcnt(8)
	v_lshlrev_b32_e32 v198, 16, v184
	v_and_b32_e32 v199, 0xffff0000, v184
	v_lshlrev_b32_e32 v214, 16, v176
	v_and_b32_e32 v215, 0xffff0000, v176
	v_lshlrev_b32_e32 v176, 16, v177
	v_and_b32_e32 v177, 0xffff0000, v177
	v_pk_fma_f32 v[198:199], v[114:115], v[198:199], v[208:209]
	v_lshlrev_b32_e32 v114, 16, v185
	v_and_b32_e32 v115, 0xffff0000, v185
	v_pk_fma_f32 v[116:117], v[116:117], v[212:213], v[196:197]
	v_pk_fma_f32 v[120:121], v[120:121], v[214:215], v[200:201]
	v_pk_fma_f32 v[122:123], v[122:123], v[176:177], v[202:203]
	v_pk_fma_f32 v[200:201], v[112:113], v[114:115], v[210:211]
	v_pk_mul_f32 v[172:173], v[116:117], v[116:117]
	v_pk_mul_f32 v[176:177], v[118:119], v[118:119]
	v_pk_mul_f32 v[196:197], v[120:121], v[120:121]
	v_pk_mul_f32 v[202:203], v[122:123], v[122:123]
	v_pk_mul_f32 v[112:113], v[198:199], v[198:199]
	v_pk_mul_f32 v[114:115], v[200:201], v[200:201]
	v_add_f32_e32 v169, v202, v203
	v_add_f32_e32 v184, v196, v197
	v_add_f32_e32 v176, v176, v177
	v_add_f32_e32 v172, v172, v173
	v_add_f32_e32 v114, v114, v115
	v_add_f32_e32 v112, v112, v113
	v_pk_mul_f32 v[180:181], v[124:125], v[124:125]
	v_pk_mul_f32 v[204:205], v[126:127], v[126:127]
	v_add_f32_e32 v169, v184, v169
	v_add_f32_e32 v172, v172, v176
	v_add_f32_e32 v112, v112, v114
	v_and_b32_e32 v114, 64, v194
	v_add_f32_e32 v169, v172, v169
	v_add_f32_e32 v172, v204, v205
	v_add_f32_e32 v173, v180, v181
	v_xor_b32_e32 v113, 1, v194
	v_add_u32_e32 v114, 64, v114
	v_add_f32_e32 v172, v173, v172
	v_cmp_lt_i32_e32 vcc, v113, v114
	v_add_f32_e32 v169, v172, v169
	v_add_f32_e32 v112, v112, v169
	v_cndmask_b32_e32 v113, v194, v113, vcc
	v_lshlrev_b32_e32 v195, 2, v113
	ds_bpermute_b32 v113, v195, v112
	global_store_dwordx4 v[166:167], v[116:119], off
	global_store_dwordx4 v[166:167], v[120:123], off offset:64
	global_store_dwordx4 v[166:167], v[124:127], off offset:512
	global_store_dwordx4 v[166:167], v[198:201], off offset:576
	s_waitcnt lgkmcnt(0)
	v_add_f32_e32 v112, v112, v113
	v_xor_b32_e32 v113, 2, v194
	v_cmp_lt_i32_e32 vcc, v113, v114
	s_nop 1
	v_cndmask_b32_e32 v113, v194, v113, vcc
	v_lshlrev_b32_e32 v196, 2, v113
	ds_bpermute_b32 v113, v196, v112
	s_mov_b32 vcc_lo, 0x11111111
	s_mov_b32 vcc_hi, 0x11111111
	s_and_saveexec_b64 s[26:27], vcc
	s_cbranch_execz .LBB0_2123
	v_lshl_add_u64 v[114:115], v[160:161], 2, s[10:11]
	s_waitcnt lgkmcnt(0)
	v_add_f32_e32 v112, v112, v113
	global_atomic_add_f32 v[114:115], v112, off
.LBB0_2123:
	s_or_b64 exec, exec, s[26:27]
	v_fmamk_f32 v112, v168, 0x3a800000, v193
	s_waitcnt lgkmcnt(0)
	v_mul_f32_e32 v113, 0x4b800000, v112
	v_cmp_gt_f32_e32 vcc, s55, v112
	v_or_b32_e32 v166, 32, v160
	v_ashrrev_i32_e32 v167, 31, v166
	v_cndmask_b32_e32 v112, v112, v113, vcc
	v_rsq_f32_e32 v112, v112
	v_lshlrev_b64 v[114:115], 11, v[166:167]
	v_lshl_add_u64 v[114:115], s[6:7], 0, v[114:115]
	v_mul_f32_e32 v113, 0x45800000, v112
	v_cndmask_b32_e32 v198, v112, v113, vcc
	v_lshlrev_b64 v[112:113], 12, v[166:167]
	v_lshl_add_u64 v[112:113], s[4:5], 0, v[112:113]
	v_lshl_add_u64 v[168:169], v[156:157], 2, v[112:113]
	v_lshl_add_u64 v[172:173], v[156:157], 1, v[114:115]
	global_load_dwordx4 v[124:127], v[168:169], off
	global_load_dwordx4 v[120:123], v[168:169], off offset:64
	global_load_dwordx4 v[116:119], v[168:169], off offset:512
	global_load_dwordx4 v[112:115], v[168:169], off offset:576
	global_load_dwordx2 v[184:185], v[172:173], off
	global_load_dwordx2 v[180:181], v[172:173], off offset:32
	global_load_dwordx2 v[176:177], v[172:173], off offset:256
	s_nop 0
	global_load_dwordx2 v[172:173], v[172:173], off offset:288
	v_lshl_add_u64 v[200:201], v[166:167], 2, s[12:13]
	global_load_dword v161, v[200:201], off
	v_pk_mul_f32 v[108:109], v[108:109], v[198:199] op_sel_hi:[1,0]
	s_waitcnt vmcnt(16)
	v_lshlrev_b32_e32 v200, 16, v182
	v_mul_f32_e32 v108, 0xbfb8aa3b, v108
	v_exp_f32_e32 v197, v108
	v_mul_f32_e32 v108, 0xbfb8aa3b, v109
	v_exp_f32_e32 v199, v108
	v_and_b32_e32 v201, 0xffff0000, v182
	v_pk_mul_f32 v[108:109], v[110:111], v[198:199] op_sel_hi:[1,0]
	s_nop 0
	v_mul_f32_e32 v108, 0xbfb8aa3b, v108
	v_exp_f32_e32 v108, v108
	v_mul_f32_e32 v109, 0xbfb8aa3b, v109
	v_add_f32_e32 v110, 1.0, v197
	v_add_f32_e32 v111, 1.0, v199
	v_exp_f32_e32 v109, v109
	v_rcp_f32_e32 v110, v110
	v_rcp_f32_e32 v111, v111
	v_pk_mul_f32 v[104:105], v[104:105], v[198:199] op_sel_hi:[1,0]
	v_add_f32_e32 v108, 1.0, v108
	v_mul_f32_e32 v104, 0xbfb8aa3b, v104
	v_rcp_f32_e32 v202, v108
	v_add_f32_e32 v108, 1.0, v109
	v_exp_f32_e32 v182, v104
	v_mul_f32_e32 v104, 0xbfb8aa3b, v105
	v_rcp_f32_e32 v203, v108
	v_pk_fma_f32 v[108:109], v[110:111], v[200:201], v[140:141]
	v_lshlrev_b32_e32 v110, 16, v183
	v_and_b32_e32 v111, 0xffff0000, v183
	v_exp_f32_e32 v183, v104
	v_pk_mul_f32 v[104:105], v[106:107], v[198:199] op_sel_hi:[1,0]
	v_add_f32_e32 v106, 1.0, v182
	v_mul_f32_e32 v104, 0xbfb8aa3b, v104
	v_exp_f32_e32 v104, v104
	v_mul_f32_e32 v105, 0xbfb8aa3b, v105
	v_add_f32_e32 v107, 1.0, v183
	v_exp_f32_e32 v105, v105
	v_rcp_f32_e32 v106, v106
	v_rcp_f32_e32 v107, v107
	v_pk_mul_f32 v[100:101], v[100:101], v[198:199] op_sel_hi:[1,0]
	v_add_f32_e32 v104, 1.0, v104
	v_mul_f32_e32 v100, 0xbfb8aa3b, v100
	s_waitcnt vmcnt(15)
	v_lshlrev_b32_e32 v182, 16, v178
	v_and_b32_e32 v183, 0xffff0000, v178
	v_rcp_f32_e32 v200, v104
	v_add_f32_e32 v104, 1.0, v105
	v_exp_f32_e32 v178, v100
	v_mul_f32_e32 v100, 0xbfb8aa3b, v101
	v_rcp_f32_e32 v201, v104
	v_pk_fma_f32 v[104:105], v[106:107], v[182:183], v[136:137]
	v_lshlrev_b32_e32 v106, 16, v179
	v_and_b32_e32 v107, 0xffff0000, v179
	v_exp_f32_e32 v179, v100
	v_pk_mul_f32 v[100:101], v[102:103], v[198:199] op_sel_hi:[1,0]
	v_add_f32_e32 v102, 1.0, v178
	v_mul_f32_e32 v100, 0xbfb8aa3b, v100
	v_exp_f32_e32 v100, v100
	v_mul_f32_e32 v101, 0xbfb8aa3b, v101
	v_add_f32_e32 v103, 1.0, v179
	v_exp_f32_e32 v101, v101
	v_rcp_f32_e32 v102, v102
	v_rcp_f32_e32 v103, v103
	v_pk_mul_f32 v[96:97], v[96:97], v[198:199] op_sel_hi:[1,0]
	v_add_f32_e32 v100, 1.0, v100
	v_mul_f32_e32 v96, 0xbfb8aa3b, v96
	s_waitcnt vmcnt(14)
	v_lshlrev_b32_e32 v178, 16, v174
	v_and_b32_e32 v179, 0xffff0000, v174
	v_rcp_f32_e32 v182, v100
	v_add_f32_e32 v100, 1.0, v101
	v_exp_f32_e32 v174, v96
	v_mul_f32_e32 v96, 0xbfb8aa3b, v97
	v_rcp_f32_e32 v183, v100
	v_pk_fma_f32 v[100:101], v[102:103], v[178:179], v[132:133]
	v_lshlrev_b32_e32 v102, 16, v175
	v_and_b32_e32 v103, 0xffff0000, v175
	v_exp_f32_e32 v175, v96
	v_pk_mul_f32 v[96:97], v[98:99], v[198:199] op_sel_hi:[1,0]
	v_add_f32_e32 v98, 1.0, v174
	v_mul_f32_e32 v96, 0xbfb8aa3b, v96
	v_mul_f32_e32 v97, 0xbfb8aa3b, v97
	v_exp_f32_e32 v96, v96
	v_exp_f32_e32 v97, v97
	v_add_f32_e32 v99, 1.0, v175
	v_rcp_f32_e32 v98, v98
	v_rcp_f32_e32 v99, v99
	v_add_f32_e32 v96, 1.0, v96
	v_add_f32_e32 v97, 1.0, v97
	v_rcp_f32_e32 v96, v96
	v_rcp_f32_e32 v97, v97
	v_pk_fma_f32 v[106:107], v[200:201], v[106:107], v[138:139]
	v_pk_fma_f32 v[110:111], v[202:203], v[110:111], v[142:143]
	v_pk_mul_f32 v[136:137], v[104:105], v[104:105]
	v_pk_mul_f32 v[138:139], v[106:107], v[106:107]
	s_waitcnt vmcnt(13)
	v_lshlrev_b32_e32 v174, 16, v170
	v_and_b32_e32 v175, 0xffff0000, v170
	v_pk_mul_f32 v[140:141], v[108:109], v[108:109]
	v_pk_mul_f32 v[142:143], v[110:111], v[110:111]
	v_pk_fma_f32 v[102:103], v[182:183], v[102:103], v[134:135]
	v_pk_fma_f32 v[128:129], v[98:99], v[174:175], v[128:129]
	v_lshlrev_b32_e32 v98, 16, v171
	v_and_b32_e32 v99, 0xffff0000, v171
	v_add_f32_e32 v138, v138, v139
	v_add_f32_e32 v136, v136, v137
	v_pk_mul_f32 v[132:133], v[100:101], v[100:101]
	v_pk_mul_f32 v[134:135], v[102:103], v[102:103]
	v_pk_fma_f32 v[130:131], v[96:97], v[98:99], v[130:131]
	v_add_f32_e32 v136, v136, v138
	v_add_f32_e32 v137, v142, v143
	v_add_f32_e32 v138, v140, v141
	v_pk_mul_f32 v[96:97], v[128:129], v[128:129]
	v_pk_mul_f32 v[98:99], v[130:131], v[130:131]
	v_add_f32_e32 v137, v138, v137
	v_add_f32_e32 v134, v134, v135
	v_add_f32_e32 v132, v132, v133
	v_add_f32_e32 v136, v137, v136
	v_add_f32_e32 v132, v132, v134
	v_add_f32_e32 v98, v98, v99
	v_add_f32_e32 v96, v96, v97
	v_add_f32_e32 v132, v132, v136
	v_add_f32_e32 v96, v96, v98
	v_add_f32_e32 v96, v96, v132
	ds_bpermute_b32 v97, v195, v96
	global_store_dwordx4 v[164:165], v[108:111], off
	global_store_dwordx4 v[164:165], v[104:107], off offset:64
	global_store_dwordx4 v[164:165], v[100:103], off offset:512
	global_store_dwordx4 v[164:165], v[128:131], off offset:576
	s_waitcnt lgkmcnt(0)
	v_add_f32_e32 v96, v96, v97
	ds_bpermute_b32 v97, v196, v96
	s_mov_b32 vcc_lo, 0x11111111
	s_mov_b32 vcc_hi, 0x11111111
	s_and_saveexec_b64 s[26:27], vcc
	s_cbranch_execz .LBB0_2125
	v_lshl_add_u64 v[98:99], v[162:163], 2, s[10:11]
	s_waitcnt lgkmcnt(0)
	v_add_f32_e32 v96, v96, v97
	global_atomic_add_f32 v[98:99], v96, off
.LBB0_2125:
	s_or_b64 exec, exec, s[26:27]
	s_waitcnt vmcnt(4)
	v_fmamk_f32 v96, v161, 0x3a800000, v193
	s_waitcnt lgkmcnt(0)
	v_mul_f32_e32 v97, 0x4b800000, v96
	v_cmp_gt_f32_e32 vcc, s55, v96
	v_or_b32_e32 v128, 48, v160
	v_ashrrev_i32_e32 v129, 31, v128
	v_cndmask_b32_e32 v96, v96, v97, vcc
	v_rsq_f32_e32 v96, v96
	v_lshlrev_b64 v[98:99], 11, v[128:129]
	v_lshl_add_u64 v[98:99], s[6:7], 0, v[98:99]
	v_mul_f32_e32 v97, 0x45800000, v96
	v_cndmask_b32_e32 v142, v96, v97, vcc
	v_lshlrev_b64 v[96:97], 12, v[128:129]
	v_lshl_add_u64 v[96:97], s[4:5], 0, v[96:97]
	v_lshl_add_u64 v[130:131], v[156:157], 2, v[96:97]
	v_lshl_add_u64 v[132:133], v[156:157], 1, v[98:99]
	global_load_dwordx4 v[108:111], v[130:131], off
	global_load_dwordx4 v[104:107], v[130:131], off offset:64
	global_load_dwordx4 v[100:103], v[130:131], off offset:512
	global_load_dwordx4 v[96:99], v[130:131], off offset:576
	global_load_dwordx2 v[138:139], v[132:133], off
	global_load_dwordx2 v[136:137], v[132:133], off offset:32
	global_load_dwordx2 v[134:135], v[132:133], off offset:256
	s_nop 0
	global_load_dwordx2 v[132:133], v[132:133], off offset:288
	v_lshl_add_u64 v[140:141], v[128:129], 2, s[12:13]
	global_load_dword v140, v[140:141], off
	v_pk_mul_f32 v[92:93], v[92:93], v[142:143] op_sel_hi:[1,0]
	v_lshlrev_b32_e32 v162, 16, v184
	v_mul_f32_e32 v92, 0xbfb8aa3b, v92
	v_exp_f32_e32 v141, v92
	v_mul_f32_e32 v92, 0xbfb8aa3b, v93
	v_exp_f32_e32 v143, v92
	v_and_b32_e32 v163, 0xffff0000, v184
	v_pk_mul_f32 v[88:89], v[88:89], v[142:143] op_sel_hi:[1,0]
	s_nop 0
	v_mul_f32_e32 v88, 0xbfb8aa3b, v88
	v_pk_mul_f32 v[92:93], v[94:95], v[142:143] op_sel_hi:[1,0]
	v_add_f32_e32 v94, 1.0, v141
	v_exp_f32_e32 v141, v88
	v_mul_f32_e32 v88, 0xbfb8aa3b, v89
	v_add_f32_e32 v95, 1.0, v143
	v_exp_f32_e32 v143, v88
	v_mul_f32_e32 v92, 0xbfb8aa3b, v92
	v_exp_f32_e32 v92, v92
	v_mul_f32_e32 v93, 0xbfb8aa3b, v93
	v_pk_mul_f32 v[84:85], v[84:85], v[142:143] op_sel_hi:[1,0]
	v_pk_mul_f32 v[88:89], v[90:91], v[142:143] op_sel_hi:[1,0]
	v_mul_f32_e32 v84, 0xbfb8aa3b, v84
	v_add_f32_e32 v90, 1.0, v141
	v_exp_f32_e32 v141, v84
	v_mul_f32_e32 v84, 0xbfb8aa3b, v85
	v_add_f32_e32 v91, 1.0, v143
	v_exp_f32_e32 v143, v84
	v_exp_f32_e32 v93, v93
	v_add_f32_e32 v92, 1.0, v92
	v_mul_f32_e32 v88, 0xbfb8aa3b, v88
	v_pk_mul_f32 v[80:81], v[80:81], v[142:143] op_sel_hi:[1,0]
	v_rcp_f32_e32 v94, v94
	v_mul_f32_e32 v80, 0xbfb8aa3b, v80
	v_rcp_f32_e32 v95, v95
	v_rcp_f32_e32 v164, v92
	v_add_f32_e32 v92, 1.0, v93
	v_exp_f32_e32 v88, v88
	v_mul_f32_e32 v89, 0xbfb8aa3b, v89
	v_pk_mul_f32 v[84:85], v[86:87], v[142:143] op_sel_hi:[1,0]
	v_add_f32_e32 v86, 1.0, v141
	v_exp_f32_e32 v141, v80
	v_mul_f32_e32 v80, 0xbfb8aa3b, v81
	v_rcp_f32_e32 v165, v92
	v_exp_f32_e32 v89, v89
	v_add_f32_e32 v87, 1.0, v143
	v_exp_f32_e32 v143, v80
	v_pk_fma_f32 v[92:93], v[94:95], v[162:163], v[124:125]
	v_lshlrev_b32_e32 v94, 16, v185
	v_and_b32_e32 v95, 0xffff0000, v185
	v_add_f32_e32 v88, 1.0, v88
	v_mul_f32_e32 v84, 0xbfb8aa3b, v84
	v_pk_fma_f32 v[94:95], v[164:165], v[94:95], v[126:127]
	v_rcp_f32_e32 v90, v90
	v_rcp_f32_e32 v91, v91
	v_rcp_f32_e32 v164, v88
	v_add_f32_e32 v88, 1.0, v89
	v_exp_f32_e32 v84, v84
	v_mul_f32_e32 v85, 0xbfb8aa3b, v85
	v_pk_mul_f32 v[80:81], v[82:83], v[142:143] op_sel_hi:[1,0]
	v_rcp_f32_e32 v165, v88
	v_exp_f32_e32 v85, v85
	v_mul_f32_e32 v80, 0xbfb8aa3b, v80
	v_mul_f32_e32 v81, 0xbfb8aa3b, v81
	v_exp_f32_e32 v80, v80
	v_exp_f32_e32 v81, v81
	v_lshlrev_b32_e32 v162, 16, v180
	v_and_b32_e32 v163, 0xffff0000, v180
	v_pk_fma_f32 v[88:89], v[90:91], v[162:163], v[120:121]
	v_lshlrev_b32_e32 v90, 16, v181
	v_and_b32_e32 v91, 0xffff0000, v181
	v_add_f32_e32 v84, 1.0, v84
	v_pk_fma_f32 v[90:91], v[164:165], v[90:91], v[122:123]
	v_rcp_f32_e32 v86, v86
	v_rcp_f32_e32 v87, v87
	v_rcp_f32_e32 v164, v84
	v_add_f32_e32 v84, 1.0, v85
	v_add_f32_e32 v82, 1.0, v141
	v_add_f32_e32 v83, 1.0, v143
	v_rcp_f32_e32 v165, v84
	v_rcp_f32_e32 v82, v82
	v_rcp_f32_e32 v83, v83
	v_add_f32_e32 v80, 1.0, v80
	v_add_f32_e32 v81, 1.0, v81
	v_rcp_f32_e32 v80, v80
	v_rcp_f32_e32 v81, v81
	v_lshlrev_b32_e32 v162, 16, v176
	v_and_b32_e32 v163, 0xffff0000, v176
	v_pk_mul_f32 v[120:121], v[88:89], v[88:89]
	v_pk_mul_f32 v[122:123], v[90:91], v[90:91]
	v_pk_fma_f32 v[84:85], v[86:87], v[162:163], v[116:117]
	v_lshlrev_b32_e32 v86, 16, v177
	v_and_b32_e32 v87, 0xffff0000, v177
	v_lshlrev_b32_e32 v142, 16, v172
	v_and_b32_e32 v143, 0xffff0000, v172
	v_pk_mul_f32 v[124:125], v[92:93], v[92:93]
	v_pk_mul_f32 v[126:127], v[94:95], v[94:95]
	v_pk_fma_f32 v[86:87], v[164:165], v[86:87], v[118:119]
	v_pk_fma_f32 v[112:113], v[82:83], v[142:143], v[112:113]
	v_lshlrev_b32_e32 v82, 16, v173
	v_and_b32_e32 v83, 0xffff0000, v173
	v_add_f32_e32 v122, v122, v123
	v_add_f32_e32 v120, v120, v121
	v_pk_mul_f32 v[116:117], v[84:85], v[84:85]
	v_pk_mul_f32 v[118:119], v[86:87], v[86:87]
	v_pk_fma_f32 v[114:115], v[80:81], v[82:83], v[114:115]
	v_add_f32_e32 v120, v120, v122
	v_add_f32_e32 v121, v126, v127
	v_add_f32_e32 v122, v124, v125
	v_pk_mul_f32 v[80:81], v[112:113], v[112:113]
	v_pk_mul_f32 v[82:83], v[114:115], v[114:115]
	v_add_f32_e32 v121, v122, v121
	v_add_f32_e32 v118, v118, v119
	v_add_f32_e32 v116, v116, v117
	v_add_f32_e32 v120, v121, v120
	v_add_f32_e32 v116, v116, v118
	v_add_f32_e32 v82, v82, v83
	v_add_f32_e32 v80, v80, v81
	v_add_f32_e32 v116, v116, v120
	v_add_f32_e32 v80, v80, v82
	v_add_f32_e32 v80, v80, v116
	ds_bpermute_b32 v81, v195, v80
	global_store_dwordx4 v[168:169], v[92:95], off
	global_store_dwordx4 v[168:169], v[88:91], off offset:64
	global_store_dwordx4 v[168:169], v[84:87], off offset:512
	global_store_dwordx4 v[168:169], v[112:115], off offset:576
	s_waitcnt lgkmcnt(0)
	v_add_f32_e32 v80, v80, v81
	ds_bpermute_b32 v81, v196, v80
	s_mov_b32 vcc_lo, 0x11111111
	s_mov_b32 vcc_hi, 0x11111111
	s_and_saveexec_b64 s[26:27], vcc
	s_cbranch_execz .LBB0_2127
	v_lshl_add_u64 v[82:83], v[166:167], 2, s[10:11]
	s_waitcnt lgkmcnt(0)
	v_add_f32_e32 v80, v80, v81
	global_atomic_add_f32 v[82:83], v80, off
.LBB0_2127:
	s_or_b64 exec, exec, s[26:27]
	s_waitcnt vmcnt(4)
	v_fmamk_f32 v80, v140, 0x3a800000, v193
	s_waitcnt lgkmcnt(0)
	v_mul_f32_e32 v81, 0x4b800000, v80
	v_cmp_gt_f32_e32 vcc, s55, v80
	v_add_u32_e32 v112, 0x80, v160
	v_ashrrev_i32_e32 v113, 31, v112
	v_cndmask_b32_e32 v80, v80, v81, vcc
	v_rsq_f32_e32 v80, v80
	v_lshlrev_b64 v[82:83], 11, v[112:113]
	v_lshl_add_u64 v[82:83], s[6:7], 0, v[82:83]
	v_mul_f32_e32 v81, 0x45800000, v80
	v_cndmask_b32_e32 v126, v80, v81, vcc
	v_lshlrev_b64 v[80:81], 12, v[112:113]
	v_lshl_add_u64 v[80:81], s[4:5], 0, v[80:81]
	v_lshl_add_u64 v[114:115], v[156:157], 2, v[80:81]
	v_lshl_add_u64 v[116:117], v[156:157], 1, v[82:83]
	global_load_dwordx4 v[92:95], v[114:115], off
	global_load_dwordx4 v[88:91], v[114:115], off offset:64
	global_load_dwordx4 v[84:87], v[114:115], off offset:512
	global_load_dwordx4 v[80:83], v[114:115], off offset:576
	global_load_dwordx2 v[122:123], v[116:117], off
	global_load_dwordx2 v[120:121], v[116:117], off offset:32
	global_load_dwordx2 v[118:119], v[116:117], off offset:256
	s_nop 0
	global_load_dwordx2 v[116:117], v[116:117], off offset:288
	s_nop 0
	global_load_dword v124, v[158:159], off offset:512
	v_pk_mul_f32 v[76:77], v[76:77], v[126:127] op_sel_hi:[1,0]
	v_lshlrev_b32_e32 v140, 16, v138
	v_mul_f32_e32 v76, 0xbfb8aa3b, v76
	v_exp_f32_e32 v125, v76
	v_mul_f32_e32 v76, 0xbfb8aa3b, v77
	v_exp_f32_e32 v127, v76
	v_and_b32_e32 v141, 0xffff0000, v138
	v_lshlrev_b32_e32 v138, 16, v136
	v_pk_mul_f32 v[72:73], v[72:73], v[126:127] op_sel_hi:[1,0]
	v_pk_mul_f32 v[76:77], v[78:79], v[126:127] op_sel_hi:[1,0]
	v_mul_f32_e32 v72, 0xbfb8aa3b, v72
	v_add_f32_e32 v78, 1.0, v125
	v_exp_f32_e32 v125, v72
	v_mul_f32_e32 v72, 0xbfb8aa3b, v73
	v_add_f32_e32 v79, 1.0, v127
	v_exp_f32_e32 v127, v72
	v_mul_f32_e32 v76, 0xbfb8aa3b, v76
	v_exp_f32_e32 v76, v76
	v_mul_f32_e32 v77, 0xbfb8aa3b, v77
	v_pk_mul_f32 v[68:69], v[68:69], v[126:127] op_sel_hi:[1,0]
	v_pk_mul_f32 v[72:73], v[74:75], v[126:127] op_sel_hi:[1,0]
	v_mul_f32_e32 v68, 0xbfb8aa3b, v68
	v_add_f32_e32 v74, 1.0, v125
	v_exp_f32_e32 v125, v68
	v_mul_f32_e32 v68, 0xbfb8aa3b, v69
	v_add_f32_e32 v75, 1.0, v127
	v_exp_f32_e32 v127, v68
	v_mul_f32_e32 v72, 0xbfb8aa3b, v72
	v_exp_f32_e32 v77, v77
	v_exp_f32_e32 v72, v72
	v_pk_mul_f32 v[64:65], v[64:65], v[126:127] op_sel_hi:[1,0]
	v_pk_mul_f32 v[68:69], v[70:71], v[126:127] op_sel_hi:[1,0]
	v_mul_f32_e32 v64, 0xbfb8aa3b, v64
	v_add_f32_e32 v70, 1.0, v125
	v_exp_f32_e32 v125, v64
	v_mul_f32_e32 v64, 0xbfb8aa3b, v65
	v_add_f32_e32 v71, 1.0, v127
	v_exp_f32_e32 v127, v64
	v_mul_f32_e32 v73, 0xbfb8aa3b, v73
	v_rcp_f32_e32 v78, v78
	v_rcp_f32_e32 v79, v79
	v_exp_f32_e32 v73, v73
	v_mul_f32_e32 v68, 0xbfb8aa3b, v68
	v_exp_f32_e32 v68, v68
	v_mul_f32_e32 v69, 0xbfb8aa3b, v69
	v_pk_mul_f32 v[64:65], v[66:67], v[126:127] op_sel_hi:[1,0]
	v_add_f32_e32 v76, 1.0, v76
	v_rcp_f32_e32 v74, v74
	v_rcp_f32_e32 v75, v75
	v_exp_f32_e32 v69, v69
	v_mul_f32_e32 v64, 0xbfb8aa3b, v64
	v_mul_f32_e32 v65, 0xbfb8aa3b, v65
	v_rcp_f32_e32 v142, v76
	v_add_f32_e32 v76, 1.0, v77
	v_add_f32_e32 v72, 1.0, v72
	v_exp_f32_e32 v64, v64
	v_exp_f32_e32 v65, v65
	v_rcp_f32_e32 v143, v76
	v_pk_fma_f32 v[76:77], v[78:79], v[140:141], v[108:109]
	v_rcp_f32_e32 v140, v72
	v_add_f32_e32 v72, 1.0, v73
	v_lshlrev_b32_e32 v78, 16, v139
	v_and_b32_e32 v79, 0xffff0000, v139
	v_and_b32_e32 v139, 0xffff0000, v136
	v_rcp_f32_e32 v141, v72
	v_add_f32_e32 v68, 1.0, v68
	v_pk_fma_f32 v[72:73], v[74:75], v[138:139], v[104:105]
	v_rcp_f32_e32 v70, v70
	v_rcp_f32_e32 v71, v71
	v_rcp_f32_e32 v138, v68
	v_add_f32_e32 v68, 1.0, v69
	v_add_f32_e32 v66, 1.0, v125
	v_add_f32_e32 v67, 1.0, v127
	v_rcp_f32_e32 v139, v68
	v_rcp_f32_e32 v66, v66
	v_rcp_f32_e32 v67, v67
	v_add_f32_e32 v64, 1.0, v64
	v_add_f32_e32 v65, 1.0, v65
	v_lshlrev_b32_e32 v74, 16, v137
	v_and_b32_e32 v75, 0xffff0000, v137
	v_rcp_f32_e32 v64, v64
	v_rcp_f32_e32 v65, v65
	v_pk_fma_f32 v[74:75], v[140:141], v[74:75], v[106:107]
	v_lshlrev_b32_e32 v136, 16, v134
	v_and_b32_e32 v137, 0xffff0000, v134
	v_pk_fma_f32 v[78:79], v[142:143], v[78:79], v[110:111]
	v_pk_mul_f32 v[104:105], v[72:73], v[72:73]
	v_pk_mul_f32 v[106:107], v[74:75], v[74:75]
	v_pk_fma_f32 v[68:69], v[70:71], v[136:137], v[100:101]
	v_lshlrev_b32_e32 v70, 16, v135
	v_and_b32_e32 v71, 0xffff0000, v135
	v_lshlrev_b32_e32 v126, 16, v132
	v_and_b32_e32 v127, 0xffff0000, v132
	v_pk_mul_f32 v[108:109], v[76:77], v[76:77]
	v_pk_mul_f32 v[110:111], v[78:79], v[78:79]
	v_pk_fma_f32 v[70:71], v[138:139], v[70:71], v[102:103]
	v_pk_fma_f32 v[96:97], v[66:67], v[126:127], v[96:97]
	v_lshlrev_b32_e32 v66, 16, v133
	v_and_b32_e32 v67, 0xffff0000, v133
	v_add_f32_e32 v106, v106, v107
	v_add_f32_e32 v104, v104, v105
	v_pk_mul_f32 v[100:101], v[68:69], v[68:69]
	v_pk_mul_f32 v[102:103], v[70:71], v[70:71]
	v_pk_fma_f32 v[98:99], v[64:65], v[66:67], v[98:99]
	v_add_f32_e32 v104, v104, v106
	v_add_f32_e32 v105, v110, v111
	v_add_f32_e32 v106, v108, v109
	v_pk_mul_f32 v[64:65], v[96:97], v[96:97]
	v_pk_mul_f32 v[66:67], v[98:99], v[98:99]
	v_add_f32_e32 v105, v106, v105
	v_add_f32_e32 v102, v102, v103
	v_add_f32_e32 v100, v100, v101
	v_add_f32_e32 v104, v105, v104
	v_add_f32_e32 v100, v100, v102
	v_add_f32_e32 v66, v66, v67
	v_add_f32_e32 v64, v64, v65
	v_add_f32_e32 v100, v100, v104
	v_add_f32_e32 v64, v64, v66
	v_add_f32_e32 v64, v64, v100
	ds_bpermute_b32 v65, v195, v64
	global_store_dwordx4 v[130:131], v[76:79], off
	global_store_dwordx4 v[130:131], v[72:75], off offset:64
	global_store_dwordx4 v[130:131], v[68:71], off offset:512
	global_store_dwordx4 v[130:131], v[96:99], off offset:576
	s_waitcnt lgkmcnt(0)
	v_add_f32_e32 v64, v64, v65
	ds_bpermute_b32 v65, v196, v64
	s_mov_b32 vcc_lo, 0x11111111
	s_mov_b32 vcc_hi, 0x11111111
	s_and_saveexec_b64 s[26:27], vcc
	s_cbranch_execz .LBB0_2129
	v_lshl_add_u64 v[66:67], v[128:129], 2, s[10:11]
	s_waitcnt lgkmcnt(0)
	v_add_f32_e32 v64, v64, v65
	global_atomic_add_f32 v[66:67], v64, off
.LBB0_2129:
	s_or_b64 exec, exec, s[26:27]
	s_waitcnt vmcnt(4)
	v_fmamk_f32 v64, v124, 0x3a800000, v193
	s_waitcnt lgkmcnt(0)
	v_mul_f32_e32 v65, 0x4b800000, v64
	v_cmp_gt_f32_e32 vcc, s55, v64
	v_or_b32_e32 v96, 16, v112
	v_ashrrev_i32_e32 v97, 31, v96
	v_cndmask_b32_e32 v64, v64, v65, vcc
	v_rsq_f32_e32 v64, v64
	v_lshlrev_b64 v[66:67], 11, v[96:97]
	v_lshl_add_u64 v[66:67], s[6:7], 0, v[66:67]
	v_mul_f32_e32 v65, 0x45800000, v64
	v_cndmask_b32_e32 v110, v64, v65, vcc
	v_lshlrev_b64 v[64:65], 12, v[96:97]
	v_lshl_add_u64 v[64:65], s[4:5], 0, v[64:65]
	v_lshl_add_u64 v[98:99], v[156:157], 2, v[64:65]
	v_lshl_add_u64 v[100:101], v[156:157], 1, v[66:67]
	global_load_dwordx4 v[76:79], v[98:99], off
	global_load_dwordx4 v[72:75], v[98:99], off offset:64
	global_load_dwordx4 v[68:71], v[98:99], off offset:512
	global_load_dwordx4 v[64:67], v[98:99], off offset:576
	global_load_dwordx2 v[106:107], v[100:101], off
	global_load_dwordx2 v[104:105], v[100:101], off offset:32
	global_load_dwordx2 v[102:103], v[100:101], off offset:256
	s_nop 0
	global_load_dwordx2 v[100:101], v[100:101], off offset:288
	v_lshl_add_u64 v[108:109], v[96:97], 2, s[12:13]
	global_load_dword v108, v[108:109], off
	v_pk_mul_f32 v[60:61], v[60:61], v[110:111] op_sel_hi:[1,0]
	v_lshlrev_b32_e32 v124, 16, v122
	v_mul_f32_e32 v60, 0xbfb8aa3b, v60
	v_exp_f32_e32 v109, v60
	v_mul_f32_e32 v60, 0xbfb8aa3b, v61
	v_exp_f32_e32 v111, v60
	v_and_b32_e32 v125, 0xffff0000, v122
	v_lshlrev_b32_e32 v122, 16, v120
	v_pk_mul_f32 v[56:57], v[56:57], v[110:111] op_sel_hi:[1,0]
	v_pk_mul_f32 v[60:61], v[62:63], v[110:111] op_sel_hi:[1,0]
	v_mul_f32_e32 v56, 0xbfb8aa3b, v56
	v_add_f32_e32 v62, 1.0, v109
	v_exp_f32_e32 v109, v56
	v_mul_f32_e32 v56, 0xbfb8aa3b, v57
	v_add_f32_e32 v63, 1.0, v111
	v_exp_f32_e32 v111, v56
	v_mul_f32_e32 v60, 0xbfb8aa3b, v60
	v_exp_f32_e32 v60, v60
	v_mul_f32_e32 v61, 0xbfb8aa3b, v61
	v_pk_mul_f32 v[52:53], v[52:53], v[110:111] op_sel_hi:[1,0]
	v_pk_mul_f32 v[56:57], v[58:59], v[110:111] op_sel_hi:[1,0]
	v_mul_f32_e32 v52, 0xbfb8aa3b, v52
	v_add_f32_e32 v58, 1.0, v109
	v_exp_f32_e32 v109, v52
	v_mul_f32_e32 v52, 0xbfb8aa3b, v53
	v_add_f32_e32 v59, 1.0, v111
	v_exp_f32_e32 v111, v52
	v_mul_f32_e32 v56, 0xbfb8aa3b, v56
	v_exp_f32_e32 v61, v61
	v_exp_f32_e32 v56, v56
	v_pk_mul_f32 v[48:49], v[48:49], v[110:111] op_sel_hi:[1,0]
	v_pk_mul_f32 v[52:53], v[54:55], v[110:111] op_sel_hi:[1,0]
	v_mul_f32_e32 v48, 0xbfb8aa3b, v48
	v_add_f32_e32 v54, 1.0, v109
	v_exp_f32_e32 v109, v48
	v_mul_f32_e32 v48, 0xbfb8aa3b, v49
	v_add_f32_e32 v55, 1.0, v111
	v_exp_f32_e32 v111, v48
	v_mul_f32_e32 v57, 0xbfb8aa3b, v57
	v_rcp_f32_e32 v62, v62
	v_rcp_f32_e32 v63, v63
	v_exp_f32_e32 v57, v57
	v_mul_f32_e32 v52, 0xbfb8aa3b, v52
	v_exp_f32_e32 v52, v52
	v_mul_f32_e32 v53, 0xbfb8aa3b, v53
	v_pk_mul_f32 v[48:49], v[50:51], v[110:111] op_sel_hi:[1,0]
	v_add_f32_e32 v60, 1.0, v60
	v_rcp_f32_e32 v58, v58
	v_rcp_f32_e32 v59, v59
	v_exp_f32_e32 v53, v53
	v_mul_f32_e32 v48, 0xbfb8aa3b, v48
	v_mul_f32_e32 v49, 0xbfb8aa3b, v49
	v_rcp_f32_e32 v126, v60
	v_add_f32_e32 v60, 1.0, v61
	v_add_f32_e32 v56, 1.0, v56
	v_exp_f32_e32 v48, v48
	v_exp_f32_e32 v49, v49
	v_rcp_f32_e32 v127, v60
	v_pk_fma_f32 v[60:61], v[62:63], v[124:125], v[92:93]
	v_rcp_f32_e32 v124, v56
	v_add_f32_e32 v56, 1.0, v57
	v_lshlrev_b32_e32 v62, 16, v123
	v_and_b32_e32 v63, 0xffff0000, v123
	v_and_b32_e32 v123, 0xffff0000, v120
	v_rcp_f32_e32 v125, v56
	v_add_f32_e32 v52, 1.0, v52
	v_pk_fma_f32 v[56:57], v[58:59], v[122:123], v[88:89]
	v_rcp_f32_e32 v54, v54
	v_rcp_f32_e32 v55, v55
	v_rcp_f32_e32 v122, v52
	v_add_f32_e32 v52, 1.0, v53
	v_add_f32_e32 v50, 1.0, v109
	v_add_f32_e32 v51, 1.0, v111
	v_rcp_f32_e32 v123, v52
	v_rcp_f32_e32 v50, v50
	v_rcp_f32_e32 v51, v51
	v_add_f32_e32 v48, 1.0, v48
	v_add_f32_e32 v49, 1.0, v49
	v_lshlrev_b32_e32 v58, 16, v121
	v_and_b32_e32 v59, 0xffff0000, v121
	v_rcp_f32_e32 v48, v48
	v_rcp_f32_e32 v49, v49
	v_pk_fma_f32 v[58:59], v[124:125], v[58:59], v[90:91]
	v_lshlrev_b32_e32 v120, 16, v118
	v_and_b32_e32 v121, 0xffff0000, v118
	v_pk_fma_f32 v[62:63], v[126:127], v[62:63], v[94:95]
	v_pk_mul_f32 v[88:89], v[56:57], v[56:57]
	v_pk_mul_f32 v[90:91], v[58:59], v[58:59]
	v_pk_fma_f32 v[52:53], v[54:55], v[120:121], v[84:85]
	v_lshlrev_b32_e32 v54, 16, v119
	v_and_b32_e32 v55, 0xffff0000, v119
	v_lshlrev_b32_e32 v110, 16, v116
	v_and_b32_e32 v111, 0xffff0000, v116
	v_pk_mul_f32 v[92:93], v[60:61], v[60:61]
	v_pk_mul_f32 v[94:95], v[62:63], v[62:63]
	v_pk_fma_f32 v[54:55], v[122:123], v[54:55], v[86:87]
	v_pk_fma_f32 v[80:81], v[50:51], v[110:111], v[80:81]
	v_lshlrev_b32_e32 v50, 16, v117
	v_and_b32_e32 v51, 0xffff0000, v117
	v_add_f32_e32 v90, v90, v91
	v_add_f32_e32 v88, v88, v89
	v_pk_mul_f32 v[84:85], v[52:53], v[52:53]
	v_pk_mul_f32 v[86:87], v[54:55], v[54:55]
	v_pk_fma_f32 v[82:83], v[48:49], v[50:51], v[82:83]
	v_add_f32_e32 v88, v88, v90
	v_add_f32_e32 v89, v94, v95
	v_add_f32_e32 v90, v92, v93
	v_pk_mul_f32 v[48:49], v[80:81], v[80:81]
	v_pk_mul_f32 v[50:51], v[82:83], v[82:83]
	v_add_f32_e32 v89, v90, v89
	v_add_f32_e32 v86, v86, v87
	v_add_f32_e32 v84, v84, v85
	v_add_f32_e32 v88, v89, v88
	v_add_f32_e32 v84, v84, v86
	v_add_f32_e32 v50, v50, v51
	v_add_f32_e32 v48, v48, v49
	v_add_f32_e32 v84, v84, v88
	v_add_f32_e32 v48, v48, v50
	v_add_f32_e32 v48, v48, v84
	ds_bpermute_b32 v49, v195, v48
	global_store_dwordx4 v[114:115], v[60:63], off
	global_store_dwordx4 v[114:115], v[56:59], off offset:64
	global_store_dwordx4 v[114:115], v[52:55], off offset:512
	global_store_dwordx4 v[114:115], v[80:83], off offset:576
	s_waitcnt lgkmcnt(0)
	v_add_f32_e32 v48, v48, v49
	ds_bpermute_b32 v49, v196, v48
	s_mov_b32 vcc_lo, 0x11111111
	s_mov_b32 vcc_hi, 0x11111111
	s_and_saveexec_b64 s[26:27], vcc
	s_cbranch_execz .LBB0_2131
	v_lshl_add_u64 v[50:51], v[112:113], 2, s[10:11]
	s_waitcnt lgkmcnt(0)
	v_add_f32_e32 v48, v48, v49
	global_atomic_add_f32 v[50:51], v48, off
.LBB0_2131:
	s_or_b64 exec, exec, s[26:27]
	s_waitcnt vmcnt(4)
	v_fmamk_f32 v48, v108, 0x3a800000, v193
	s_waitcnt lgkmcnt(0)
	v_mul_f32_e32 v49, 0x4b800000, v48
	v_cmp_gt_f32_e32 vcc, s55, v48
	v_or_b32_e32 v80, 32, v112
	v_ashrrev_i32_e32 v81, 31, v80
	v_cndmask_b32_e32 v48, v48, v49, vcc
	v_rsq_f32_e32 v48, v48
	v_lshlrev_b64 v[50:51], 11, v[80:81]
	v_lshl_add_u64 v[50:51], s[6:7], 0, v[50:51]
	v_mul_f32_e32 v49, 0x45800000, v48
	v_cndmask_b32_e32 v94, v48, v49, vcc
	v_lshlrev_b64 v[48:49], 12, v[80:81]
	v_lshl_add_u64 v[48:49], s[4:5], 0, v[48:49]
	v_lshl_add_u64 v[82:83], v[156:157], 2, v[48:49]
	v_lshl_add_u64 v[84:85], v[156:157], 1, v[50:51]
	global_load_dwordx4 v[60:63], v[82:83], off
	global_load_dwordx4 v[56:59], v[82:83], off offset:64
	global_load_dwordx4 v[52:55], v[82:83], off offset:512
	global_load_dwordx4 v[48:51], v[82:83], off offset:576
	global_load_dwordx2 v[90:91], v[84:85], off
	global_load_dwordx2 v[88:89], v[84:85], off offset:32
	global_load_dwordx2 v[86:87], v[84:85], off offset:256
	s_nop 0
	global_load_dwordx2 v[84:85], v[84:85], off offset:288
	v_lshl_add_u64 v[92:93], v[80:81], 2, s[12:13]
	global_load_dword v92, v[92:93], off
	v_pk_mul_f32 v[44:45], v[44:45], v[94:95] op_sel_hi:[1,0]
	v_lshlrev_b32_e32 v108, 16, v106
	v_mul_f32_e32 v44, 0xbfb8aa3b, v44
	v_exp_f32_e32 v93, v44
	v_mul_f32_e32 v44, 0xbfb8aa3b, v45
	v_exp_f32_e32 v95, v44
	v_and_b32_e32 v109, 0xffff0000, v106
	v_lshlrev_b32_e32 v106, 16, v104
	v_pk_mul_f32 v[40:41], v[40:41], v[94:95] op_sel_hi:[1,0]
	v_pk_mul_f32 v[44:45], v[46:47], v[94:95] op_sel_hi:[1,0]
	v_mul_f32_e32 v40, 0xbfb8aa3b, v40
	v_add_f32_e32 v46, 1.0, v93
	v_exp_f32_e32 v93, v40
	v_mul_f32_e32 v40, 0xbfb8aa3b, v41
	v_add_f32_e32 v47, 1.0, v95
	v_exp_f32_e32 v95, v40
	v_mul_f32_e32 v44, 0xbfb8aa3b, v44
	v_exp_f32_e32 v44, v44
	v_mul_f32_e32 v45, 0xbfb8aa3b, v45
	v_pk_mul_f32 v[36:37], v[36:37], v[94:95] op_sel_hi:[1,0]
	v_pk_mul_f32 v[40:41], v[42:43], v[94:95] op_sel_hi:[1,0]
	v_mul_f32_e32 v36, 0xbfb8aa3b, v36
	v_add_f32_e32 v42, 1.0, v93
	v_exp_f32_e32 v93, v36
	v_mul_f32_e32 v36, 0xbfb8aa3b, v37
	v_add_f32_e32 v43, 1.0, v95
	v_exp_f32_e32 v95, v36
	v_mul_f32_e32 v40, 0xbfb8aa3b, v40
	v_exp_f32_e32 v45, v45
	v_exp_f32_e32 v40, v40
	v_pk_mul_f32 v[32:33], v[32:33], v[94:95] op_sel_hi:[1,0]
	v_pk_mul_f32 v[36:37], v[38:39], v[94:95] op_sel_hi:[1,0]
	v_mul_f32_e32 v32, 0xbfb8aa3b, v32
	v_add_f32_e32 v38, 1.0, v93
	v_exp_f32_e32 v93, v32
	v_mul_f32_e32 v32, 0xbfb8aa3b, v33
	v_add_f32_e32 v39, 1.0, v95
	v_exp_f32_e32 v95, v32
	v_mul_f32_e32 v41, 0xbfb8aa3b, v41
	v_rcp_f32_e32 v46, v46
	v_rcp_f32_e32 v47, v47
	v_exp_f32_e32 v41, v41
	v_mul_f32_e32 v36, 0xbfb8aa3b, v36
	v_exp_f32_e32 v36, v36
	v_mul_f32_e32 v37, 0xbfb8aa3b, v37
	v_pk_mul_f32 v[32:33], v[34:35], v[94:95] op_sel_hi:[1,0]
	v_add_f32_e32 v44, 1.0, v44
	v_rcp_f32_e32 v42, v42
	v_rcp_f32_e32 v43, v43
	v_exp_f32_e32 v37, v37
	v_mul_f32_e32 v32, 0xbfb8aa3b, v32
	v_mul_f32_e32 v33, 0xbfb8aa3b, v33
	v_rcp_f32_e32 v110, v44
	v_add_f32_e32 v44, 1.0, v45
	v_add_f32_e32 v40, 1.0, v40
	v_exp_f32_e32 v32, v32
	v_exp_f32_e32 v33, v33
	v_rcp_f32_e32 v111, v44
	v_pk_fma_f32 v[44:45], v[46:47], v[108:109], v[76:77]
	v_rcp_f32_e32 v108, v40
	v_add_f32_e32 v40, 1.0, v41
	v_lshlrev_b32_e32 v46, 16, v107
	v_and_b32_e32 v47, 0xffff0000, v107
	v_and_b32_e32 v107, 0xffff0000, v104
	v_rcp_f32_e32 v109, v40
	v_add_f32_e32 v36, 1.0, v36
	v_pk_fma_f32 v[40:41], v[42:43], v[106:107], v[72:73]
	v_rcp_f32_e32 v38, v38
	v_rcp_f32_e32 v39, v39
	v_rcp_f32_e32 v106, v36
	v_add_f32_e32 v36, 1.0, v37
	v_add_f32_e32 v34, 1.0, v93
	v_add_f32_e32 v35, 1.0, v95
	v_rcp_f32_e32 v107, v36
	v_rcp_f32_e32 v34, v34
	v_rcp_f32_e32 v35, v35
	v_add_f32_e32 v32, 1.0, v32
	v_add_f32_e32 v33, 1.0, v33
	v_lshlrev_b32_e32 v42, 16, v105
	v_and_b32_e32 v43, 0xffff0000, v105
	v_rcp_f32_e32 v32, v32
	v_rcp_f32_e32 v33, v33
	v_pk_fma_f32 v[42:43], v[108:109], v[42:43], v[74:75]
	v_lshlrev_b32_e32 v104, 16, v102
	v_and_b32_e32 v105, 0xffff0000, v102
	v_pk_fma_f32 v[46:47], v[110:111], v[46:47], v[78:79]
	v_pk_mul_f32 v[72:73], v[40:41], v[40:41]
	v_pk_mul_f32 v[74:75], v[42:43], v[42:43]
	v_pk_fma_f32 v[36:37], v[38:39], v[104:105], v[68:69]
	v_lshlrev_b32_e32 v38, 16, v103
	v_and_b32_e32 v39, 0xffff0000, v103
	v_lshlrev_b32_e32 v94, 16, v100
	v_and_b32_e32 v95, 0xffff0000, v100
	v_pk_mul_f32 v[76:77], v[44:45], v[44:45]
	v_pk_mul_f32 v[78:79], v[46:47], v[46:47]
	v_pk_fma_f32 v[38:39], v[106:107], v[38:39], v[70:71]
	v_pk_fma_f32 v[64:65], v[34:35], v[94:95], v[64:65]
	v_lshlrev_b32_e32 v34, 16, v101
	v_and_b32_e32 v35, 0xffff0000, v101
	v_add_f32_e32 v74, v74, v75
	v_add_f32_e32 v72, v72, v73
	v_pk_mul_f32 v[68:69], v[36:37], v[36:37]
	v_pk_mul_f32 v[70:71], v[38:39], v[38:39]
	v_pk_fma_f32 v[66:67], v[32:33], v[34:35], v[66:67]
	v_add_f32_e32 v72, v72, v74
	v_add_f32_e32 v73, v78, v79
	v_add_f32_e32 v74, v76, v77
	v_pk_mul_f32 v[32:33], v[64:65], v[64:65]
	v_pk_mul_f32 v[34:35], v[66:67], v[66:67]
	v_add_f32_e32 v73, v74, v73
	v_add_f32_e32 v70, v70, v71
	v_add_f32_e32 v68, v68, v69
	v_add_f32_e32 v72, v73, v72
	v_add_f32_e32 v68, v68, v70
	v_add_f32_e32 v34, v34, v35
	v_add_f32_e32 v32, v32, v33
	v_add_f32_e32 v68, v68, v72
	v_add_f32_e32 v32, v32, v34
	v_add_f32_e32 v32, v32, v68
	ds_bpermute_b32 v33, v195, v32
	global_store_dwordx4 v[98:99], v[44:47], off
	global_store_dwordx4 v[98:99], v[40:43], off offset:64
	global_store_dwordx4 v[98:99], v[36:39], off offset:512
	global_store_dwordx4 v[98:99], v[64:67], off offset:576
	s_waitcnt lgkmcnt(0)
	v_add_f32_e32 v32, v32, v33
	ds_bpermute_b32 v33, v196, v32
	s_mov_b32 vcc_lo, 0x11111111
	s_mov_b32 vcc_hi, 0x11111111
	s_and_saveexec_b64 s[26:27], vcc
	s_cbranch_execz .LBB0_2133
	v_lshl_add_u64 v[34:35], v[96:97], 2, s[10:11]
	s_waitcnt lgkmcnt(0)
	v_add_f32_e32 v32, v32, v33
	global_atomic_add_f32 v[34:35], v32, off
.LBB0_2133:
	s_or_b64 exec, exec, s[26:27]
	s_waitcnt vmcnt(4)
	v_fmamk_f32 v32, v92, 0x3a800000, v193
	s_waitcnt lgkmcnt(0)
	v_mul_f32_e32 v33, 0x4b800000, v32
	v_cmp_gt_f32_e32 vcc, s55, v32
	v_or_b32_e32 v64, 48, v112
	v_ashrrev_i32_e32 v65, 31, v64
	v_cndmask_b32_e32 v32, v32, v33, vcc
	v_rsq_f32_e32 v32, v32
	v_lshlrev_b64 v[34:35], 11, v[64:65]
	v_lshl_add_u64 v[34:35], s[6:7], 0, v[34:35]
	v_mul_f32_e32 v33, 0x45800000, v32
	v_cndmask_b32_e32 v78, v32, v33, vcc
	v_lshlrev_b64 v[32:33], 12, v[64:65]
	v_lshl_add_u64 v[32:33], s[4:5], 0, v[32:33]
	v_lshl_add_u64 v[66:67], v[156:157], 2, v[32:33]
	v_lshl_add_u64 v[68:69], v[156:157], 1, v[34:35]
	global_load_dwordx4 v[44:47], v[66:67], off
	global_load_dwordx4 v[40:43], v[66:67], off offset:64
	global_load_dwordx4 v[36:39], v[66:67], off offset:512
	global_load_dwordx4 v[32:35], v[66:67], off offset:576
	global_load_dwordx2 v[74:75], v[68:69], off
	global_load_dwordx2 v[72:73], v[68:69], off offset:32
	global_load_dwordx2 v[70:71], v[68:69], off offset:256
	s_nop 0
	global_load_dwordx2 v[68:69], v[68:69], off offset:288
	v_lshl_add_u64 v[76:77], v[64:65], 2, s[12:13]
	global_load_dword v76, v[76:77], off
	v_pk_mul_f32 v[28:29], v[28:29], v[78:79] op_sel_hi:[1,0]
	v_lshlrev_b32_e32 v92, 16, v90
	v_mul_f32_e32 v28, 0xbfb8aa3b, v28
	v_exp_f32_e32 v77, v28
	v_mul_f32_e32 v28, 0xbfb8aa3b, v29
	v_exp_f32_e32 v79, v28
	v_and_b32_e32 v93, 0xffff0000, v90
	v_lshlrev_b32_e32 v90, 16, v88
	v_pk_mul_f32 v[24:25], v[24:25], v[78:79] op_sel_hi:[1,0]
	v_pk_mul_f32 v[28:29], v[30:31], v[78:79] op_sel_hi:[1,0]
	v_mul_f32_e32 v24, 0xbfb8aa3b, v24
	v_add_f32_e32 v30, 1.0, v77
	v_exp_f32_e32 v77, v24
	v_mul_f32_e32 v24, 0xbfb8aa3b, v25
	v_add_f32_e32 v31, 1.0, v79
	v_exp_f32_e32 v79, v24
	v_mul_f32_e32 v28, 0xbfb8aa3b, v28
	v_exp_f32_e32 v28, v28
	v_mul_f32_e32 v29, 0xbfb8aa3b, v29
	v_pk_mul_f32 v[20:21], v[20:21], v[78:79] op_sel_hi:[1,0]
	v_pk_mul_f32 v[24:25], v[26:27], v[78:79] op_sel_hi:[1,0]
	v_mul_f32_e32 v20, 0xbfb8aa3b, v20
	v_add_f32_e32 v26, 1.0, v77
	v_exp_f32_e32 v77, v20
	v_mul_f32_e32 v20, 0xbfb8aa3b, v21
	v_add_f32_e32 v27, 1.0, v79
	v_exp_f32_e32 v79, v20
	v_mul_f32_e32 v24, 0xbfb8aa3b, v24
	v_exp_f32_e32 v29, v29
	v_exp_f32_e32 v24, v24
	v_pk_mul_f32 v[16:17], v[16:17], v[78:79] op_sel_hi:[1,0]
	v_pk_mul_f32 v[20:21], v[22:23], v[78:79] op_sel_hi:[1,0]
	v_mul_f32_e32 v16, 0xbfb8aa3b, v16
	v_add_f32_e32 v22, 1.0, v77
	v_exp_f32_e32 v77, v16
	v_mul_f32_e32 v16, 0xbfb8aa3b, v17
	v_add_f32_e32 v23, 1.0, v79
	v_exp_f32_e32 v79, v16
	v_mul_f32_e32 v25, 0xbfb8aa3b, v25
	v_rcp_f32_e32 v30, v30
	v_rcp_f32_e32 v31, v31
	v_exp_f32_e32 v25, v25
	v_mul_f32_e32 v20, 0xbfb8aa3b, v20
	v_exp_f32_e32 v20, v20
	v_mul_f32_e32 v21, 0xbfb8aa3b, v21
	v_pk_mul_f32 v[16:17], v[18:19], v[78:79] op_sel_hi:[1,0]
	v_add_f32_e32 v28, 1.0, v28
	v_rcp_f32_e32 v26, v26
	v_rcp_f32_e32 v27, v27
	v_exp_f32_e32 v21, v21
	v_mul_f32_e32 v16, 0xbfb8aa3b, v16
	v_mul_f32_e32 v17, 0xbfb8aa3b, v17
	v_rcp_f32_e32 v94, v28
	v_add_f32_e32 v28, 1.0, v29
	v_add_f32_e32 v24, 1.0, v24
	v_exp_f32_e32 v16, v16
	v_exp_f32_e32 v17, v17
	v_rcp_f32_e32 v95, v28
	v_pk_fma_f32 v[28:29], v[30:31], v[92:93], v[60:61]
	v_rcp_f32_e32 v92, v24
	v_add_f32_e32 v24, 1.0, v25
	v_lshlrev_b32_e32 v30, 16, v91
	v_and_b32_e32 v31, 0xffff0000, v91
	v_and_b32_e32 v91, 0xffff0000, v88
	v_rcp_f32_e32 v93, v24
	v_add_f32_e32 v20, 1.0, v20
	v_pk_fma_f32 v[24:25], v[26:27], v[90:91], v[56:57]
	v_rcp_f32_e32 v22, v22
	v_rcp_f32_e32 v23, v23
	v_rcp_f32_e32 v90, v20
	v_add_f32_e32 v20, 1.0, v21
	v_add_f32_e32 v18, 1.0, v77
	v_add_f32_e32 v19, 1.0, v79
	v_rcp_f32_e32 v91, v20
	v_rcp_f32_e32 v18, v18
	v_rcp_f32_e32 v19, v19
	v_add_f32_e32 v16, 1.0, v16
	v_add_f32_e32 v17, 1.0, v17
	v_lshlrev_b32_e32 v26, 16, v89
	v_and_b32_e32 v27, 0xffff0000, v89
	v_rcp_f32_e32 v16, v16
	v_rcp_f32_e32 v17, v17
	v_pk_fma_f32 v[26:27], v[92:93], v[26:27], v[58:59]
	v_lshlrev_b32_e32 v88, 16, v86
	v_and_b32_e32 v89, 0xffff0000, v86
	v_pk_fma_f32 v[30:31], v[94:95], v[30:31], v[62:63]
	v_pk_mul_f32 v[56:57], v[24:25], v[24:25]
	v_pk_mul_f32 v[58:59], v[26:27], v[26:27]
	v_pk_fma_f32 v[20:21], v[22:23], v[88:89], v[52:53]
	v_lshlrev_b32_e32 v22, 16, v87
	v_and_b32_e32 v23, 0xffff0000, v87
	v_lshlrev_b32_e32 v78, 16, v84
	v_and_b32_e32 v79, 0xffff0000, v84
	v_pk_mul_f32 v[60:61], v[28:29], v[28:29]
	v_pk_mul_f32 v[62:63], v[30:31], v[30:31]
	v_pk_fma_f32 v[22:23], v[90:91], v[22:23], v[54:55]
	v_pk_fma_f32 v[48:49], v[18:19], v[78:79], v[48:49]
	v_lshlrev_b32_e32 v18, 16, v85
	v_and_b32_e32 v19, 0xffff0000, v85
	v_add_f32_e32 v58, v58, v59
	v_add_f32_e32 v56, v56, v57
	v_pk_mul_f32 v[52:53], v[20:21], v[20:21]
	v_pk_mul_f32 v[54:55], v[22:23], v[22:23]
	v_pk_fma_f32 v[50:51], v[16:17], v[18:19], v[50:51]
	v_add_f32_e32 v56, v56, v58
	v_add_f32_e32 v57, v62, v63
	v_add_f32_e32 v58, v60, v61
	v_pk_mul_f32 v[16:17], v[48:49], v[48:49]
	v_pk_mul_f32 v[18:19], v[50:51], v[50:51]
	v_add_f32_e32 v57, v58, v57
	v_add_f32_e32 v54, v54, v55
	v_add_f32_e32 v52, v52, v53
	v_add_f32_e32 v56, v57, v56
	v_add_f32_e32 v52, v52, v54
	v_add_f32_e32 v18, v18, v19
	v_add_f32_e32 v16, v16, v17
	v_add_f32_e32 v52, v52, v56
	v_add_f32_e32 v16, v16, v18
	v_add_f32_e32 v16, v16, v52
	ds_bpermute_b32 v17, v195, v16
	global_store_dwordx4 v[82:83], v[28:31], off
	global_store_dwordx4 v[82:83], v[24:27], off offset:64
	global_store_dwordx4 v[82:83], v[20:23], off offset:512
	global_store_dwordx4 v[82:83], v[48:51], off offset:576
	s_waitcnt lgkmcnt(0)
	v_add_f32_e32 v16, v16, v17
	ds_bpermute_b32 v17, v196, v16
	s_mov_b32 vcc_lo, 0x11111111
	s_mov_b32 vcc_hi, 0x11111111
	s_and_saveexec_b64 s[26:27], vcc
	s_cbranch_execz .LBB0_2135
	v_lshl_add_u64 v[18:19], v[80:81], 2, s[10:11]
	s_waitcnt lgkmcnt(0)
	v_add_f32_e32 v16, v16, v17
	global_atomic_add_f32 v[18:19], v16, off
.LBB0_2135:
	s_or_b64 exec, exec, s[26:27]
	s_waitcnt vmcnt(4)
	v_fmamk_f32 v16, v76, 0x3a800000, v193
	s_waitcnt lgkmcnt(0)
	v_mul_f32_e32 v17, 0x4b800000, v16
	v_cmp_gt_f32_e32 vcc, s55, v16
	v_and_b32_e32 v19, 0xffff0000, v74
	s_nop 0
	v_cndmask_b32_e32 v16, v16, v17, vcc
	v_rsq_f32_e32 v16, v16
	s_nop 0
	v_mul_f32_e32 v17, 0x45800000, v16
	v_cndmask_b32_e32 v16, v16, v17, vcc
	v_pk_mul_f32 v[12:13], v[12:13], v[16:17] op_sel_hi:[1,0]
	s_nop 0
	v_mul_f32_e32 v12, 0xbfb8aa3b, v12
	v_exp_f32_e32 v17, v12
	v_mul_f32_e32 v13, 0xbfb8aa3b, v13
	v_exp_f32_e32 v18, v13
	v_pk_mul_f32 v[12:13], v[14:15], v[16:17] op_sel_hi:[1,0]
	s_nop 0
	v_mul_f32_e32 v12, 0xbfb8aa3b, v12
	v_exp_f32_e32 v12, v12
	v_mul_f32_e32 v13, 0xbfb8aa3b, v13
	v_add_f32_e32 v14, 1.0, v17
	v_add_f32_e32 v15, 1.0, v18
	v_exp_f32_e32 v13, v13
	v_pk_mul_f32 v[8:9], v[8:9], v[16:17] op_sel_hi:[1,0]
	v_rcp_f32_e32 v14, v14
	v_rcp_f32_e32 v15, v15
	v_mul_f32_e32 v8, 0xbfb8aa3b, v8
	v_exp_f32_e32 v17, v8
	v_add_f32_e32 v12, 1.0, v12
	v_lshlrev_b32_e32 v18, 16, v74
	v_rcp_f32_e32 v20, v12
	v_add_f32_e32 v12, 1.0, v13
	v_mul_f32_e32 v8, 0xbfb8aa3b, v9
	v_rcp_f32_e32 v21, v12
	v_pk_fma_f32 v[12:13], v[14:15], v[18:19], v[44:45]
	v_exp_f32_e32 v18, v8
	v_pk_mul_f32 v[8:9], v[10:11], v[16:17] op_sel_hi:[1,0]
	v_add_f32_e32 v10, 1.0, v17
	v_mul_f32_e32 v8, 0xbfb8aa3b, v8
	v_exp_f32_e32 v8, v8
	v_mul_f32_e32 v9, 0xbfb8aa3b, v9
	v_add_f32_e32 v11, 1.0, v18
	v_exp_f32_e32 v9, v9
	v_pk_mul_f32 v[4:5], v[4:5], v[16:17] op_sel_hi:[1,0]
	v_rcp_f32_e32 v10, v10
	v_rcp_f32_e32 v11, v11
	v_mul_f32_e32 v4, 0xbfb8aa3b, v4
	v_exp_f32_e32 v17, v4
	v_add_f32_e32 v8, 1.0, v8
	v_lshlrev_b32_e32 v18, 16, v72
	v_and_b32_e32 v19, 0xffff0000, v72
	v_rcp_f32_e32 v24, v8
	v_add_f32_e32 v8, 1.0, v9
	v_mul_f32_e32 v4, 0xbfb8aa3b, v5
	v_rcp_f32_e32 v25, v8
	v_pk_fma_f32 v[8:9], v[10:11], v[18:19], v[40:41]
	v_exp_f32_e32 v18, v4
	v_pk_mul_f32 v[4:5], v[6:7], v[16:17] op_sel_hi:[1,0]
	v_pk_mul_f32 v[0:1], v[0:1], v[16:17] op_sel_hi:[1,0]
	v_mul_f32_e32 v4, 0xbfb8aa3b, v4
	v_exp_f32_e32 v4, v4
	v_mul_f32_e32 v5, 0xbfb8aa3b, v5
	v_add_f32_e32 v6, 1.0, v17
	v_add_f32_e32 v7, 1.0, v18
	v_exp_f32_e32 v5, v5
	v_mul_f32_e32 v0, 0xbfb8aa3b, v0
	v_rcp_f32_e32 v6, v6
	v_rcp_f32_e32 v7, v7
	v_exp_f32_e32 v17, v0
	v_add_f32_e32 v4, 1.0, v4
	v_lshlrev_b32_e32 v18, 16, v70
	v_and_b32_e32 v19, 0xffff0000, v70
	v_rcp_f32_e32 v28, v4
	v_add_f32_e32 v4, 1.0, v5
	v_mul_f32_e32 v0, 0xbfb8aa3b, v1
	v_rcp_f32_e32 v29, v4
	v_pk_fma_f32 v[4:5], v[6:7], v[18:19], v[36:37]
	v_exp_f32_e32 v18, v0
	v_pk_mul_f32 v[0:1], v[2:3], v[16:17] op_sel_hi:[1,0]
	v_add_f32_e32 v2, 1.0, v17
	v_mul_f32_e32 v0, 0xbfb8aa3b, v0
	v_mul_f32_e32 v1, 0xbfb8aa3b, v1
	v_exp_f32_e32 v0, v0
	v_exp_f32_e32 v1, v1
	v_add_f32_e32 v3, 1.0, v18
	v_rcp_f32_e32 v2, v2
	v_rcp_f32_e32 v3, v3
	v_add_f32_e32 v0, 1.0, v0
	v_add_f32_e32 v1, 1.0, v1
	v_rcp_f32_e32 v0, v0
	v_rcp_f32_e32 v1, v1
	v_lshlrev_b32_e32 v14, 16, v75
	v_and_b32_e32 v15, 0xffff0000, v75
	v_lshlrev_b32_e32 v10, 16, v73
	v_and_b32_e32 v11, 0xffff0000, v73
	v_pk_fma_f32 v[14:15], v[20:21], v[14:15], v[46:47]
	v_pk_fma_f32 v[10:11], v[24:25], v[10:11], v[42:43]
	v_lshlrev_b32_e32 v6, 16, v71
	v_and_b32_e32 v7, 0xffff0000, v71
	v_lshlrev_b32_e32 v16, 16, v68
	v_and_b32_e32 v17, 0xffff0000, v68
	v_pk_mul_f32 v[20:21], v[12:13], v[12:13]
	v_pk_mul_f32 v[22:23], v[14:15], v[14:15]
	v_pk_mul_f32 v[24:25], v[8:9], v[8:9]
	v_pk_mul_f32 v[26:27], v[10:11], v[10:11]
	v_pk_fma_f32 v[6:7], v[28:29], v[6:7], v[38:39]
	v_pk_fma_f32 v[16:17], v[2:3], v[16:17], v[32:33]
	v_lshlrev_b32_e32 v2, 16, v69
	v_and_b32_e32 v3, 0xffff0000, v69
	v_pk_mul_f32 v[28:29], v[4:5], v[4:5]
	v_pk_mul_f32 v[30:31], v[6:7], v[6:7]
	v_pk_fma_f32 v[18:19], v[0:1], v[2:3], v[34:35]
	v_add_f32_e32 v26, v26, v27
	v_add_f32_e32 v24, v24, v25
	v_add_f32_e32 v22, v22, v23
	v_add_f32_e32 v20, v20, v21
	v_pk_mul_f32 v[0:1], v[16:17], v[16:17]
	v_pk_mul_f32 v[2:3], v[18:19], v[18:19]
	v_add_f32_e32 v24, v24, v26
	v_add_f32_e32 v20, v20, v22
	v_add_f32_e32 v21, v30, v31
	v_add_f32_e32 v22, v28, v29
	v_add_f32_e32 v20, v20, v24
	v_add_f32_e32 v21, v22, v21
	v_add_f32_e32 v2, v2, v3
	v_add_f32_e32 v0, v0, v1
	v_add_f32_e32 v20, v21, v20
	v_add_f32_e32 v0, v0, v2
	v_add_f32_e32 v0, v0, v20
	ds_bpermute_b32 v1, v195, v0
	global_store_dwordx4 v[66:67], v[12:15], off
	global_store_dwordx4 v[66:67], v[8:11], off offset:64
	global_store_dwordx4 v[66:67], v[4:7], off offset:512
	global_store_dwordx4 v[66:67], v[16:19], off offset:576
	s_waitcnt lgkmcnt(0)
	v_add_f32_e32 v0, v0, v1
	ds_bpermute_b32 v1, v196, v0
	s_mov_b32 vcc_lo, 0x11111111
	s_mov_b32 vcc_hi, 0x11111111
	s_and_saveexec_b64 s[26:27], vcc
	s_cbranch_execz .LBB0_2137
	v_lshl_add_u64 v[2:3], v[64:65], 2, s[10:11]
	s_waitcnt lgkmcnt(0)
	v_add_f32_e32 v0, v0, v1
	global_atomic_add_f32 v[2:3], v0, off
